# GEMM K-loops: the per-load 64-bit VALU address adds replaced by saddr-form LDS-DMA loads (SGPR base + 32-bit VGPR offset; +128 offsets precomputed once per tile), 12-14 VALU ops fewer per loop body
# speedup vs baseline: 1.0053x; 1.0053x over previous
.LBB0_196:
	s_ashr_i32 s79, s78, 31
	s_lshl_b64 s[12:13], s[78:79], 19
	s_add_u32 s80, s19, s12
	s_addc_u32 s81, s66, s13
	s_and_b64 s[12:13], s[6:7], exec
	s_cselect_b32 s15, s81, s9
	s_cselect_b32 s23, s80, s8
	s_ashr_i32 s77, s76, 31
	s_lshl_b64 s[12:13], s[76:77], 19
	s_add_u32 s82, s67, s12
	s_addc_u32 s83, s88, s13
	s_and_b64 s[12:13], s[6:7], exec
	s_cselect_b32 s77, s83, s85
	s_cselect_b32 s79, s82, s84
	s_add_u32 s8, s8, 0x40080
	s_addc_u32 s9, s9, 0
	s_add_u32 vcc_lo, s84, 0x100
	v_mov_b32_e32 v2, 0
	s_addc_u32 vcc_hi, s85, 0
	s_mov_b32 s12, -2
	v_mov_b32_e32 v3, v2
	v_mov_b32_e32 v4, v2
	v_mov_b32_e32 v5, v2
	v_mov_b32_e32 v6, v2
	v_mov_b32_e32 v7, v2
	v_mov_b32_e32 v8, v2
	v_mov_b32_e32 v9, v2
	v_mov_b32_e32 v18, v2
	v_mov_b32_e32 v19, v2
	v_mov_b32_e32 v20, v2
	v_mov_b32_e32 v21, v2
	v_mov_b32_e32 v22, v2
	v_mov_b32_e32 v23, v2
	v_mov_b32_e32 v24, v2
	v_mov_b32_e32 v25, v2
	v_mov_b32_e32 v50, v2
	v_mov_b32_e32 v51, v2
	v_mov_b32_e32 v52, v2
	v_mov_b32_e32 v53, v2
	v_mov_b32_e32 v54, v2
	v_mov_b32_e32 v55, v2
	v_mov_b32_e32 v56, v2
	v_mov_b32_e32 v57, v2
	v_mov_b32_e32 v66, v2
	v_mov_b32_e32 v67, v2
	v_mov_b32_e32 v68, v2
	v_mov_b32_e32 v69, v2
	v_mov_b32_e32 v70, v2
	v_mov_b32_e32 v71, v2
	v_mov_b32_e32 v72, v2
	v_mov_b32_e32 v73, v2
	v_mov_b32_e32 v10, v2
	v_mov_b32_e32 v11, v2
	v_mov_b32_e32 v12, v2
	v_mov_b32_e32 v13, v2
	v_mov_b32_e32 v14, v2
	v_mov_b32_e32 v15, v2
	v_mov_b32_e32 v16, v2
	v_mov_b32_e32 v17, v2
	v_mov_b32_e32 v26, v2
	v_mov_b32_e32 v27, v2
	v_mov_b32_e32 v28, v2
	v_mov_b32_e32 v29, v2
	v_mov_b32_e32 v30, v2
	v_mov_b32_e32 v31, v2
	v_mov_b32_e32 v32, v2
	v_mov_b32_e32 v33, v2
	v_mov_b32_e32 v58, v2
	v_mov_b32_e32 v59, v2
	v_mov_b32_e32 v60, v2
	v_mov_b32_e32 v61, v2
	v_mov_b32_e32 v62, v2
	v_mov_b32_e32 v63, v2
	v_mov_b32_e32 v64, v2
	v_mov_b32_e32 v65, v2
	v_mov_b32_e32 v74, v2
	v_mov_b32_e32 v75, v2
	v_mov_b32_e32 v76, v2
	v_mov_b32_e32 v77, v2
	v_mov_b32_e32 v78, v2
	v_mov_b32_e32 v79, v2
	v_mov_b32_e32 v80, v2
	v_mov_b32_e32 v81, v2
	v_mov_b32_e32 v82, v2
	v_mov_b32_e32 v83, v2
	v_mov_b32_e32 v84, v2
	v_mov_b32_e32 v85, v2
	v_mov_b32_e32 v86, v2
	v_mov_b32_e32 v87, v2
	v_mov_b32_e32 v88, v2
	v_mov_b32_e32 v89, v2
	v_mov_b32_e32 v98, v2
	v_mov_b32_e32 v99, v2
	v_mov_b32_e32 v100, v2
	v_mov_b32_e32 v101, v2
	v_mov_b32_e32 v102, v2
	v_mov_b32_e32 v103, v2
	v_mov_b32_e32 v104, v2
	v_mov_b32_e32 v105, v2
	v_mov_b32_e32 v114, v2
	v_mov_b32_e32 v115, v2
	v_mov_b32_e32 v116, v2
	v_mov_b32_e32 v117, v2
	v_mov_b32_e32 v118, v2
	v_mov_b32_e32 v119, v2
	v_mov_b32_e32 v120, v2
	v_mov_b32_e32 v121, v2
	v_mov_b32_e32 v130, v2
	v_mov_b32_e32 v131, v2
	v_mov_b32_e32 v132, v2
	v_mov_b32_e32 v133, v2
	v_mov_b32_e32 v134, v2
	v_mov_b32_e32 v135, v2
	v_mov_b32_e32 v136, v2
	v_mov_b32_e32 v137, v2
	v_mov_b32_e32 v90, v2
	v_mov_b32_e32 v91, v2
	v_mov_b32_e32 v92, v2
	v_mov_b32_e32 v93, v2
	v_mov_b32_e32 v94, v2
	v_mov_b32_e32 v95, v2
	v_mov_b32_e32 v96, v2
	v_mov_b32_e32 v97, v2
	v_mov_b32_e32 v106, v2
	v_mov_b32_e32 v107, v2
	v_mov_b32_e32 v108, v2
	v_mov_b32_e32 v109, v2
	v_mov_b32_e32 v110, v2
	v_mov_b32_e32 v111, v2
	v_mov_b32_e32 v112, v2
	v_mov_b32_e32 v113, v2
	v_mov_b32_e32 v122, v2
	v_mov_b32_e32 v123, v2
	v_mov_b32_e32 v124, v2
	v_mov_b32_e32 v125, v2
	v_mov_b32_e32 v126, v2
	v_mov_b32_e32 v127, v2
	v_mov_b32_e32 v128, v2
	v_mov_b32_e32 v129, v2
	v_mov_b32_e32 v138, v2
	v_mov_b32_e32 v139, v2
	v_mov_b32_e32 v140, v2
	v_mov_b32_e32 v141, v2
	v_mov_b32_e32 v142, v2
	v_mov_b32_e32 v143, v2
	v_mov_b32_e32 v144, v2
	v_mov_b32_e32 v145, v2
	v_add_u32_e32 v251, 0x80, v150
	v_add_u32_e32 v252, 0x80, v154
	v_add_u32_e32 v253, 0x80, v148
	v_add_u32_e32 v254, 0x80, v152
.LBB0_197:
	ds_read_b128 v[34:37], v184
	ds_read_b128 v[38:41], v184 offset:1024
	ds_read_b128 v[42:45], v184 offset:2048
	ds_read_b128 v[46:49], v184 offset:3072
	ds_read_b128 v[166:169], v185
	ds_read_b128 v[170:173], v185 offset:1024
	ds_read_b128 v[190:193], v185 offset:2048
	ds_read_b128 v[194:197], v185 offset:3072
	s_add_u32 s13, s8, 0xfffc0080
	s_addc_u32 s24, s9, -1
	s_cmp_eq_u32 s12, 12
	s_cselect_b32 s87, s15, s24
	s_cselect_b32 s86, s23, s13
	s_cselect_b32 s85, s77, vcc_hi
	s_cselect_b32 s84, s79, vcc_lo
	s_nop 0
	s_add_i32 m0, s90, 0xc000
	ds_read_b128 v[198:201], v186
	ds_read_b128 v[202:205], v186 offset:1024
	ds_read_b128 v[206:209], v186 offset:2048
	ds_read_b128 v[210:213], v186 offset:3072
	ds_read_b128 v[214:217], v186 offset:4096
	ds_read_b128 v[218:221], v186 offset:5120
	ds_read_b128 v[222:225], v186 offset:6144
	ds_read_b128 v[226:229], v186 offset:7168
	global_load_lds_dwordx4 v158, s[8:9]
	s_nop 0
	s_add_i32 m0, s90, 0xe000
	s_nop 0
	global_load_lds_dwordx4 v160, s[8:9]
	s_waitcnt vmcnt(8)
	s_waitcnt lgkmcnt(0)
	s_barrier
	s_setprio 1
	s_waitcnt lgkmcnt(0)
	v_mfma_f32_16x16x32_bf16 v[142:145], v[34:37], v[198:201], v[142:145]
	v_mfma_f32_16x16x32_bf16 v[138:141], v[42:45], v[198:201], v[138:141]
	v_mfma_f32_16x16x32_bf16 v[126:129], v[34:37], v[206:209], v[126:129]
	v_mfma_f32_16x16x32_bf16 v[122:125], v[42:45], v[206:209], v[122:125]
	v_mfma_f32_16x16x32_bf16 v[110:113], v[34:37], v[214:217], v[110:113]
	v_mfma_f32_16x16x32_bf16 v[106:109], v[42:45], v[214:217], v[106:109]
	v_mfma_f32_16x16x32_bf16 v[94:97], v[34:37], v[222:225], v[94:97]
	v_mfma_f32_16x16x32_bf16 v[90:93], v[42:45], v[222:225], v[90:93]
	v_mfma_f32_16x16x32_bf16 v[142:145], v[38:41], v[202:205], v[142:145]
	v_mfma_f32_16x16x32_bf16 v[138:141], v[46:49], v[202:205], v[138:141]
	v_mfma_f32_16x16x32_bf16 v[126:129], v[38:41], v[210:213], v[126:129]
	v_mfma_f32_16x16x32_bf16 v[122:125], v[46:49], v[210:213], v[122:125]
	v_mfma_f32_16x16x32_bf16 v[110:113], v[38:41], v[218:221], v[110:113]
	v_mfma_f32_16x16x32_bf16 v[106:109], v[46:49], v[218:221], v[106:109]
	v_mfma_f32_16x16x32_bf16 v[94:97], v[38:41], v[226:229], v[94:97]
	v_mfma_f32_16x16x32_bf16 v[90:93], v[46:49], v[226:229], v[90:93]
	s_setprio 0
	s_setprio 1
	v_mfma_f32_16x16x32_bf16 v[134:137], v[166:169], v[198:201], v[134:137]
	v_mfma_f32_16x16x32_bf16 v[130:133], v[190:193], v[198:201], v[130:133]
	v_mfma_f32_16x16x32_bf16 v[118:121], v[166:169], v[206:209], v[118:121]
	v_mfma_f32_16x16x32_bf16 v[114:117], v[190:193], v[206:209], v[114:117]
	v_mfma_f32_16x16x32_bf16 v[102:105], v[166:169], v[214:217], v[102:105]
	v_mfma_f32_16x16x32_bf16 v[98:101], v[190:193], v[214:217], v[98:101]
	v_mfma_f32_16x16x32_bf16 v[86:89], v[166:169], v[222:225], v[86:89]
	v_mfma_f32_16x16x32_bf16 v[82:85], v[190:193], v[222:225], v[82:85]
	v_mfma_f32_16x16x32_bf16 v[134:137], v[170:173], v[202:205], v[134:137]
	v_mfma_f32_16x16x32_bf16 v[130:133], v[194:197], v[202:205], v[130:133]
	v_mfma_f32_16x16x32_bf16 v[118:121], v[170:173], v[210:213], v[118:121]
	v_mfma_f32_16x16x32_bf16 v[114:117], v[194:197], v[210:213], v[114:117]
	v_mfma_f32_16x16x32_bf16 v[102:105], v[170:173], v[218:221], v[102:105]
	v_mfma_f32_16x16x32_bf16 v[98:101], v[194:197], v[218:221], v[98:101]
	v_mfma_f32_16x16x32_bf16 v[86:89], v[170:173], v[226:229], v[86:89]
	v_mfma_f32_16x16x32_bf16 v[82:85], v[194:197], v[226:229], v[82:85]
	s_setprio 0
	s_barrier
	s_add_i32 s13, s62, s89
	s_nop 0
	s_mov_b32 m0, s13
	ds_read_b128 v[198:201], v186 offset:16384
	ds_read_b128 v[202:205], v186 offset:17408
	ds_read_b128 v[206:209], v186 offset:18432
	ds_read_b128 v[210:213], v186 offset:19456
	ds_read_b128 v[214:217], v186 offset:20480
	ds_read_b128 v[218:221], v186 offset:21504
	ds_read_b128 v[222:225], v186 offset:22528
	ds_read_b128 v[226:229], v186 offset:23552
	global_load_lds_dwordx4 v150, s[84:85]
	s_add_i32 m0, s13, 0x2000
	s_add_u32 s24, s84, 0x40000
	v_lshl_add_u64 v[232:233], s[84:85], 0, v[154:155]
	s_addc_u32 s25, s85, 0
	s_add_i32 s13, s63, s89
	global_load_lds_dwordx4 v154, s[84:85]
	s_nop 0
	s_mov_b32 m0, s13
	v_lshl_add_u64 v[236:237], s[86:87], 0, v[152:153]
	global_load_lds_dwordx4 v150, s[24:25]
	s_nop 0
	s_add_i32 m0, s13, 0x2000
	s_nop 0
	global_load_lds_dwordx4 v154, s[24:25]
	s_nop 0
	s_mov_b32 m0, s90
	s_nop 0
	global_load_lds_dwordx4 v148, s[86:87]
	s_mov_b32 m0, s91
	s_nop 0
	global_load_lds_dwordx4 v152, s[86:87]
	s_waitcnt vmcnt(8)
	s_waitcnt lgkmcnt(0)
	s_barrier
	s_setprio 1
	s_waitcnt lgkmcnt(0)
	v_mfma_f32_16x16x32_bf16 v[78:81], v[34:37], v[198:201], v[78:81]
	v_mfma_f32_16x16x32_bf16 v[74:77], v[42:45], v[198:201], v[74:77]
	v_mfma_f32_16x16x32_bf16 v[62:65], v[34:37], v[206:209], v[62:65]
	v_mfma_f32_16x16x32_bf16 v[58:61], v[42:45], v[206:209], v[58:61]
	v_mfma_f32_16x16x32_bf16 v[30:33], v[34:37], v[214:217], v[30:33]
	v_mfma_f32_16x16x32_bf16 v[26:29], v[42:45], v[214:217], v[26:29]
	v_mfma_f32_16x16x32_bf16 v[14:17], v[34:37], v[222:225], v[14:17]
	v_mfma_f32_16x16x32_bf16 v[10:13], v[42:45], v[222:225], v[10:13]
	v_mfma_f32_16x16x32_bf16 v[78:81], v[38:41], v[202:205], v[78:81]
	v_mfma_f32_16x16x32_bf16 v[74:77], v[46:49], v[202:205], v[74:77]
	v_mfma_f32_16x16x32_bf16 v[62:65], v[38:41], v[210:213], v[62:65]
	v_mfma_f32_16x16x32_bf16 v[58:61], v[46:49], v[210:213], v[58:61]
	v_mfma_f32_16x16x32_bf16 v[30:33], v[38:41], v[218:221], v[30:33]
	v_mfma_f32_16x16x32_bf16 v[26:29], v[46:49], v[218:221], v[26:29]
	v_mfma_f32_16x16x32_bf16 v[14:17], v[38:41], v[226:229], v[14:17]
	v_mfma_f32_16x16x32_bf16 v[10:13], v[46:49], v[226:229], v[10:13]
	s_setprio 0
	s_setprio 1
	v_mfma_f32_16x16x32_bf16 v[22:25], v[166:169], v[214:217], v[22:25]
	v_mfma_f32_16x16x32_bf16 v[18:21], v[190:193], v[214:217], v[18:21]
	v_mfma_f32_16x16x32_bf16 v[6:9], v[166:169], v[222:225], v[6:9]
	v_mfma_f32_16x16x32_bf16 v[2:5], v[190:193], v[222:225], v[2:5]
	v_mfma_f32_16x16x32_bf16 v[34:37], v[166:169], v[198:201], v[70:73]
	v_mfma_f32_16x16x32_bf16 v[38:41], v[190:193], v[198:201], v[66:69]
	v_mfma_f32_16x16x32_bf16 v[42:45], v[166:169], v[206:209], v[54:57]
	v_mfma_f32_16x16x32_bf16 v[46:49], v[190:193], v[206:209], v[50:53]
	v_mfma_f32_16x16x32_bf16 v[22:25], v[170:173], v[218:221], v[22:25]
	v_mfma_f32_16x16x32_bf16 v[18:21], v[194:197], v[218:221], v[18:21]
	v_mfma_f32_16x16x32_bf16 v[6:9], v[170:173], v[226:229], v[6:9]
	v_mfma_f32_16x16x32_bf16 v[2:5], v[194:197], v[226:229], v[2:5]
	v_mfma_f32_16x16x32_bf16 v[34:37], v[170:173], v[202:205], v[34:37]
	v_mfma_f32_16x16x32_bf16 v[38:41], v[194:197], v[202:205], v[38:41]
	v_mfma_f32_16x16x32_bf16 v[42:45], v[170:173], v[210:213], v[42:45]
	v_mfma_f32_16x16x32_bf16 v[46:49], v[194:197], v[210:213], v[46:49]
	s_setprio 0
	s_barrier
	s_add_i32 s13, 0, 0x18000
	s_add_i32 s3, 0, 0x1c000
	v_add_u32_e32 v70, s13, v175
	v_add_u32_e32 v194, s3, v175
	ds_read_b128 v[50:53], v70
	ds_read_b128 v[54:57], v70 offset:1024
	ds_read_b128 v[66:69], v70 offset:2048
	ds_read_b128 v[70:73], v70 offset:3072
	ds_read_b128 v[166:169], v194
	ds_read_b128 v[170:173], v194 offset:1024
	ds_read_b128 v[190:193], v194 offset:2048
	ds_read_b128 v[194:197], v194 offset:3072
	s_add_u32 s24, s86, 0x40000
	s_addc_u32 s25, s87, 0
	s_mov_b32 m0, s92
	s_nop 0
	ds_read_b128 v[198:201], v186 offset:32768
	ds_read_b128 v[202:205], v186 offset:33792
	ds_read_b128 v[206:209], v186 offset:34816
	ds_read_b128 v[210:213], v186 offset:35840
	ds_read_b128 v[214:217], v186 offset:36864
	ds_read_b128 v[218:221], v186 offset:37888
	ds_read_b128 v[222:225], v186 offset:38912
	ds_read_b128 v[226:229], v186 offset:39936
	global_load_lds_dwordx4 v148, s[24:25]
	s_nop 0
	s_mov_b32 m0, s93
	s_nop 0
	global_load_lds_dwordx4 v152, s[24:25]
	s_waitcnt vmcnt(8)
	s_waitcnt lgkmcnt(0)
	s_barrier
	s_setprio 1
	s_waitcnt lgkmcnt(0)
	v_mfma_f32_16x16x32_bf16 v[142:145], v[50:53], v[198:201], v[142:145]
	v_mfma_f32_16x16x32_bf16 v[138:141], v[66:69], v[198:201], v[138:141]
	v_mfma_f32_16x16x32_bf16 v[126:129], v[50:53], v[206:209], v[126:129]
	v_mfma_f32_16x16x32_bf16 v[122:125], v[66:69], v[206:209], v[122:125]
	v_mfma_f32_16x16x32_bf16 v[110:113], v[50:53], v[214:217], v[110:113]
	v_mfma_f32_16x16x32_bf16 v[106:109], v[66:69], v[214:217], v[106:109]
	v_mfma_f32_16x16x32_bf16 v[94:97], v[50:53], v[222:225], v[94:97]
	v_mfma_f32_16x16x32_bf16 v[90:93], v[66:69], v[222:225], v[90:93]
	v_mfma_f32_16x16x32_bf16 v[142:145], v[54:57], v[202:205], v[142:145]
	v_mfma_f32_16x16x32_bf16 v[138:141], v[70:73], v[202:205], v[138:141]
	v_mfma_f32_16x16x32_bf16 v[126:129], v[54:57], v[210:213], v[126:129]
	v_mfma_f32_16x16x32_bf16 v[122:125], v[70:73], v[210:213], v[122:125]
	v_mfma_f32_16x16x32_bf16 v[110:113], v[54:57], v[218:221], v[110:113]
	v_mfma_f32_16x16x32_bf16 v[106:109], v[70:73], v[218:221], v[106:109]
	v_mfma_f32_16x16x32_bf16 v[94:97], v[54:57], v[226:229], v[94:97]
	v_mfma_f32_16x16x32_bf16 v[90:93], v[70:73], v[226:229], v[90:93]
	s_setprio 0
	s_setprio 1
	v_mfma_f32_16x16x32_bf16 v[134:137], v[166:169], v[198:201], v[134:137]
	v_mfma_f32_16x16x32_bf16 v[130:133], v[190:193], v[198:201], v[130:133]
	v_mfma_f32_16x16x32_bf16 v[118:121], v[166:169], v[206:209], v[118:121]
	v_mfma_f32_16x16x32_bf16 v[114:117], v[190:193], v[206:209], v[114:117]
	v_mfma_f32_16x16x32_bf16 v[102:105], v[166:169], v[214:217], v[102:105]
	v_mfma_f32_16x16x32_bf16 v[98:101], v[190:193], v[214:217], v[98:101]
	v_mfma_f32_16x16x32_bf16 v[86:89], v[166:169], v[222:225], v[86:89]
	v_mfma_f32_16x16x32_bf16 v[82:85], v[190:193], v[222:225], v[82:85]
	v_mfma_f32_16x16x32_bf16 v[134:137], v[170:173], v[202:205], v[134:137]
	v_mfma_f32_16x16x32_bf16 v[130:133], v[194:197], v[202:205], v[130:133]
	v_mfma_f32_16x16x32_bf16 v[118:121], v[170:173], v[210:213], v[118:121]
	v_mfma_f32_16x16x32_bf16 v[114:117], v[194:197], v[210:213], v[114:117]
	v_mfma_f32_16x16x32_bf16 v[102:105], v[170:173], v[218:221], v[102:105]
	v_mfma_f32_16x16x32_bf16 v[98:101], v[194:197], v[218:221], v[98:101]
	v_mfma_f32_16x16x32_bf16 v[86:89], v[170:173], v[226:229], v[86:89]
	v_mfma_f32_16x16x32_bf16 v[82:85], v[194:197], v[226:229], v[82:85]
	s_setprio 0
	s_barrier
	s_add_i32 s13, s13, s89
	s_nop 0
	s_mov_b32 m0, s13
	ds_read_b128 v[198:201], v186 offset:49152
	ds_read_b128 v[202:205], v186 offset:50176
	ds_read_b128 v[206:209], v186 offset:51200
	ds_read_b128 v[210:213], v186 offset:52224
	ds_read_b128 v[214:217], v186 offset:53248
	ds_read_b128 v[218:221], v186 offset:54272
	ds_read_b128 v[222:225], v186 offset:55296
	ds_read_b128 v[226:229], v186 offset:56320
	global_load_lds_dwordx4 v251, s[84:85]
	s_add_i32 m0, s13, 0x2000
	s_add_u32 s24, s84, 0x40080
	s_nop 0
	s_addc_u32 s25, s85, 0
	s_add_i32 s3, s3, s89
	global_load_lds_dwordx4 v252, s[84:85]
	s_nop 0
	s_mov_b32 m0, s3
	s_nop 0
	global_load_lds_dwordx4 v150, s[24:25]
	s_nop 0
	s_add_i32 m0, s3, 0x2000
	s_nop 0
	global_load_lds_dwordx4 v154, s[24:25]
	s_nop 0
	s_mov_b32 m0, s97
	s_nop 0
	global_load_lds_dwordx4 v253, s[86:87]
	s_nop 0
	s_mov_b32 m0, s4
	s_nop 0
	global_load_lds_dwordx4 v254, s[86:87]
	s_waitcnt vmcnt(8)
	s_waitcnt lgkmcnt(0)
	s_barrier
	s_setprio 1
	s_waitcnt lgkmcnt(0)
	v_mfma_f32_16x16x32_bf16 v[78:81], v[50:53], v[198:201], v[78:81]
	v_mfma_f32_16x16x32_bf16 v[74:77], v[66:69], v[198:201], v[74:77]
	v_mfma_f32_16x16x32_bf16 v[62:65], v[50:53], v[206:209], v[62:65]
	v_mfma_f32_16x16x32_bf16 v[58:61], v[66:69], v[206:209], v[58:61]
	v_mfma_f32_16x16x32_bf16 v[30:33], v[50:53], v[214:217], v[30:33]
	v_mfma_f32_16x16x32_bf16 v[26:29], v[66:69], v[214:217], v[26:29]
	v_mfma_f32_16x16x32_bf16 v[14:17], v[50:53], v[222:225], v[14:17]
	v_mfma_f32_16x16x32_bf16 v[10:13], v[66:69], v[222:225], v[10:13]
	v_mfma_f32_16x16x32_bf16 v[78:81], v[54:57], v[202:205], v[78:81]
	v_mfma_f32_16x16x32_bf16 v[74:77], v[70:73], v[202:205], v[74:77]
	v_mfma_f32_16x16x32_bf16 v[62:65], v[54:57], v[210:213], v[62:65]
	v_mfma_f32_16x16x32_bf16 v[58:61], v[70:73], v[210:213], v[58:61]
	v_mfma_f32_16x16x32_bf16 v[30:33], v[54:57], v[218:221], v[30:33]
	v_mfma_f32_16x16x32_bf16 v[26:29], v[70:73], v[218:221], v[26:29]
	v_mfma_f32_16x16x32_bf16 v[14:17], v[54:57], v[226:229], v[14:17]
	v_mfma_f32_16x16x32_bf16 v[10:13], v[70:73], v[226:229], v[10:13]
	s_setprio 0
	s_setprio 1
	v_mfma_f32_16x16x32_bf16 v[34:37], v[166:169], v[198:201], v[34:37]
	v_mfma_f32_16x16x32_bf16 v[70:73], v[170:173], v[202:205], v[34:37]
	v_mfma_f32_16x16x32_bf16 v[34:37], v[190:193], v[198:201], v[38:41]
	v_mfma_f32_16x16x32_bf16 v[66:69], v[194:197], v[202:205], v[34:37]
	v_mfma_f32_16x16x32_bf16 v[34:37], v[166:169], v[206:209], v[42:45]
	v_mfma_f32_16x16x32_bf16 v[54:57], v[170:173], v[210:213], v[34:37]
	v_mfma_f32_16x16x32_bf16 v[34:37], v[190:193], v[206:209], v[46:49]
	v_mfma_f32_16x16x32_bf16 v[22:25], v[166:169], v[214:217], v[22:25]
	v_mfma_f32_16x16x32_bf16 v[18:21], v[190:193], v[214:217], v[18:21]
	v_mfma_f32_16x16x32_bf16 v[6:9], v[166:169], v[222:225], v[6:9]
	v_mfma_f32_16x16x32_bf16 v[2:5], v[190:193], v[222:225], v[2:5]
	v_mfma_f32_16x16x32_bf16 v[50:53], v[194:197], v[210:213], v[34:37]
	v_mfma_f32_16x16x32_bf16 v[22:25], v[170:173], v[218:221], v[22:25]
	v_mfma_f32_16x16x32_bf16 v[18:21], v[194:197], v[218:221], v[18:21]
	v_mfma_f32_16x16x32_bf16 v[6:9], v[170:173], v[226:229], v[6:9]
	v_mfma_f32_16x16x32_bf16 v[2:5], v[194:197], v[226:229], v[2:5]
	s_setprio 0
	s_barrier
	s_add_i32 s12, s12, 2
	s_add_u32 s8, s8, 0x100
	s_addc_u32 s9, s9, 0
	s_add_u32 vcc_lo, vcc_lo, 0x100
	s_addc_u32 vcc_hi, vcc_hi, 0
	s_cmp_gt_u32 s12, 13
	s_cbranch_scc0 .LBB0_197
	s_and_b64 vcc, exec, s[74:75]
	s_cbranch_vccz .LBB0_200
	s_barrier

.LBB0_632:
	s_add_i32 s81, s87, -2
	s_add_u32 s88, s88, 0x40080
	s_addc_u32 s89, s89, 0
	s_add_u32 s83, s90, 0x100
	v_mov_b32_e32 v2, 0
	s_addc_u32 vcc_lo, s91, 0
	s_mov_b32 s12, 0
	v_mov_b32_e32 v3, v2
	v_mov_b32_e32 v4, v2
	v_mov_b32_e32 v5, v2
	v_mov_b32_e32 v6, v2
	v_mov_b32_e32 v7, v2
	v_mov_b32_e32 v8, v2
	v_mov_b32_e32 v9, v2
	v_mov_b32_e32 v10, v2
	v_mov_b32_e32 v11, v2
	v_mov_b32_e32 v12, v2
	v_mov_b32_e32 v13, v2
	v_mov_b32_e32 v14, v2
	v_mov_b32_e32 v15, v2
	v_mov_b32_e32 v16, v2
	v_mov_b32_e32 v17, v2
	v_mov_b32_e32 v22, v2
	v_mov_b32_e32 v23, v2
	v_mov_b32_e32 v24, v2
	v_mov_b32_e32 v25, v2
	v_mov_b32_e32 v30, v2
	v_mov_b32_e32 v31, v2
	v_mov_b32_e32 v32, v2
	v_mov_b32_e32 v33, v2
	v_mov_b32_e32 v38, v2
	v_mov_b32_e32 v39, v2
	v_mov_b32_e32 v40, v2
	v_mov_b32_e32 v41, v2
	v_mov_b32_e32 v46, v2
	v_mov_b32_e32 v47, v2
	v_mov_b32_e32 v48, v2
	v_mov_b32_e32 v49, v2
	v_mov_b32_e32 v18, v2
	v_mov_b32_e32 v19, v2
	v_mov_b32_e32 v20, v2
	v_mov_b32_e32 v21, v2
	v_mov_b32_e32 v26, v2
	v_mov_b32_e32 v27, v2
	v_mov_b32_e32 v28, v2
	v_mov_b32_e32 v29, v2
	v_mov_b32_e32 v34, v2
	v_mov_b32_e32 v35, v2
	v_mov_b32_e32 v36, v2
	v_mov_b32_e32 v37, v2
	v_mov_b32_e32 v42, v2
	v_mov_b32_e32 v43, v2
	v_mov_b32_e32 v44, v2
	v_mov_b32_e32 v45, v2
	v_mov_b32_e32 v50, v2
	v_mov_b32_e32 v51, v2
	v_mov_b32_e32 v52, v2
	v_mov_b32_e32 v53, v2
	v_mov_b32_e32 v54, v2
	v_mov_b32_e32 v55, v2
	v_mov_b32_e32 v56, v2
	v_mov_b32_e32 v57, v2
	v_mov_b32_e32 v58, v2
	v_mov_b32_e32 v59, v2
	v_mov_b32_e32 v60, v2
	v_mov_b32_e32 v61, v2
	v_mov_b32_e32 v62, v2
	v_mov_b32_e32 v63, v2
	v_mov_b32_e32 v64, v2
	v_mov_b32_e32 v65, v2
	v_mov_b32_e32 v66, v2
	v_mov_b32_e32 v67, v2
	v_mov_b32_e32 v68, v2
	v_mov_b32_e32 v69, v2
	v_mov_b32_e32 v70, v2
	v_mov_b32_e32 v71, v2
	v_mov_b32_e32 v72, v2
	v_mov_b32_e32 v73, v2
	v_mov_b32_e32 v74, v2
	v_mov_b32_e32 v75, v2
	v_mov_b32_e32 v76, v2
	v_mov_b32_e32 v77, v2
	v_mov_b32_e32 v78, v2
	v_mov_b32_e32 v79, v2
	v_mov_b32_e32 v80, v2
	v_mov_b32_e32 v81, v2
	v_mov_b32_e32 v86, v2
	v_mov_b32_e32 v87, v2
	v_mov_b32_e32 v88, v2
	v_mov_b32_e32 v89, v2
	v_mov_b32_e32 v94, v2
	v_mov_b32_e32 v95, v2
	v_mov_b32_e32 v96, v2
	v_mov_b32_e32 v97, v2
	v_mov_b32_e32 v102, v2
	v_mov_b32_e32 v103, v2
	v_mov_b32_e32 v104, v2
	v_mov_b32_e32 v105, v2
	v_mov_b32_e32 v110, v2
	v_mov_b32_e32 v111, v2
	v_mov_b32_e32 v112, v2
	v_mov_b32_e32 v113, v2
	v_mov_b32_e32 v82, v2
	v_mov_b32_e32 v83, v2
	v_mov_b32_e32 v84, v2
	v_mov_b32_e32 v85, v2
	v_mov_b32_e32 v90, v2
	v_mov_b32_e32 v91, v2
	v_mov_b32_e32 v92, v2
	v_mov_b32_e32 v93, v2
	v_mov_b32_e32 v98, v2
	v_mov_b32_e32 v99, v2
	v_mov_b32_e32 v100, v2
	v_mov_b32_e32 v101, v2
	v_mov_b32_e32 v106, v2
	v_mov_b32_e32 v107, v2
	v_mov_b32_e32 v108, v2
	v_mov_b32_e32 v109, v2
	v_mov_b32_e32 v114, v2
	v_mov_b32_e32 v115, v2
	v_mov_b32_e32 v116, v2
	v_mov_b32_e32 v117, v2
	v_mov_b32_e32 v118, v2
	v_mov_b32_e32 v119, v2
	v_mov_b32_e32 v120, v2
	v_mov_b32_e32 v121, v2
	v_mov_b32_e32 v122, v2
	v_mov_b32_e32 v123, v2
	v_mov_b32_e32 v124, v2
	v_mov_b32_e32 v125, v2
	v_mov_b32_e32 v126, v2
	v_mov_b32_e32 v127, v2
	v_mov_b32_e32 v128, v2
	v_mov_b32_e32 v129, v2
	v_add_u32_e32 v251, 0x80, v134
	v_add_u32_e32 v252, 0x80, v130
	v_add_u32_e32 v253, 0x80, v136
	v_add_u32_e32 v254, 0x80, v132
.LBB0_633:
	ds_read_b128 v[152:155], v148
	ds_read_b128 v[156:159], v148 offset:1024
	ds_read_b128 v[160:163], v148 offset:2048
	ds_read_b128 v[164:167], v148 offset:3072
	ds_read_b128 v[168:171], v149
	ds_read_b128 v[172:175], v149 offset:1024
	ds_read_b128 v[176:179], v149 offset:2048
	ds_read_b128 v[180:183], v149 offset:3072
	s_add_i32 s13, s12, 2
	s_add_u32 s3, s88, 0xfffc0080
	s_addc_u32 s24, s89, -1
	s_cmp_eq_u32 s81, s12
	s_cselect_b32 s93, s7, s24
	s_cselect_b32 s92, s6, s3
	s_cselect_b32 s91, s85, vcc_lo
	s_cselect_b32 s90, s84, s83
	s_nop 0
	s_add_i32 m0, s22, 0xc000
	ds_read_b128 v[184:187], v150
	ds_read_b128 v[188:191], v150 offset:1024
	ds_read_b128 v[192:195], v150 offset:2048
	ds_read_b128 v[196:199], v150 offset:3072
	ds_read_b128 v[200:203], v150 offset:4096
	ds_read_b128 v[204:207], v150 offset:5120
	ds_read_b128 v[208:211], v150 offset:6144
	ds_read_b128 v[212:215], v150 offset:7168
	global_load_lds_dwordx4 v140, s[88:89]
	s_nop 0
	s_add_i32 m0, s22, 0xe000
	s_nop 0
	global_load_lds_dwordx4 v142, s[88:89]
	s_waitcnt vmcnt(8)
	s_waitcnt lgkmcnt(0)
	s_barrier
	s_setprio 1
	s_waitcnt lgkmcnt(0)
	v_mfma_f32_16x16x32_bf16 v[126:129], v[152:155], v[184:187], v[126:129]
	v_mfma_f32_16x16x32_bf16 v[122:125], v[160:163], v[184:187], v[122:125]
	v_mfma_f32_16x16x32_bf16 v[118:121], v[152:155], v[192:195], v[118:121]
	v_mfma_f32_16x16x32_bf16 v[114:117], v[160:163], v[192:195], v[114:117]
	v_mfma_f32_16x16x32_bf16 v[106:109], v[152:155], v[200:203], v[106:109]
	v_mfma_f32_16x16x32_bf16 v[98:101], v[160:163], v[200:203], v[98:101]
	v_mfma_f32_16x16x32_bf16 v[90:93], v[152:155], v[208:211], v[90:93]
	v_mfma_f32_16x16x32_bf16 v[82:85], v[160:163], v[208:211], v[82:85]
	v_mfma_f32_16x16x32_bf16 v[126:129], v[156:159], v[188:191], v[126:129]
	v_mfma_f32_16x16x32_bf16 v[122:125], v[164:167], v[188:191], v[122:125]
	v_mfma_f32_16x16x32_bf16 v[118:121], v[156:159], v[196:199], v[118:121]
	v_mfma_f32_16x16x32_bf16 v[114:117], v[164:167], v[196:199], v[114:117]
	v_mfma_f32_16x16x32_bf16 v[106:109], v[156:159], v[204:207], v[106:109]
	v_mfma_f32_16x16x32_bf16 v[98:101], v[164:167], v[204:207], v[98:101]
	v_mfma_f32_16x16x32_bf16 v[90:93], v[156:159], v[212:215], v[90:93]
	v_mfma_f32_16x16x32_bf16 v[82:85], v[164:167], v[212:215], v[82:85]
	s_setprio 0
	s_setprio 1
	v_mfma_f32_16x16x32_bf16 v[110:113], v[168:171], v[184:187], v[110:113]
	v_mfma_f32_16x16x32_bf16 v[102:105], v[176:179], v[184:187], v[102:105]
	v_mfma_f32_16x16x32_bf16 v[94:97], v[168:171], v[192:195], v[94:97]
	v_mfma_f32_16x16x32_bf16 v[86:89], v[176:179], v[192:195], v[86:89]
	v_mfma_f32_16x16x32_bf16 v[78:81], v[168:171], v[200:203], v[78:81]
	v_mfma_f32_16x16x32_bf16 v[74:77], v[176:179], v[200:203], v[74:77]
	v_mfma_f32_16x16x32_bf16 v[70:73], v[168:171], v[208:211], v[70:73]
	v_mfma_f32_16x16x32_bf16 v[66:69], v[176:179], v[208:211], v[66:69]
	v_mfma_f32_16x16x32_bf16 v[110:113], v[172:175], v[188:191], v[110:113]
	v_mfma_f32_16x16x32_bf16 v[102:105], v[180:183], v[188:191], v[102:105]
	v_mfma_f32_16x16x32_bf16 v[94:97], v[172:175], v[196:199], v[94:97]
	v_mfma_f32_16x16x32_bf16 v[86:89], v[180:183], v[196:199], v[86:89]
	v_mfma_f32_16x16x32_bf16 v[78:81], v[172:175], v[204:207], v[78:81]
	v_mfma_f32_16x16x32_bf16 v[74:77], v[180:183], v[204:207], v[74:77]
	v_mfma_f32_16x16x32_bf16 v[70:73], v[172:175], v[212:215], v[70:73]
	v_mfma_f32_16x16x32_bf16 v[66:69], v[180:183], v[212:215], v[66:69]
	s_setprio 0
	s_barrier
	s_add_i32 s3, s60, s4
	s_nop 0
	s_mov_b32 m0, s3
	ds_read_b128 v[184:187], v150 offset:16384
	ds_read_b128 v[188:191], v150 offset:17408
	ds_read_b128 v[192:195], v150 offset:18432
	ds_read_b128 v[196:199], v150 offset:19456
	ds_read_b128 v[200:203], v150 offset:20480
	ds_read_b128 v[204:207], v150 offset:21504
	ds_read_b128 v[208:211], v150 offset:22528
	ds_read_b128 v[212:215], v150 offset:23552
	global_load_lds_dwordx4 v134, s[90:91]
	s_add_i32 m0, s3, 0x2000
	s_add_u32 s24, s90, 0x40000
	v_lshl_add_u64 v[218:219], s[90:91], 0, v[130:131]
	s_addc_u32 s25, s91, 0
	s_add_i32 s3, s61, s4
	global_load_lds_dwordx4 v130, s[90:91]
	v_lshl_add_u64 v[220:221], s[24:25], 0, v[134:135]
	s_mov_b32 m0, s3
	v_lshl_add_u64 v[222:223], s[92:93], 0, v[132:133]
	global_load_lds_dwordx4 v134, s[24:25]
	v_lshl_add_u64 v[220:221], s[24:25], 0, v[130:131]
	s_add_i32 m0, s3, 0x2000
	s_nop 0
	global_load_lds_dwordx4 v130, s[24:25]
	v_lshl_add_u64 v[220:221], s[92:93], 0, v[136:137]
	s_mov_b32 m0, s22
	s_nop 0
	global_load_lds_dwordx4 v136, s[92:93]
	s_mov_b32 m0, s23
	s_nop 0
	global_load_lds_dwordx4 v132, s[92:93]
	s_waitcnt vmcnt(8)
	s_waitcnt lgkmcnt(0)
	s_barrier
	s_setprio 1
	s_waitcnt lgkmcnt(0)
	v_mfma_f32_16x16x32_bf16 v[62:65], v[152:155], v[184:187], v[62:65]
	v_mfma_f32_16x16x32_bf16 v[58:61], v[160:163], v[184:187], v[58:61]
	v_mfma_f32_16x16x32_bf16 v[54:57], v[152:155], v[192:195], v[54:57]
	v_mfma_f32_16x16x32_bf16 v[50:53], v[160:163], v[192:195], v[50:53]
	v_mfma_f32_16x16x32_bf16 v[42:45], v[152:155], v[200:203], v[42:45]
	v_mfma_f32_16x16x32_bf16 v[34:37], v[160:163], v[200:203], v[34:37]
	v_mfma_f32_16x16x32_bf16 v[26:29], v[152:155], v[208:211], v[26:29]
	v_mfma_f32_16x16x32_bf16 v[18:21], v[160:163], v[208:211], v[18:21]
	v_mfma_f32_16x16x32_bf16 v[62:65], v[156:159], v[188:191], v[62:65]
	v_mfma_f32_16x16x32_bf16 v[58:61], v[164:167], v[188:191], v[58:61]
	v_mfma_f32_16x16x32_bf16 v[54:57], v[156:159], v[196:199], v[54:57]
	v_mfma_f32_16x16x32_bf16 v[50:53], v[164:167], v[196:199], v[50:53]
	v_mfma_f32_16x16x32_bf16 v[42:45], v[156:159], v[204:207], v[42:45]
	v_mfma_f32_16x16x32_bf16 v[34:37], v[164:167], v[204:207], v[34:37]
	v_mfma_f32_16x16x32_bf16 v[26:29], v[156:159], v[212:215], v[26:29]
	v_mfma_f32_16x16x32_bf16 v[18:21], v[164:167], v[212:215], v[18:21]
	s_setprio 0
	s_setprio 1
	v_mfma_f32_16x16x32_bf16 v[46:49], v[168:171], v[184:187], v[46:49]
	v_mfma_f32_16x16x32_bf16 v[38:41], v[176:179], v[184:187], v[38:41]
	v_mfma_f32_16x16x32_bf16 v[30:33], v[168:171], v[192:195], v[30:33]
	v_mfma_f32_16x16x32_bf16 v[22:25], v[176:179], v[192:195], v[22:25]
	v_mfma_f32_16x16x32_bf16 v[14:17], v[168:171], v[200:203], v[14:17]
	v_mfma_f32_16x16x32_bf16 v[10:13], v[176:179], v[200:203], v[10:13]
	v_mfma_f32_16x16x32_bf16 v[6:9], v[168:171], v[208:211], v[6:9]
	v_mfma_f32_16x16x32_bf16 v[2:5], v[176:179], v[208:211], v[2:5]
	v_mfma_f32_16x16x32_bf16 v[46:49], v[172:175], v[188:191], v[46:49]
	v_mfma_f32_16x16x32_bf16 v[38:41], v[180:183], v[188:191], v[38:41]
	v_mfma_f32_16x16x32_bf16 v[30:33], v[172:175], v[196:199], v[30:33]
	v_mfma_f32_16x16x32_bf16 v[22:25], v[180:183], v[196:199], v[22:25]
	v_mfma_f32_16x16x32_bf16 v[14:17], v[172:175], v[204:207], v[14:17]
	v_mfma_f32_16x16x32_bf16 v[10:13], v[180:183], v[204:207], v[10:13]
	v_mfma_f32_16x16x32_bf16 v[6:9], v[172:175], v[212:215], v[6:9]
	v_mfma_f32_16x16x32_bf16 v[2:5], v[180:183], v[212:215], v[2:5]
	s_setprio 0
	s_barrier
	s_add_i32 s3, 0, 0x18000
	v_add_u32_e32 v151, s3, v1
	s_add_i32 s12, 0, 0x1c000
	ds_read_b128 v[152:155], v151
	ds_read_b128 v[156:159], v151 offset:1024
	ds_read_b128 v[160:163], v151 offset:2048
	ds_read_b128 v[164:167], v151 offset:3072
	v_add_u32_e32 v151, s12, v1
	ds_read_b128 v[168:171], v151
	ds_read_b128 v[172:175], v151 offset:1024
	ds_read_b128 v[176:179], v151 offset:2048
	ds_read_b128 v[180:183], v151 offset:3072
	s_add_u32 s24, s92, 0x40000
	s_addc_u32 s25, s93, 0
	s_mov_b32 m0, s33
	v_lshl_add_u64 v[224:225], s[24:25], 0, v[136:137]
	ds_read_b128 v[184:187], v150 offset:32768
	ds_read_b128 v[188:191], v150 offset:33792
	ds_read_b128 v[192:195], v150 offset:34816
	ds_read_b128 v[196:199], v150 offset:35840
	ds_read_b128 v[200:203], v150 offset:36864
	ds_read_b128 v[204:207], v150 offset:37888
	ds_read_b128 v[208:211], v150 offset:38912
	ds_read_b128 v[212:215], v150 offset:39936
	global_load_lds_dwordx4 v136, s[24:25]
	v_lshl_add_u64 v[224:225], s[24:25], 0, v[132:133]
	s_mov_b32 m0, s44
	s_nop 0
	global_load_lds_dwordx4 v132, s[24:25]
	s_waitcnt vmcnt(8)
	s_waitcnt lgkmcnt(0)
	s_barrier
	s_setprio 1
	s_waitcnt lgkmcnt(0)
	v_mfma_f32_16x16x32_bf16 v[126:129], v[152:155], v[184:187], v[126:129]
	v_mfma_f32_16x16x32_bf16 v[122:125], v[160:163], v[184:187], v[122:125]
	v_mfma_f32_16x16x32_bf16 v[118:121], v[152:155], v[192:195], v[118:121]
	v_mfma_f32_16x16x32_bf16 v[114:117], v[160:163], v[192:195], v[114:117]
	v_mfma_f32_16x16x32_bf16 v[106:109], v[152:155], v[200:203], v[106:109]
	v_mfma_f32_16x16x32_bf16 v[98:101], v[160:163], v[200:203], v[98:101]
	v_mfma_f32_16x16x32_bf16 v[90:93], v[152:155], v[208:211], v[90:93]
	v_mfma_f32_16x16x32_bf16 v[82:85], v[160:163], v[208:211], v[82:85]
	v_mfma_f32_16x16x32_bf16 v[126:129], v[156:159], v[188:191], v[126:129]
	v_mfma_f32_16x16x32_bf16 v[122:125], v[164:167], v[188:191], v[122:125]
	v_mfma_f32_16x16x32_bf16 v[118:121], v[156:159], v[196:199], v[118:121]
	v_mfma_f32_16x16x32_bf16 v[114:117], v[164:167], v[196:199], v[114:117]
	v_mfma_f32_16x16x32_bf16 v[106:109], v[156:159], v[204:207], v[106:109]
	v_mfma_f32_16x16x32_bf16 v[98:101], v[164:167], v[204:207], v[98:101]
	v_mfma_f32_16x16x32_bf16 v[90:93], v[156:159], v[212:215], v[90:93]
	v_mfma_f32_16x16x32_bf16 v[82:85], v[164:167], v[212:215], v[82:85]
	s_setprio 0
	s_setprio 1
	v_mfma_f32_16x16x32_bf16 v[110:113], v[168:171], v[184:187], v[110:113]
	v_mfma_f32_16x16x32_bf16 v[102:105], v[176:179], v[184:187], v[102:105]
	v_mfma_f32_16x16x32_bf16 v[94:97], v[168:171], v[192:195], v[94:97]
	v_mfma_f32_16x16x32_bf16 v[86:89], v[176:179], v[192:195], v[86:89]
	v_mfma_f32_16x16x32_bf16 v[78:81], v[168:171], v[200:203], v[78:81]
	v_mfma_f32_16x16x32_bf16 v[74:77], v[176:179], v[200:203], v[74:77]
	v_mfma_f32_16x16x32_bf16 v[70:73], v[168:171], v[208:211], v[70:73]
	v_mfma_f32_16x16x32_bf16 v[66:69], v[176:179], v[208:211], v[66:69]
	v_mfma_f32_16x16x32_bf16 v[110:113], v[172:175], v[188:191], v[110:113]
	v_mfma_f32_16x16x32_bf16 v[102:105], v[180:183], v[188:191], v[102:105]
	v_mfma_f32_16x16x32_bf16 v[94:97], v[172:175], v[196:199], v[94:97]
	v_mfma_f32_16x16x32_bf16 v[86:89], v[180:183], v[196:199], v[86:89]
	v_mfma_f32_16x16x32_bf16 v[78:81], v[172:175], v[204:207], v[78:81]
	v_mfma_f32_16x16x32_bf16 v[74:77], v[180:183], v[204:207], v[74:77]
	v_mfma_f32_16x16x32_bf16 v[70:73], v[172:175], v[212:215], v[70:73]
	v_mfma_f32_16x16x32_bf16 v[66:69], v[180:183], v[212:215], v[66:69]
	s_setprio 0
	s_barrier
	s_add_i32 s3, s3, s4
	s_nop 0
	s_mov_b32 m0, s3
	ds_read_b128 v[184:187], v150 offset:49152
	ds_read_b128 v[188:191], v150 offset:50176
	ds_read_b128 v[192:195], v150 offset:51200
	ds_read_b128 v[196:199], v150 offset:52224
	ds_read_b128 v[200:203], v150 offset:53248
	ds_read_b128 v[204:207], v150 offset:54272
	ds_read_b128 v[208:211], v150 offset:55296
	ds_read_b128 v[212:215], v150 offset:56320
	global_load_lds_dwordx4 v251, s[90:91]
	s_add_i32 m0, s3, 0x2000
	s_add_u32 s24, s90, 0x40080
	s_nop 0
	s_addc_u32 s25, s91, 0
	s_add_i32 s3, s12, s4
	global_load_lds_dwordx4 v252, s[90:91]
	s_nop 0
	s_mov_b32 m0, s3
	s_nop 0
	global_load_lds_dwordx4 v134, s[24:25]
	s_nop 0
	s_add_i32 m0, s3, 0x2000
	s_nop 0
	global_load_lds_dwordx4 v130, s[24:25]
	s_nop 0
	s_mov_b32 m0, s48
	s_nop 0
	global_load_lds_dwordx4 v253, s[92:93]
	s_nop 0
	s_mov_b32 m0, s49
	s_nop 0
	global_load_lds_dwordx4 v254, s[92:93]
	s_waitcnt vmcnt(8)
	s_waitcnt lgkmcnt(0)
	s_barrier
	s_setprio 1
	s_waitcnt lgkmcnt(0)
	v_mfma_f32_16x16x32_bf16 v[62:65], v[152:155], v[184:187], v[62:65]
	v_mfma_f32_16x16x32_bf16 v[58:61], v[160:163], v[184:187], v[58:61]
	v_mfma_f32_16x16x32_bf16 v[54:57], v[152:155], v[192:195], v[54:57]
	v_mfma_f32_16x16x32_bf16 v[50:53], v[160:163], v[192:195], v[50:53]
	v_mfma_f32_16x16x32_bf16 v[42:45], v[152:155], v[200:203], v[42:45]
	v_mfma_f32_16x16x32_bf16 v[34:37], v[160:163], v[200:203], v[34:37]
	v_mfma_f32_16x16x32_bf16 v[26:29], v[152:155], v[208:211], v[26:29]
	v_mfma_f32_16x16x32_bf16 v[18:21], v[160:163], v[208:211], v[18:21]
	v_mfma_f32_16x16x32_bf16 v[62:65], v[156:159], v[188:191], v[62:65]
	v_mfma_f32_16x16x32_bf16 v[58:61], v[164:167], v[188:191], v[58:61]
	v_mfma_f32_16x16x32_bf16 v[54:57], v[156:159], v[196:199], v[54:57]
	v_mfma_f32_16x16x32_bf16 v[50:53], v[164:167], v[196:199], v[50:53]
	v_mfma_f32_16x16x32_bf16 v[42:45], v[156:159], v[204:207], v[42:45]
	v_mfma_f32_16x16x32_bf16 v[34:37], v[164:167], v[204:207], v[34:37]
	v_mfma_f32_16x16x32_bf16 v[26:29], v[156:159], v[212:215], v[26:29]
	v_mfma_f32_16x16x32_bf16 v[18:21], v[164:167], v[212:215], v[18:21]
	s_setprio 0
	s_setprio 1
	v_mfma_f32_16x16x32_bf16 v[46:49], v[168:171], v[184:187], v[46:49]
	v_mfma_f32_16x16x32_bf16 v[38:41], v[176:179], v[184:187], v[38:41]
	v_mfma_f32_16x16x32_bf16 v[30:33], v[168:171], v[192:195], v[30:33]
	v_mfma_f32_16x16x32_bf16 v[22:25], v[176:179], v[192:195], v[22:25]
	v_mfma_f32_16x16x32_bf16 v[14:17], v[168:171], v[200:203], v[14:17]
	v_mfma_f32_16x16x32_bf16 v[10:13], v[176:179], v[200:203], v[10:13]
	v_mfma_f32_16x16x32_bf16 v[6:9], v[168:171], v[208:211], v[6:9]
	v_mfma_f32_16x16x32_bf16 v[2:5], v[176:179], v[208:211], v[2:5]
	v_mfma_f32_16x16x32_bf16 v[46:49], v[172:175], v[188:191], v[46:49]
	v_mfma_f32_16x16x32_bf16 v[38:41], v[180:183], v[188:191], v[38:41]
	v_mfma_f32_16x16x32_bf16 v[30:33], v[172:175], v[196:199], v[30:33]
	v_mfma_f32_16x16x32_bf16 v[22:25], v[180:183], v[196:199], v[22:25]
	v_mfma_f32_16x16x32_bf16 v[14:17], v[172:175], v[204:207], v[14:17]
	v_mfma_f32_16x16x32_bf16 v[10:13], v[180:183], v[204:207], v[10:13]
	v_mfma_f32_16x16x32_bf16 v[6:9], v[172:175], v[212:215], v[6:9]
	v_mfma_f32_16x16x32_bf16 v[2:5], v[180:183], v[212:215], v[2:5]
	s_setprio 0
	s_barrier
	s_add_u32 s88, s88, 0x100
	s_addc_u32 s89, s89, 0
	s_add_u32 s83, s83, 0x100
	s_addc_u32 vcc_lo, vcc_lo, 0
	s_cmp_ge_i32 s13, s87
	s_mov_b32 s12, s13
	s_cbranch_scc0 .LBB0_633
	s_and_b64 vcc, exec, s[76:77]
	s_cbranch_vccz .LBB0_636
	s_barrier

.LBB0_662:
	s_ashr_i32 s73, s72, 31
	s_lshl_b64 s[12:13], s[72:73], 19
	v_cmp_lt_i64_e32 vcc, s[74:75], v[150:151]
	s_add_u32 s74, s19, s12
	s_addc_u32 s75, s27, s13
	s_and_b64 s[12:13], vcc, exec
	s_cselect_b32 s37, s75, s83
	s_cselect_b32 s49, s74, s82
	s_ashr_i32 s71, s70, 31
	s_lshl_b64 s[12:13], s[70:71], 19
	s_add_u32 s76, s66, s12
	s_addc_u32 s77, s67, s13
	s_and_b64 s[12:13], vcc, exec
	s_cselect_b32 s71, s77, s85
	s_cselect_b32 s73, s76, s84
	s_add_u32 s82, s82, 0x40080
	s_addc_u32 s83, s83, 0
	s_add_u32 s79, s84, 0x100
	v_mov_b32_e32 v2, 0
	s_addc_u32 vcc_lo, s85, 0
	s_mov_b32 s12, -2
	s_waitcnt lgkmcnt(0)
	v_mov_b32_e32 v3, v2
	v_mov_b32_e32 v4, v2
	v_mov_b32_e32 v5, v2
	v_mov_b32_e32 v6, v2
	v_mov_b32_e32 v7, v2
	v_mov_b32_e32 v8, v2
	v_mov_b32_e32 v9, v2
	v_mov_b32_e32 v10, v2
	v_mov_b32_e32 v11, v2
	v_mov_b32_e32 v12, v2
	v_mov_b32_e32 v13, v2
	v_mov_b32_e32 v14, v2
	v_mov_b32_e32 v15, v2
	v_mov_b32_e32 v16, v2
	v_mov_b32_e32 v17, v2
	v_mov_b32_e32 v18, v2
	v_mov_b32_e32 v19, v2
	v_mov_b32_e32 v20, v2
	v_mov_b32_e32 v21, v2
	v_mov_b32_e32 v22, v2
	v_mov_b32_e32 v23, v2
	v_mov_b32_e32 v24, v2
	v_mov_b32_e32 v25, v2
	v_mov_b32_e32 v26, v2
	v_mov_b32_e32 v27, v2
	v_mov_b32_e32 v28, v2
	v_mov_b32_e32 v29, v2
	v_mov_b32_e32 v30, v2
	v_mov_b32_e32 v31, v2
	v_mov_b32_e32 v32, v2
	v_mov_b32_e32 v33, v2
	v_mov_b32_e32 v66, v2
	v_mov_b32_e32 v67, v2
	v_mov_b32_e32 v68, v2
	v_mov_b32_e32 v69, v2
	v_mov_b32_e32 v70, v2
	v_mov_b32_e32 v71, v2
	v_mov_b32_e32 v72, v2
	v_mov_b32_e32 v73, v2
	v_mov_b32_e32 v74, v2
	v_mov_b32_e32 v75, v2
	v_mov_b32_e32 v76, v2
	v_mov_b32_e32 v77, v2
	v_mov_b32_e32 v78, v2
	v_mov_b32_e32 v79, v2
	v_mov_b32_e32 v80, v2
	v_mov_b32_e32 v81, v2
	v_mov_b32_e32 v82, v2
	v_mov_b32_e32 v83, v2
	v_mov_b32_e32 v84, v2
	v_mov_b32_e32 v85, v2
	v_mov_b32_e32 v86, v2
	v_mov_b32_e32 v87, v2
	v_mov_b32_e32 v88, v2
	v_mov_b32_e32 v89, v2
	v_mov_b32_e32 v90, v2
	v_mov_b32_e32 v91, v2
	v_mov_b32_e32 v92, v2
	v_mov_b32_e32 v93, v2
	v_mov_b32_e32 v94, v2
	v_mov_b32_e32 v95, v2
	v_mov_b32_e32 v96, v2
	v_mov_b32_e32 v97, v2
	v_mov_b32_e32 v34, v2
	v_mov_b32_e32 v35, v2
	v_mov_b32_e32 v36, v2
	v_mov_b32_e32 v37, v2
	v_mov_b32_e32 v38, v2
	v_mov_b32_e32 v39, v2
	v_mov_b32_e32 v40, v2
	v_mov_b32_e32 v41, v2
	v_mov_b32_e32 v42, v2
	v_mov_b32_e32 v43, v2
	v_mov_b32_e32 v44, v2
	v_mov_b32_e32 v45, v2
	v_mov_b32_e32 v46, v2
	v_mov_b32_e32 v47, v2
	v_mov_b32_e32 v48, v2
	v_mov_b32_e32 v49, v2
	v_mov_b32_e32 v50, v2
	v_mov_b32_e32 v51, v2
	v_mov_b32_e32 v52, v2
	v_mov_b32_e32 v53, v2
	v_mov_b32_e32 v54, v2
	v_mov_b32_e32 v55, v2
	v_mov_b32_e32 v56, v2
	v_mov_b32_e32 v57, v2
	v_mov_b32_e32 v58, v2
	v_mov_b32_e32 v59, v2
	v_mov_b32_e32 v60, v2
	v_mov_b32_e32 v61, v2
	v_mov_b32_e32 v62, v2
	v_mov_b32_e32 v63, v2
	v_mov_b32_e32 v64, v2
	v_mov_b32_e32 v65, v2
	v_mov_b32_e32 v106, v2
	v_mov_b32_e32 v107, v2
	v_mov_b32_e32 v108, v2
	v_mov_b32_e32 v109, v2
	v_mov_b32_e32 v110, v2
	v_mov_b32_e32 v111, v2
	v_mov_b32_e32 v112, v2
	v_mov_b32_e32 v113, v2
	v_mov_b32_e32 v114, v2
	v_mov_b32_e32 v115, v2
	v_mov_b32_e32 v116, v2
	v_mov_b32_e32 v117, v2
	v_mov_b32_e32 v118, v2
	v_mov_b32_e32 v119, v2
	v_mov_b32_e32 v120, v2
	v_mov_b32_e32 v121, v2
	v_mov_b32_e32 v122, v2
	v_mov_b32_e32 v123, v2
	v_mov_b32_e32 v124, v2
	v_mov_b32_e32 v125, v2
	v_mov_b32_e32 v126, v2
	v_mov_b32_e32 v127, v2
	v_mov_b32_e32 v128, v2
	v_mov_b32_e32 v129, v2
	v_mov_b32_e32 v130, v2
	v_mov_b32_e32 v131, v2
	v_mov_b32_e32 v132, v2
	v_mov_b32_e32 v133, v2
	v_mov_b32_e32 v134, v2
	v_mov_b32_e32 v135, v2
	v_mov_b32_e32 v136, v2
	v_mov_b32_e32 v137, v2
	v_add_u32_e32 v251, 0x80, v140
	v_add_u32_e32 v252, 0x80, v144
	v_add_u32_e32 v253, 0x80, v138
	v_add_u32_e32 v254, 0x80, v142
.LBB0_663:
	ds_read_b128 v[98:101], v222
	ds_read_b128 v[102:105], v222 offset:1024
	ds_read_b128 v[154:157], v222 offset:2048
	ds_read_b128 v[158:161], v222 offset:3072
	ds_read_b128 v[162:165], v223
	ds_read_b128 v[166:169], v223 offset:1024
	ds_read_b128 v[170:173], v223 offset:2048
	ds_read_b128 v[174:177], v223 offset:3072
	s_add_u32 s3, s82, 0xfffc0080
	s_addc_u32 s13, s83, -1
	s_cmp_eq_u32 s12, 12
	s_cselect_b32 s87, s37, s13
	s_cselect_b32 s86, s49, s3
	s_cselect_b32 s85, s71, vcc_lo
	s_cselect_b32 s84, s73, s79
	s_nop 0
	s_add_i32 m0, s22, 0xc000
	ds_read_b128 v[178:181], v224
	ds_read_b128 v[182:185], v224 offset:1024
	ds_read_b128 v[186:189], v224 offset:2048
	ds_read_b128 v[190:193], v224 offset:3072
	ds_read_b128 v[194:197], v224 offset:4096
	ds_read_b128 v[198:201], v224 offset:5120
	ds_read_b128 v[202:205], v224 offset:6144
	ds_read_b128 v[206:209], v224 offset:7168
	global_load_lds_dwordx4 v146, s[82:83]
	s_nop 0
	s_add_i32 m0, s22, 0xe000
	s_nop 0
	global_load_lds_dwordx4 v148, s[82:83]
	s_waitcnt vmcnt(8)
	s_waitcnt lgkmcnt(0)
	s_barrier
	s_setprio 1
	s_waitcnt lgkmcnt(0)
	v_mfma_f32_16x16x32_bf16 v[134:137], v[98:101], v[178:181], v[134:137]
	v_mfma_f32_16x16x32_bf16 v[130:133], v[154:157], v[178:181], v[130:133]
	v_mfma_f32_16x16x32_bf16 v[126:129], v[98:101], v[186:189], v[126:129]
	v_mfma_f32_16x16x32_bf16 v[122:125], v[154:157], v[186:189], v[122:125]
	v_mfma_f32_16x16x32_bf16 v[118:121], v[98:101], v[194:197], v[118:121]
	v_mfma_f32_16x16x32_bf16 v[114:117], v[154:157], v[194:197], v[114:117]
	v_mfma_f32_16x16x32_bf16 v[110:113], v[98:101], v[202:205], v[110:113]
	v_mfma_f32_16x16x32_bf16 v[106:109], v[154:157], v[202:205], v[106:109]
	v_mfma_f32_16x16x32_bf16 v[134:137], v[102:105], v[182:185], v[134:137]
	v_mfma_f32_16x16x32_bf16 v[130:133], v[158:161], v[182:185], v[130:133]
	v_mfma_f32_16x16x32_bf16 v[126:129], v[102:105], v[190:193], v[126:129]
	v_mfma_f32_16x16x32_bf16 v[122:125], v[158:161], v[190:193], v[122:125]
	v_mfma_f32_16x16x32_bf16 v[118:121], v[102:105], v[198:201], v[118:121]
	v_mfma_f32_16x16x32_bf16 v[114:117], v[158:161], v[198:201], v[114:117]
	v_mfma_f32_16x16x32_bf16 v[110:113], v[102:105], v[206:209], v[110:113]
	v_mfma_f32_16x16x32_bf16 v[106:109], v[158:161], v[206:209], v[106:109]
	s_setprio 0
	s_setprio 1
	v_mfma_f32_16x16x32_bf16 v[62:65], v[162:165], v[178:181], v[62:65]
	v_mfma_f32_16x16x32_bf16 v[58:61], v[170:173], v[178:181], v[58:61]
	v_mfma_f32_16x16x32_bf16 v[54:57], v[162:165], v[186:189], v[54:57]
	v_mfma_f32_16x16x32_bf16 v[50:53], v[170:173], v[186:189], v[50:53]
	v_mfma_f32_16x16x32_bf16 v[46:49], v[162:165], v[194:197], v[46:49]
	v_mfma_f32_16x16x32_bf16 v[42:45], v[170:173], v[194:197], v[42:45]
	v_mfma_f32_16x16x32_bf16 v[38:41], v[162:165], v[202:205], v[38:41]
	v_mfma_f32_16x16x32_bf16 v[34:37], v[170:173], v[202:205], v[34:37]
	v_mfma_f32_16x16x32_bf16 v[62:65], v[166:169], v[182:185], v[62:65]
	v_mfma_f32_16x16x32_bf16 v[58:61], v[174:177], v[182:185], v[58:61]
	v_mfma_f32_16x16x32_bf16 v[54:57], v[166:169], v[190:193], v[54:57]
	v_mfma_f32_16x16x32_bf16 v[50:53], v[174:177], v[190:193], v[50:53]
	v_mfma_f32_16x16x32_bf16 v[46:49], v[166:169], v[198:201], v[46:49]
	v_mfma_f32_16x16x32_bf16 v[42:45], v[174:177], v[198:201], v[42:45]
	v_mfma_f32_16x16x32_bf16 v[38:41], v[166:169], v[206:209], v[38:41]
	v_mfma_f32_16x16x32_bf16 v[34:37], v[174:177], v[206:209], v[34:37]
	s_setprio 0
	s_barrier
	s_add_i32 s3, s93, s5
	s_nop 0
	s_mov_b32 m0, s3
	ds_read_b128 v[178:181], v224 offset:16384
	ds_read_b128 v[182:185], v224 offset:17408
	ds_read_b128 v[186:189], v224 offset:18432
	ds_read_b128 v[190:193], v224 offset:19456
	ds_read_b128 v[194:197], v224 offset:20480
	ds_read_b128 v[198:201], v224 offset:21504
	ds_read_b128 v[202:205], v224 offset:22528
	ds_read_b128 v[206:209], v224 offset:23552
	global_load_lds_dwordx4 v140, s[84:85]
	s_add_i32 m0, s3, 0x2000
	s_add_u32 s24, s84, 0x40000
	v_lshl_add_u64 v[212:213], s[84:85], 0, v[144:145]
	s_addc_u32 s25, s85, 0
	s_add_i32 s3, s48, s5
	global_load_lds_dwordx4 v144, s[84:85]
	s_nop 0
	s_mov_b32 m0, s3
	v_lshl_add_u64 v[216:217], s[86:87], 0, v[142:143]
	global_load_lds_dwordx4 v140, s[24:25]
	s_nop 0
	s_add_i32 m0, s3, 0x2000
	s_nop 0
	global_load_lds_dwordx4 v144, s[24:25]
	s_nop 0
	s_mov_b32 m0, s22
	s_nop 0
	global_load_lds_dwordx4 v138, s[86:87]
	s_mov_b32 m0, s23
	s_nop 0
	global_load_lds_dwordx4 v142, s[86:87]
	s_waitcnt vmcnt(8)
	s_waitcnt lgkmcnt(0)
	s_barrier
	s_setprio 1
	s_waitcnt lgkmcnt(0)
	v_mfma_f32_16x16x32_bf16 v[94:97], v[98:101], v[178:181], v[94:97]
	v_mfma_f32_16x16x32_bf16 v[90:93], v[154:157], v[178:181], v[90:93]
	v_mfma_f32_16x16x32_bf16 v[86:89], v[98:101], v[186:189], v[86:89]
	v_mfma_f32_16x16x32_bf16 v[82:85], v[154:157], v[186:189], v[82:85]
	v_mfma_f32_16x16x32_bf16 v[78:81], v[98:101], v[194:197], v[78:81]
	v_mfma_f32_16x16x32_bf16 v[74:77], v[154:157], v[194:197], v[74:77]
	v_mfma_f32_16x16x32_bf16 v[70:73], v[98:101], v[202:205], v[70:73]
	v_mfma_f32_16x16x32_bf16 v[66:69], v[154:157], v[202:205], v[66:69]
	v_mfma_f32_16x16x32_bf16 v[94:97], v[102:105], v[182:185], v[94:97]
	v_mfma_f32_16x16x32_bf16 v[90:93], v[158:161], v[182:185], v[90:93]
	v_mfma_f32_16x16x32_bf16 v[86:89], v[102:105], v[190:193], v[86:89]
	v_mfma_f32_16x16x32_bf16 v[82:85], v[158:161], v[190:193], v[82:85]
	v_mfma_f32_16x16x32_bf16 v[78:81], v[102:105], v[198:201], v[78:81]
	v_mfma_f32_16x16x32_bf16 v[74:77], v[158:161], v[198:201], v[74:77]
	v_mfma_f32_16x16x32_bf16 v[70:73], v[102:105], v[206:209], v[70:73]
	v_mfma_f32_16x16x32_bf16 v[66:69], v[158:161], v[206:209], v[66:69]
	s_setprio 0
	s_setprio 1
	v_mfma_f32_16x16x32_bf16 v[30:33], v[162:165], v[178:181], v[30:33]
	v_mfma_f32_16x16x32_bf16 v[26:29], v[170:173], v[178:181], v[26:29]
	v_mfma_f32_16x16x32_bf16 v[22:25], v[162:165], v[186:189], v[22:25]
	v_mfma_f32_16x16x32_bf16 v[18:21], v[170:173], v[186:189], v[18:21]
	v_mfma_f32_16x16x32_bf16 v[14:17], v[162:165], v[194:197], v[14:17]
	v_mfma_f32_16x16x32_bf16 v[10:13], v[170:173], v[194:197], v[10:13]
	v_mfma_f32_16x16x32_bf16 v[6:9], v[162:165], v[202:205], v[6:9]
	v_mfma_f32_16x16x32_bf16 v[2:5], v[170:173], v[202:205], v[2:5]
	v_mfma_f32_16x16x32_bf16 v[30:33], v[166:169], v[182:185], v[30:33]
	v_mfma_f32_16x16x32_bf16 v[26:29], v[174:177], v[182:185], v[26:29]
	v_mfma_f32_16x16x32_bf16 v[22:25], v[166:169], v[190:193], v[22:25]
	v_mfma_f32_16x16x32_bf16 v[18:21], v[174:177], v[190:193], v[18:21]
	v_mfma_f32_16x16x32_bf16 v[14:17], v[166:169], v[198:201], v[14:17]
	v_mfma_f32_16x16x32_bf16 v[10:13], v[174:177], v[198:201], v[10:13]
	v_mfma_f32_16x16x32_bf16 v[6:9], v[166:169], v[206:209], v[6:9]
	v_mfma_f32_16x16x32_bf16 v[2:5], v[174:177], v[206:209], v[2:5]
	s_setprio 0
	s_barrier
	s_add_i32 s3, 0, 0x18000
	s_add_i32 s13, 0, 0x1c000
	v_add_u32_e32 v158, s3, v220
	v_add_u32_e32 v174, s13, v220
	ds_read_b128 v[98:101], v158
	ds_read_b128 v[102:105], v158 offset:1024
	ds_read_b128 v[154:157], v158 offset:2048
	ds_read_b128 v[158:161], v158 offset:3072
	ds_read_b128 v[162:165], v174
	ds_read_b128 v[166:169], v174 offset:1024
	ds_read_b128 v[170:173], v174 offset:2048
	ds_read_b128 v[174:177], v174 offset:3072
	s_add_u32 s24, s86, 0x40000
	s_addc_u32 s25, s87, 0
	s_mov_b32 m0, s33
	v_lshl_add_u64 v[218:219], s[24:25], 0, v[138:139]
	ds_read_b128 v[178:181], v224 offset:32768
	ds_read_b128 v[182:185], v224 offset:33792
	ds_read_b128 v[186:189], v224 offset:34816
	ds_read_b128 v[190:193], v224 offset:35840
	ds_read_b128 v[194:197], v224 offset:36864
	ds_read_b128 v[198:201], v224 offset:37888
	ds_read_b128 v[202:205], v224 offset:38912
	ds_read_b128 v[206:209], v224 offset:39936
	global_load_lds_dwordx4 v138, s[24:25]
	v_lshl_add_u64 v[218:219], s[24:25], 0, v[142:143]
	s_mov_b32 m0, s44
	s_nop 0
	global_load_lds_dwordx4 v142, s[24:25]
	s_waitcnt vmcnt(8)
	s_waitcnt lgkmcnt(0)
	s_barrier
	s_setprio 1
	s_waitcnt lgkmcnt(0)
	v_mfma_f32_16x16x32_bf16 v[134:137], v[98:101], v[178:181], v[134:137]
	v_mfma_f32_16x16x32_bf16 v[130:133], v[154:157], v[178:181], v[130:133]
	v_mfma_f32_16x16x32_bf16 v[126:129], v[98:101], v[186:189], v[126:129]
	v_mfma_f32_16x16x32_bf16 v[122:125], v[154:157], v[186:189], v[122:125]
	v_mfma_f32_16x16x32_bf16 v[118:121], v[98:101], v[194:197], v[118:121]
	v_mfma_f32_16x16x32_bf16 v[114:117], v[154:157], v[194:197], v[114:117]
	v_mfma_f32_16x16x32_bf16 v[110:113], v[98:101], v[202:205], v[110:113]
	v_mfma_f32_16x16x32_bf16 v[106:109], v[154:157], v[202:205], v[106:109]
	v_mfma_f32_16x16x32_bf16 v[134:137], v[102:105], v[182:185], v[134:137]
	v_mfma_f32_16x16x32_bf16 v[130:133], v[158:161], v[182:185], v[130:133]
	v_mfma_f32_16x16x32_bf16 v[126:129], v[102:105], v[190:193], v[126:129]
	v_mfma_f32_16x16x32_bf16 v[122:125], v[158:161], v[190:193], v[122:125]
	v_mfma_f32_16x16x32_bf16 v[118:121], v[102:105], v[198:201], v[118:121]
	v_mfma_f32_16x16x32_bf16 v[114:117], v[158:161], v[198:201], v[114:117]
	v_mfma_f32_16x16x32_bf16 v[110:113], v[102:105], v[206:209], v[110:113]
	v_mfma_f32_16x16x32_bf16 v[106:109], v[158:161], v[206:209], v[106:109]
	s_setprio 0
	s_setprio 1
	v_mfma_f32_16x16x32_bf16 v[62:65], v[162:165], v[178:181], v[62:65]
	v_mfma_f32_16x16x32_bf16 v[58:61], v[170:173], v[178:181], v[58:61]
	v_mfma_f32_16x16x32_bf16 v[54:57], v[162:165], v[186:189], v[54:57]
	v_mfma_f32_16x16x32_bf16 v[50:53], v[170:173], v[186:189], v[50:53]
	v_mfma_f32_16x16x32_bf16 v[46:49], v[162:165], v[194:197], v[46:49]
	v_mfma_f32_16x16x32_bf16 v[42:45], v[170:173], v[194:197], v[42:45]
	v_mfma_f32_16x16x32_bf16 v[38:41], v[162:165], v[202:205], v[38:41]
	v_mfma_f32_16x16x32_bf16 v[34:37], v[170:173], v[202:205], v[34:37]
	v_mfma_f32_16x16x32_bf16 v[62:65], v[166:169], v[182:185], v[62:65]
	v_mfma_f32_16x16x32_bf16 v[58:61], v[174:177], v[182:185], v[58:61]
	v_mfma_f32_16x16x32_bf16 v[54:57], v[166:169], v[190:193], v[54:57]
	v_mfma_f32_16x16x32_bf16 v[50:53], v[174:177], v[190:193], v[50:53]
	v_mfma_f32_16x16x32_bf16 v[46:49], v[166:169], v[198:201], v[46:49]
	v_mfma_f32_16x16x32_bf16 v[42:45], v[174:177], v[198:201], v[42:45]
	v_mfma_f32_16x16x32_bf16 v[38:41], v[166:169], v[206:209], v[38:41]
	v_mfma_f32_16x16x32_bf16 v[34:37], v[174:177], v[206:209], v[34:37]
	s_setprio 0
	s_barrier
	s_add_i32 s3, s3, s5
	s_nop 0
	s_mov_b32 m0, s3
	ds_read_b128 v[178:181], v224 offset:49152
	ds_read_b128 v[182:185], v224 offset:50176
	ds_read_b128 v[186:189], v224 offset:51200
	ds_read_b128 v[190:193], v224 offset:52224
	ds_read_b128 v[194:197], v224 offset:53248
	ds_read_b128 v[198:201], v224 offset:54272
	ds_read_b128 v[202:205], v224 offset:55296
	ds_read_b128 v[206:209], v224 offset:56320
	global_load_lds_dwordx4 v251, s[84:85]
	s_add_i32 m0, s3, 0x2000
	s_add_u32 s24, s84, 0x40080
	s_nop 0
	s_addc_u32 s25, s85, 0
	s_add_i32 s3, s13, s5
	global_load_lds_dwordx4 v252, s[84:85]
	s_nop 0
	s_mov_b32 m0, s3
	s_nop 0
	global_load_lds_dwordx4 v140, s[24:25]
	s_nop 0
	s_add_i32 m0, s3, 0x2000
	s_nop 0
	global_load_lds_dwordx4 v144, s[24:25]
	s_nop 0
	s_mov_b32 m0, s90
	s_nop 0
	global_load_lds_dwordx4 v253, s[86:87]
	s_nop 0
	s_mov_b32 m0, s91
	s_nop 0
	global_load_lds_dwordx4 v254, s[86:87]
	s_waitcnt vmcnt(8)
	s_waitcnt lgkmcnt(0)
	s_barrier
	s_setprio 1
	s_waitcnt lgkmcnt(0)
	v_mfma_f32_16x16x32_bf16 v[94:97], v[98:101], v[178:181], v[94:97]
	v_mfma_f32_16x16x32_bf16 v[90:93], v[154:157], v[178:181], v[90:93]
	v_mfma_f32_16x16x32_bf16 v[86:89], v[98:101], v[186:189], v[86:89]
	v_mfma_f32_16x16x32_bf16 v[82:85], v[154:157], v[186:189], v[82:85]
	v_mfma_f32_16x16x32_bf16 v[78:81], v[98:101], v[194:197], v[78:81]
	v_mfma_f32_16x16x32_bf16 v[74:77], v[154:157], v[194:197], v[74:77]
	v_mfma_f32_16x16x32_bf16 v[70:73], v[98:101], v[202:205], v[70:73]
	v_mfma_f32_16x16x32_bf16 v[66:69], v[154:157], v[202:205], v[66:69]
	v_mfma_f32_16x16x32_bf16 v[94:97], v[102:105], v[182:185], v[94:97]
	v_mfma_f32_16x16x32_bf16 v[90:93], v[158:161], v[182:185], v[90:93]
	v_mfma_f32_16x16x32_bf16 v[86:89], v[102:105], v[190:193], v[86:89]
	v_mfma_f32_16x16x32_bf16 v[82:85], v[158:161], v[190:193], v[82:85]
	v_mfma_f32_16x16x32_bf16 v[78:81], v[102:105], v[198:201], v[78:81]
	v_mfma_f32_16x16x32_bf16 v[74:77], v[158:161], v[198:201], v[74:77]
	v_mfma_f32_16x16x32_bf16 v[70:73], v[102:105], v[206:209], v[70:73]
	v_mfma_f32_16x16x32_bf16 v[66:69], v[158:161], v[206:209], v[66:69]
	s_setprio 0
	s_setprio 1
	v_mfma_f32_16x16x32_bf16 v[30:33], v[162:165], v[178:181], v[30:33]
	v_mfma_f32_16x16x32_bf16 v[26:29], v[170:173], v[178:181], v[26:29]
	v_mfma_f32_16x16x32_bf16 v[22:25], v[162:165], v[186:189], v[22:25]
	v_mfma_f32_16x16x32_bf16 v[18:21], v[170:173], v[186:189], v[18:21]
	v_mfma_f32_16x16x32_bf16 v[14:17], v[162:165], v[194:197], v[14:17]
	v_mfma_f32_16x16x32_bf16 v[10:13], v[170:173], v[194:197], v[10:13]
	v_mfma_f32_16x16x32_bf16 v[6:9], v[162:165], v[202:205], v[6:9]
	v_mfma_f32_16x16x32_bf16 v[2:5], v[170:173], v[202:205], v[2:5]
	v_mfma_f32_16x16x32_bf16 v[30:33], v[166:169], v[182:185], v[30:33]
	v_mfma_f32_16x16x32_bf16 v[26:29], v[174:177], v[182:185], v[26:29]
	v_mfma_f32_16x16x32_bf16 v[22:25], v[166:169], v[190:193], v[22:25]
	v_mfma_f32_16x16x32_bf16 v[18:21], v[174:177], v[190:193], v[18:21]
	v_mfma_f32_16x16x32_bf16 v[14:17], v[166:169], v[198:201], v[14:17]
	v_mfma_f32_16x16x32_bf16 v[10:13], v[174:177], v[198:201], v[10:13]
	v_mfma_f32_16x16x32_bf16 v[6:9], v[166:169], v[206:209], v[6:9]
	v_mfma_f32_16x16x32_bf16 v[2:5], v[174:177], v[206:209], v[2:5]
	s_setprio 0
	s_barrier
	s_add_i32 s12, s12, 2
	s_add_u32 s82, s82, 0x100
	s_addc_u32 s83, s83, 0
	s_add_u32 s79, s79, 0x100
	s_addc_u32 vcc_lo, vcc_lo, 0
	s_cmp_gt_u32 s12, 13
	s_cbranch_scc0 .LBB0_663
	s_ashr_i32 s3, s78, 3
	s_ashr_i32 s79, s78, 31
	s_mul_hi_i32 s37, s3, 0x6000
	s_mulk_i32 s3, 0x6000
	s_add_u32 s12, s88, s3
	s_addc_u32 s13, s89, s37
	s_lshl_b64 s[24:25], s[78:79], 20
	s_add_u32 s24, s16, s24
	s_addc_u32 s25, s17, s25
	s_lshl_b64 s[82:83], s[78:79], 19
	s_add_u32 s82, s61, s82
	s_addc_u32 s83, s62, s83
	v_lshl_or_b32 v154, s80, 8, v221
	s_add_u32 s84, s63, s3
	v_ashrrev_i32_e32 v155, 31, v154
	v_mov_b32_e32 v98, v1
	s_addc_u32 s85, s81, s37
	v_lshlrev_b64 v[158:159], 2, v[154:155]
	v_lshl_add_u64 v[160:161], s[84:85], 0, v[158:159]
	v_lshl_add_u64 v[162:163], s[30:31], 0, v[158:159]
	v_lshl_add_u64 v[156:157], s[12:13], 0, v[158:159]
	v_add_u32_e32 v216, s60, v98
	global_load_dwordx4 v[98:101], v[160:161], off offset:16
	global_load_dwordx4 v[102:105], v[160:161], off
	global_load_dwordx4 v[164:167], v[162:163], off offset:16
	global_load_dwordx4 v[168:171], v[162:163], off
	global_load_dwordx4 v[172:175], v[156:157], off offset:16
	global_load_dwordx4 v[176:179], v[156:157], off
	v_ashrrev_i32_e32 v217, 31, v216
	v_lshl_add_u64 v[214:215], s[24:25], 0, v[158:159]
	v_lshlrev_b64 v[186:187], 1, v[154:155]
	v_lshlrev_b64 v[154:155], 12, v[216:217]
	v_lshl_add_u64 v[198:199], s[82:83], 0, v[186:187]
	s_lshl_b32 s49, s78, 8
	v_add_u32_e32 v218, 0x90, v216
	v_ashrrev_i32_e32 v219, 31, v218
	v_add_u32_e32 v204, 0xa0, v216
	v_ashrrev_i32_e32 v205, 31, v204
	s_waitcnt vmcnt(0)
	v_pk_add_f32 v[178:179], v[178:179], 1.0 op_sel_hi:[1,0]
	v_pk_add_f32 v[176:177], v[176:177], 1.0 op_sel_hi:[1,0]
	v_pk_mul_f32 v[188:189], v[170:171], v[178:179]
	v_pk_add_f32 v[170:171], v[172:173], 1.0 op_sel_hi:[1,0]
	v_pk_mul_f32 v[190:191], v[168:169], v[176:177]
	v_pk_add_f32 v[168:169], v[174:175], 1.0 op_sel_hi:[1,0]
	v_pk_mul_f32 v[194:195], v[164:165], v[170:171]
	v_lshl_add_u64 v[164:165], v[214:215], 0, v[154:155]
	v_pk_mul_f32 v[192:193], v[166:167], v[168:169]
	global_load_dwordx4 v[166:169], v[164:165], off offset:16 nt
	global_load_dwordx4 v[170:173], v[164:165], off nt
	v_add_u32_e32 v154, 16, v216
	v_ashrrev_i32_e32 v155, 31, v154
	v_lshlrev_b64 v[158:159], 12, v[154:155]
	v_lshl_add_u64 v[158:159], v[214:215], 0, v[158:159]
	global_load_dwordx4 v[174:177], v[158:159], off offset:16 nt
	global_load_dwordx4 v[178:181], v[158:159], off nt
	s_waitcnt vmcnt(3)
	v_pk_fma_f32 v[166:167], v[130:131], v[98:99], v[166:167]
	s_waitcnt vmcnt(2)
	v_pk_fma_f32 v[136:137], v[136:137], v[104:105], v[172:173]
	v_pk_fma_f32 v[134:135], v[134:135], v[102:103], v[170:171]
	v_pk_fma_f32 v[170:171], v[132:133], v[100:101], v[168:169]
	v_lshlrev_b64 v[168:169], 11, v[216:217]
	v_cvt_pk_f16_f32 v133, v170, v171
	v_cvt_pk_f16_f32 v131, v136, v137
	v_cvt_pk_f16_f32 v132, v166, v167
	v_cvt_pk_f16_f32 v130, v134, v135
	v_lshl_add_u64 v[168:169], v[198:199], 0, v[168:169]
	global_store_dwordx4 v[168:169], v[130:133], off
	s_waitcnt vmcnt(1)
	v_pk_fma_f32 v[128:129], v[128:129], v[104:105], v[180:181]
	v_pk_fma_f32 v[126:127], v[126:127], v[102:103], v[178:179]
	v_mul_f32_e32 v130, v135, v135
	v_mul_f32_e32 v131, v137, v137
	v_fmac_f32_e32 v130, v134, v134
	v_fmac_f32_e32 v131, v136, v136
	v_add_f32_e32 v130, v130, v131
	v_mul_f32_e32 v131, v167, v167
	v_mul_f32_e32 v132, v171, v171
	v_fmac_f32_e32 v131, v166, v166
	v_fmac_f32_e32 v132, v170, v170
	v_add_f32_e32 v131, v131, v132
	v_add_f32_e32 v226, v130, v131
	v_pk_mul_f32 v[130:131], v[188:189], v[136:137]
	v_pk_mul_f32 v[132:133], v[190:191], v[134:135]
	v_pk_mul_f32 v[136:137], v[192:193], v[170:171]
	v_cvt_pk_bf16_f32 v132, v132, v133
	v_cvt_pk_bf16_f32 v133, v130, v131
	v_add_u32_e32 v130, s49, v216
	v_pk_mul_f32 v[134:135], v[194:195], v[166:167]
	v_ashrrev_i32_e32 v131, 31, v130
	v_cvt_pk_bf16_f32 v134, v134, v135
	v_cvt_pk_bf16_f32 v135, v136, v137
	v_lshlrev_b64 v[136:137], 11, v[130:131]
	v_lshl_add_u64 v[136:137], s[0:1], 0, v[136:137]
	v_lshl_add_u64 v[170:171], v[136:137], 0, v[186:187]
	v_pk_fma_f32 v[124:125], v[124:125], v[100:101], v[176:177]
	v_pk_fma_f32 v[122:123], v[122:123], v[98:99], v[174:175]
	v_lshlrev_b64 v[136:137], 11, v[154:155]
	global_store_dwordx4 v[170:171], v[132:135], off
	v_lshl_add_u64 v[172:173], v[198:199], 0, v[136:137]
	v_pk_mul_f32 v[136:137], v[192:193], v[124:125]
	v_cvt_pk_f16_f32 v135, v124, v125
	v_cvt_pk_f16_f32 v133, v128, v129
	v_cvt_pk_f16_f32 v134, v122, v123
	v_cvt_pk_f16_f32 v132, v126, v127
	global_store_dwordx4 v[172:173], v[132:135], off
	v_pk_mul_f32 v[166:167], v[194:195], v[122:123]
	s_nop 0
	v_pk_mul_f32 v[134:135], v[188:189], v[128:129]
	v_pk_mul_f32 v[132:133], v[190:191], v[126:127]
	s_nop 0
	v_cvt_pk_bf16_f32 v132, v132, v133
	v_cvt_pk_bf16_f32 v133, v134, v135
	v_cvt_pk_bf16_f32 v134, v166, v167
	v_cvt_pk_bf16_f32 v135, v136, v137
	v_add_u32_e32 v136, s49, v154
	v_ashrrev_i32_e32 v137, 31, v136
	v_lshlrev_b64 v[136:137], 11, v[136:137]
	v_lshl_add_u64 v[136:137], s[0:1], 0, v[136:137]
	v_lshl_add_u64 v[178:179], v[136:137], 0, v[186:187]
	v_add_u32_e32 v136, 32, v216
	v_ashrrev_i32_e32 v137, 31, v136
	global_store_dwordx4 v[178:179], v[132:135], off
	v_add_u32_e32 v154, 48, v216
	v_ashrrev_i32_e32 v155, 31, v154
	v_lshlrev_b64 v[132:133], 12, v[136:137]
	v_lshl_add_u64 v[180:181], v[214:215], 0, v[132:133]
	global_load_dwordx4 v[132:135], v[180:181], off offset:16 nt
	global_load_dwordx4 v[174:177], v[180:181], off nt
	v_lshlrev_b64 v[166:167], 12, v[154:155]
	v_lshl_add_u64 v[182:183], v[214:215], 0, v[166:167]
	global_load_dwordx4 v[200:203], v[182:183], off offset:16 nt
	global_load_dwordx4 v[206:209], v[182:183], off nt
	v_lshlrev_b64 v[166:167], 11, v[136:137]
	v_add_u32_e32 v136, s49, v136
	v_ashrrev_i32_e32 v137, 31, v136
	v_lshlrev_b64 v[136:137], 11, v[136:137]
	v_lshl_add_u64 v[136:137], s[0:1], 0, v[136:137]
	v_lshl_add_u64 v[184:185], v[136:137], 0, v[186:187]
	v_lshlrev_b64 v[136:137], 11, v[154:155]
	s_waitcnt vmcnt(3)
	v_pk_fma_f32 v[116:117], v[116:117], v[100:101], v[134:135]
	s_waitcnt vmcnt(2)
	v_pk_fma_f32 v[120:121], v[120:121], v[104:105], v[176:177]
	v_pk_fma_f32 v[118:119], v[118:119], v[102:103], v[174:175]
	v_pk_fma_f32 v[114:115], v[114:115], v[98:99], v[132:133]
	v_cvt_pk_f16_f32 v135, v116, v117
	v_cvt_pk_f16_f32 v133, v120, v121
	v_cvt_pk_f16_f32 v134, v114, v115
	v_cvt_pk_f16_f32 v132, v118, v119
	v_lshl_add_u64 v[176:177], v[198:199], 0, v[166:167]
	global_store_dwordx4 v[176:177], v[132:135], off
	v_pk_mul_f32 v[166:167], v[192:193], v[116:117]
	v_pk_mul_f32 v[174:175], v[194:195], v[114:115]
	v_pk_mul_f32 v[134:135], v[188:189], v[120:121]
	v_pk_mul_f32 v[132:133], v[190:191], v[118:119]
	s_waitcnt vmcnt(1)
	v_pk_fma_f32 v[112:113], v[112:113], v[104:105], v[208:209]
	v_cvt_pk_bf16_f32 v132, v132, v133
	v_cvt_pk_bf16_f32 v133, v134, v135
	v_cvt_pk_bf16_f32 v134, v174, v175
	v_cvt_pk_bf16_f32 v135, v166, v167
	v_pk_fma_f32 v[110:111], v[110:111], v[102:103], v[206:207]
	v_pk_fma_f32 v[108:109], v[108:109], v[100:101], v[202:203]
	v_pk_fma_f32 v[106:107], v[106:107], v[98:99], v[200:201]
	global_store_dwordx4 v[184:185], v[132:135], off
	v_lshl_add_u64 v[174:175], v[198:199], 0, v[136:137]
	v_pk_mul_f32 v[136:137], v[192:193], v[108:109]
	v_cvt_pk_f16_f32 v135, v108, v109
	v_cvt_pk_f16_f32 v133, v112, v113
	v_cvt_pk_f16_f32 v134, v106, v107
	v_cvt_pk_f16_f32 v132, v110, v111
	global_store_dwordx4 v[174:175], v[132:135], off
	v_pk_mul_f32 v[166:167], v[194:195], v[106:107]
	v_add_u32_e32 v206, 0x80, v216
	v_pk_mul_f32 v[134:135], v[188:189], v[112:113]
	v_pk_mul_f32 v[132:133], v[190:191], v[110:111]
	v_ashrrev_i32_e32 v207, 31, v206
	v_cvt_pk_bf16_f32 v132, v132, v133
	v_cvt_pk_bf16_f32 v133, v134, v135
	v_cvt_pk_bf16_f32 v134, v166, v167
	v_cvt_pk_bf16_f32 v135, v136, v137
	v_add_u32_e32 v136, s49, v154
	v_ashrrev_i32_e32 v137, 31, v136
	v_lshlrev_b64 v[136:137], 11, v[136:137]
	v_lshl_add_u64 v[136:137], s[0:1], 0, v[136:137]
	v_lshl_add_u64 v[166:167], v[136:137], 0, v[186:187]
	global_store_dwordx4 v[166:167], v[132:135], off
	v_lshlrev_b64 v[136:137], 12, v[218:219]
	v_lshl_add_u64 v[210:211], v[214:215], 0, v[136:137]
	v_lshlrev_b64 v[132:133], 12, v[206:207]
	v_lshl_add_u64 v[196:197], v[214:215], 0, v[132:133]
	global_load_dwordx4 v[200:203], v[196:197], off offset:16 nt
	global_load_dwordx4 v[132:135], v[196:197], off nt
	global_load_dwordx4 v[228:231], v[210:211], off offset:16 nt
	global_load_dwordx4 v[232:235], v[210:211], off nt
	s_waitcnt vmcnt(2)
	v_pk_fma_f32 v[136:137], v[96:97], v[104:105], v[134:135]
	v_pk_fma_f32 v[154:155], v[94:95], v[102:103], v[132:133]
	v_pk_fma_f32 v[132:133], v[92:93], v[100:101], v[202:203]
	v_pk_fma_f32 v[134:135], v[90:91], v[98:99], v[200:201]
	v_lshlrev_b64 v[94:95], 11, v[206:207]
	v_cvt_pk_f16_f32 v93, v132, v133
	v_cvt_pk_f16_f32 v91, v136, v137
	v_cvt_pk_f16_f32 v92, v134, v135
	v_cvt_pk_f16_f32 v90, v154, v155
	v_lshl_add_u64 v[208:209], v[198:199], 0, v[94:95]
	global_store_dwordx4 v[208:209], v[90:93], off
	v_pk_mul_f32 v[94:95], v[192:193], v[132:133]
	v_pk_mul_f32 v[96:97], v[194:195], v[134:135]
	v_pk_mul_f32 v[92:93], v[188:189], v[136:137]
	v_pk_mul_f32 v[90:91], v[190:191], v[154:155]
	s_nop 0
	v_cvt_pk_bf16_f32 v90, v90, v91
	v_cvt_pk_bf16_f32 v91, v92, v93
	v_cvt_pk_bf16_f32 v92, v96, v97
	v_cvt_pk_bf16_f32 v93, v94, v95
	v_add_u32_e32 v94, s49, v206
	v_ashrrev_i32_e32 v95, 31, v94
	v_lshlrev_b64 v[94:95], 11, v[94:95]
	v_lshl_add_u64 v[94:95], s[0:1], 0, v[94:95]
	v_lshl_add_u64 v[212:213], v[94:95], 0, v[186:187]
	global_store_dwordx4 v[212:213], v[90:93], off
	s_waitcnt vmcnt(2)
	v_pk_fma_f32 v[94:95], v[88:89], v[104:105], v[234:235]
	v_pk_fma_f32 v[96:97], v[86:87], v[102:103], v[232:233]
	v_pk_fma_f32 v[90:91], v[84:85], v[100:101], v[230:231]
	v_pk_fma_f32 v[92:93], v[82:83], v[98:99], v[228:229]
	v_lshlrev_b64 v[86:87], 11, v[218:219]
	v_cvt_pk_f16_f32 v85, v90, v91
	v_cvt_pk_f16_f32 v83, v94, v95
	v_cvt_pk_f16_f32 v84, v92, v93
	v_cvt_pk_f16_f32 v82, v96, v97
	v_lshl_add_u64 v[206:207], v[198:199], 0, v[86:87]
	global_store_dwordx4 v[206:207], v[82:85], off
	v_pk_mul_f32 v[86:87], v[192:193], v[90:91]
	v_pk_mul_f32 v[88:89], v[194:195], v[92:93]
	v_pk_mul_f32 v[84:85], v[188:189], v[94:95]
	v_pk_mul_f32 v[82:83], v[190:191], v[96:97]
	s_nop 0
	v_cvt_pk_bf16_f32 v82, v82, v83
	v_cvt_pk_bf16_f32 v83, v84, v85
	v_cvt_pk_bf16_f32 v84, v88, v89
	v_cvt_pk_bf16_f32 v85, v86, v87
	v_add_u32_e32 v86, s49, v218
	v_ashrrev_i32_e32 v87, 31, v86
	v_lshlrev_b64 v[86:87], 11, v[86:87]
	v_lshl_add_u64 v[86:87], s[0:1], 0, v[86:87]
	v_lshl_add_u64 v[202:203], v[86:87], 0, v[186:187]
	global_store_dwordx4 v[202:203], v[82:85], off
	v_add_u32_e32 v218, 0xb0, v216
	v_ashrrev_i32_e32 v219, 31, v218
	v_lshlrev_b64 v[82:83], 12, v[204:205]
	v_lshl_add_u64 v[200:201], v[214:215], 0, v[82:83]
	global_load_dwordx4 v[82:85], v[200:201], off offset:16 nt
	global_load_dwordx4 v[86:89], v[200:201], off nt
	v_lshlrev_b64 v[216:217], 12, v[218:219]
	v_lshl_add_u64 v[214:215], v[214:215], 0, v[216:217]
	global_load_dwordx4 v[228:231], v[214:215], off offset:16 nt
	global_load_dwordx4 v[232:235], v[214:215], off nt
	s_waitcnt vmcnt(3)
	v_pk_fma_f32 v[76:77], v[76:77], v[100:101], v[84:85]
	s_waitcnt vmcnt(2)
	v_pk_fma_f32 v[80:81], v[80:81], v[104:105], v[88:89]
	v_pk_fma_f32 v[78:79], v[78:79], v[102:103], v[86:87]
	v_pk_fma_f32 v[74:75], v[74:75], v[98:99], v[82:83]
	v_lshlrev_b64 v[86:87], 11, v[204:205]
	v_cvt_pk_f16_f32 v85, v76, v77
	v_cvt_pk_f16_f32 v83, v80, v81
	v_cvt_pk_f16_f32 v84, v74, v75
	v_cvt_pk_f16_f32 v82, v78, v79
	v_lshl_add_u64 v[216:217], v[198:199], 0, v[86:87]
	global_store_dwordx4 v[216:217], v[82:85], off
	v_pk_mul_f32 v[86:87], v[192:193], v[76:77]
	v_pk_mul_f32 v[88:89], v[194:195], v[74:75]
	v_pk_mul_f32 v[84:85], v[188:189], v[80:81]
	v_pk_mul_f32 v[82:83], v[190:191], v[78:79]
	s_nop 0
	v_cvt_pk_bf16_f32 v82, v82, v83
	v_cvt_pk_bf16_f32 v83, v84, v85
	v_cvt_pk_bf16_f32 v84, v88, v89
	v_cvt_pk_bf16_f32 v85, v86, v87
	v_add_u32_e32 v86, s49, v204
	v_ashrrev_i32_e32 v87, 31, v86
	v_lshlrev_b64 v[86:87], 11, v[86:87]
	v_lshl_add_u64 v[86:87], s[0:1], 0, v[86:87]
	v_lshl_add_u64 v[204:205], v[86:87], 0, v[186:187]
	global_store_dwordx4 v[204:205], v[82:85], off
	s_waitcnt vmcnt(2)
	v_pk_fma_f32 v[86:87], v[72:73], v[104:105], v[234:235]
	v_pk_fma_f32 v[88:89], v[70:71], v[102:103], v[232:233]
	v_pk_fma_f32 v[82:83], v[68:69], v[100:101], v[230:231]
	v_pk_fma_f32 v[84:85], v[66:67], v[98:99], v[228:229]
	v_lshlrev_b64 v[70:71], 11, v[218:219]
	v_cvt_pk_f16_f32 v69, v82, v83
	v_cvt_pk_f16_f32 v67, v86, v87
	v_cvt_pk_f16_f32 v68, v84, v85
	v_cvt_pk_f16_f32 v66, v88, v89
	v_lshl_add_u64 v[98:99], v[198:199], 0, v[70:71]
	global_store_dwordx4 v[98:99], v[66:69], off
	v_pk_mul_f32 v[70:71], v[192:193], v[82:83]
	v_pk_mul_f32 v[72:73], v[194:195], v[84:85]
	v_pk_mul_f32 v[68:69], v[188:189], v[86:87]
	v_pk_mul_f32 v[66:67], v[190:191], v[88:89]
	s_nop 0
	v_cvt_pk_bf16_f32 v66, v66, v67
	v_cvt_pk_bf16_f32 v67, v68, v69
	v_cvt_pk_bf16_f32 v68, v72, v73
	v_cvt_pk_bf16_f32 v69, v70, v71
	v_add_u32_e32 v70, s49, v218
	v_ashrrev_i32_e32 v71, 31, v70
	v_lshlrev_b64 v[70:71], 11, v[70:71]
	v_lshl_add_u64 v[70:71], s[0:1], 0, v[70:71]
	v_lshl_add_u64 v[100:101], v[70:71], 0, v[186:187]
	global_store_dwordx4 v[100:101], v[66:69], off
	global_load_dwordx4 v[66:69], v[160:161], off offset:528
	s_nop 0
	global_load_dwordx4 v[70:73], v[160:161], off offset:512
	global_load_dwordx4 v[186:189], v[162:163], off offset:528
	s_nop 0
	global_load_dwordx4 v[160:163], v[162:163], off offset:512
	s_nop 0
	global_load_dwordx4 v[190:193], v[156:157], off offset:528
	global_load_dwordx4 v[102:105], v[156:157], off offset:512
	s_waitcnt vmcnt(0)
	v_pk_add_f32 v[104:105], v[104:105], 1.0 op_sel_hi:[1,0]
	v_pk_add_f32 v[156:157], v[102:103], 1.0 op_sel_hi:[1,0]
	v_pk_mul_f32 v[102:103], v[162:163], v[104:105]
	v_pk_mul_f32 v[104:105], v[160:161], v[156:157]
	v_pk_add_f32 v[156:157], v[192:193], 1.0 op_sel_hi:[1,0]
	v_pk_add_f32 v[160:161], v[190:191], 1.0 op_sel_hi:[1,0]
	v_pk_mul_f32 v[156:157], v[188:189], v[156:157]
	v_pk_mul_f32 v[160:161], v[186:187], v[160:161]
	global_load_dwordx4 v[186:189], v[164:165], off offset:528 nt
	s_nop 0
	global_load_dwordx4 v[162:165], v[164:165], off offset:512 nt
	s_nop 0
	global_load_dwordx4 v[190:193], v[158:159], off offset:528 nt
	global_load_dwordx4 v[228:231], v[158:159], off offset:512 nt
	s_waitcnt vmcnt(3)
	v_pk_fma_f32 v[158:159], v[60:61], v[68:69], v[188:189]
	s_waitcnt vmcnt(2)
	v_pk_fma_f32 v[64:65], v[64:65], v[72:73], v[164:165]
	v_pk_fma_f32 v[62:63], v[62:63], v[70:71], v[162:163]
	v_pk_fma_f32 v[162:163], v[58:59], v[66:67], v[186:187]
	v_cvt_pk_f16_f32 v61, v158, v159
	v_cvt_pk_f16_f32 v59, v64, v65
	v_cvt_pk_f16_f32 v60, v162, v163
	v_cvt_pk_f16_f32 v58, v62, v63
	global_store_dwordx4 v[168:169], v[58:61], off offset:256
	s_waitcnt vmcnt(1)
	v_pk_fma_f32 v[56:57], v[56:57], v[72:73], v[230:231]
	v_pk_fma_f32 v[54:55], v[54:55], v[70:71], v[228:229]
	v_mul_f32_e32 v58, v63, v63
	v_mul_f32_e32 v59, v65, v65
	v_fmac_f32_e32 v58, v62, v62
	v_fmac_f32_e32 v59, v64, v64
	v_add_f32_e32 v58, v58, v59
	v_mul_f32_e32 v59, v163, v163
	v_mul_f32_e32 v60, v159, v159
	v_fmac_f32_e32 v59, v162, v162
	v_fmac_f32_e32 v60, v158, v158
	v_add_f32_e32 v59, v59, v60
	v_pk_mul_f32 v[60:61], v[104:105], v[62:63]
	v_pk_mul_f32 v[62:63], v[160:161], v[162:163]
	v_pk_mul_f32 v[64:65], v[102:103], v[64:65]
	v_pk_mul_f32 v[158:159], v[156:157], v[158:159]
	v_cvt_pk_bf16_f32 v60, v60, v61
	v_cvt_pk_bf16_f32 v61, v64, v65
	v_cvt_pk_bf16_f32 v62, v62, v63
	v_pk_fma_f32 v[52:53], v[52:53], v[68:69], v[192:193]
	v_cvt_pk_bf16_f32 v63, v158, v159
	v_pk_fma_f32 v[50:51], v[50:51], v[66:67], v[190:191]
	global_store_dwordx4 v[170:171], v[60:63], off offset:256
	v_pk_mul_f32 v[64:65], v[156:157], v[52:53]
	v_pk_mul_f32 v[158:159], v[160:161], v[50:51]
	v_cvt_pk_f16_f32 v63, v52, v53
	v_cvt_pk_f16_f32 v61, v56, v57
	v_cvt_pk_f16_f32 v62, v50, v51
	v_cvt_pk_f16_f32 v60, v54, v55
	global_store_dwordx4 v[172:173], v[60:63], off offset:256
	v_add_f32_e32 v58, v58, v59
	v_xor_b32_e32 v59, 16, v225
	v_pk_mul_f32 v[62:63], v[102:103], v[56:57]
	v_pk_mul_f32 v[60:61], v[104:105], v[54:55]
	v_add_f32_e32 v58, v226, v58
	v_cvt_pk_bf16_f32 v60, v60, v61
	v_cvt_pk_bf16_f32 v61, v62, v63
	v_cvt_pk_bf16_f32 v62, v158, v159
	v_cvt_pk_bf16_f32 v63, v64, v65
	global_store_dwordx4 v[178:179], v[60:63], off offset:256
	global_load_dwordx4 v[60:63], v[180:181], off offset:528 nt
	s_nop 0
	global_load_dwordx4 v[162:165], v[180:181], off offset:512 nt
	global_load_dwordx4 v[168:171], v[182:183], off offset:528 nt
	s_nop 0
	global_load_dwordx4 v[178:181], v[182:183], off offset:512 nt
	s_waitcnt vmcnt(3)
	v_pk_fma_f32 v[44:45], v[44:45], v[68:69], v[62:63]
	s_waitcnt vmcnt(2)
	v_pk_fma_f32 v[48:49], v[48:49], v[72:73], v[164:165]
	v_pk_fma_f32 v[46:47], v[46:47], v[70:71], v[162:163]
	v_pk_fma_f32 v[42:43], v[42:43], v[66:67], v[60:61]
	v_cvt_pk_f16_f32 v63, v44, v45
	v_cvt_pk_f16_f32 v61, v48, v49
	v_cvt_pk_f16_f32 v62, v42, v43
	v_cvt_pk_f16_f32 v60, v46, v47
	global_store_dwordx4 v[176:177], v[60:63], off offset:256
	v_pk_mul_f32 v[64:65], v[156:157], v[44:45]
	v_pk_mul_f32 v[158:159], v[160:161], v[42:43]
	v_pk_mul_f32 v[62:63], v[102:103], v[48:49]
	v_pk_mul_f32 v[60:61], v[104:105], v[46:47]
	s_waitcnt vmcnt(1)
	v_pk_fma_f32 v[40:41], v[40:41], v[72:73], v[180:181]
	v_cvt_pk_bf16_f32 v60, v60, v61
	v_cvt_pk_bf16_f32 v61, v62, v63
	v_cvt_pk_bf16_f32 v62, v158, v159
	v_cvt_pk_bf16_f32 v63, v64, v65
	v_pk_fma_f32 v[38:39], v[38:39], v[70:71], v[178:179]
	v_pk_fma_f32 v[36:37], v[36:37], v[68:69], v[170:171]
	v_pk_fma_f32 v[34:35], v[34:35], v[66:67], v[168:169]
	global_store_dwordx4 v[184:185], v[60:63], off offset:256
	v_pk_mul_f32 v[64:65], v[156:157], v[36:37]
	v_pk_mul_f32 v[158:159], v[160:161], v[34:35]
	v_cvt_pk_f16_f32 v63, v36, v37
	v_cvt_pk_f16_f32 v61, v40, v41
	v_cvt_pk_f16_f32 v62, v34, v35
	v_cvt_pk_f16_f32 v60, v38, v39
	global_store_dwordx4 v[174:175], v[60:63], off offset:256
	s_nop 1
	v_pk_mul_f32 v[62:63], v[102:103], v[40:41]
	v_pk_mul_f32 v[60:61], v[104:105], v[38:39]
	s_nop 0
	v_cvt_pk_bf16_f32 v60, v60, v61
	v_cvt_pk_bf16_f32 v61, v62, v63
	v_cvt_pk_bf16_f32 v62, v158, v159
	v_cvt_pk_bf16_f32 v63, v64, v65
	global_store_dwordx4 v[166:167], v[60:63], off offset:256
	global_load_dwordx4 v[60:63], v[196:197], off offset:528 nt
	s_nop 0
	global_load_dwordx4 v[162:165], v[196:197], off offset:512 nt
	global_load_dwordx4 v[166:169], v[210:211], off offset:528 nt
	global_load_dwordx4 v[170:173], v[210:211], off offset:512 nt
	s_waitcnt vmcnt(3)
	v_pk_fma_f32 v[28:29], v[28:29], v[68:69], v[62:63]
	s_waitcnt vmcnt(2)
	v_pk_fma_f32 v[32:33], v[32:33], v[72:73], v[164:165]
	v_pk_fma_f32 v[30:31], v[30:31], v[70:71], v[162:163]
	v_pk_fma_f32 v[26:27], v[26:27], v[66:67], v[60:61]
	v_cvt_pk_f16_f32 v63, v28, v29
	v_cvt_pk_f16_f32 v61, v32, v33
	v_cvt_pk_f16_f32 v62, v26, v27
	v_cvt_pk_f16_f32 v60, v30, v31
	global_store_dwordx4 v[208:209], v[60:63], off offset:256
	v_pk_mul_f32 v[64:65], v[156:157], v[28:29]
	v_pk_mul_f32 v[158:159], v[160:161], v[26:27]
	v_pk_mul_f32 v[62:63], v[102:103], v[32:33]
	v_pk_mul_f32 v[60:61], v[104:105], v[30:31]
	s_waitcnt vmcnt(1)
	v_pk_fma_f32 v[24:25], v[24:25], v[72:73], v[172:173]
	v_cvt_pk_bf16_f32 v60, v60, v61
	v_cvt_pk_bf16_f32 v61, v62, v63
	v_cvt_pk_bf16_f32 v62, v158, v159
	v_cvt_pk_bf16_f32 v63, v64, v65
	v_pk_fma_f32 v[22:23], v[22:23], v[70:71], v[170:171]
	v_pk_fma_f32 v[20:21], v[20:21], v[68:69], v[168:169]
	v_pk_fma_f32 v[18:19], v[18:19], v[66:67], v[166:167]
	global_store_dwordx4 v[212:213], v[60:63], off offset:256
	v_pk_mul_f32 v[64:65], v[156:157], v[20:21]
	v_pk_mul_f32 v[158:159], v[160:161], v[18:19]
	v_cvt_pk_f16_f32 v63, v20, v21
	v_cvt_pk_f16_f32 v61, v24, v25
	v_cvt_pk_f16_f32 v62, v18, v19
	v_cvt_pk_f16_f32 v60, v22, v23
	global_store_dwordx4 v[206:207], v[60:63], off offset:256
	s_nop 1
	v_pk_mul_f32 v[62:63], v[102:103], v[24:25]
	v_pk_mul_f32 v[60:61], v[104:105], v[22:23]
	s_nop 0
	v_cvt_pk_bf16_f32 v60, v60, v61
	v_cvt_pk_bf16_f32 v61, v62, v63
	v_cvt_pk_bf16_f32 v62, v158, v159
	v_cvt_pk_bf16_f32 v63, v64, v65
	global_store_dwordx4 v[202:203], v[60:63], off offset:256
	global_load_dwordx4 v[60:63], v[200:201], off offset:528 nt
	s_nop 0
	global_load_dwordx4 v[162:165], v[200:201], off offset:512 nt
	global_load_dwordx4 v[166:169], v[214:215], off offset:528 nt
	global_load_dwordx4 v[170:173], v[214:215], off offset:512 nt
	s_waitcnt vmcnt(3)
	v_pk_fma_f32 v[12:13], v[12:13], v[68:69], v[62:63]
	s_waitcnt vmcnt(2)
	v_pk_fma_f32 v[16:17], v[16:17], v[72:73], v[164:165]
	v_pk_fma_f32 v[14:15], v[14:15], v[70:71], v[162:163]
	v_pk_fma_f32 v[10:11], v[10:11], v[66:67], v[60:61]
	v_cvt_pk_f16_f32 v63, v12, v13
	v_cvt_pk_f16_f32 v61, v16, v17
	v_cvt_pk_f16_f32 v62, v10, v11
	v_cvt_pk_f16_f32 v60, v14, v15
	global_store_dwordx4 v[216:217], v[60:63], off offset:256
	v_pk_mul_f32 v[64:65], v[156:157], v[12:13]
	v_pk_mul_f32 v[158:159], v[160:161], v[10:11]
	v_pk_mul_f32 v[62:63], v[102:103], v[16:17]
	v_pk_mul_f32 v[60:61], v[104:105], v[14:15]
	s_waitcnt vmcnt(1)
	v_pk_fma_f32 v[8:9], v[8:9], v[72:73], v[172:173]
	v_cvt_pk_bf16_f32 v60, v60, v61
	v_cvt_pk_bf16_f32 v61, v62, v63
	v_cvt_pk_bf16_f32 v62, v158, v159
	v_cvt_pk_bf16_f32 v63, v64, v65
	v_pk_fma_f32 v[6:7], v[6:7], v[70:71], v[170:171]
	v_pk_fma_f32 v[4:5], v[4:5], v[68:69], v[168:169]
	v_pk_fma_f32 v[2:3], v[2:3], v[66:67], v[166:167]
	global_store_dwordx4 v[204:205], v[60:63], off offset:256
	v_pk_mul_f32 v[64:65], v[156:157], v[4:5]
	v_pk_mul_f32 v[66:67], v[160:161], v[2:3]
	v_cvt_pk_f16_f32 v63, v4, v5
	v_cvt_pk_f16_f32 v61, v8, v9
	v_cvt_pk_f16_f32 v62, v2, v3
	v_cvt_pk_f16_f32 v60, v6, v7
	global_store_dwordx4 v[98:99], v[60:63], off offset:256
	s_nop 1
	v_pk_mul_f32 v[60:61], v[104:105], v[6:7]
	v_pk_mul_f32 v[62:63], v[102:103], v[8:9]
	v_cvt_pk_bf16_f32 v60, v60, v61
	s_nop 0
	v_cvt_pk_bf16_f32 v61, v62, v63
	v_cvt_pk_bf16_f32 v62, v66, v67
	v_cvt_pk_bf16_f32 v63, v64, v65
	global_store_dwordx4 v[100:101], v[60:63], off offset:256
	s_nop 1
	v_and_b32_e32 v60, 64, v225
	v_add_u32_e32 v60, 64, v60
	v_cmp_lt_i32_e32 vcc, v59, v60
	v_xor_b32_e32 v61, 32, v225
	s_nop 0
	v_cndmask_b32_e32 v59, v225, v59, vcc
	v_lshlrev_b32_e32 v59, 2, v59
	v_cmp_lt_i32_e32 vcc, v61, v60
	s_nop 1
	v_cndmask_b32_e32 v60, v225, v61, vcc
	ds_bpermute_b32 v61, v59, v58
	v_lshlrev_b32_e32 v60, 2, v60
	s_waitcnt lgkmcnt(0)
	v_add_f32_e32 v58, v58, v61
	ds_bpermute_b32 v61, v60, v58
	s_and_saveexec_b64 s[78:79], s[6:7]
	s_cbranch_execz .LBB0_666
	v_lshl_add_u64 v[62:63], v[130:131], 2, s[52:53]
	s_waitcnt lgkmcnt(0)
	v_add_f32_e32 v58, v58, v61
	global_atomic_add_f32 v[62:63], v58, off

.LBB0_776:
	s_ashr_i32 s75, s74, 31
	s_lshl_b64 s[12:13], s[74:75], 19
	s_add_u32 s80, s4, s12
	s_addc_u32 s81, s5, s13
	s_and_b64 s[12:13], s[78:79], exec
	s_cselect_b32 s11, s81, s85
	s_cselect_b32 s37, s80, s84
	s_ashr_i32 s77, s76, 31
	s_lshl_b64 s[12:13], s[76:77], 19
	s_add_u32 s82, s19, s12
	s_addc_u32 s83, s22, s13
	s_and_b64 s[12:13], s[78:79], exec
	s_cselect_b32 s75, s83, s87
	s_cselect_b32 s77, s82, s86
	s_add_u32 s84, s84, 0x40080
	s_addc_u32 s85, s85, 0
	s_add_u32 s92, s86, 0x100
	v_mov_b32_e32 v2, 0
	s_addc_u32 s93, s87, 0
	s_mov_b32 s12, -2
	v_mov_b32_e32 v3, v2
	v_mov_b32_e32 v4, v2
	v_mov_b32_e32 v5, v2
	v_mov_b32_e32 v6, v2
	v_mov_b32_e32 v7, v2
	v_mov_b32_e32 v8, v2
	v_mov_b32_e32 v9, v2
	v_mov_b32_e32 v18, v2
	v_mov_b32_e32 v19, v2
	v_mov_b32_e32 v20, v2
	v_mov_b32_e32 v21, v2
	v_mov_b32_e32 v22, v2
	v_mov_b32_e32 v23, v2
	v_mov_b32_e32 v24, v2
	v_mov_b32_e32 v25, v2
	v_mov_b32_e32 v34, v2
	v_mov_b32_e32 v35, v2
	v_mov_b32_e32 v36, v2
	v_mov_b32_e32 v37, v2
	v_mov_b32_e32 v38, v2
	v_mov_b32_e32 v39, v2
	v_mov_b32_e32 v40, v2
	v_mov_b32_e32 v41, v2
	v_mov_b32_e32 v66, v2
	v_mov_b32_e32 v67, v2
	v_mov_b32_e32 v68, v2
	v_mov_b32_e32 v69, v2
	v_mov_b32_e32 v70, v2
	v_mov_b32_e32 v71, v2
	v_mov_b32_e32 v72, v2
	v_mov_b32_e32 v73, v2
	v_mov_b32_e32 v10, v2
	v_mov_b32_e32 v11, v2
	v_mov_b32_e32 v12, v2
	v_mov_b32_e32 v13, v2
	v_mov_b32_e32 v14, v2
	v_mov_b32_e32 v15, v2
	v_mov_b32_e32 v16, v2
	v_mov_b32_e32 v17, v2
	v_mov_b32_e32 v26, v2
	v_mov_b32_e32 v27, v2
	v_mov_b32_e32 v28, v2
	v_mov_b32_e32 v29, v2
	v_mov_b32_e32 v30, v2
	v_mov_b32_e32 v31, v2
	v_mov_b32_e32 v32, v2
	v_mov_b32_e32 v33, v2
	v_mov_b32_e32 v42, v2
	v_mov_b32_e32 v43, v2
	v_mov_b32_e32 v44, v2
	v_mov_b32_e32 v45, v2
	v_mov_b32_e32 v46, v2
	v_mov_b32_e32 v47, v2
	v_mov_b32_e32 v48, v2
	v_mov_b32_e32 v49, v2
	v_mov_b32_e32 v74, v2
	v_mov_b32_e32 v75, v2
	v_mov_b32_e32 v76, v2
	v_mov_b32_e32 v77, v2
	v_mov_b32_e32 v78, v2
	v_mov_b32_e32 v79, v2
	v_mov_b32_e32 v80, v2
	v_mov_b32_e32 v81, v2
	v_mov_b32_e32 v82, v2
	v_mov_b32_e32 v83, v2
	v_mov_b32_e32 v84, v2
	v_mov_b32_e32 v85, v2
	v_mov_b32_e32 v86, v2
	v_mov_b32_e32 v87, v2
	v_mov_b32_e32 v88, v2
	v_mov_b32_e32 v89, v2
	v_mov_b32_e32 v98, v2
	v_mov_b32_e32 v99, v2
	v_mov_b32_e32 v100, v2
	v_mov_b32_e32 v101, v2
	v_mov_b32_e32 v102, v2
	v_mov_b32_e32 v103, v2
	v_mov_b32_e32 v104, v2
	v_mov_b32_e32 v105, v2
	v_mov_b32_e32 v114, v2
	v_mov_b32_e32 v115, v2
	v_mov_b32_e32 v116, v2
	v_mov_b32_e32 v117, v2
	v_mov_b32_e32 v118, v2
	v_mov_b32_e32 v119, v2
	v_mov_b32_e32 v120, v2
	v_mov_b32_e32 v121, v2
	v_mov_b32_e32 v130, v2
	v_mov_b32_e32 v131, v2
	v_mov_b32_e32 v132, v2
	v_mov_b32_e32 v133, v2
	v_mov_b32_e32 v134, v2
	v_mov_b32_e32 v135, v2
	v_mov_b32_e32 v136, v2
	v_mov_b32_e32 v137, v2
	v_mov_b32_e32 v90, v2
	v_mov_b32_e32 v91, v2
	v_mov_b32_e32 v92, v2
	v_mov_b32_e32 v93, v2
	v_mov_b32_e32 v94, v2
	v_mov_b32_e32 v95, v2
	v_mov_b32_e32 v96, v2
	v_mov_b32_e32 v97, v2
	v_mov_b32_e32 v106, v2
	v_mov_b32_e32 v107, v2
	v_mov_b32_e32 v108, v2
	v_mov_b32_e32 v109, v2
	v_mov_b32_e32 v110, v2
	v_mov_b32_e32 v111, v2
	v_mov_b32_e32 v112, v2
	v_mov_b32_e32 v113, v2
	v_mov_b32_e32 v122, v2
	v_mov_b32_e32 v123, v2
	v_mov_b32_e32 v124, v2
	v_mov_b32_e32 v125, v2
	v_mov_b32_e32 v126, v2
	v_mov_b32_e32 v127, v2
	v_mov_b32_e32 v128, v2
	v_mov_b32_e32 v129, v2
	v_mov_b32_e32 v138, v2
	v_mov_b32_e32 v139, v2
	v_mov_b32_e32 v140, v2
	v_mov_b32_e32 v141, v2
	v_mov_b32_e32 v142, v2
	v_mov_b32_e32 v143, v2
	v_mov_b32_e32 v144, v2
	v_mov_b32_e32 v145, v2
	v_add_u32_e32 v251, 0x80, v150
	v_add_u32_e32 v252, 0x80, v154
	v_add_u32_e32 v253, 0x80, v148
	v_add_u32_e32 v254, 0x80, v152
.LBB0_777:
	ds_read_b128 v[50:53], v182
	ds_read_b128 v[54:57], v182 offset:1024
	ds_read_b128 v[58:61], v182 offset:2048
	ds_read_b128 v[62:65], v182 offset:3072
	ds_read_b128 v[166:169], v183
	ds_read_b128 v[188:191], v183 offset:1024
	ds_read_b128 v[192:195], v183 offset:2048
	ds_read_b128 v[196:199], v183 offset:3072
	s_add_u32 s3, s84, 0xfffc0080
	s_addc_u32 s13, s85, -1
	s_cmp_eq_u32 s12, 12
	s_cselect_b32 s89, s11, s13
	s_cselect_b32 s88, s37, s3
	s_cselect_b32 s87, s75, s93
	s_cselect_b32 s86, s77, s92
	s_nop 0
	s_add_i32 m0, s33, 0xc000
	ds_read_b128 v[200:203], v184
	ds_read_b128 v[204:207], v184 offset:1024
	ds_read_b128 v[208:211], v184 offset:2048
	ds_read_b128 v[212:215], v184 offset:3072
	ds_read_b128 v[216:219], v184 offset:4096
	ds_read_b128 v[220:223], v184 offset:5120
	ds_read_b128 v[224:227], v184 offset:6144
	ds_read_b128 v[228:231], v184 offset:7168
	global_load_lds_dwordx4 v158, s[84:85]
	s_nop 0
	s_add_i32 m0, s33, 0xe000
	s_nop 0
	global_load_lds_dwordx4 v160, s[84:85]
	s_waitcnt vmcnt(8)
	s_waitcnt lgkmcnt(0)
	s_barrier
	s_setprio 1
	s_waitcnt lgkmcnt(0)
	v_mfma_f32_16x16x32_bf16 v[142:145], v[50:53], v[200:203], v[142:145]
	v_mfma_f32_16x16x32_bf16 v[138:141], v[58:61], v[200:203], v[138:141]
	v_mfma_f32_16x16x32_bf16 v[126:129], v[50:53], v[208:211], v[126:129]
	v_mfma_f32_16x16x32_bf16 v[122:125], v[58:61], v[208:211], v[122:125]
	v_mfma_f32_16x16x32_bf16 v[110:113], v[50:53], v[216:219], v[110:113]
	v_mfma_f32_16x16x32_bf16 v[106:109], v[58:61], v[216:219], v[106:109]
	v_mfma_f32_16x16x32_bf16 v[94:97], v[50:53], v[224:227], v[94:97]
	v_mfma_f32_16x16x32_bf16 v[90:93], v[58:61], v[224:227], v[90:93]
	v_mfma_f32_16x16x32_bf16 v[142:145], v[54:57], v[204:207], v[142:145]
	v_mfma_f32_16x16x32_bf16 v[138:141], v[62:65], v[204:207], v[138:141]
	v_mfma_f32_16x16x32_bf16 v[126:129], v[54:57], v[212:215], v[126:129]
	v_mfma_f32_16x16x32_bf16 v[122:125], v[62:65], v[212:215], v[122:125]
	v_mfma_f32_16x16x32_bf16 v[110:113], v[54:57], v[220:223], v[110:113]
	v_mfma_f32_16x16x32_bf16 v[106:109], v[62:65], v[220:223], v[106:109]
	v_mfma_f32_16x16x32_bf16 v[94:97], v[54:57], v[228:231], v[94:97]
	v_mfma_f32_16x16x32_bf16 v[90:93], v[62:65], v[228:231], v[90:93]
	s_setprio 0
	s_setprio 1
	v_mfma_f32_16x16x32_bf16 v[134:137], v[166:169], v[200:203], v[134:137]
	v_mfma_f32_16x16x32_bf16 v[130:133], v[192:195], v[200:203], v[130:133]
	v_mfma_f32_16x16x32_bf16 v[118:121], v[166:169], v[208:211], v[118:121]
	v_mfma_f32_16x16x32_bf16 v[114:117], v[192:195], v[208:211], v[114:117]
	v_mfma_f32_16x16x32_bf16 v[102:105], v[166:169], v[216:219], v[102:105]
	v_mfma_f32_16x16x32_bf16 v[98:101], v[192:195], v[216:219], v[98:101]
	v_mfma_f32_16x16x32_bf16 v[86:89], v[166:169], v[224:227], v[86:89]
	v_mfma_f32_16x16x32_bf16 v[82:85], v[192:195], v[224:227], v[82:85]
	v_mfma_f32_16x16x32_bf16 v[134:137], v[188:191], v[204:207], v[134:137]
	v_mfma_f32_16x16x32_bf16 v[130:133], v[196:199], v[204:207], v[130:133]
	v_mfma_f32_16x16x32_bf16 v[118:121], v[188:191], v[212:215], v[118:121]
	v_mfma_f32_16x16x32_bf16 v[114:117], v[196:199], v[212:215], v[114:117]
	v_mfma_f32_16x16x32_bf16 v[102:105], v[188:191], v[220:223], v[102:105]
	v_mfma_f32_16x16x32_bf16 v[98:101], v[196:199], v[220:223], v[98:101]
	v_mfma_f32_16x16x32_bf16 v[86:89], v[188:191], v[228:231], v[86:89]
	v_mfma_f32_16x16x32_bf16 v[82:85], v[196:199], v[228:231], v[82:85]
	s_setprio 0
	s_barrier
	s_add_i32 s3, s66, s23
	s_nop 0
	s_mov_b32 m0, s3
	ds_read_b128 v[200:203], v184 offset:16384
	ds_read_b128 v[204:207], v184 offset:17408
	ds_read_b128 v[208:211], v184 offset:18432
	ds_read_b128 v[212:215], v184 offset:19456
	ds_read_b128 v[216:219], v184 offset:20480
	ds_read_b128 v[220:223], v184 offset:21504
	ds_read_b128 v[224:227], v184 offset:22528
	ds_read_b128 v[228:231], v184 offset:23552
	global_load_lds_dwordx4 v150, s[86:87]
	s_add_i32 m0, s3, 0x2000
	s_add_u32 s24, s86, 0x40000
	v_lshl_add_u64 v[232:233], s[86:87], 0, v[154:155]
	s_addc_u32 s25, s87, 0
	s_add_i32 s3, s67, s23
	global_load_lds_dwordx4 v154, s[86:87]
	s_nop 0
	s_mov_b32 m0, s3
	v_lshl_add_u64 v[236:237], s[88:89], 0, v[152:153]
	global_load_lds_dwordx4 v150, s[24:25]
	s_nop 0
	s_add_i32 m0, s3, 0x2000
	s_nop 0
	global_load_lds_dwordx4 v154, s[24:25]
	s_nop 0
	s_mov_b32 m0, s33
	s_nop 0
	global_load_lds_dwordx4 v148, s[88:89]
	s_mov_b32 m0, s44
	s_nop 0
	global_load_lds_dwordx4 v152, s[88:89]
	s_waitcnt vmcnt(8)
	s_waitcnt lgkmcnt(0)
	s_barrier
	s_setprio 1
	s_waitcnt lgkmcnt(0)
	v_mfma_f32_16x16x32_bf16 v[78:81], v[50:53], v[200:203], v[78:81]
	v_mfma_f32_16x16x32_bf16 v[74:77], v[58:61], v[200:203], v[74:77]
	v_mfma_f32_16x16x32_bf16 v[46:49], v[50:53], v[208:211], v[46:49]
	v_mfma_f32_16x16x32_bf16 v[42:45], v[58:61], v[208:211], v[42:45]
	v_mfma_f32_16x16x32_bf16 v[30:33], v[50:53], v[216:219], v[30:33]
	v_mfma_f32_16x16x32_bf16 v[26:29], v[58:61], v[216:219], v[26:29]
	v_mfma_f32_16x16x32_bf16 v[14:17], v[50:53], v[224:227], v[14:17]
	v_mfma_f32_16x16x32_bf16 v[10:13], v[58:61], v[224:227], v[10:13]
	v_mfma_f32_16x16x32_bf16 v[78:81], v[54:57], v[204:207], v[78:81]
	v_mfma_f32_16x16x32_bf16 v[74:77], v[62:65], v[204:207], v[74:77]
	v_mfma_f32_16x16x32_bf16 v[46:49], v[54:57], v[212:215], v[46:49]
	v_mfma_f32_16x16x32_bf16 v[42:45], v[62:65], v[212:215], v[42:45]
	v_mfma_f32_16x16x32_bf16 v[30:33], v[54:57], v[220:223], v[30:33]
	v_mfma_f32_16x16x32_bf16 v[26:29], v[62:65], v[220:223], v[26:29]
	v_mfma_f32_16x16x32_bf16 v[14:17], v[54:57], v[228:231], v[14:17]
	v_mfma_f32_16x16x32_bf16 v[10:13], v[62:65], v[228:231], v[10:13]
	s_setprio 0
	s_setprio 1
	v_mfma_f32_16x16x32_bf16 v[38:41], v[166:169], v[208:211], v[38:41]
	v_mfma_f32_16x16x32_bf16 v[34:37], v[192:195], v[208:211], v[34:37]
	v_mfma_f32_16x16x32_bf16 v[22:25], v[166:169], v[216:219], v[22:25]
	v_mfma_f32_16x16x32_bf16 v[18:21], v[192:195], v[216:219], v[18:21]
	v_mfma_f32_16x16x32_bf16 v[6:9], v[166:169], v[224:227], v[6:9]
	v_mfma_f32_16x16x32_bf16 v[2:5], v[192:195], v[224:227], v[2:5]
	v_mfma_f32_16x16x32_bf16 v[50:53], v[166:169], v[200:203], v[70:73]
	v_mfma_f32_16x16x32_bf16 v[54:57], v[192:195], v[200:203], v[66:69]
	v_mfma_f32_16x16x32_bf16 v[38:41], v[188:191], v[212:215], v[38:41]
	v_mfma_f32_16x16x32_bf16 v[34:37], v[196:199], v[212:215], v[34:37]
	v_mfma_f32_16x16x32_bf16 v[22:25], v[188:191], v[220:223], v[22:25]
	v_mfma_f32_16x16x32_bf16 v[18:21], v[196:199], v[220:223], v[18:21]
	v_mfma_f32_16x16x32_bf16 v[6:9], v[188:191], v[228:231], v[6:9]
	v_mfma_f32_16x16x32_bf16 v[2:5], v[196:199], v[228:231], v[2:5]
	v_mfma_f32_16x16x32_bf16 v[50:53], v[188:191], v[204:207], v[50:53]
	v_mfma_f32_16x16x32_bf16 v[54:57], v[196:199], v[204:207], v[54:57]
	s_setprio 0
	s_barrier
	s_add_i32 s3, 0, 0x18000
	s_add_i32 s13, 0, 0x1c000
	v_add_u32_e32 v70, s3, v173
	v_add_u32_e32 v187, s13, v173
	ds_read_b128 v[58:61], v70
	ds_read_b128 v[62:65], v70 offset:1024
	ds_read_b128 v[66:69], v70 offset:2048
	ds_read_b128 v[70:73], v70 offset:3072
	ds_read_b128 v[166:169], v187
	ds_read_b128 v[188:191], v187 offset:1024
	ds_read_b128 v[192:195], v187 offset:2048
	ds_read_b128 v[196:199], v187 offset:3072
	s_add_u32 s24, s88, 0x40000
	s_addc_u32 s25, s89, 0
	s_mov_b32 m0, s45
	s_nop 0
	ds_read_b128 v[200:203], v184 offset:32768
	ds_read_b128 v[204:207], v184 offset:33792
	ds_read_b128 v[208:211], v184 offset:34816
	ds_read_b128 v[212:215], v184 offset:35840
	ds_read_b128 v[216:219], v184 offset:36864
	ds_read_b128 v[220:223], v184 offset:37888
	ds_read_b128 v[224:227], v184 offset:38912
	ds_read_b128 v[228:231], v184 offset:39936
	global_load_lds_dwordx4 v148, s[24:25]
	s_nop 0
	s_mov_b32 m0, s48
	s_nop 0
	global_load_lds_dwordx4 v152, s[24:25]
	s_waitcnt vmcnt(8)
	s_waitcnt lgkmcnt(0)
	s_barrier
	s_setprio 1
	s_waitcnt lgkmcnt(0)
	v_mfma_f32_16x16x32_bf16 v[142:145], v[58:61], v[200:203], v[142:145]
	v_mfma_f32_16x16x32_bf16 v[138:141], v[66:69], v[200:203], v[138:141]
	v_mfma_f32_16x16x32_bf16 v[126:129], v[58:61], v[208:211], v[126:129]
	v_mfma_f32_16x16x32_bf16 v[122:125], v[66:69], v[208:211], v[122:125]
	v_mfma_f32_16x16x32_bf16 v[110:113], v[58:61], v[216:219], v[110:113]
	v_mfma_f32_16x16x32_bf16 v[106:109], v[66:69], v[216:219], v[106:109]
	v_mfma_f32_16x16x32_bf16 v[94:97], v[58:61], v[224:227], v[94:97]
	v_mfma_f32_16x16x32_bf16 v[90:93], v[66:69], v[224:227], v[90:93]
	v_mfma_f32_16x16x32_bf16 v[142:145], v[62:65], v[204:207], v[142:145]
	v_mfma_f32_16x16x32_bf16 v[138:141], v[70:73], v[204:207], v[138:141]
	v_mfma_f32_16x16x32_bf16 v[126:129], v[62:65], v[212:215], v[126:129]
	v_mfma_f32_16x16x32_bf16 v[122:125], v[70:73], v[212:215], v[122:125]
	v_mfma_f32_16x16x32_bf16 v[110:113], v[62:65], v[220:223], v[110:113]
	v_mfma_f32_16x16x32_bf16 v[106:109], v[70:73], v[220:223], v[106:109]
	v_mfma_f32_16x16x32_bf16 v[94:97], v[62:65], v[228:231], v[94:97]
	v_mfma_f32_16x16x32_bf16 v[90:93], v[70:73], v[228:231], v[90:93]
	s_setprio 0
	s_setprio 1
	v_mfma_f32_16x16x32_bf16 v[134:137], v[166:169], v[200:203], v[134:137]
	v_mfma_f32_16x16x32_bf16 v[130:133], v[192:195], v[200:203], v[130:133]
	v_mfma_f32_16x16x32_bf16 v[118:121], v[166:169], v[208:211], v[118:121]
	v_mfma_f32_16x16x32_bf16 v[114:117], v[192:195], v[208:211], v[114:117]
	v_mfma_f32_16x16x32_bf16 v[102:105], v[166:169], v[216:219], v[102:105]
	v_mfma_f32_16x16x32_bf16 v[98:101], v[192:195], v[216:219], v[98:101]
	v_mfma_f32_16x16x32_bf16 v[86:89], v[166:169], v[224:227], v[86:89]
	v_mfma_f32_16x16x32_bf16 v[82:85], v[192:195], v[224:227], v[82:85]
	v_mfma_f32_16x16x32_bf16 v[134:137], v[188:191], v[204:207], v[134:137]
	v_mfma_f32_16x16x32_bf16 v[130:133], v[196:199], v[204:207], v[130:133]
	v_mfma_f32_16x16x32_bf16 v[118:121], v[188:191], v[212:215], v[118:121]
	v_mfma_f32_16x16x32_bf16 v[114:117], v[196:199], v[212:215], v[114:117]
	v_mfma_f32_16x16x32_bf16 v[102:105], v[188:191], v[220:223], v[102:105]
	v_mfma_f32_16x16x32_bf16 v[98:101], v[196:199], v[220:223], v[98:101]
	v_mfma_f32_16x16x32_bf16 v[86:89], v[188:191], v[228:231], v[86:89]
	v_mfma_f32_16x16x32_bf16 v[82:85], v[196:199], v[228:231], v[82:85]
	s_setprio 0
	s_barrier
	s_add_i32 s3, s3, s23
	s_nop 0
	s_mov_b32 m0, s3
	ds_read_b128 v[200:203], v184 offset:49152
	ds_read_b128 v[204:207], v184 offset:50176
	ds_read_b128 v[208:211], v184 offset:51200
	ds_read_b128 v[212:215], v184 offset:52224
	ds_read_b128 v[216:219], v184 offset:53248
	ds_read_b128 v[220:223], v184 offset:54272
	ds_read_b128 v[224:227], v184 offset:55296
	ds_read_b128 v[228:231], v184 offset:56320
	global_load_lds_dwordx4 v251, s[86:87]
	s_add_i32 m0, s3, 0x2000
	s_add_u32 s24, s86, 0x40080
	s_nop 0
	s_addc_u32 s25, s87, 0
	s_add_i32 s3, s13, s23
	global_load_lds_dwordx4 v252, s[86:87]
	s_nop 0
	s_mov_b32 m0, s3
	s_nop 0
	global_load_lds_dwordx4 v150, s[24:25]
	s_nop 0
	s_add_i32 m0, s3, 0x2000
	s_nop 0
	global_load_lds_dwordx4 v154, s[24:25]
	s_nop 0
	s_mov_b32 m0, s60
	s_nop 0
	global_load_lds_dwordx4 v253, s[88:89]
	s_nop 0
	s_mov_b32 m0, s61
	s_nop 0
	global_load_lds_dwordx4 v254, s[88:89]
	s_waitcnt vmcnt(8)
	s_waitcnt lgkmcnt(0)
	s_barrier
	s_setprio 1
	s_waitcnt lgkmcnt(0)
	v_mfma_f32_16x16x32_bf16 v[78:81], v[58:61], v[200:203], v[78:81]
	v_mfma_f32_16x16x32_bf16 v[74:77], v[66:69], v[200:203], v[74:77]
	v_mfma_f32_16x16x32_bf16 v[46:49], v[58:61], v[208:211], v[46:49]
	v_mfma_f32_16x16x32_bf16 v[42:45], v[66:69], v[208:211], v[42:45]
	v_mfma_f32_16x16x32_bf16 v[30:33], v[58:61], v[216:219], v[30:33]
	v_mfma_f32_16x16x32_bf16 v[26:29], v[66:69], v[216:219], v[26:29]
	v_mfma_f32_16x16x32_bf16 v[14:17], v[58:61], v[224:227], v[14:17]
	v_mfma_f32_16x16x32_bf16 v[10:13], v[66:69], v[224:227], v[10:13]
	v_mfma_f32_16x16x32_bf16 v[78:81], v[62:65], v[204:207], v[78:81]
	v_mfma_f32_16x16x32_bf16 v[74:77], v[70:73], v[204:207], v[74:77]
	v_mfma_f32_16x16x32_bf16 v[46:49], v[62:65], v[212:215], v[46:49]
	v_mfma_f32_16x16x32_bf16 v[42:45], v[70:73], v[212:215], v[42:45]
	v_mfma_f32_16x16x32_bf16 v[30:33], v[62:65], v[220:223], v[30:33]
	v_mfma_f32_16x16x32_bf16 v[26:29], v[70:73], v[220:223], v[26:29]
	v_mfma_f32_16x16x32_bf16 v[14:17], v[62:65], v[228:231], v[14:17]
	v_mfma_f32_16x16x32_bf16 v[10:13], v[70:73], v[228:231], v[10:13]
	s_setprio 0
	s_setprio 1
	v_mfma_f32_16x16x32_bf16 v[50:53], v[166:169], v[200:203], v[50:53]
	v_mfma_f32_16x16x32_bf16 v[70:73], v[188:191], v[204:207], v[50:53]
	v_mfma_f32_16x16x32_bf16 v[50:53], v[192:195], v[200:203], v[54:57]
	v_mfma_f32_16x16x32_bf16 v[38:41], v[166:169], v[208:211], v[38:41]
	v_mfma_f32_16x16x32_bf16 v[34:37], v[192:195], v[208:211], v[34:37]
	v_mfma_f32_16x16x32_bf16 v[22:25], v[166:169], v[216:219], v[22:25]
	v_mfma_f32_16x16x32_bf16 v[18:21], v[192:195], v[216:219], v[18:21]
	v_mfma_f32_16x16x32_bf16 v[6:9], v[166:169], v[224:227], v[6:9]
	v_mfma_f32_16x16x32_bf16 v[2:5], v[192:195], v[224:227], v[2:5]
	v_mfma_f32_16x16x32_bf16 v[66:69], v[196:199], v[204:207], v[50:53]
	v_mfma_f32_16x16x32_bf16 v[38:41], v[188:191], v[212:215], v[38:41]
	v_mfma_f32_16x16x32_bf16 v[34:37], v[196:199], v[212:215], v[34:37]
	v_mfma_f32_16x16x32_bf16 v[22:25], v[188:191], v[220:223], v[22:25]
	v_mfma_f32_16x16x32_bf16 v[18:21], v[196:199], v[220:223], v[18:21]
	v_mfma_f32_16x16x32_bf16 v[6:9], v[188:191], v[228:231], v[6:9]
	v_mfma_f32_16x16x32_bf16 v[2:5], v[196:199], v[228:231], v[2:5]
	s_setprio 0
	s_barrier
	s_add_i32 s12, s12, 2
	s_add_u32 s84, s84, 0x100
	s_addc_u32 s85, s85, 0
	s_add_u32 s92, s92, 0x100
	s_addc_u32 s93, s93, 0
	s_cmp_gt_u32 s12, 13
	s_cbranch_scc0 .LBB0_777
	s_and_b64 vcc, exec, s[70:71]
	s_cbranch_vccz .LBB0_780
	s_barrier

.LBB0_817:
	s_add_i32 s80, s21, -2
	s_add_u32 s81, s70, 0x100
	v_mov_b32_e32 v2, 0
	s_addc_u32 s82, s71, 0
	s_mov_b32 s12, 0
	v_mov_b32_e32 v3, v2
	v_mov_b32_e32 v4, v2
	v_mov_b32_e32 v5, v2
	v_mov_b32_e32 v6, v2
	v_mov_b32_e32 v7, v2
	v_mov_b32_e32 v8, v2
	v_mov_b32_e32 v9, v2
	v_mov_b32_e32 v10, v2
	v_mov_b32_e32 v11, v2
	v_mov_b32_e32 v12, v2
	v_mov_b32_e32 v13, v2
	v_mov_b32_e32 v14, v2
	v_mov_b32_e32 v15, v2
	v_mov_b32_e32 v16, v2
	v_mov_b32_e32 v17, v2
	v_mov_b32_e32 v18, v2
	v_mov_b32_e32 v19, v2
	v_mov_b32_e32 v20, v2
	v_mov_b32_e32 v21, v2
	v_mov_b32_e32 v26, v2
	v_mov_b32_e32 v27, v2
	v_mov_b32_e32 v28, v2
	v_mov_b32_e32 v29, v2
	v_mov_b32_e32 v34, v2
	v_mov_b32_e32 v35, v2
	v_mov_b32_e32 v36, v2
	v_mov_b32_e32 v37, v2
	v_mov_b32_e32 v42, v2
	v_mov_b32_e32 v43, v2
	v_mov_b32_e32 v44, v2
	v_mov_b32_e32 v45, v2
	v_mov_b32_e32 v22, v2
	v_mov_b32_e32 v23, v2
	v_mov_b32_e32 v24, v2
	v_mov_b32_e32 v25, v2
	v_mov_b32_e32 v30, v2
	v_mov_b32_e32 v31, v2
	v_mov_b32_e32 v32, v2
	v_mov_b32_e32 v33, v2
	v_mov_b32_e32 v38, v2
	v_mov_b32_e32 v39, v2
	v_mov_b32_e32 v40, v2
	v_mov_b32_e32 v41, v2
	v_mov_b32_e32 v46, v2
	v_mov_b32_e32 v47, v2
	v_mov_b32_e32 v48, v2
	v_mov_b32_e32 v49, v2
	v_mov_b32_e32 v50, v2
	v_mov_b32_e32 v51, v2
	v_mov_b32_e32 v52, v2
	v_mov_b32_e32 v53, v2
	v_mov_b32_e32 v54, v2
	v_mov_b32_e32 v55, v2
	v_mov_b32_e32 v56, v2
	v_mov_b32_e32 v57, v2
	v_mov_b32_e32 v58, v2
	v_mov_b32_e32 v59, v2
	v_mov_b32_e32 v60, v2
	v_mov_b32_e32 v61, v2
	v_mov_b32_e32 v62, v2
	v_mov_b32_e32 v63, v2
	v_mov_b32_e32 v64, v2
	v_mov_b32_e32 v65, v2
	v_mov_b32_e32 v66, v2
	v_mov_b32_e32 v67, v2
	v_mov_b32_e32 v68, v2
	v_mov_b32_e32 v69, v2
	v_mov_b32_e32 v70, v2
	v_mov_b32_e32 v71, v2
	v_mov_b32_e32 v72, v2
	v_mov_b32_e32 v73, v2
	v_mov_b32_e32 v74, v2
	v_mov_b32_e32 v75, v2
	v_mov_b32_e32 v76, v2
	v_mov_b32_e32 v77, v2
	v_mov_b32_e32 v78, v2
	v_mov_b32_e32 v79, v2
	v_mov_b32_e32 v80, v2
	v_mov_b32_e32 v81, v2
	v_mov_b32_e32 v82, v2
	v_mov_b32_e32 v83, v2
	v_mov_b32_e32 v84, v2
	v_mov_b32_e32 v85, v2
	v_mov_b32_e32 v90, v2
	v_mov_b32_e32 v91, v2
	v_mov_b32_e32 v92, v2
	v_mov_b32_e32 v93, v2
	v_mov_b32_e32 v98, v2
	v_mov_b32_e32 v99, v2
	v_mov_b32_e32 v100, v2
	v_mov_b32_e32 v101, v2
	v_mov_b32_e32 v106, v2
	v_mov_b32_e32 v107, v2
	v_mov_b32_e32 v108, v2
	v_mov_b32_e32 v109, v2
	v_mov_b32_e32 v86, v2
	v_mov_b32_e32 v87, v2
	v_mov_b32_e32 v88, v2
	v_mov_b32_e32 v89, v2
	v_mov_b32_e32 v94, v2
	v_mov_b32_e32 v95, v2
	v_mov_b32_e32 v96, v2
	v_mov_b32_e32 v97, v2
	v_mov_b32_e32 v102, v2
	v_mov_b32_e32 v103, v2
	v_mov_b32_e32 v104, v2
	v_mov_b32_e32 v105, v2
	v_mov_b32_e32 v110, v2
	v_mov_b32_e32 v111, v2
	v_mov_b32_e32 v112, v2
	v_mov_b32_e32 v113, v2
	v_mov_b32_e32 v114, v2
	v_mov_b32_e32 v115, v2
	v_mov_b32_e32 v116, v2
	v_mov_b32_e32 v117, v2
	v_mov_b32_e32 v118, v2
	v_mov_b32_e32 v119, v2
	v_mov_b32_e32 v120, v2
	v_mov_b32_e32 v121, v2
	v_mov_b32_e32 v122, v2
	v_mov_b32_e32 v123, v2
	v_mov_b32_e32 v124, v2
	v_mov_b32_e32 v125, v2
	v_mov_b32_e32 v126, v2
	v_mov_b32_e32 v127, v2
	v_mov_b32_e32 v128, v2
	v_mov_b32_e32 v129, v2
	v_add_u32_e32 v251, 0x80, v134
	v_add_u32_e32 v252, 0x80, v130
	v_add_u32_e32 v253, 0x80, v136
	v_add_u32_e32 v254, 0x80, v132
.LBB0_818:
	ds_read_b128 v[152:155], v148
	ds_read_b128 v[156:159], v148 offset:1024
	ds_read_b128 v[160:163], v148 offset:2048
	ds_read_b128 v[164:167], v148 offset:3072
	ds_read_b128 v[168:171], v149
	ds_read_b128 v[172:175], v149 offset:1024
	ds_read_b128 v[176:179], v149 offset:2048
	ds_read_b128 v[180:183], v149 offset:3072
	s_add_i32 s13, s12, 2
	s_add_u32 s70, s68, 0x100
	s_addc_u32 s71, s69, 0
	s_cmp_eq_u32 s80, s12
	s_cselect_b32 s75, s7, s71
	s_cselect_b32 s74, s6, s70
	s_cselect_b32 s73, s53, s82
	s_cselect_b32 s72, s52, s81
	v_lshl_add_u64 v[216:217], s[68:69], 0, v[140:141]
	s_add_i32 m0, s36, 0xc000
	ds_read_b128 v[184:187], v150
	ds_read_b128 v[188:191], v150 offset:1024
	ds_read_b128 v[192:195], v150 offset:2048
	ds_read_b128 v[196:199], v150 offset:3072
	ds_read_b128 v[200:203], v150 offset:4096
	ds_read_b128 v[204:207], v150 offset:5120
	ds_read_b128 v[208:211], v150 offset:6144
	ds_read_b128 v[212:215], v150 offset:7168
	global_load_lds_dwordx4 v[216:217], off
	v_lshl_add_u64 v[216:217], s[68:69], 0, v[142:143]
	s_add_i32 m0, s36, 0xe000
	s_nop 0
	global_load_lds_dwordx4 v[216:217], off
	s_waitcnt vmcnt(8)
	s_waitcnt lgkmcnt(0)
	s_barrier
	s_setprio 1
	s_waitcnt lgkmcnt(0)
	v_mfma_f32_16x16x32_bf16 v[126:129], v[152:155], v[184:187], v[126:129]
	v_mfma_f32_16x16x32_bf16 v[122:125], v[160:163], v[184:187], v[122:125]
	v_mfma_f32_16x16x32_bf16 v[118:121], v[152:155], v[192:195], v[118:121]
	v_mfma_f32_16x16x32_bf16 v[114:117], v[160:163], v[192:195], v[114:117]
	v_mfma_f32_16x16x32_bf16 v[110:113], v[152:155], v[200:203], v[110:113]
	v_mfma_f32_16x16x32_bf16 v[102:105], v[160:163], v[200:203], v[102:105]
	v_mfma_f32_16x16x32_bf16 v[94:97], v[152:155], v[208:211], v[94:97]
	v_mfma_f32_16x16x32_bf16 v[86:89], v[160:163], v[208:211], v[86:89]
	v_mfma_f32_16x16x32_bf16 v[126:129], v[156:159], v[188:191], v[126:129]
	v_mfma_f32_16x16x32_bf16 v[122:125], v[164:167], v[188:191], v[122:125]
	v_mfma_f32_16x16x32_bf16 v[118:121], v[156:159], v[196:199], v[118:121]
	v_mfma_f32_16x16x32_bf16 v[114:117], v[164:167], v[196:199], v[114:117]
	v_mfma_f32_16x16x32_bf16 v[110:113], v[156:159], v[204:207], v[110:113]
	v_mfma_f32_16x16x32_bf16 v[102:105], v[164:167], v[204:207], v[102:105]
	v_mfma_f32_16x16x32_bf16 v[94:97], v[156:159], v[212:215], v[94:97]
	v_mfma_f32_16x16x32_bf16 v[86:89], v[164:167], v[212:215], v[86:89]
	s_setprio 0
	s_setprio 1
	v_mfma_f32_16x16x32_bf16 v[106:109], v[168:171], v[184:187], v[106:109]
	v_mfma_f32_16x16x32_bf16 v[98:101], v[176:179], v[184:187], v[98:101]
	v_mfma_f32_16x16x32_bf16 v[90:93], v[168:171], v[192:195], v[90:93]
	v_mfma_f32_16x16x32_bf16 v[82:85], v[176:179], v[192:195], v[82:85]
	v_mfma_f32_16x16x32_bf16 v[78:81], v[168:171], v[200:203], v[78:81]
	v_mfma_f32_16x16x32_bf16 v[74:77], v[176:179], v[200:203], v[74:77]
	v_mfma_f32_16x16x32_bf16 v[70:73], v[168:171], v[208:211], v[70:73]
	v_mfma_f32_16x16x32_bf16 v[66:69], v[176:179], v[208:211], v[66:69]
	v_mfma_f32_16x16x32_bf16 v[106:109], v[172:175], v[188:191], v[106:109]
	v_mfma_f32_16x16x32_bf16 v[98:101], v[180:183], v[188:191], v[98:101]
	v_mfma_f32_16x16x32_bf16 v[90:93], v[172:175], v[196:199], v[90:93]
	v_mfma_f32_16x16x32_bf16 v[82:85], v[180:183], v[196:199], v[82:85]
	v_mfma_f32_16x16x32_bf16 v[78:81], v[172:175], v[204:207], v[78:81]
	v_mfma_f32_16x16x32_bf16 v[74:77], v[180:183], v[204:207], v[74:77]
	v_mfma_f32_16x16x32_bf16 v[70:73], v[172:175], v[212:215], v[70:73]
	v_mfma_f32_16x16x32_bf16 v[66:69], v[180:183], v[212:215], v[66:69]
	s_setprio 0
	s_barrier
	s_add_i32 s3, s63, s27
	s_nop 0
	s_mov_b32 m0, s3
	ds_read_b128 v[184:187], v150 offset:16384
	ds_read_b128 v[188:191], v150 offset:17408
	ds_read_b128 v[192:195], v150 offset:18432
	ds_read_b128 v[196:199], v150 offset:19456
	ds_read_b128 v[200:203], v150 offset:20480
	ds_read_b128 v[204:207], v150 offset:21504
	ds_read_b128 v[208:211], v150 offset:22528
	ds_read_b128 v[212:215], v150 offset:23552
	global_load_lds_dwordx4 v134, s[72:73]
	s_add_i32 m0, s3, 0x2000
	s_add_u32 s24, s72, 0xb0000
	v_lshl_add_u64 v[218:219], s[72:73], 0, v[130:131]
	s_addc_u32 s25, s73, 0
	s_add_i32 s3, s66, s27
	global_load_lds_dwordx4 v130, s[72:73]
	s_nop 0
	s_mov_b32 m0, s3
	v_lshl_add_u64 v[222:223], s[74:75], 0, v[132:133]
	global_load_lds_dwordx4 v134, s[24:25]
	s_nop 0
	s_add_i32 m0, s3, 0x2000
	s_nop 0
	global_load_lds_dwordx4 v130, s[24:25]
	s_nop 0
	s_mov_b32 m0, s36
	s_nop 0
	global_load_lds_dwordx4 v136, s[74:75]
	s_mov_b32 m0, s37
	s_nop 0
	global_load_lds_dwordx4 v132, s[74:75]
	s_waitcnt vmcnt(8)
	s_waitcnt lgkmcnt(0)
	s_barrier
	s_setprio 1
	s_waitcnt lgkmcnt(0)
	v_mfma_f32_16x16x32_bf16 v[62:65], v[152:155], v[184:187], v[62:65]
	v_mfma_f32_16x16x32_bf16 v[58:61], v[160:163], v[184:187], v[58:61]
	v_mfma_f32_16x16x32_bf16 v[54:57], v[152:155], v[192:195], v[54:57]
	v_mfma_f32_16x16x32_bf16 v[50:53], v[160:163], v[192:195], v[50:53]
	v_mfma_f32_16x16x32_bf16 v[46:49], v[152:155], v[200:203], v[46:49]
	v_mfma_f32_16x16x32_bf16 v[38:41], v[160:163], v[200:203], v[38:41]
	v_mfma_f32_16x16x32_bf16 v[30:33], v[152:155], v[208:211], v[30:33]
	v_mfma_f32_16x16x32_bf16 v[22:25], v[160:163], v[208:211], v[22:25]
	v_mfma_f32_16x16x32_bf16 v[62:65], v[156:159], v[188:191], v[62:65]
	v_mfma_f32_16x16x32_bf16 v[58:61], v[164:167], v[188:191], v[58:61]
	v_mfma_f32_16x16x32_bf16 v[54:57], v[156:159], v[196:199], v[54:57]
	v_mfma_f32_16x16x32_bf16 v[50:53], v[164:167], v[196:199], v[50:53]
	v_mfma_f32_16x16x32_bf16 v[46:49], v[156:159], v[204:207], v[46:49]
	v_mfma_f32_16x16x32_bf16 v[38:41], v[164:167], v[204:207], v[38:41]
	v_mfma_f32_16x16x32_bf16 v[30:33], v[156:159], v[212:215], v[30:33]
	v_mfma_f32_16x16x32_bf16 v[22:25], v[164:167], v[212:215], v[22:25]
	s_setprio 0
	s_setprio 1
	v_mfma_f32_16x16x32_bf16 v[42:45], v[168:171], v[184:187], v[42:45]
	v_mfma_f32_16x16x32_bf16 v[34:37], v[176:179], v[184:187], v[34:37]
	v_mfma_f32_16x16x32_bf16 v[26:29], v[168:171], v[192:195], v[26:29]
	v_mfma_f32_16x16x32_bf16 v[18:21], v[176:179], v[192:195], v[18:21]
	v_mfma_f32_16x16x32_bf16 v[14:17], v[168:171], v[200:203], v[14:17]
	v_mfma_f32_16x16x32_bf16 v[10:13], v[176:179], v[200:203], v[10:13]
	v_mfma_f32_16x16x32_bf16 v[6:9], v[168:171], v[208:211], v[6:9]
	v_mfma_f32_16x16x32_bf16 v[2:5], v[176:179], v[208:211], v[2:5]
	v_mfma_f32_16x16x32_bf16 v[42:45], v[172:175], v[188:191], v[42:45]
	v_mfma_f32_16x16x32_bf16 v[34:37], v[180:183], v[188:191], v[34:37]
	v_mfma_f32_16x16x32_bf16 v[26:29], v[172:175], v[196:199], v[26:29]
	v_mfma_f32_16x16x32_bf16 v[18:21], v[180:183], v[196:199], v[18:21]
	v_mfma_f32_16x16x32_bf16 v[14:17], v[172:175], v[204:207], v[14:17]
	v_mfma_f32_16x16x32_bf16 v[10:13], v[180:183], v[204:207], v[10:13]
	v_mfma_f32_16x16x32_bf16 v[6:9], v[172:175], v[212:215], v[6:9]
	v_mfma_f32_16x16x32_bf16 v[2:5], v[180:183], v[212:215], v[2:5]
	s_setprio 0
	s_barrier
	s_add_i32 s3, 0, 0x18000
	v_add_u32_e32 v151, s3, v1
	s_add_i32 s12, 0, 0x1c000
	ds_read_b128 v[152:155], v151
	ds_read_b128 v[156:159], v151 offset:1024
	ds_read_b128 v[160:163], v151 offset:2048
	ds_read_b128 v[164:167], v151 offset:3072
	v_add_u32_e32 v151, s12, v1
	ds_read_b128 v[168:171], v151
	ds_read_b128 v[172:175], v151 offset:1024
	ds_read_b128 v[176:179], v151 offset:2048
	ds_read_b128 v[180:183], v151 offset:3072
	s_add_u32 s24, s74, 0xb0000
	s_addc_u32 s25, s75, 0
	s_mov_b32 m0, s44
	s_nop 0
	ds_read_b128 v[184:187], v150 offset:32768
	ds_read_b128 v[188:191], v150 offset:33792
	ds_read_b128 v[192:195], v150 offset:34816
	ds_read_b128 v[196:199], v150 offset:35840
	ds_read_b128 v[200:203], v150 offset:36864
	ds_read_b128 v[204:207], v150 offset:37888
	ds_read_b128 v[208:211], v150 offset:38912
	ds_read_b128 v[212:215], v150 offset:39936
	global_load_lds_dwordx4 v136, s[24:25]
	s_nop 0
	s_mov_b32 m0, s45
	s_nop 0
	global_load_lds_dwordx4 v132, s[24:25]
	s_waitcnt vmcnt(8)
	s_waitcnt lgkmcnt(0)
	s_barrier
	s_setprio 1
	s_waitcnt lgkmcnt(0)
	v_mfma_f32_16x16x32_bf16 v[126:129], v[152:155], v[184:187], v[126:129]
	v_mfma_f32_16x16x32_bf16 v[122:125], v[160:163], v[184:187], v[122:125]
	v_mfma_f32_16x16x32_bf16 v[118:121], v[152:155], v[192:195], v[118:121]
	v_mfma_f32_16x16x32_bf16 v[114:117], v[160:163], v[192:195], v[114:117]
	v_mfma_f32_16x16x32_bf16 v[110:113], v[152:155], v[200:203], v[110:113]
	v_mfma_f32_16x16x32_bf16 v[102:105], v[160:163], v[200:203], v[102:105]
	v_mfma_f32_16x16x32_bf16 v[94:97], v[152:155], v[208:211], v[94:97]
	v_mfma_f32_16x16x32_bf16 v[86:89], v[160:163], v[208:211], v[86:89]
	v_mfma_f32_16x16x32_bf16 v[126:129], v[156:159], v[188:191], v[126:129]
	v_mfma_f32_16x16x32_bf16 v[122:125], v[164:167], v[188:191], v[122:125]
	v_mfma_f32_16x16x32_bf16 v[118:121], v[156:159], v[196:199], v[118:121]
	v_mfma_f32_16x16x32_bf16 v[114:117], v[164:167], v[196:199], v[114:117]
	v_mfma_f32_16x16x32_bf16 v[110:113], v[156:159], v[204:207], v[110:113]
	v_mfma_f32_16x16x32_bf16 v[102:105], v[164:167], v[204:207], v[102:105]
	v_mfma_f32_16x16x32_bf16 v[94:97], v[156:159], v[212:215], v[94:97]
	v_mfma_f32_16x16x32_bf16 v[86:89], v[164:167], v[212:215], v[86:89]
	s_setprio 0
	s_setprio 1
	v_mfma_f32_16x16x32_bf16 v[106:109], v[168:171], v[184:187], v[106:109]
	v_mfma_f32_16x16x32_bf16 v[98:101], v[176:179], v[184:187], v[98:101]
	v_mfma_f32_16x16x32_bf16 v[90:93], v[168:171], v[192:195], v[90:93]
	v_mfma_f32_16x16x32_bf16 v[82:85], v[176:179], v[192:195], v[82:85]
	v_mfma_f32_16x16x32_bf16 v[78:81], v[168:171], v[200:203], v[78:81]
	v_mfma_f32_16x16x32_bf16 v[74:77], v[176:179], v[200:203], v[74:77]
	v_mfma_f32_16x16x32_bf16 v[70:73], v[168:171], v[208:211], v[70:73]
	v_mfma_f32_16x16x32_bf16 v[66:69], v[176:179], v[208:211], v[66:69]
	v_mfma_f32_16x16x32_bf16 v[106:109], v[172:175], v[188:191], v[106:109]
	v_mfma_f32_16x16x32_bf16 v[98:101], v[180:183], v[188:191], v[98:101]
	v_mfma_f32_16x16x32_bf16 v[90:93], v[172:175], v[196:199], v[90:93]
	v_mfma_f32_16x16x32_bf16 v[82:85], v[180:183], v[196:199], v[82:85]
	v_mfma_f32_16x16x32_bf16 v[78:81], v[172:175], v[204:207], v[78:81]
	v_mfma_f32_16x16x32_bf16 v[74:77], v[180:183], v[204:207], v[74:77]
	v_mfma_f32_16x16x32_bf16 v[70:73], v[172:175], v[212:215], v[70:73]
	v_mfma_f32_16x16x32_bf16 v[66:69], v[180:183], v[212:215], v[66:69]
	s_setprio 0
	s_barrier
	s_add_i32 s3, s3, s27
	s_nop 0
	s_mov_b32 m0, s3
	ds_read_b128 v[184:187], v150 offset:49152
	ds_read_b128 v[188:191], v150 offset:50176
	ds_read_b128 v[192:195], v150 offset:51200
	ds_read_b128 v[196:199], v150 offset:52224
	ds_read_b128 v[200:203], v150 offset:53248
	ds_read_b128 v[204:207], v150 offset:54272
	ds_read_b128 v[208:211], v150 offset:55296
	ds_read_b128 v[212:215], v150 offset:56320
	global_load_lds_dwordx4 v251, s[72:73]
	s_add_i32 m0, s3, 0x2000
	s_add_u32 s24, s72, 0xb0080
	s_nop 0
	s_addc_u32 s25, s73, 0
	s_add_i32 s3, s12, s27
	global_load_lds_dwordx4 v252, s[72:73]
	s_nop 0
	s_mov_b32 m0, s3
	s_nop 0
	global_load_lds_dwordx4 v134, s[24:25]
	s_nop 0
	s_add_i32 m0, s3, 0x2000
	s_nop 0
	global_load_lds_dwordx4 v130, s[24:25]
	s_nop 0
	s_mov_b32 m0, s60
	s_nop 0
	global_load_lds_dwordx4 v253, s[74:75]
	s_nop 0
	s_mov_b32 m0, s61
	s_nop 0
	global_load_lds_dwordx4 v254, s[74:75]
	s_waitcnt vmcnt(8)
	s_waitcnt lgkmcnt(0)
	s_barrier
	s_setprio 1
	s_waitcnt lgkmcnt(0)
	v_mfma_f32_16x16x32_bf16 v[62:65], v[152:155], v[184:187], v[62:65]
	v_mfma_f32_16x16x32_bf16 v[58:61], v[160:163], v[184:187], v[58:61]
	v_mfma_f32_16x16x32_bf16 v[54:57], v[152:155], v[192:195], v[54:57]
	v_mfma_f32_16x16x32_bf16 v[50:53], v[160:163], v[192:195], v[50:53]
	v_mfma_f32_16x16x32_bf16 v[46:49], v[152:155], v[200:203], v[46:49]
	v_mfma_f32_16x16x32_bf16 v[38:41], v[160:163], v[200:203], v[38:41]
	v_mfma_f32_16x16x32_bf16 v[30:33], v[152:155], v[208:211], v[30:33]
	v_mfma_f32_16x16x32_bf16 v[22:25], v[160:163], v[208:211], v[22:25]
	v_mfma_f32_16x16x32_bf16 v[62:65], v[156:159], v[188:191], v[62:65]
	v_mfma_f32_16x16x32_bf16 v[58:61], v[164:167], v[188:191], v[58:61]
	v_mfma_f32_16x16x32_bf16 v[54:57], v[156:159], v[196:199], v[54:57]
	v_mfma_f32_16x16x32_bf16 v[50:53], v[164:167], v[196:199], v[50:53]
	v_mfma_f32_16x16x32_bf16 v[46:49], v[156:159], v[204:207], v[46:49]
	v_mfma_f32_16x16x32_bf16 v[38:41], v[164:167], v[204:207], v[38:41]
	v_mfma_f32_16x16x32_bf16 v[30:33], v[156:159], v[212:215], v[30:33]
	v_mfma_f32_16x16x32_bf16 v[22:25], v[164:167], v[212:215], v[22:25]
	s_setprio 0
	s_setprio 1
	v_mfma_f32_16x16x32_bf16 v[42:45], v[168:171], v[184:187], v[42:45]
	v_mfma_f32_16x16x32_bf16 v[34:37], v[176:179], v[184:187], v[34:37]
	v_mfma_f32_16x16x32_bf16 v[26:29], v[168:171], v[192:195], v[26:29]
	v_mfma_f32_16x16x32_bf16 v[18:21], v[176:179], v[192:195], v[18:21]
	v_mfma_f32_16x16x32_bf16 v[14:17], v[168:171], v[200:203], v[14:17]
	v_mfma_f32_16x16x32_bf16 v[10:13], v[176:179], v[200:203], v[10:13]
	v_mfma_f32_16x16x32_bf16 v[6:9], v[168:171], v[208:211], v[6:9]
	v_mfma_f32_16x16x32_bf16 v[2:5], v[176:179], v[208:211], v[2:5]
	v_mfma_f32_16x16x32_bf16 v[42:45], v[172:175], v[188:191], v[42:45]
	v_mfma_f32_16x16x32_bf16 v[34:37], v[180:183], v[188:191], v[34:37]
	v_mfma_f32_16x16x32_bf16 v[26:29], v[172:175], v[196:199], v[26:29]
	v_mfma_f32_16x16x32_bf16 v[18:21], v[180:183], v[196:199], v[18:21]
	v_mfma_f32_16x16x32_bf16 v[14:17], v[172:175], v[204:207], v[14:17]
	v_mfma_f32_16x16x32_bf16 v[10:13], v[180:183], v[204:207], v[10:13]
	v_mfma_f32_16x16x32_bf16 v[6:9], v[172:175], v[212:215], v[6:9]
	v_mfma_f32_16x16x32_bf16 v[2:5], v[180:183], v[212:215], v[2:5]
	s_setprio 0
	s_barrier
	s_add_u32 s81, s81, 0x100
	s_addc_u32 s82, s82, 0
	s_cmp_ge_i32 s13, s21
	s_mov_b64 s[68:69], s[70:71]
	s_mov_b32 s12, s13
	s_cbranch_scc0 .LBB0_818
	s_and_b64 vcc, exec, s[16:17]
	s_cbranch_vccz .LBB0_821
	s_barrier

.LBB0_903:
	s_add_u32 s69, s72, 0x100
	v_mov_b32_e32 v2, 0
	s_addc_u32 s87, s73, 0
	s_mov_b32 s12, -2
	s_waitcnt lgkmcnt(0)
	v_mov_b32_e32 v3, v2
	v_mov_b32_e32 v4, v2
	v_mov_b32_e32 v5, v2
	v_mov_b32_e32 v6, v2
	v_mov_b32_e32 v7, v2
	v_mov_b32_e32 v8, v2
	v_mov_b32_e32 v9, v2
	v_mov_b32_e32 v10, v2
	v_mov_b32_e32 v11, v2
	v_mov_b32_e32 v12, v2
	v_mov_b32_e32 v13, v2
	v_mov_b32_e32 v14, v2
	v_mov_b32_e32 v15, v2
	v_mov_b32_e32 v16, v2
	v_mov_b32_e32 v17, v2
	v_mov_b32_e32 v18, v2
	v_mov_b32_e32 v19, v2
	v_mov_b32_e32 v20, v2
	v_mov_b32_e32 v21, v2
	v_mov_b32_e32 v22, v2
	v_mov_b32_e32 v23, v2
	v_mov_b32_e32 v24, v2
	v_mov_b32_e32 v25, v2
	v_mov_b32_e32 v26, v2
	v_mov_b32_e32 v27, v2
	v_mov_b32_e32 v28, v2
	v_mov_b32_e32 v29, v2
	v_mov_b32_e32 v30, v2
	v_mov_b32_e32 v31, v2
	v_mov_b32_e32 v32, v2
	v_mov_b32_e32 v33, v2
	v_mov_b32_e32 v66, v2
	v_mov_b32_e32 v67, v2
	v_mov_b32_e32 v68, v2
	v_mov_b32_e32 v69, v2
	v_mov_b32_e32 v70, v2
	v_mov_b32_e32 v71, v2
	v_mov_b32_e32 v72, v2
	v_mov_b32_e32 v73, v2
	v_mov_b32_e32 v74, v2
	v_mov_b32_e32 v75, v2
	v_mov_b32_e32 v76, v2
	v_mov_b32_e32 v77, v2
	v_mov_b32_e32 v78, v2
	v_mov_b32_e32 v79, v2
	v_mov_b32_e32 v80, v2
	v_mov_b32_e32 v81, v2
	v_mov_b32_e32 v82, v2
	v_mov_b32_e32 v83, v2
	v_mov_b32_e32 v84, v2
	v_mov_b32_e32 v85, v2
	v_mov_b32_e32 v86, v2
	v_mov_b32_e32 v87, v2
	v_mov_b32_e32 v88, v2
	v_mov_b32_e32 v89, v2
	v_mov_b32_e32 v90, v2
	v_mov_b32_e32 v91, v2
	v_mov_b32_e32 v92, v2
	v_mov_b32_e32 v93, v2
	v_mov_b32_e32 v94, v2
	v_mov_b32_e32 v95, v2
	v_mov_b32_e32 v96, v2
	v_mov_b32_e32 v97, v2
	v_mov_b32_e32 v34, v2
	v_mov_b32_e32 v35, v2
	v_mov_b32_e32 v36, v2
	v_mov_b32_e32 v37, v2
	v_mov_b32_e32 v38, v2
	v_mov_b32_e32 v39, v2
	v_mov_b32_e32 v40, v2
	v_mov_b32_e32 v41, v2
	v_mov_b32_e32 v42, v2
	v_mov_b32_e32 v43, v2
	v_mov_b32_e32 v44, v2
	v_mov_b32_e32 v45, v2
	v_mov_b32_e32 v46, v2
	v_mov_b32_e32 v47, v2
	v_mov_b32_e32 v48, v2
	v_mov_b32_e32 v49, v2
	v_mov_b32_e32 v50, v2
	v_mov_b32_e32 v51, v2
	v_mov_b32_e32 v52, v2
	v_mov_b32_e32 v53, v2
	v_mov_b32_e32 v54, v2
	v_mov_b32_e32 v55, v2
	v_mov_b32_e32 v56, v2
	v_mov_b32_e32 v57, v2
	v_mov_b32_e32 v58, v2
	v_mov_b32_e32 v59, v2
	v_mov_b32_e32 v60, v2
	v_mov_b32_e32 v61, v2
	v_mov_b32_e32 v62, v2
	v_mov_b32_e32 v63, v2
	v_mov_b32_e32 v64, v2
	v_mov_b32_e32 v65, v2
	v_mov_b32_e32 v98, v2
	v_mov_b32_e32 v99, v2
	v_mov_b32_e32 v100, v2
	v_mov_b32_e32 v101, v2
	v_mov_b32_e32 v102, v2
	v_mov_b32_e32 v103, v2
	v_mov_b32_e32 v104, v2
	v_mov_b32_e32 v105, v2
	v_mov_b32_e32 v106, v2
	v_mov_b32_e32 v107, v2
	v_mov_b32_e32 v108, v2
	v_mov_b32_e32 v109, v2
	v_mov_b32_e32 v110, v2
	v_mov_b32_e32 v111, v2
	v_mov_b32_e32 v112, v2
	v_mov_b32_e32 v113, v2
	v_mov_b32_e32 v114, v2
	v_mov_b32_e32 v115, v2
	v_mov_b32_e32 v116, v2
	v_mov_b32_e32 v117, v2
	v_mov_b32_e32 v118, v2
	v_mov_b32_e32 v119, v2
	v_mov_b32_e32 v120, v2
	v_mov_b32_e32 v121, v2
	v_mov_b32_e32 v122, v2
	v_mov_b32_e32 v123, v2
	v_mov_b32_e32 v124, v2
	v_mov_b32_e32 v125, v2
	v_mov_b32_e32 v126, v2
	v_mov_b32_e32 v127, v2
	v_mov_b32_e32 v128, v2
	v_mov_b32_e32 v129, v2
	v_add_u32_e32 v251, 0x80, v140
	v_add_u32_e32 v252, 0x80, v144
	v_add_u32_e32 v253, 0x80, v138
	v_add_u32_e32 v254, 0x80, v142
.LBB0_904:
	ds_read_b128 v[130:133], v228
	ds_read_b128 v[134:137], v228 offset:1024
	ds_read_b128 v[154:157], v228 offset:2048
	ds_read_b128 v[158:161], v228 offset:3072
	ds_read_b128 v[162:165], v229
	ds_read_b128 v[166:169], v229 offset:1024
	ds_read_b128 v[170:173], v229 offset:2048
	ds_read_b128 v[174:177], v229 offset:3072
	s_add_u32 s72, s70, 0x100
	s_addc_u32 s73, s71, 0
	s_cmp_eq_u32 s12, 40
	s_cselect_b32 s77, s1, s73
	s_cselect_b32 s76, s0, s72
	s_cselect_b32 s75, s11, s87
	s_cselect_b32 s74, s10, s69
	v_lshl_add_u64 v[210:211], s[70:71], 0, v[146:147]
	s_add_i32 m0, s33, 0xc000
	ds_read_b128 v[178:181], v230
	ds_read_b128 v[182:185], v230 offset:1024
	ds_read_b128 v[186:189], v230 offset:2048
	ds_read_b128 v[190:193], v230 offset:3072
	ds_read_b128 v[194:197], v230 offset:4096
	ds_read_b128 v[198:201], v230 offset:5120
	ds_read_b128 v[202:205], v230 offset:6144
	ds_read_b128 v[206:209], v230 offset:7168
	global_load_lds_dwordx4 v[210:211], off
	v_lshl_add_u64 v[210:211], s[70:71], 0, v[148:149]
	s_add_i32 m0, s33, 0xe000
	s_nop 0
	global_load_lds_dwordx4 v[210:211], off
	s_waitcnt vmcnt(8)
	s_waitcnt lgkmcnt(0)
	s_barrier
	s_setprio 1
	s_waitcnt lgkmcnt(0)
	v_mfma_f32_16x16x32_bf16 v[126:129], v[130:133], v[178:181], v[126:129]
	v_mfma_f32_16x16x32_bf16 v[122:125], v[154:157], v[178:181], v[122:125]
	v_mfma_f32_16x16x32_bf16 v[118:121], v[130:133], v[186:189], v[118:121]
	v_mfma_f32_16x16x32_bf16 v[114:117], v[154:157], v[186:189], v[114:117]
	v_mfma_f32_16x16x32_bf16 v[110:113], v[130:133], v[194:197], v[110:113]
	v_mfma_f32_16x16x32_bf16 v[106:109], v[154:157], v[194:197], v[106:109]
	v_mfma_f32_16x16x32_bf16 v[102:105], v[130:133], v[202:205], v[102:105]
	v_mfma_f32_16x16x32_bf16 v[98:101], v[154:157], v[202:205], v[98:101]
	v_mfma_f32_16x16x32_bf16 v[126:129], v[134:137], v[182:185], v[126:129]
	v_mfma_f32_16x16x32_bf16 v[122:125], v[158:161], v[182:185], v[122:125]
	v_mfma_f32_16x16x32_bf16 v[118:121], v[134:137], v[190:193], v[118:121]
	v_mfma_f32_16x16x32_bf16 v[114:117], v[158:161], v[190:193], v[114:117]
	v_mfma_f32_16x16x32_bf16 v[110:113], v[134:137], v[198:201], v[110:113]
	v_mfma_f32_16x16x32_bf16 v[106:109], v[158:161], v[198:201], v[106:109]
	v_mfma_f32_16x16x32_bf16 v[102:105], v[134:137], v[206:209], v[102:105]
	v_mfma_f32_16x16x32_bf16 v[98:101], v[158:161], v[206:209], v[98:101]
	s_setprio 0
	s_setprio 1
	v_mfma_f32_16x16x32_bf16 v[62:65], v[162:165], v[178:181], v[62:65]
	v_mfma_f32_16x16x32_bf16 v[58:61], v[170:173], v[178:181], v[58:61]
	v_mfma_f32_16x16x32_bf16 v[54:57], v[162:165], v[186:189], v[54:57]
	v_mfma_f32_16x16x32_bf16 v[50:53], v[170:173], v[186:189], v[50:53]
	v_mfma_f32_16x16x32_bf16 v[46:49], v[162:165], v[194:197], v[46:49]
	v_mfma_f32_16x16x32_bf16 v[42:45], v[170:173], v[194:197], v[42:45]
	v_mfma_f32_16x16x32_bf16 v[38:41], v[162:165], v[202:205], v[38:41]
	v_mfma_f32_16x16x32_bf16 v[34:37], v[170:173], v[202:205], v[34:37]
	v_mfma_f32_16x16x32_bf16 v[62:65], v[166:169], v[182:185], v[62:65]
	v_mfma_f32_16x16x32_bf16 v[58:61], v[174:177], v[182:185], v[58:61]
	v_mfma_f32_16x16x32_bf16 v[54:57], v[166:169], v[190:193], v[54:57]
	v_mfma_f32_16x16x32_bf16 v[50:53], v[174:177], v[190:193], v[50:53]
	v_mfma_f32_16x16x32_bf16 v[46:49], v[166:169], v[198:201], v[46:49]
	v_mfma_f32_16x16x32_bf16 v[42:45], v[174:177], v[198:201], v[42:45]
	v_mfma_f32_16x16x32_bf16 v[38:41], v[166:169], v[206:209], v[38:41]
	v_mfma_f32_16x16x32_bf16 v[34:37], v[174:177], v[206:209], v[34:37]
	s_setprio 0
	s_barrier
	s_add_i32 s3, s82, s27
	s_nop 0
	s_mov_b32 m0, s3
	ds_read_b128 v[178:181], v230 offset:16384
	ds_read_b128 v[182:185], v230 offset:17408
	ds_read_b128 v[186:189], v230 offset:18432
	ds_read_b128 v[190:193], v230 offset:19456
	ds_read_b128 v[194:197], v230 offset:20480
	ds_read_b128 v[198:201], v230 offset:21504
	ds_read_b128 v[202:205], v230 offset:22528
	ds_read_b128 v[206:209], v230 offset:23552
	global_load_lds_dwordx4 v140, s[74:75]
	s_add_i32 m0, s3, 0x2000
	s_add_u32 s24, s74, 0xb0000
	v_lshl_add_u64 v[212:213], s[74:75], 0, v[144:145]
	s_addc_u32 s25, s75, 0
	s_add_i32 s3, s83, s27
	global_load_lds_dwordx4 v144, s[74:75]
	s_nop 0
	s_mov_b32 m0, s3
	v_lshl_add_u64 v[216:217], s[76:77], 0, v[142:143]
	global_load_lds_dwordx4 v140, s[24:25]
	s_nop 0
	s_add_i32 m0, s3, 0x2000
	s_nop 0
	global_load_lds_dwordx4 v144, s[24:25]
	s_nop 0
	s_mov_b32 m0, s33
	s_nop 0
	global_load_lds_dwordx4 v138, s[76:77]
	s_mov_b32 m0, s36
	s_nop 0
	global_load_lds_dwordx4 v142, s[76:77]
	s_waitcnt vmcnt(8)
	s_waitcnt lgkmcnt(0)
	s_barrier
	s_setprio 1
	s_waitcnt lgkmcnt(0)
	v_mfma_f32_16x16x32_bf16 v[94:97], v[130:133], v[178:181], v[94:97]
	v_mfma_f32_16x16x32_bf16 v[90:93], v[154:157], v[178:181], v[90:93]
	v_mfma_f32_16x16x32_bf16 v[86:89], v[130:133], v[186:189], v[86:89]
	v_mfma_f32_16x16x32_bf16 v[82:85], v[154:157], v[186:189], v[82:85]
	v_mfma_f32_16x16x32_bf16 v[78:81], v[130:133], v[194:197], v[78:81]
	v_mfma_f32_16x16x32_bf16 v[74:77], v[154:157], v[194:197], v[74:77]
	v_mfma_f32_16x16x32_bf16 v[70:73], v[130:133], v[202:205], v[70:73]
	v_mfma_f32_16x16x32_bf16 v[66:69], v[154:157], v[202:205], v[66:69]
	v_mfma_f32_16x16x32_bf16 v[94:97], v[134:137], v[182:185], v[94:97]
	v_mfma_f32_16x16x32_bf16 v[90:93], v[158:161], v[182:185], v[90:93]
	v_mfma_f32_16x16x32_bf16 v[86:89], v[134:137], v[190:193], v[86:89]
	v_mfma_f32_16x16x32_bf16 v[82:85], v[158:161], v[190:193], v[82:85]
	v_mfma_f32_16x16x32_bf16 v[78:81], v[134:137], v[198:201], v[78:81]
	v_mfma_f32_16x16x32_bf16 v[74:77], v[158:161], v[198:201], v[74:77]
	v_mfma_f32_16x16x32_bf16 v[70:73], v[134:137], v[206:209], v[70:73]
	v_mfma_f32_16x16x32_bf16 v[66:69], v[158:161], v[206:209], v[66:69]
	s_setprio 0
	s_setprio 1
	v_mfma_f32_16x16x32_bf16 v[30:33], v[162:165], v[178:181], v[30:33]
	v_mfma_f32_16x16x32_bf16 v[26:29], v[170:173], v[178:181], v[26:29]
	v_mfma_f32_16x16x32_bf16 v[22:25], v[162:165], v[186:189], v[22:25]
	v_mfma_f32_16x16x32_bf16 v[18:21], v[170:173], v[186:189], v[18:21]
	v_mfma_f32_16x16x32_bf16 v[14:17], v[162:165], v[194:197], v[14:17]
	v_mfma_f32_16x16x32_bf16 v[10:13], v[170:173], v[194:197], v[10:13]
	v_mfma_f32_16x16x32_bf16 v[6:9], v[162:165], v[202:205], v[6:9]
	v_mfma_f32_16x16x32_bf16 v[2:5], v[170:173], v[202:205], v[2:5]
	v_mfma_f32_16x16x32_bf16 v[30:33], v[166:169], v[182:185], v[30:33]
	v_mfma_f32_16x16x32_bf16 v[26:29], v[174:177], v[182:185], v[26:29]
	v_mfma_f32_16x16x32_bf16 v[22:25], v[166:169], v[190:193], v[22:25]
	v_mfma_f32_16x16x32_bf16 v[18:21], v[174:177], v[190:193], v[18:21]
	v_mfma_f32_16x16x32_bf16 v[14:17], v[166:169], v[198:201], v[14:17]
	v_mfma_f32_16x16x32_bf16 v[10:13], v[174:177], v[198:201], v[10:13]
	v_mfma_f32_16x16x32_bf16 v[6:9], v[166:169], v[206:209], v[6:9]
	v_mfma_f32_16x16x32_bf16 v[2:5], v[174:177], v[206:209], v[2:5]
	s_setprio 0
	s_barrier
	s_add_i32 s3, 0, 0x18000
	s_add_i32 s13, 0, 0x1c000
	v_add_u32_e32 v158, s3, v226
	v_add_u32_e32 v174, s13, v226
	ds_read_b128 v[130:133], v158
	ds_read_b128 v[134:137], v158 offset:1024
	ds_read_b128 v[154:157], v158 offset:2048
	ds_read_b128 v[158:161], v158 offset:3072
	ds_read_b128 v[162:165], v174
	ds_read_b128 v[166:169], v174 offset:1024
	ds_read_b128 v[170:173], v174 offset:2048
	ds_read_b128 v[174:177], v174 offset:3072
	s_add_u32 s24, s76, 0xb0000
	s_addc_u32 s25, s77, 0
	s_mov_b32 m0, s37
	s_nop 0
	ds_read_b128 v[178:181], v230 offset:32768
	ds_read_b128 v[182:185], v230 offset:33792
	ds_read_b128 v[186:189], v230 offset:34816
	ds_read_b128 v[190:193], v230 offset:35840
	ds_read_b128 v[194:197], v230 offset:36864
	ds_read_b128 v[198:201], v230 offset:37888
	ds_read_b128 v[202:205], v230 offset:38912
	ds_read_b128 v[206:209], v230 offset:39936
	global_load_lds_dwordx4 v138, s[24:25]
	s_nop 0
	s_mov_b32 m0, s44
	s_nop 0
	global_load_lds_dwordx4 v142, s[24:25]
	s_waitcnt vmcnt(8)
	s_waitcnt lgkmcnt(0)
	s_barrier
	s_setprio 1
	s_waitcnt lgkmcnt(0)
	v_mfma_f32_16x16x32_bf16 v[126:129], v[130:133], v[178:181], v[126:129]
	v_mfma_f32_16x16x32_bf16 v[122:125], v[154:157], v[178:181], v[122:125]
	v_mfma_f32_16x16x32_bf16 v[118:121], v[130:133], v[186:189], v[118:121]
	v_mfma_f32_16x16x32_bf16 v[114:117], v[154:157], v[186:189], v[114:117]
	v_mfma_f32_16x16x32_bf16 v[110:113], v[130:133], v[194:197], v[110:113]
	v_mfma_f32_16x16x32_bf16 v[106:109], v[154:157], v[194:197], v[106:109]
	v_mfma_f32_16x16x32_bf16 v[102:105], v[130:133], v[202:205], v[102:105]
	v_mfma_f32_16x16x32_bf16 v[98:101], v[154:157], v[202:205], v[98:101]
	v_mfma_f32_16x16x32_bf16 v[126:129], v[134:137], v[182:185], v[126:129]
	v_mfma_f32_16x16x32_bf16 v[122:125], v[158:161], v[182:185], v[122:125]
	v_mfma_f32_16x16x32_bf16 v[118:121], v[134:137], v[190:193], v[118:121]
	v_mfma_f32_16x16x32_bf16 v[114:117], v[158:161], v[190:193], v[114:117]
	v_mfma_f32_16x16x32_bf16 v[110:113], v[134:137], v[198:201], v[110:113]
	v_mfma_f32_16x16x32_bf16 v[106:109], v[158:161], v[198:201], v[106:109]
	v_mfma_f32_16x16x32_bf16 v[102:105], v[134:137], v[206:209], v[102:105]
	v_mfma_f32_16x16x32_bf16 v[98:101], v[158:161], v[206:209], v[98:101]
	s_setprio 0
	s_setprio 1
	v_mfma_f32_16x16x32_bf16 v[62:65], v[162:165], v[178:181], v[62:65]
	v_mfma_f32_16x16x32_bf16 v[58:61], v[170:173], v[178:181], v[58:61]
	v_mfma_f32_16x16x32_bf16 v[54:57], v[162:165], v[186:189], v[54:57]
	v_mfma_f32_16x16x32_bf16 v[50:53], v[170:173], v[186:189], v[50:53]
	v_mfma_f32_16x16x32_bf16 v[46:49], v[162:165], v[194:197], v[46:49]
	v_mfma_f32_16x16x32_bf16 v[42:45], v[170:173], v[194:197], v[42:45]
	v_mfma_f32_16x16x32_bf16 v[38:41], v[162:165], v[202:205], v[38:41]
	v_mfma_f32_16x16x32_bf16 v[34:37], v[170:173], v[202:205], v[34:37]
	v_mfma_f32_16x16x32_bf16 v[62:65], v[166:169], v[182:185], v[62:65]
	v_mfma_f32_16x16x32_bf16 v[58:61], v[174:177], v[182:185], v[58:61]
	v_mfma_f32_16x16x32_bf16 v[54:57], v[166:169], v[190:193], v[54:57]
	v_mfma_f32_16x16x32_bf16 v[50:53], v[174:177], v[190:193], v[50:53]
	v_mfma_f32_16x16x32_bf16 v[46:49], v[166:169], v[198:201], v[46:49]
	v_mfma_f32_16x16x32_bf16 v[42:45], v[174:177], v[198:201], v[42:45]
	v_mfma_f32_16x16x32_bf16 v[38:41], v[166:169], v[206:209], v[38:41]
	v_mfma_f32_16x16x32_bf16 v[34:37], v[174:177], v[206:209], v[34:37]
	s_setprio 0
	s_barrier
	s_add_i32 s3, s3, s27
	s_nop 0
	s_mov_b32 m0, s3
	ds_read_b128 v[178:181], v230 offset:49152
	ds_read_b128 v[182:185], v230 offset:50176
	ds_read_b128 v[186:189], v230 offset:51200
	ds_read_b128 v[190:193], v230 offset:52224
	ds_read_b128 v[194:197], v230 offset:53248
	ds_read_b128 v[198:201], v230 offset:54272
	ds_read_b128 v[202:205], v230 offset:55296
	ds_read_b128 v[206:209], v230 offset:56320
	global_load_lds_dwordx4 v251, s[74:75]
	s_add_i32 m0, s3, 0x2000
	s_add_u32 s24, s74, 0xb0080
	s_nop 0
	s_addc_u32 s25, s75, 0
	s_add_i32 s3, s13, s27
	global_load_lds_dwordx4 v252, s[74:75]
	s_nop 0
	s_mov_b32 m0, s3
	s_nop 0
	global_load_lds_dwordx4 v140, s[24:25]
	s_nop 0
	s_add_i32 m0, s3, 0x2000
	s_nop 0
	global_load_lds_dwordx4 v144, s[24:25]
	s_nop 0
	s_mov_b32 m0, s79
	s_nop 0
	global_load_lds_dwordx4 v253, s[76:77]
	s_nop 0
	s_mov_b32 m0, s80
	s_nop 0
	global_load_lds_dwordx4 v254, s[76:77]
	s_waitcnt vmcnt(8)
	s_waitcnt lgkmcnt(0)
	s_barrier
	s_setprio 1
	s_waitcnt lgkmcnt(0)
	v_mfma_f32_16x16x32_bf16 v[94:97], v[130:133], v[178:181], v[94:97]
	v_mfma_f32_16x16x32_bf16 v[90:93], v[154:157], v[178:181], v[90:93]
	v_mfma_f32_16x16x32_bf16 v[86:89], v[130:133], v[186:189], v[86:89]
	v_mfma_f32_16x16x32_bf16 v[82:85], v[154:157], v[186:189], v[82:85]
	v_mfma_f32_16x16x32_bf16 v[78:81], v[130:133], v[194:197], v[78:81]
	v_mfma_f32_16x16x32_bf16 v[74:77], v[154:157], v[194:197], v[74:77]
	v_mfma_f32_16x16x32_bf16 v[70:73], v[130:133], v[202:205], v[70:73]
	v_mfma_f32_16x16x32_bf16 v[66:69], v[154:157], v[202:205], v[66:69]
	v_mfma_f32_16x16x32_bf16 v[94:97], v[134:137], v[182:185], v[94:97]
	v_mfma_f32_16x16x32_bf16 v[90:93], v[158:161], v[182:185], v[90:93]
	v_mfma_f32_16x16x32_bf16 v[86:89], v[134:137], v[190:193], v[86:89]
	v_mfma_f32_16x16x32_bf16 v[82:85], v[158:161], v[190:193], v[82:85]
	v_mfma_f32_16x16x32_bf16 v[78:81], v[134:137], v[198:201], v[78:81]
	v_mfma_f32_16x16x32_bf16 v[74:77], v[158:161], v[198:201], v[74:77]
	v_mfma_f32_16x16x32_bf16 v[70:73], v[134:137], v[206:209], v[70:73]
	v_mfma_f32_16x16x32_bf16 v[66:69], v[158:161], v[206:209], v[66:69]
	s_setprio 0
	s_setprio 1
	v_mfma_f32_16x16x32_bf16 v[30:33], v[162:165], v[178:181], v[30:33]
	v_mfma_f32_16x16x32_bf16 v[26:29], v[170:173], v[178:181], v[26:29]
	v_mfma_f32_16x16x32_bf16 v[22:25], v[162:165], v[186:189], v[22:25]
	v_mfma_f32_16x16x32_bf16 v[18:21], v[170:173], v[186:189], v[18:21]
	v_mfma_f32_16x16x32_bf16 v[14:17], v[162:165], v[194:197], v[14:17]
	v_mfma_f32_16x16x32_bf16 v[10:13], v[170:173], v[194:197], v[10:13]
	v_mfma_f32_16x16x32_bf16 v[6:9], v[162:165], v[202:205], v[6:9]
	v_mfma_f32_16x16x32_bf16 v[2:5], v[170:173], v[202:205], v[2:5]
	v_mfma_f32_16x16x32_bf16 v[30:33], v[166:169], v[182:185], v[30:33]
	v_mfma_f32_16x16x32_bf16 v[26:29], v[174:177], v[182:185], v[26:29]
	v_mfma_f32_16x16x32_bf16 v[22:25], v[166:169], v[190:193], v[22:25]
	v_mfma_f32_16x16x32_bf16 v[18:21], v[174:177], v[190:193], v[18:21]
	v_mfma_f32_16x16x32_bf16 v[14:17], v[166:169], v[198:201], v[14:17]
	v_mfma_f32_16x16x32_bf16 v[10:13], v[174:177], v[198:201], v[10:13]
	v_mfma_f32_16x16x32_bf16 v[6:9], v[166:169], v[206:209], v[6:9]
	v_mfma_f32_16x16x32_bf16 v[2:5], v[174:177], v[206:209], v[2:5]
	s_setprio 0
	s_barrier
	s_add_i32 s12, s12, 2
	s_add_u32 s69, s69, 0x100
	s_addc_u32 s87, s87, 0
	s_cmp_gt_u32 s12, 41
	s_mov_b64 s[70:71], s[72:73]
	s_cbranch_scc0 .LBB0_904
	s_ashr_i32 s3, s68, 3
	s_ashr_i32 s69, s68, 31
	s_mul_hi_i32 s72, s3, 0x6000
	s_mulk_i32 s3, 0x6000
	s_add_u32 s12, s66, s3
	v_mov_b32_e32 v130, v1
	s_addc_u32 s13, s67, s72
	s_lshl_b64 s[24:25], s[68:69], 19
	v_lshl_or_b32 v166, s86, 8, v227
	s_add_u32 s70, s48, s24
	v_add_u32_e32 v160, s78, v130
	v_ashrrev_i32_e32 v167, 31, v166
	s_addc_u32 s71, s49, s25
	v_lshlrev_b64 v[156:157], 1, v[166:167]
	v_ashrrev_i32_e32 v161, 31, v160
	v_lshlrev_b64 v[130:131], 2, v[166:167]
	v_lshl_add_u64 v[162:163], s[70:71], 0, v[156:157]
	v_lshlrev_b64 v[154:155], 11, v[160:161]
	v_add_u32_e32 v170, 16, v160
	v_lshl_add_u64 v[172:173], s[12:13], 0, v[130:131]
	v_lshl_add_u64 v[174:175], v[162:163], 0, v[154:155]
	v_ashrrev_i32_e32 v171, 31, v170
	s_add_u32 s12, s60, s24
	v_lshl_add_u64 v[132:133], s[16:17], 0, v[130:131]
	global_load_dwordx4 v[180:183], v[172:173], off offset:16
	global_load_dwordx4 v[184:187], v[172:173], off
	global_load_dwordx4 v[188:191], v[132:133], off offset:16
	global_load_dwordx4 v[192:195], v[132:133], off
	global_load_dwordx4 v[196:199], v[174:175], off nt
	v_lshlrev_b64 v[204:205], 11, v[170:171]
	s_addc_u32 s13, s61, s25
	v_lshl_add_u64 v[178:179], v[162:163], 0, v[204:205]
	s_add_u32 s24, s62, s3
	global_load_dwordx4 v[200:203], v[178:179], off nt
	s_addc_u32 s25, s63, s72
	v_lshl_add_u64 v[176:177], s[24:25], 0, v[130:131]
	global_load_dwordx4 v[134:137], v[176:177], off
	global_load_dwordx4 v[130:133], v[176:177], off offset:16
	v_lshl_add_u64 v[158:159], s[12:13], 0, v[156:157]
	s_lshl_b32 s12, s68, 8
	v_lshl_add_u64 v[164:165], v[158:159], 0, v[154:155]
	v_add_u32_e32 v154, s12, v160
	v_ashrrev_i32_e32 v155, 31, v154
	v_lshlrev_b64 v[168:169], 11, v[154:155]
	v_lshl_add_u64 v[168:169], s[20:21], 0, v[168:169]
	v_add_u32_e32 v170, s12, v170
	v_lshl_add_u64 v[168:169], v[168:169], 0, v[156:157]
	v_ashrrev_i32_e32 v171, 31, v170
	v_lshlrev_b64 v[170:171], 11, v[170:171]
	v_lshl_add_u64 v[170:171], s[20:21], 0, v[170:171]
	s_waitcnt vmcnt(0)
	v_pk_add_f32 v[182:183], v[182:183], 1.0 op_sel_hi:[1,0]
	v_pk_add_f32 v[186:187], v[186:187], 1.0 op_sel_hi:[1,0]
	v_pk_add_f32 v[184:185], v[184:185], 1.0 op_sel_hi:[1,0]
	v_pk_add_f32 v[180:181], v[180:181], 1.0 op_sel_hi:[1,0]
	v_pk_mul_f32 v[216:217], v[194:195], v[186:187]
	v_pk_mul_f32 v[218:219], v[192:193], v[184:185]
	v_pk_mul_f32 v[220:221], v[190:191], v[182:183]
	v_pk_mul_f32 v[222:223], v[188:189], v[180:181]
	v_cvt_f32_f16_e32 v180, v198
	v_cvt_f32_f16_sdwa v181, v198 dst_sel:DWORD dst_unused:UNUSED_PAD src0_sel:WORD_1
	v_cvt_f32_f16_e32 v182, v199
	v_cvt_f32_f16_sdwa v183, v199 dst_sel:DWORD dst_unused:UNUSED_PAD src0_sel:WORD_1
	v_cvt_f32_f16_e32 v184, v196
	v_cvt_f32_f16_sdwa v185, v196 dst_sel:DWORD dst_unused:UNUSED_PAD src0_sel:WORD_1
	v_cvt_f32_f16_e32 v186, v197
	v_cvt_f32_f16_sdwa v187, v197 dst_sel:DWORD dst_unused:UNUSED_PAD src0_sel:WORD_1
	v_cvt_f32_f16_e32 v188, v202
	v_cvt_f32_f16_sdwa v189, v202 dst_sel:DWORD dst_unused:UNUSED_PAD src0_sel:WORD_1
	v_cvt_f32_f16_e32 v190, v203
	v_cvt_f32_f16_sdwa v191, v203 dst_sel:DWORD dst_unused:UNUSED_PAD src0_sel:WORD_1
	v_cvt_f32_f16_e32 v192, v200
	v_cvt_f32_f16_sdwa v193, v200 dst_sel:DWORD dst_unused:UNUSED_PAD src0_sel:WORD_1
	v_cvt_f32_f16_e32 v194, v201
	v_cvt_f32_f16_sdwa v195, v201 dst_sel:DWORD dst_unused:UNUSED_PAD src0_sel:WORD_1
	v_pk_fma_f32 v[128:129], v[128:129], v[136:137], v[186:187]
	v_pk_fma_f32 v[126:127], v[126:127], v[134:135], v[184:185]
	v_pk_fma_f32 v[124:125], v[124:125], v[132:133], v[182:183]
	v_pk_fma_f32 v[122:123], v[122:123], v[130:131], v[180:181]
	v_cvt_pk_f16_f32 v183, v124, v125
	v_cvt_pk_f16_f32 v181, v128, v129
	v_cvt_pk_f16_f32 v182, v122, v123
	v_cvt_pk_f16_f32 v180, v126, v127
	v_pk_fma_f32 v[120:121], v[120:121], v[136:137], v[194:195]
	v_pk_fma_f32 v[118:119], v[118:119], v[134:135], v[192:193]
	v_pk_fma_f32 v[116:117], v[116:117], v[132:133], v[190:191]
	v_pk_fma_f32 v[114:115], v[114:115], v[130:131], v[188:189]
	v_pk_mul_f32 v[188:189], v[216:217], v[128:129]
	v_pk_mul_f32 v[190:191], v[218:219], v[126:127]
	global_store_dwordx4 v[164:165], v[180:183], off
	v_pk_mul_f32 v[192:193], v[220:221], v[124:125]
	v_pk_mul_f32 v[194:195], v[222:223], v[122:123]
	v_cvt_pk_bf16_f32 v180, v190, v191
	v_cvt_pk_bf16_f32 v181, v188, v189
	v_cvt_pk_f16_f32 v187, v116, v117
	v_cvt_pk_f16_f32 v185, v120, v121
	v_cvt_pk_f16_f32 v186, v114, v115
	v_cvt_pk_bf16_f32 v182, v194, v195
	v_cvt_pk_bf16_f32 v183, v192, v193
	global_store_dwordx4 v[168:169], v[180:183], off
	v_cvt_pk_f16_f32 v184, v118, v119
	v_pk_mul_f32 v[188:189], v[222:223], v[114:115]
	v_lshl_add_u64 v[180:181], v[158:159], 0, v[204:205]
	global_store_dwordx4 v[180:181], v[184:187], off
	v_pk_mul_f32 v[182:183], v[218:219], v[118:119]
	v_add_u32_e32 v192, 48, v160
	v_pk_mul_f32 v[184:185], v[216:217], v[120:121]
	v_pk_mul_f32 v[186:187], v[220:221], v[116:117]
	v_cvt_pk_bf16_f32 v182, v182, v183
	v_cvt_pk_bf16_f32 v183, v184, v185
	v_cvt_pk_bf16_f32 v184, v188, v189
	v_ashrrev_i32_e32 v193, 31, v192
	v_cvt_pk_bf16_f32 v185, v186, v187
	v_lshl_add_u64 v[186:187], v[170:171], 0, v[156:157]
	global_store_dwordx4 v[186:187], v[182:185], off
	v_mul_f32_e32 v127, v127, v127
	v_mul_f32_e32 v129, v129, v129
	v_add_u32_e32 v182, 32, v160
	v_ashrrev_i32_e32 v183, 31, v182
	v_lshlrev_b64 v[170:171], 11, v[182:183]
	v_lshl_add_u64 v[188:189], v[162:163], 0, v[170:171]
	global_load_dwordx4 v[194:197], v[188:189], off nt
	v_lshlrev_b64 v[184:185], 11, v[192:193]
	v_lshl_add_u64 v[190:191], v[162:163], 0, v[184:185]
	global_load_dwordx4 v[198:201], v[190:191], off nt
	v_add_u32_e32 v182, s12, v182
	v_add_u32_e32 v192, s12, v192
	v_ashrrev_i32_e32 v183, 31, v182
	v_ashrrev_i32_e32 v193, 31, v192
	v_lshlrev_b64 v[182:183], 11, v[182:183]
	v_lshlrev_b64 v[192:193], 11, v[192:193]
	v_lshl_add_u64 v[182:183], s[20:21], 0, v[182:183]
	v_lshl_add_u64 v[202:203], s[20:21], 0, v[192:193]
	v_lshl_add_u64 v[192:193], v[182:183], 0, v[156:157]
	v_lshl_add_u64 v[170:171], v[158:159], 0, v[170:171]
	v_lshl_add_u64 v[184:185], v[158:159], 0, v[184:185]
	v_mul_f32_e32 v123, v123, v123
	v_mul_f32_e32 v125, v125, v125
	v_fmac_f32_e32 v127, v126, v126
	v_fmac_f32_e32 v129, v128, v128
	v_fmac_f32_e32 v123, v122, v122
	v_fmac_f32_e32 v125, v124, v124
	v_add_f32_e32 v122, v127, v129
	v_add_f32_e32 v123, v123, v125
	v_add_f32_e32 v122, v122, v123
	s_waitcnt vmcnt(1)
	v_cvt_f32_f16_e32 v182, v196
	v_cvt_f32_f16_sdwa v183, v196 dst_sel:DWORD dst_unused:UNUSED_PAD src0_sel:WORD_1
	v_cvt_f32_f16_e32 v196, v197
	v_cvt_f32_f16_sdwa v197, v197 dst_sel:DWORD dst_unused:UNUSED_PAD src0_sel:WORD_1
	v_cvt_f32_f16_e32 v204, v194
	v_cvt_f32_f16_sdwa v205, v194 dst_sel:DWORD dst_unused:UNUSED_PAD src0_sel:WORD_1
	v_cvt_f32_f16_e32 v194, v195
	v_cvt_f32_f16_sdwa v195, v195 dst_sel:DWORD dst_unused:UNUSED_PAD src0_sel:WORD_1
	s_waitcnt vmcnt(0)
	v_cvt_f32_f16_e32 v206, v200
	v_cvt_f32_f16_sdwa v207, v200 dst_sel:DWORD dst_unused:UNUSED_PAD src0_sel:WORD_1
	v_cvt_f32_f16_e32 v208, v198
	v_cvt_f32_f16_sdwa v209, v198 dst_sel:DWORD dst_unused:UNUSED_PAD src0_sel:WORD_1
	v_cvt_f32_f16_e32 v198, v199
	v_cvt_f32_f16_sdwa v199, v199 dst_sel:DWORD dst_unused:UNUSED_PAD src0_sel:WORD_1
	v_cvt_f32_f16_e32 v200, v201
	v_cvt_f32_f16_sdwa v201, v201 dst_sel:DWORD dst_unused:UNUSED_PAD src0_sel:WORD_1
	v_pk_fma_f32 v[112:113], v[112:113], v[136:137], v[194:195]
	v_pk_fma_f32 v[110:111], v[110:111], v[134:135], v[204:205]
	v_pk_fma_f32 v[108:109], v[108:109], v[132:133], v[196:197]
	v_pk_fma_f32 v[106:107], v[106:107], v[130:131], v[182:183]
	v_cvt_pk_f16_f32 v197, v108, v109
	v_cvt_pk_f16_f32 v195, v112, v113
	v_cvt_pk_f16_f32 v196, v106, v107
	v_cvt_pk_f16_f32 v194, v110, v111
	v_pk_mul_f32 v[182:183], v[216:217], v[112:113]
	v_pk_fma_f32 v[104:105], v[104:105], v[136:137], v[198:199]
	v_pk_fma_f32 v[102:103], v[102:103], v[134:135], v[208:209]
	v_pk_fma_f32 v[98:99], v[98:99], v[130:131], v[206:207]
	v_pk_mul_f32 v[204:205], v[218:219], v[110:111]
	v_pk_mul_f32 v[206:207], v[220:221], v[108:109]
	global_store_dwordx4 v[170:171], v[194:197], off
	v_pk_fma_f32 v[100:101], v[100:101], v[132:133], v[200:201]
	v_pk_mul_f32 v[208:209], v[222:223], v[106:107]
	v_cvt_pk_bf16_f32 v194, v204, v205
	v_cvt_pk_bf16_f32 v195, v182, v183
	v_add_u32_e32 v182, 0x80, v160
	v_cvt_pk_f16_f32 v199, v104, v105
	v_cvt_pk_f16_f32 v198, v102, v103
	v_cvt_pk_bf16_f32 v196, v208, v209
	v_cvt_pk_bf16_f32 v197, v206, v207
	v_ashrrev_i32_e32 v183, 31, v182
	v_add_u32_e32 v206, 0x90, v160
	v_cvt_pk_f16_f32 v201, v100, v101
	v_cvt_pk_f16_f32 v200, v98, v99
	v_pk_mul_f32 v[210:211], v[216:217], v[104:105]
	v_pk_mul_f32 v[212:213], v[218:219], v[102:103]
	global_store_dwordx4 v[192:193], v[194:197], off
	global_store_dwordx4 v[184:185], v[198:201], off
	v_ashrrev_i32_e32 v207, 31, v206
	v_lshl_add_u64 v[196:197], v[202:203], 0, v[156:157]
	v_cvt_pk_bf16_f32 v198, v212, v213
	v_cvt_pk_bf16_f32 v199, v210, v211
	v_lshlrev_b64 v[194:195], 11, v[182:183]
	v_pk_mul_f32 v[214:215], v[220:221], v[100:101]
	v_pk_mul_f32 v[224:225], v[222:223], v[98:99]
	v_lshlrev_b64 v[208:209], 11, v[206:207]
	v_cvt_pk_bf16_f32 v200, v224, v225
	v_cvt_pk_bf16_f32 v201, v214, v215
	global_store_dwordx4 v[196:197], v[198:201], off
	v_lshl_add_u64 v[204:205], v[162:163], 0, v[208:209]
	global_load_dwordx4 v[236:239], v[204:205], off nt
	v_lshl_add_u64 v[198:199], v[162:163], 0, v[194:195]
	global_load_dwordx4 v[232:235], v[198:199], off nt
	v_lshl_add_u64 v[212:213], v[158:159], 0, v[194:195]
	v_add_u32_e32 v182, s12, v182
	v_add_u32_e32 v194, s12, v206
	v_ashrrev_i32_e32 v183, 31, v182
	v_ashrrev_i32_e32 v195, 31, v194
	v_lshlrev_b64 v[182:183], 11, v[182:183]
	v_lshlrev_b64 v[194:195], 11, v[194:195]
	v_lshl_add_u64 v[182:183], s[20:21], 0, v[182:183]
	v_lshl_add_u64 v[194:195], s[20:21], 0, v[194:195]
	v_lshl_add_u64 v[210:211], v[158:159], 0, v[208:209]
	v_lshl_add_u64 v[214:215], v[182:183], 0, v[156:157]
	v_lshl_add_u64 v[208:209], v[194:195], 0, v[156:157]
	v_add_u32_e32 v200, 0xa0, v160
	v_ashrrev_i32_e32 v201, 31, v200
	v_lshlrev_b64 v[240:241], 11, v[200:201]
	v_lshl_add_u64 v[202:203], v[162:163], 0, v[240:241]
	s_waitcnt vmcnt(0)
	v_cvt_f32_f16_e32 v182, v234
	v_cvt_f32_f16_sdwa v183, v234 dst_sel:DWORD dst_unused:UNUSED_PAD src0_sel:WORD_1
	v_cvt_f32_f16_e32 v194, v235
	v_cvt_f32_f16_sdwa v195, v235 dst_sel:DWORD dst_unused:UNUSED_PAD src0_sel:WORD_1
	v_cvt_f32_f16_e32 v206, v232
	v_cvt_f32_f16_sdwa v207, v232 dst_sel:DWORD dst_unused:UNUSED_PAD src0_sel:WORD_1
	v_cvt_f32_f16_e32 v224, v233
	v_cvt_f32_f16_sdwa v225, v233 dst_sel:DWORD dst_unused:UNUSED_PAD src0_sel:WORD_1
	v_cvt_f32_f16_e32 v232, v238
	v_cvt_f32_f16_sdwa v233, v238 dst_sel:DWORD dst_unused:UNUSED_PAD src0_sel:WORD_1
	v_cvt_f32_f16_e32 v234, v239
	v_cvt_f32_f16_sdwa v235, v239 dst_sel:DWORD dst_unused:UNUSED_PAD src0_sel:WORD_1
	v_cvt_f32_f16_e32 v238, v236
	v_cvt_f32_f16_sdwa v239, v236 dst_sel:DWORD dst_unused:UNUSED_PAD src0_sel:WORD_1
	v_cvt_f32_f16_e32 v236, v237
	v_cvt_f32_f16_sdwa v237, v237 dst_sel:DWORD dst_unused:UNUSED_PAD src0_sel:WORD_1
	v_pk_fma_f32 v[96:97], v[96:97], v[136:137], v[224:225]
	v_pk_fma_f32 v[94:95], v[94:95], v[134:135], v[206:207]
	v_pk_fma_f32 v[92:93], v[92:93], v[132:133], v[194:195]
	v_pk_fma_f32 v[90:91], v[90:91], v[130:131], v[182:183]
	v_pk_fma_f32 v[84:85], v[84:85], v[132:133], v[234:235]
	v_pk_fma_f32 v[82:83], v[82:83], v[130:131], v[232:233]
	v_cvt_pk_f16_f32 v235, v92, v93
	v_cvt_pk_f16_f32 v233, v96, v97
	v_cvt_pk_f16_f32 v234, v90, v91
	v_cvt_pk_f16_f32 v232, v94, v95
	v_pk_mul_f32 v[206:207], v[220:221], v[92:93]
	v_pk_mul_f32 v[182:183], v[216:217], v[96:97]
	v_pk_mul_f32 v[194:195], v[218:219], v[94:95]
	v_pk_mul_f32 v[224:225], v[222:223], v[90:91]
	global_store_dwordx4 v[212:213], v[232:235], off
	v_pk_fma_f32 v[88:89], v[88:89], v[136:137], v[236:237]
	v_pk_fma_f32 v[86:87], v[86:87], v[134:135], v[238:239]
	v_cvt_pk_bf16_f32 v232, v194, v195
	v_cvt_pk_bf16_f32 v233, v182, v183
	v_cvt_pk_bf16_f32 v234, v224, v225
	v_cvt_pk_bf16_f32 v235, v206, v207
	v_add_u32_e32 v206, 0xb0, v160
	v_ashrrev_i32_e32 v207, 31, v206
	v_cvt_pk_f16_f32 v239, v84, v85
	v_cvt_pk_f16_f32 v237, v88, v89
	v_cvt_pk_f16_f32 v238, v82, v83
	v_cvt_pk_f16_f32 v236, v86, v87
	v_pk_mul_f32 v[242:243], v[216:217], v[88:89]
	v_pk_mul_f32 v[244:245], v[218:219], v[86:87]
	v_pk_mul_f32 v[246:247], v[220:221], v[84:85]
	v_pk_mul_f32 v[248:249], v[222:223], v[82:83]
	global_store_dwordx4 v[214:215], v[232:235], off
	global_store_dwordx4 v[210:211], v[236:239], off
	v_lshlrev_b64 v[194:195], 11, v[206:207]
	v_cvt_pk_bf16_f32 v232, v244, v245
	v_cvt_pk_bf16_f32 v233, v242, v243
	v_cvt_pk_bf16_f32 v234, v248, v249
	v_cvt_pk_bf16_f32 v235, v246, v247
	global_store_dwordx4 v[208:209], v[232:235], off
	global_load_dwordx4 v[232:235], v[202:203], off nt
	v_lshl_add_u64 v[224:225], v[162:163], 0, v[194:195]
	global_load_dwordx4 v[160:163], v[224:225], off nt
	v_lshl_add_u64 v[182:183], v[158:159], 0, v[240:241]
	v_lshl_add_u64 v[194:195], v[158:159], 0, v[194:195]
	v_add_u32_e32 v158, s12, v200
	v_add_u32_e32 v200, s12, v206
	v_ashrrev_i32_e32 v159, 31, v158
	v_ashrrev_i32_e32 v201, 31, v200
	v_lshlrev_b64 v[158:159], 11, v[158:159]
	v_lshlrev_b64 v[200:201], 11, v[200:201]
	v_lshl_add_u64 v[158:159], s[20:21], 0, v[158:159]
	v_lshl_add_u64 v[200:201], s[20:21], 0, v[200:201]
	v_lshl_add_u64 v[206:207], v[158:159], 0, v[156:157]
	v_lshl_add_u64 v[200:201], v[200:201], 0, v[156:157]
	s_waitcnt vmcnt(1)
	v_cvt_f32_f16_e32 v158, v234
	v_cvt_f32_f16_sdwa v159, v234 dst_sel:DWORD dst_unused:UNUSED_PAD src0_sel:WORD_1
	v_cvt_f32_f16_e32 v156, v235
	v_cvt_f32_f16_sdwa v157, v235 dst_sel:DWORD dst_unused:UNUSED_PAD src0_sel:WORD_1
	v_cvt_f32_f16_e32 v234, v232
	v_cvt_f32_f16_sdwa v235, v232 dst_sel:DWORD dst_unused:UNUSED_PAD src0_sel:WORD_1
	v_cvt_f32_f16_e32 v232, v233
	v_cvt_f32_f16_sdwa v233, v233 dst_sel:DWORD dst_unused:UNUSED_PAD src0_sel:WORD_1
	s_waitcnt vmcnt(0)
	v_cvt_f32_f16_e32 v236, v162
	v_cvt_f32_f16_sdwa v237, v162 dst_sel:DWORD dst_unused:UNUSED_PAD src0_sel:WORD_1
	v_cvt_f32_f16_e32 v238, v163
	v_cvt_f32_f16_sdwa v239, v163 dst_sel:DWORD dst_unused:UNUSED_PAD src0_sel:WORD_1
	v_cvt_f32_f16_e32 v240, v160
	v_cvt_f32_f16_sdwa v241, v160 dst_sel:DWORD dst_unused:UNUSED_PAD src0_sel:WORD_1
	v_cvt_f32_f16_e32 v242, v161
	v_cvt_f32_f16_sdwa v243, v161 dst_sel:DWORD dst_unused:UNUSED_PAD src0_sel:WORD_1
	v_pk_fma_f32 v[160:161], v[80:81], v[136:137], v[232:233]
	v_pk_fma_f32 v[162:163], v[78:79], v[134:135], v[234:235]
	v_pk_fma_f32 v[156:157], v[76:77], v[132:133], v[156:157]
	v_pk_fma_f32 v[158:159], v[74:75], v[130:131], v[158:159]
	v_pk_fma_f32 v[74:75], v[68:69], v[132:133], v[238:239]
	v_pk_fma_f32 v[76:77], v[66:67], v[130:131], v[236:237]
	v_cvt_pk_f16_f32 v69, v156, v157
	v_cvt_pk_f16_f32 v67, v160, v161
	v_cvt_pk_f16_f32 v68, v158, v159
	v_cvt_pk_f16_f32 v66, v162, v163
	v_pk_fma_f32 v[78:79], v[72:73], v[136:137], v[242:243]
	v_pk_fma_f32 v[80:81], v[70:71], v[134:135], v[240:241]
	v_pk_mul_f32 v[130:131], v[216:217], v[160:161]
	v_pk_mul_f32 v[132:133], v[218:219], v[162:163]
	v_pk_mul_f32 v[134:135], v[220:221], v[156:157]
	v_pk_mul_f32 v[136:137], v[222:223], v[158:159]
	global_store_dwordx4 v[182:183], v[66:69], off
	v_cvt_pk_f16_f32 v73, v74, v75
	v_cvt_pk_f16_f32 v71, v78, v79
	v_cvt_pk_bf16_f32 v66, v132, v133
	v_cvt_pk_bf16_f32 v67, v130, v131
	v_cvt_pk_bf16_f32 v68, v136, v137
	v_cvt_pk_bf16_f32 v69, v134, v135
	v_cvt_pk_f16_f32 v72, v76, v77
	v_cvt_pk_f16_f32 v70, v80, v81
	v_pk_mul_f32 v[216:217], v[216:217], v[78:79]
	v_pk_mul_f32 v[218:219], v[218:219], v[80:81]
	v_pk_mul_f32 v[220:221], v[220:221], v[74:75]
	v_pk_mul_f32 v[222:223], v[222:223], v[76:77]
	global_store_dwordx4 v[206:207], v[66:69], off
	global_store_dwordx4 v[194:195], v[70:73], off
	s_nop 0
	v_cvt_pk_bf16_f32 v66, v218, v219
	v_cvt_pk_bf16_f32 v67, v216, v217
	v_cvt_pk_bf16_f32 v68, v222, v223
	v_cvt_pk_bf16_f32 v69, v220, v221
	global_store_dwordx4 v[200:201], v[66:69], off
	global_load_dwordx4 v[130:133], v[172:173], off offset:512
	global_load_dwordx4 v[134:137], v[172:173], off offset:528
	s_nop 0
	global_load_dwordx4 v[172:175], v[174:175], off offset:256 nt
	s_nop 0
	global_load_dwordx4 v[216:219], v[178:179], off offset:256 nt
	v_or_b32_e32 v66, 0x80, v166
	v_ashrrev_i32_e32 v67, 31, v66
	v_lshl_add_u64 v[66:67], v[66:67], 2, s[16:17]
	global_load_dwordx4 v[220:223], v[66:67], off
	global_load_dwordx4 v[232:235], v[66:67], off offset:16
	global_load_dwordx4 v[70:73], v[176:177], off offset:512
	s_nop 0
	global_load_dwordx4 v[66:69], v[176:177], off offset:528
	s_waitcnt vmcnt(7)
	v_pk_add_f32 v[132:133], v[132:133], 1.0 op_sel_hi:[1,0]
	v_pk_add_f32 v[166:167], v[130:131], 1.0 op_sel_hi:[1,0]
	s_waitcnt vmcnt(5)
	v_cvt_f32_f16_e32 v178, v174
	v_cvt_f32_f16_sdwa v179, v174 dst_sel:DWORD dst_unused:UNUSED_PAD src0_sel:WORD_1
	v_cvt_f32_f16_e32 v174, v175
	v_cvt_f32_f16_sdwa v175, v175 dst_sel:DWORD dst_unused:UNUSED_PAD src0_sel:WORD_1
	v_cvt_f32_f16_e32 v236, v172
	v_cvt_f32_f16_sdwa v237, v172 dst_sel:DWORD dst_unused:UNUSED_PAD src0_sel:WORD_1
	v_cvt_f32_f16_e32 v172, v173
	v_cvt_f32_f16_sdwa v173, v173 dst_sel:DWORD dst_unused:UNUSED_PAD src0_sel:WORD_1
	s_waitcnt vmcnt(4)
	v_cvt_f32_f16_e32 v238, v218
	v_cvt_f32_f16_sdwa v239, v218 dst_sel:DWORD dst_unused:UNUSED_PAD src0_sel:WORD_1
	v_cvt_f32_f16_e32 v218, v219
	v_cvt_f32_f16_sdwa v219, v219 dst_sel:DWORD dst_unused:UNUSED_PAD src0_sel:WORD_1
	v_cvt_f32_f16_e32 v240, v216
	v_cvt_f32_f16_sdwa v241, v216 dst_sel:DWORD dst_unused:UNUSED_PAD src0_sel:WORD_1
	v_cvt_f32_f16_e32 v216, v217
	v_cvt_f32_f16_sdwa v217, v217 dst_sel:DWORD dst_unused:UNUSED_PAD src0_sel:WORD_1
	v_pk_add_f32 v[136:137], v[136:137], 1.0 op_sel_hi:[1,0]
	v_pk_add_f32 v[176:177], v[134:135], 1.0 op_sel_hi:[1,0]
	s_waitcnt vmcnt(3)
	v_pk_mul_f32 v[130:131], v[222:223], v[132:133]
	s_waitcnt vmcnt(1)
	v_pk_fma_f32 v[64:65], v[64:65], v[72:73], v[172:173]
	v_pk_fma_f32 v[62:63], v[62:63], v[70:71], v[236:237]
	s_waitcnt vmcnt(0)
	v_pk_fma_f32 v[60:61], v[60:61], v[68:69], v[174:175]
	v_pk_fma_f32 v[58:59], v[58:59], v[66:67], v[178:179]
	v_pk_mul_f32 v[132:133], v[220:221], v[166:167]
	v_pk_mul_f32 v[134:135], v[234:235], v[136:137]
	v_pk_mul_f32 v[136:137], v[232:233], v[176:177]
	v_cvt_pk_f16_f32 v175, v60, v61
	v_cvt_pk_f16_f32 v173, v64, v65
	v_cvt_pk_f16_f32 v174, v58, v59
	v_cvt_pk_f16_f32 v172, v62, v63
	v_pk_mul_f32 v[166:167], v[130:131], v[64:65]
	v_pk_fma_f32 v[56:57], v[56:57], v[72:73], v[216:217]
	v_pk_fma_f32 v[54:55], v[54:55], v[70:71], v[240:241]
	v_pk_fma_f32 v[52:53], v[52:53], v[68:69], v[218:219]
	v_pk_fma_f32 v[50:51], v[50:51], v[66:67], v[238:239]
	v_pk_mul_f32 v[216:217], v[132:133], v[62:63]
	v_pk_mul_f32 v[218:219], v[134:135], v[60:61]
	v_pk_mul_f32 v[220:221], v[136:137], v[58:59]
	global_store_dwordx4 v[164:165], v[172:175], off offset:256
	v_cvt_pk_bf16_f32 v164, v216, v217
	v_cvt_pk_bf16_f32 v165, v166, v167
	v_cvt_pk_bf16_f32 v166, v220, v221
	v_cvt_pk_bf16_f32 v167, v218, v219
	v_cvt_pk_f16_f32 v179, v52, v53
	v_cvt_pk_f16_f32 v177, v56, v57
	v_cvt_pk_f16_f32 v178, v50, v51
	v_cvt_pk_f16_f32 v176, v54, v55
	v_pk_mul_f32 v[222:223], v[130:131], v[56:57]
	v_pk_mul_f32 v[232:233], v[132:133], v[54:55]
	v_pk_mul_f32 v[234:235], v[134:135], v[52:53]
	v_pk_mul_f32 v[236:237], v[136:137], v[50:51]
	global_store_dwordx4 v[168:169], v[164:167], off offset:256
	global_store_dwordx4 v[180:181], v[176:179], off offset:256
	v_mul_f32_e32 v63, v63, v63
	v_cvt_pk_bf16_f32 v164, v232, v233
	v_cvt_pk_bf16_f32 v165, v222, v223
	v_cvt_pk_bf16_f32 v166, v236, v237
	v_cvt_pk_bf16_f32 v167, v234, v235
	global_store_dwordx4 v[186:187], v[164:167], off offset:256
	global_load_dwordx4 v[164:167], v[188:189], off offset:256 nt
	s_nop 0
	global_load_dwordx4 v[172:175], v[190:191], off offset:256 nt
	v_mul_f32_e32 v65, v65, v65
	v_mul_f32_e32 v59, v59, v59
	v_mul_f32_e32 v61, v61, v61
	v_fmac_f32_e32 v63, v62, v62
	v_fmac_f32_e32 v65, v64, v64
	v_fmac_f32_e32 v59, v58, v58
	v_fmac_f32_e32 v61, v60, v60
	v_add_f32_e32 v58, v63, v65
	v_add_f32_e32 v59, v59, v61
	v_add_f32_e32 v58, v58, v59
	v_add_f32_e32 v59, v122, v58
	v_xor_b32_e32 v58, 32, v231
	s_waitcnt vmcnt(1)
	v_cvt_f32_f16_e32 v168, v166
	v_cvt_f32_f16_sdwa v169, v166 dst_sel:DWORD dst_unused:UNUSED_PAD src0_sel:WORD_1
	v_cvt_f32_f16_e32 v166, v167
	v_cvt_f32_f16_sdwa v167, v167 dst_sel:DWORD dst_unused:UNUSED_PAD src0_sel:WORD_1
	v_cvt_f32_f16_e32 v176, v164
	v_cvt_f32_f16_sdwa v177, v164 dst_sel:DWORD dst_unused:UNUSED_PAD src0_sel:WORD_1
	v_cvt_f32_f16_e32 v164, v165
	v_cvt_f32_f16_sdwa v165, v165 dst_sel:DWORD dst_unused:UNUSED_PAD src0_sel:WORD_1
	s_waitcnt vmcnt(0)
	v_cvt_f32_f16_e32 v178, v174
	v_cvt_f32_f16_sdwa v179, v174 dst_sel:DWORD dst_unused:UNUSED_PAD src0_sel:WORD_1
	v_cvt_f32_f16_e32 v174, v175
	v_cvt_f32_f16_sdwa v175, v175 dst_sel:DWORD dst_unused:UNUSED_PAD src0_sel:WORD_1
	v_cvt_f32_f16_e32 v180, v172
	v_cvt_f32_f16_sdwa v181, v172 dst_sel:DWORD dst_unused:UNUSED_PAD src0_sel:WORD_1
	v_cvt_f32_f16_e32 v172, v173
	v_cvt_f32_f16_sdwa v173, v173 dst_sel:DWORD dst_unused:UNUSED_PAD src0_sel:WORD_1
	v_pk_fma_f32 v[48:49], v[48:49], v[72:73], v[164:165]
	v_pk_fma_f32 v[46:47], v[46:47], v[70:71], v[176:177]
	v_pk_fma_f32 v[44:45], v[44:45], v[68:69], v[166:167]
	v_pk_fma_f32 v[42:43], v[42:43], v[66:67], v[168:169]
	v_cvt_pk_f16_f32 v167, v44, v45
	v_cvt_pk_f16_f32 v165, v48, v49
	v_cvt_pk_f16_f32 v166, v42, v43
	v_cvt_pk_f16_f32 v164, v46, v47
	v_pk_fma_f32 v[40:41], v[40:41], v[72:73], v[172:173]
	v_pk_fma_f32 v[38:39], v[38:39], v[70:71], v[180:181]
	v_pk_fma_f32 v[36:37], v[36:37], v[68:69], v[174:175]
	v_pk_fma_f32 v[34:35], v[34:35], v[66:67], v[178:179]
	v_pk_mul_f32 v[168:169], v[130:131], v[48:49]
	v_pk_mul_f32 v[176:177], v[132:133], v[46:47]
	v_pk_mul_f32 v[178:179], v[134:135], v[44:45]
	v_pk_mul_f32 v[180:181], v[136:137], v[42:43]
	global_store_dwordx4 v[170:171], v[164:167], off offset:256
	v_cvt_pk_f16_f32 v175, v36, v37
	v_cvt_pk_f16_f32 v173, v40, v41
	v_cvt_pk_bf16_f32 v164, v176, v177
	v_cvt_pk_bf16_f32 v165, v168, v169
	v_cvt_pk_bf16_f32 v166, v180, v181
	v_cvt_pk_bf16_f32 v167, v178, v179
	v_cvt_pk_f16_f32 v174, v34, v35
	v_cvt_pk_f16_f32 v172, v38, v39
	v_pk_mul_f32 v[186:187], v[130:131], v[40:41]
	v_pk_mul_f32 v[188:189], v[132:133], v[38:39]
	v_pk_mul_f32 v[190:191], v[134:135], v[36:37]
	v_pk_mul_f32 v[216:217], v[136:137], v[34:35]
	global_store_dwordx4 v[192:193], v[164:167], off offset:256
	global_store_dwordx4 v[184:185], v[172:175], off offset:256
	s_nop 0
	v_cvt_pk_bf16_f32 v164, v188, v189
	v_cvt_pk_bf16_f32 v165, v186, v187
	v_cvt_pk_bf16_f32 v166, v216, v217
	v_cvt_pk_bf16_f32 v167, v190, v191
	global_store_dwordx4 v[196:197], v[164:167], off offset:256
	global_load_dwordx4 v[164:167], v[198:199], off offset:256 nt
	s_nop 0
	global_load_dwordx4 v[168:171], v[204:205], off offset:256 nt
	s_waitcnt vmcnt(1)
	v_cvt_f32_f16_e32 v172, v166
	v_cvt_f32_f16_sdwa v173, v166 dst_sel:DWORD dst_unused:UNUSED_PAD src0_sel:WORD_1
	v_cvt_f32_f16_e32 v166, v167
	v_cvt_f32_f16_sdwa v167, v167 dst_sel:DWORD dst_unused:UNUSED_PAD src0_sel:WORD_1
	v_cvt_f32_f16_e32 v174, v164
	v_cvt_f32_f16_sdwa v175, v164 dst_sel:DWORD dst_unused:UNUSED_PAD src0_sel:WORD_1
	v_cvt_f32_f16_e32 v164, v165
	v_cvt_f32_f16_sdwa v165, v165 dst_sel:DWORD dst_unused:UNUSED_PAD src0_sel:WORD_1
	s_waitcnt vmcnt(0)
	v_cvt_f32_f16_e32 v176, v170
	v_cvt_f32_f16_sdwa v177, v170 dst_sel:DWORD dst_unused:UNUSED_PAD src0_sel:WORD_1
	v_cvt_f32_f16_e32 v170, v171
	v_cvt_f32_f16_sdwa v171, v171 dst_sel:DWORD dst_unused:UNUSED_PAD src0_sel:WORD_1
	v_cvt_f32_f16_e32 v178, v168
	v_cvt_f32_f16_sdwa v179, v168 dst_sel:DWORD dst_unused:UNUSED_PAD src0_sel:WORD_1
	v_cvt_f32_f16_e32 v168, v169
	v_cvt_f32_f16_sdwa v169, v169 dst_sel:DWORD dst_unused:UNUSED_PAD src0_sel:WORD_1
	v_pk_fma_f32 v[32:33], v[32:33], v[72:73], v[164:165]
	v_pk_fma_f32 v[30:31], v[30:31], v[70:71], v[174:175]
	v_pk_fma_f32 v[28:29], v[28:29], v[68:69], v[166:167]
	v_pk_fma_f32 v[26:27], v[26:27], v[66:67], v[172:173]
	v_cvt_pk_f16_f32 v167, v28, v29
	v_cvt_pk_f16_f32 v165, v32, v33
	v_cvt_pk_f16_f32 v166, v26, v27
	v_cvt_pk_f16_f32 v164, v30, v31
	v_pk_fma_f32 v[24:25], v[24:25], v[72:73], v[168:169]
	v_pk_fma_f32 v[22:23], v[22:23], v[70:71], v[178:179]
	v_pk_fma_f32 v[20:21], v[20:21], v[68:69], v[170:171]
	v_pk_fma_f32 v[18:19], v[18:19], v[66:67], v[176:177]
	v_pk_mul_f32 v[172:173], v[130:131], v[32:33]
	v_pk_mul_f32 v[174:175], v[132:133], v[30:31]
	v_pk_mul_f32 v[176:177], v[134:135], v[28:29]
	v_pk_mul_f32 v[178:179], v[136:137], v[26:27]
	global_store_dwordx4 v[212:213], v[164:167], off offset:256
	v_cvt_pk_f16_f32 v171, v20, v21
	v_cvt_pk_f16_f32 v169, v24, v25
	v_cvt_pk_bf16_f32 v164, v174, v175
	v_cvt_pk_bf16_f32 v165, v172, v173
	v_cvt_pk_bf16_f32 v166, v178, v179
	v_cvt_pk_bf16_f32 v167, v176, v177
	v_cvt_pk_f16_f32 v170, v18, v19
	v_cvt_pk_f16_f32 v168, v22, v23
	v_pk_mul_f32 v[180:181], v[130:131], v[24:25]
	v_pk_mul_f32 v[184:185], v[132:133], v[22:23]
	v_pk_mul_f32 v[186:187], v[134:135], v[20:21]
	v_pk_mul_f32 v[188:189], v[136:137], v[18:19]
	global_store_dwordx4 v[214:215], v[164:167], off offset:256
	global_store_dwordx4 v[210:211], v[168:171], off offset:256
	s_nop 0
	v_cvt_pk_bf16_f32 v164, v184, v185
	v_cvt_pk_bf16_f32 v165, v180, v181
	v_cvt_pk_bf16_f32 v166, v188, v189
	v_cvt_pk_bf16_f32 v167, v186, v187
	global_store_dwordx4 v[208:209], v[164:167], off offset:256
	global_load_dwordx4 v[166:169], v[202:203], off offset:256 nt
	s_nop 0
	global_load_dwordx4 v[170:173], v[224:225], off offset:256 nt
	v_and_b32_e32 v165, 64, v231
	v_xor_b32_e32 v164, 16, v231
	v_add_u32_e32 v165, 64, v165
	v_cmp_lt_i32_e32 vcc, v164, v165
	s_waitcnt vmcnt(1)
	v_cvt_f32_f16_e32 v62, v168
	v_cndmask_b32_e32 v164, v231, v164, vcc
	v_lshlrev_b32_e32 v164, 2, v164
	ds_bpermute_b32 v60, v164, v59
	v_cmp_lt_i32_e32 vcc, v58, v165
	v_cvt_f32_f16_sdwa v63, v168 dst_sel:DWORD dst_unused:UNUSED_PAD src0_sel:WORD_1
	v_cvt_f32_f16_e32 v64, v169
	v_cndmask_b32_e32 v58, v231, v58, vcc
	v_cvt_f32_f16_sdwa v65, v169 dst_sel:DWORD dst_unused:UNUSED_PAD src0_sel:WORD_1
	v_cvt_f32_f16_e32 v122, v166
	v_cvt_f32_f16_sdwa v123, v166 dst_sel:DWORD dst_unused:UNUSED_PAD src0_sel:WORD_1
	v_cvt_f32_f16_e32 v124, v167
	v_cvt_f32_f16_sdwa v125, v167 dst_sel:DWORD dst_unused:UNUSED_PAD src0_sel:WORD_1
	v_lshlrev_b32_e32 v58, 2, v58
	s_waitcnt lgkmcnt(0)
	v_add_f32_e32 v59, v59, v60
	ds_bpermute_b32 v60, v58, v59
	s_waitcnt vmcnt(0)
	v_cvt_f32_f16_e32 v126, v172
	v_cvt_f32_f16_sdwa v127, v172 dst_sel:DWORD dst_unused:UNUSED_PAD src0_sel:WORD_1
	v_cvt_f32_f16_e32 v128, v173
	v_cvt_f32_f16_sdwa v129, v173 dst_sel:DWORD dst_unused:UNUSED_PAD src0_sel:WORD_1
	v_cvt_f32_f16_e32 v166, v170
	v_cvt_f32_f16_sdwa v167, v170 dst_sel:DWORD dst_unused:UNUSED_PAD src0_sel:WORD_1
	v_cvt_f32_f16_e32 v168, v171
	v_cvt_f32_f16_sdwa v169, v171 dst_sel:DWORD dst_unused:UNUSED_PAD src0_sel:WORD_1
	v_pk_fma_f32 v[16:17], v[16:17], v[72:73], v[124:125]
	v_pk_fma_f32 v[14:15], v[14:15], v[70:71], v[122:123]
	v_pk_fma_f32 v[12:13], v[12:13], v[68:69], v[64:65]
	v_pk_fma_f32 v[10:11], v[10:11], v[66:67], v[62:63]
	v_cvt_pk_f16_f32 v65, v12, v13
	v_cvt_pk_f16_f32 v63, v16, v17
	v_cvt_pk_f16_f32 v64, v10, v11
	v_cvt_pk_f16_f32 v62, v14, v15
	v_pk_fma_f32 v[8:9], v[8:9], v[72:73], v[168:169]
	v_pk_fma_f32 v[6:7], v[6:7], v[70:71], v[166:167]
	v_pk_fma_f32 v[4:5], v[4:5], v[68:69], v[128:129]
	v_pk_fma_f32 v[2:3], v[2:3], v[66:67], v[126:127]
	v_pk_mul_f32 v[70:71], v[130:131], v[16:17]
	v_pk_mul_f32 v[72:73], v[132:133], v[14:15]
	v_pk_mul_f32 v[122:123], v[134:135], v[12:13]
	v_pk_mul_f32 v[124:125], v[136:137], v[10:11]
	global_store_dwordx4 v[182:183], v[62:65], off offset:256
	v_cvt_pk_f16_f32 v69, v4, v5
	v_cvt_pk_f16_f32 v67, v8, v9
	v_cvt_pk_bf16_f32 v62, v72, v73
	v_cvt_pk_bf16_f32 v63, v70, v71
	v_cvt_pk_bf16_f32 v64, v124, v125
	v_cvt_pk_bf16_f32 v65, v122, v123
	v_cvt_pk_f16_f32 v68, v2, v3
	v_cvt_pk_f16_f32 v66, v6, v7
	v_pk_mul_f32 v[126:127], v[130:131], v[8:9]
	v_pk_mul_f32 v[128:129], v[132:133], v[6:7]
	v_pk_mul_f32 v[130:131], v[134:135], v[4:5]
	v_pk_mul_f32 v[132:133], v[136:137], v[2:3]
	global_store_dwordx4 v[206:207], v[62:65], off offset:256
	global_store_dwordx4 v[194:195], v[66:69], off offset:256
	s_nop 0
	v_cvt_pk_bf16_f32 v62, v128, v129
	v_cvt_pk_bf16_f32 v63, v126, v127
	v_cvt_pk_bf16_f32 v64, v132, v133
	v_cvt_pk_bf16_f32 v65, v130, v131
	global_store_dwordx4 v[200:201], v[62:65], off offset:256
	s_and_saveexec_b64 s[68:69], s[6:7]
	s_cbranch_execz .LBB0_907
	v_lshl_add_u64 v[62:63], v[154:155], 2, s[28:29]
	s_waitcnt lgkmcnt(0)
	v_add_f32_e32 v59, v59, v60
	global_atomic_add_f32 v[62:63], v59, off

.LBB0_990:
	s_ashr_i32 s79, s78, 31
	s_lshl_b64 s[12:13], s[78:79], 19
	s_add_u32 s80, s19, s12
	s_addc_u32 s81, s27, s13
	s_and_b64 s[12:13], s[6:7], exec
	s_cselect_b32 s11, s81, s1
	s_cselect_b32 s23, s80, s0
	s_ashr_i32 s77, s76, 31
	s_lshl_b64 s[12:13], s[76:77], 19
	s_add_u32 s82, s36, s12
	s_addc_u32 s83, s37, s13
	s_and_b64 s[12:13], s[6:7], exec
	s_cselect_b32 s48, s83, s85
	s_cselect_b32 s49, s82, s84
	s_add_u32 s0, s0, 0x40080
	s_addc_u32 s1, s1, 0
	s_add_u32 s63, s84, 0x100
	v_mov_b32_e32 v2, 0
	s_addc_u32 s77, s85, 0
	s_mov_b32 s12, -2
	v_mov_b32_e32 v3, v2
	v_mov_b32_e32 v4, v2
	v_mov_b32_e32 v5, v2
	v_mov_b32_e32 v6, v2
	v_mov_b32_e32 v7, v2
	v_mov_b32_e32 v8, v2
	v_mov_b32_e32 v9, v2
	v_mov_b32_e32 v18, v2
	v_mov_b32_e32 v19, v2
	v_mov_b32_e32 v20, v2
	v_mov_b32_e32 v21, v2
	v_mov_b32_e32 v22, v2
	v_mov_b32_e32 v23, v2
	v_mov_b32_e32 v24, v2
	v_mov_b32_e32 v25, v2
	v_mov_b32_e32 v50, v2
	v_mov_b32_e32 v51, v2
	v_mov_b32_e32 v52, v2
	v_mov_b32_e32 v53, v2
	v_mov_b32_e32 v54, v2
	v_mov_b32_e32 v55, v2
	v_mov_b32_e32 v56, v2
	v_mov_b32_e32 v57, v2
	v_mov_b32_e32 v66, v2
	v_mov_b32_e32 v67, v2
	v_mov_b32_e32 v68, v2
	v_mov_b32_e32 v69, v2
	v_mov_b32_e32 v70, v2
	v_mov_b32_e32 v71, v2
	v_mov_b32_e32 v72, v2
	v_mov_b32_e32 v73, v2
	v_mov_b32_e32 v10, v2
	v_mov_b32_e32 v11, v2
	v_mov_b32_e32 v12, v2
	v_mov_b32_e32 v13, v2
	v_mov_b32_e32 v14, v2
	v_mov_b32_e32 v15, v2
	v_mov_b32_e32 v16, v2
	v_mov_b32_e32 v17, v2
	v_mov_b32_e32 v26, v2
	v_mov_b32_e32 v27, v2
	v_mov_b32_e32 v28, v2
	v_mov_b32_e32 v29, v2
	v_mov_b32_e32 v30, v2
	v_mov_b32_e32 v31, v2
	v_mov_b32_e32 v32, v2
	v_mov_b32_e32 v33, v2
	v_mov_b32_e32 v58, v2
	v_mov_b32_e32 v59, v2
	v_mov_b32_e32 v60, v2
	v_mov_b32_e32 v61, v2
	v_mov_b32_e32 v62, v2
	v_mov_b32_e32 v63, v2
	v_mov_b32_e32 v64, v2
	v_mov_b32_e32 v65, v2
	v_mov_b32_e32 v74, v2
	v_mov_b32_e32 v75, v2
	v_mov_b32_e32 v76, v2
	v_mov_b32_e32 v77, v2
	v_mov_b32_e32 v78, v2
	v_mov_b32_e32 v79, v2
	v_mov_b32_e32 v80, v2
	v_mov_b32_e32 v81, v2
	v_mov_b32_e32 v82, v2
	v_mov_b32_e32 v83, v2
	v_mov_b32_e32 v84, v2
	v_mov_b32_e32 v85, v2
	v_mov_b32_e32 v86, v2
	v_mov_b32_e32 v87, v2
	v_mov_b32_e32 v88, v2
	v_mov_b32_e32 v89, v2
	v_mov_b32_e32 v98, v2
	v_mov_b32_e32 v99, v2
	v_mov_b32_e32 v100, v2
	v_mov_b32_e32 v101, v2
	v_mov_b32_e32 v102, v2
	v_mov_b32_e32 v103, v2
	v_mov_b32_e32 v104, v2
	v_mov_b32_e32 v105, v2
	v_mov_b32_e32 v114, v2
	v_mov_b32_e32 v115, v2
	v_mov_b32_e32 v116, v2
	v_mov_b32_e32 v117, v2
	v_mov_b32_e32 v118, v2
	v_mov_b32_e32 v119, v2
	v_mov_b32_e32 v120, v2
	v_mov_b32_e32 v121, v2
	v_mov_b32_e32 v130, v2
	v_mov_b32_e32 v131, v2
	v_mov_b32_e32 v132, v2
	v_mov_b32_e32 v133, v2
	v_mov_b32_e32 v134, v2
	v_mov_b32_e32 v135, v2
	v_mov_b32_e32 v136, v2
	v_mov_b32_e32 v137, v2
	v_mov_b32_e32 v90, v2
	v_mov_b32_e32 v91, v2
	v_mov_b32_e32 v92, v2
	v_mov_b32_e32 v93, v2
	v_mov_b32_e32 v94, v2
	v_mov_b32_e32 v95, v2
	v_mov_b32_e32 v96, v2
	v_mov_b32_e32 v97, v2
	v_mov_b32_e32 v106, v2
	v_mov_b32_e32 v107, v2
	v_mov_b32_e32 v108, v2
	v_mov_b32_e32 v109, v2
	v_mov_b32_e32 v110, v2
	v_mov_b32_e32 v111, v2
	v_mov_b32_e32 v112, v2
	v_mov_b32_e32 v113, v2
	v_mov_b32_e32 v122, v2
	v_mov_b32_e32 v123, v2
	v_mov_b32_e32 v124, v2
	v_mov_b32_e32 v125, v2
	v_mov_b32_e32 v126, v2
	v_mov_b32_e32 v127, v2
	v_mov_b32_e32 v128, v2
	v_mov_b32_e32 v129, v2
	v_mov_b32_e32 v138, v2
	v_mov_b32_e32 v139, v2
	v_mov_b32_e32 v140, v2
	v_mov_b32_e32 v141, v2
	v_mov_b32_e32 v142, v2
	v_mov_b32_e32 v143, v2
	v_mov_b32_e32 v144, v2
	v_mov_b32_e32 v145, v2
	v_add_u32_e32 v251, 0x80, v150
	v_add_u32_e32 v252, 0x80, v154
	v_add_u32_e32 v253, 0x80, v148
	v_add_u32_e32 v254, 0x80, v152
.LBB0_991:
	ds_read_b128 v[34:37], v184
	ds_read_b128 v[38:41], v184 offset:1024
	ds_read_b128 v[42:45], v184 offset:2048
	ds_read_b128 v[46:49], v184 offset:3072
	ds_read_b128 v[166:169], v185
	ds_read_b128 v[170:173], v185 offset:1024
	ds_read_b128 v[190:193], v185 offset:2048
	ds_read_b128 v[194:197], v185 offset:3072
	s_add_u32 s3, s0, 0xfffc0080
	s_addc_u32 s13, s1, -1
	s_cmp_eq_u32 s12, 12
	s_cselect_b32 s87, s11, s13
	s_cselect_b32 s86, s23, s3
	s_cselect_b32 s85, s48, s77
	s_cselect_b32 s84, s49, s63
	s_nop 0
	s_add_i32 m0, s67, 0xc000
	ds_read_b128 v[198:201], v186
	ds_read_b128 v[202:205], v186 offset:1024
	ds_read_b128 v[206:209], v186 offset:2048
	ds_read_b128 v[210:213], v186 offset:3072
	ds_read_b128 v[214:217], v186 offset:4096
	ds_read_b128 v[218:221], v186 offset:5120
	ds_read_b128 v[222:225], v186 offset:6144
	ds_read_b128 v[226:229], v186 offset:7168
	global_load_lds_dwordx4 v158, s[0:1]
	s_nop 0
	s_add_i32 m0, s67, 0xe000
	s_nop 0
	global_load_lds_dwordx4 v160, s[0:1]
	s_waitcnt vmcnt(8)
	s_waitcnt lgkmcnt(0)
	s_barrier
	s_setprio 1
	s_waitcnt lgkmcnt(0)
	v_mfma_f32_16x16x32_bf16 v[142:145], v[34:37], v[198:201], v[142:145]
	v_mfma_f32_16x16x32_bf16 v[138:141], v[42:45], v[198:201], v[138:141]
	v_mfma_f32_16x16x32_bf16 v[126:129], v[34:37], v[206:209], v[126:129]
	v_mfma_f32_16x16x32_bf16 v[122:125], v[42:45], v[206:209], v[122:125]
	v_mfma_f32_16x16x32_bf16 v[110:113], v[34:37], v[214:217], v[110:113]
	v_mfma_f32_16x16x32_bf16 v[106:109], v[42:45], v[214:217], v[106:109]
	v_mfma_f32_16x16x32_bf16 v[94:97], v[34:37], v[222:225], v[94:97]
	v_mfma_f32_16x16x32_bf16 v[90:93], v[42:45], v[222:225], v[90:93]
	v_mfma_f32_16x16x32_bf16 v[142:145], v[38:41], v[202:205], v[142:145]
	v_mfma_f32_16x16x32_bf16 v[138:141], v[46:49], v[202:205], v[138:141]
	v_mfma_f32_16x16x32_bf16 v[126:129], v[38:41], v[210:213], v[126:129]
	v_mfma_f32_16x16x32_bf16 v[122:125], v[46:49], v[210:213], v[122:125]
	v_mfma_f32_16x16x32_bf16 v[110:113], v[38:41], v[218:221], v[110:113]
	v_mfma_f32_16x16x32_bf16 v[106:109], v[46:49], v[218:221], v[106:109]
	v_mfma_f32_16x16x32_bf16 v[94:97], v[38:41], v[226:229], v[94:97]
	v_mfma_f32_16x16x32_bf16 v[90:93], v[46:49], v[226:229], v[90:93]
	s_setprio 0
	s_setprio 1
	v_mfma_f32_16x16x32_bf16 v[134:137], v[166:169], v[198:201], v[134:137]
	v_mfma_f32_16x16x32_bf16 v[130:133], v[190:193], v[198:201], v[130:133]
	v_mfma_f32_16x16x32_bf16 v[118:121], v[166:169], v[206:209], v[118:121]
	v_mfma_f32_16x16x32_bf16 v[114:117], v[190:193], v[206:209], v[114:117]
	v_mfma_f32_16x16x32_bf16 v[102:105], v[166:169], v[214:217], v[102:105]
	v_mfma_f32_16x16x32_bf16 v[98:101], v[190:193], v[214:217], v[98:101]
	v_mfma_f32_16x16x32_bf16 v[86:89], v[166:169], v[222:225], v[86:89]
	v_mfma_f32_16x16x32_bf16 v[82:85], v[190:193], v[222:225], v[82:85]
	v_mfma_f32_16x16x32_bf16 v[134:137], v[170:173], v[202:205], v[134:137]
	v_mfma_f32_16x16x32_bf16 v[130:133], v[194:197], v[202:205], v[130:133]
	v_mfma_f32_16x16x32_bf16 v[118:121], v[170:173], v[210:213], v[118:121]
	v_mfma_f32_16x16x32_bf16 v[114:117], v[194:197], v[210:213], v[114:117]
	v_mfma_f32_16x16x32_bf16 v[102:105], v[170:173], v[218:221], v[102:105]
	v_mfma_f32_16x16x32_bf16 v[98:101], v[194:197], v[218:221], v[98:101]
	v_mfma_f32_16x16x32_bf16 v[86:89], v[170:173], v[226:229], v[86:89]
	v_mfma_f32_16x16x32_bf16 v[82:85], v[194:197], v[226:229], v[82:85]
	s_setprio 0
	s_barrier
	s_add_i32 s3, s61, s66
	s_nop 0
	s_mov_b32 m0, s3
	ds_read_b128 v[198:201], v186 offset:16384
	ds_read_b128 v[202:205], v186 offset:17408
	ds_read_b128 v[206:209], v186 offset:18432
	ds_read_b128 v[210:213], v186 offset:19456
	ds_read_b128 v[214:217], v186 offset:20480
	ds_read_b128 v[218:221], v186 offset:21504
	ds_read_b128 v[222:225], v186 offset:22528
	ds_read_b128 v[226:229], v186 offset:23552
	global_load_lds_dwordx4 v150, s[84:85]
	s_add_i32 m0, s3, 0x2000
	s_add_u32 s24, s84, 0x40000
	v_lshl_add_u64 v[232:233], s[84:85], 0, v[154:155]
	s_addc_u32 s25, s85, 0
	s_add_i32 s3, s62, s66
	global_load_lds_dwordx4 v154, s[84:85]
	s_nop 0
	s_mov_b32 m0, s3
	v_lshl_add_u64 v[236:237], s[86:87], 0, v[152:153]
	global_load_lds_dwordx4 v150, s[24:25]
	s_nop 0
	s_add_i32 m0, s3, 0x2000
	s_nop 0
	global_load_lds_dwordx4 v154, s[24:25]
	s_nop 0
	s_mov_b32 m0, s67
	s_nop 0
	global_load_lds_dwordx4 v148, s[86:87]
	s_mov_b32 m0, s88
	s_nop 0
	global_load_lds_dwordx4 v152, s[86:87]
	s_waitcnt vmcnt(8)
	s_waitcnt lgkmcnt(0)
	s_barrier
	s_setprio 1
	s_waitcnt lgkmcnt(0)
	v_mfma_f32_16x16x32_bf16 v[78:81], v[34:37], v[198:201], v[78:81]
	v_mfma_f32_16x16x32_bf16 v[74:77], v[42:45], v[198:201], v[74:77]
	v_mfma_f32_16x16x32_bf16 v[62:65], v[34:37], v[206:209], v[62:65]
	v_mfma_f32_16x16x32_bf16 v[58:61], v[42:45], v[206:209], v[58:61]
	v_mfma_f32_16x16x32_bf16 v[30:33], v[34:37], v[214:217], v[30:33]
	v_mfma_f32_16x16x32_bf16 v[26:29], v[42:45], v[214:217], v[26:29]
	v_mfma_f32_16x16x32_bf16 v[14:17], v[34:37], v[222:225], v[14:17]
	v_mfma_f32_16x16x32_bf16 v[10:13], v[42:45], v[222:225], v[10:13]
	v_mfma_f32_16x16x32_bf16 v[78:81], v[38:41], v[202:205], v[78:81]
	v_mfma_f32_16x16x32_bf16 v[74:77], v[46:49], v[202:205], v[74:77]
	v_mfma_f32_16x16x32_bf16 v[62:65], v[38:41], v[210:213], v[62:65]
	v_mfma_f32_16x16x32_bf16 v[58:61], v[46:49], v[210:213], v[58:61]
	v_mfma_f32_16x16x32_bf16 v[30:33], v[38:41], v[218:221], v[30:33]
	v_mfma_f32_16x16x32_bf16 v[26:29], v[46:49], v[218:221], v[26:29]
	v_mfma_f32_16x16x32_bf16 v[14:17], v[38:41], v[226:229], v[14:17]
	v_mfma_f32_16x16x32_bf16 v[10:13], v[46:49], v[226:229], v[10:13]
	s_setprio 0
	s_setprio 1
	v_mfma_f32_16x16x32_bf16 v[22:25], v[166:169], v[214:217], v[22:25]
	v_mfma_f32_16x16x32_bf16 v[18:21], v[190:193], v[214:217], v[18:21]
	v_mfma_f32_16x16x32_bf16 v[6:9], v[166:169], v[222:225], v[6:9]
	v_mfma_f32_16x16x32_bf16 v[2:5], v[190:193], v[222:225], v[2:5]
	v_mfma_f32_16x16x32_bf16 v[34:37], v[166:169], v[198:201], v[70:73]
	v_mfma_f32_16x16x32_bf16 v[38:41], v[190:193], v[198:201], v[66:69]
	v_mfma_f32_16x16x32_bf16 v[42:45], v[166:169], v[206:209], v[54:57]
	v_mfma_f32_16x16x32_bf16 v[46:49], v[190:193], v[206:209], v[50:53]
	v_mfma_f32_16x16x32_bf16 v[22:25], v[170:173], v[218:221], v[22:25]
	v_mfma_f32_16x16x32_bf16 v[18:21], v[194:197], v[218:221], v[18:21]
	v_mfma_f32_16x16x32_bf16 v[6:9], v[170:173], v[226:229], v[6:9]
	v_mfma_f32_16x16x32_bf16 v[2:5], v[194:197], v[226:229], v[2:5]
	v_mfma_f32_16x16x32_bf16 v[34:37], v[170:173], v[202:205], v[34:37]
	v_mfma_f32_16x16x32_bf16 v[38:41], v[194:197], v[202:205], v[38:41]
	v_mfma_f32_16x16x32_bf16 v[42:45], v[170:173], v[210:213], v[42:45]
	v_mfma_f32_16x16x32_bf16 v[46:49], v[194:197], v[210:213], v[46:49]
	s_setprio 0
	s_barrier
	s_add_i32 s3, 0, 0x18000
	s_add_i32 s13, 0, 0x1c000
	v_add_u32_e32 v70, s3, v175
	v_add_u32_e32 v194, s13, v175
	ds_read_b128 v[50:53], v70
	ds_read_b128 v[54:57], v70 offset:1024
	ds_read_b128 v[66:69], v70 offset:2048
	ds_read_b128 v[70:73], v70 offset:3072
	ds_read_b128 v[166:169], v194
	ds_read_b128 v[170:173], v194 offset:1024
	ds_read_b128 v[190:193], v194 offset:2048
	ds_read_b128 v[194:197], v194 offset:3072
	s_add_u32 s24, s86, 0x40000
	s_addc_u32 s25, s87, 0
	s_mov_b32 m0, s89
	s_nop 0
	ds_read_b128 v[198:201], v186 offset:32768
	ds_read_b128 v[202:205], v186 offset:33792
	ds_read_b128 v[206:209], v186 offset:34816
	ds_read_b128 v[210:213], v186 offset:35840
	ds_read_b128 v[214:217], v186 offset:36864
	ds_read_b128 v[218:221], v186 offset:37888
	ds_read_b128 v[222:225], v186 offset:38912
	ds_read_b128 v[226:229], v186 offset:39936
	global_load_lds_dwordx4 v148, s[24:25]
	s_nop 0
	s_mov_b32 m0, s90
	s_nop 0
	global_load_lds_dwordx4 v152, s[24:25]
	s_waitcnt vmcnt(8)
	s_waitcnt lgkmcnt(0)
	s_barrier
	s_setprio 1
	s_waitcnt lgkmcnt(0)
	v_mfma_f32_16x16x32_bf16 v[142:145], v[50:53], v[198:201], v[142:145]
	v_mfma_f32_16x16x32_bf16 v[138:141], v[66:69], v[198:201], v[138:141]
	v_mfma_f32_16x16x32_bf16 v[126:129], v[50:53], v[206:209], v[126:129]
	v_mfma_f32_16x16x32_bf16 v[122:125], v[66:69], v[206:209], v[122:125]
	v_mfma_f32_16x16x32_bf16 v[110:113], v[50:53], v[214:217], v[110:113]
	v_mfma_f32_16x16x32_bf16 v[106:109], v[66:69], v[214:217], v[106:109]
	v_mfma_f32_16x16x32_bf16 v[94:97], v[50:53], v[222:225], v[94:97]
	v_mfma_f32_16x16x32_bf16 v[90:93], v[66:69], v[222:225], v[90:93]
	v_mfma_f32_16x16x32_bf16 v[142:145], v[54:57], v[202:205], v[142:145]
	v_mfma_f32_16x16x32_bf16 v[138:141], v[70:73], v[202:205], v[138:141]
	v_mfma_f32_16x16x32_bf16 v[126:129], v[54:57], v[210:213], v[126:129]
	v_mfma_f32_16x16x32_bf16 v[122:125], v[70:73], v[210:213], v[122:125]
	v_mfma_f32_16x16x32_bf16 v[110:113], v[54:57], v[218:221], v[110:113]
	v_mfma_f32_16x16x32_bf16 v[106:109], v[70:73], v[218:221], v[106:109]
	v_mfma_f32_16x16x32_bf16 v[94:97], v[54:57], v[226:229], v[94:97]
	v_mfma_f32_16x16x32_bf16 v[90:93], v[70:73], v[226:229], v[90:93]
	s_setprio 0
	s_setprio 1
	v_mfma_f32_16x16x32_bf16 v[134:137], v[166:169], v[198:201], v[134:137]
	v_mfma_f32_16x16x32_bf16 v[130:133], v[190:193], v[198:201], v[130:133]
	v_mfma_f32_16x16x32_bf16 v[118:121], v[166:169], v[206:209], v[118:121]
	v_mfma_f32_16x16x32_bf16 v[114:117], v[190:193], v[206:209], v[114:117]
	v_mfma_f32_16x16x32_bf16 v[102:105], v[166:169], v[214:217], v[102:105]
	v_mfma_f32_16x16x32_bf16 v[98:101], v[190:193], v[214:217], v[98:101]
	v_mfma_f32_16x16x32_bf16 v[86:89], v[166:169], v[222:225], v[86:89]
	v_mfma_f32_16x16x32_bf16 v[82:85], v[190:193], v[222:225], v[82:85]
	v_mfma_f32_16x16x32_bf16 v[134:137], v[170:173], v[202:205], v[134:137]
	v_mfma_f32_16x16x32_bf16 v[130:133], v[194:197], v[202:205], v[130:133]
	v_mfma_f32_16x16x32_bf16 v[118:121], v[170:173], v[210:213], v[118:121]
	v_mfma_f32_16x16x32_bf16 v[114:117], v[194:197], v[210:213], v[114:117]
	v_mfma_f32_16x16x32_bf16 v[102:105], v[170:173], v[218:221], v[102:105]
	v_mfma_f32_16x16x32_bf16 v[98:101], v[194:197], v[218:221], v[98:101]
	v_mfma_f32_16x16x32_bf16 v[86:89], v[170:173], v[226:229], v[86:89]
	v_mfma_f32_16x16x32_bf16 v[82:85], v[194:197], v[226:229], v[82:85]
	s_setprio 0
	s_barrier
	s_add_i32 s3, s3, s66
	s_nop 0
	s_mov_b32 m0, s3
	ds_read_b128 v[198:201], v186 offset:49152
	ds_read_b128 v[202:205], v186 offset:50176
	ds_read_b128 v[206:209], v186 offset:51200
	ds_read_b128 v[210:213], v186 offset:52224
	ds_read_b128 v[214:217], v186 offset:53248
	ds_read_b128 v[218:221], v186 offset:54272
	ds_read_b128 v[222:225], v186 offset:55296
	ds_read_b128 v[226:229], v186 offset:56320
	global_load_lds_dwordx4 v251, s[84:85]
	s_add_i32 m0, s3, 0x2000
	s_add_u32 s24, s84, 0x40080
	s_nop 0
	s_addc_u32 s25, s85, 0
	s_add_i32 s3, s13, s66
	global_load_lds_dwordx4 v252, s[84:85]
	s_nop 0
	s_mov_b32 m0, s3
	s_nop 0
	global_load_lds_dwordx4 v150, s[24:25]
	s_nop 0
	s_add_i32 m0, s3, 0x2000
	s_nop 0
	global_load_lds_dwordx4 v154, s[24:25]
	s_nop 0
	s_mov_b32 m0, s93
	s_nop 0
	global_load_lds_dwordx4 v253, s[86:87]
	s_nop 0
	s_mov_b32 m0, s44
	s_nop 0
	global_load_lds_dwordx4 v254, s[86:87]
	s_waitcnt vmcnt(8)
	s_waitcnt lgkmcnt(0)
	s_barrier
	s_setprio 1
	s_waitcnt lgkmcnt(0)
	v_mfma_f32_16x16x32_bf16 v[78:81], v[50:53], v[198:201], v[78:81]
	v_mfma_f32_16x16x32_bf16 v[74:77], v[66:69], v[198:201], v[74:77]
	v_mfma_f32_16x16x32_bf16 v[62:65], v[50:53], v[206:209], v[62:65]
	v_mfma_f32_16x16x32_bf16 v[58:61], v[66:69], v[206:209], v[58:61]
	v_mfma_f32_16x16x32_bf16 v[30:33], v[50:53], v[214:217], v[30:33]
	v_mfma_f32_16x16x32_bf16 v[26:29], v[66:69], v[214:217], v[26:29]
	v_mfma_f32_16x16x32_bf16 v[14:17], v[50:53], v[222:225], v[14:17]
	v_mfma_f32_16x16x32_bf16 v[10:13], v[66:69], v[222:225], v[10:13]
	v_mfma_f32_16x16x32_bf16 v[78:81], v[54:57], v[202:205], v[78:81]
	v_mfma_f32_16x16x32_bf16 v[74:77], v[70:73], v[202:205], v[74:77]
	v_mfma_f32_16x16x32_bf16 v[62:65], v[54:57], v[210:213], v[62:65]
	v_mfma_f32_16x16x32_bf16 v[58:61], v[70:73], v[210:213], v[58:61]
	v_mfma_f32_16x16x32_bf16 v[30:33], v[54:57], v[218:221], v[30:33]
	v_mfma_f32_16x16x32_bf16 v[26:29], v[70:73], v[218:221], v[26:29]
	v_mfma_f32_16x16x32_bf16 v[14:17], v[54:57], v[226:229], v[14:17]
	v_mfma_f32_16x16x32_bf16 v[10:13], v[70:73], v[226:229], v[10:13]
	s_setprio 0
	s_setprio 1
	v_mfma_f32_16x16x32_bf16 v[34:37], v[166:169], v[198:201], v[34:37]
	v_mfma_f32_16x16x32_bf16 v[70:73], v[170:173], v[202:205], v[34:37]
	v_mfma_f32_16x16x32_bf16 v[34:37], v[190:193], v[198:201], v[38:41]
	v_mfma_f32_16x16x32_bf16 v[66:69], v[194:197], v[202:205], v[34:37]
	v_mfma_f32_16x16x32_bf16 v[34:37], v[166:169], v[206:209], v[42:45]
	v_mfma_f32_16x16x32_bf16 v[54:57], v[170:173], v[210:213], v[34:37]
	v_mfma_f32_16x16x32_bf16 v[34:37], v[190:193], v[206:209], v[46:49]
	v_mfma_f32_16x16x32_bf16 v[22:25], v[166:169], v[214:217], v[22:25]
	v_mfma_f32_16x16x32_bf16 v[18:21], v[190:193], v[214:217], v[18:21]
	v_mfma_f32_16x16x32_bf16 v[6:9], v[166:169], v[222:225], v[6:9]
	v_mfma_f32_16x16x32_bf16 v[2:5], v[190:193], v[222:225], v[2:5]
	v_mfma_f32_16x16x32_bf16 v[50:53], v[194:197], v[210:213], v[34:37]
	v_mfma_f32_16x16x32_bf16 v[22:25], v[170:173], v[218:221], v[22:25]
	v_mfma_f32_16x16x32_bf16 v[18:21], v[194:197], v[218:221], v[18:21]
	v_mfma_f32_16x16x32_bf16 v[6:9], v[170:173], v[226:229], v[6:9]
	v_mfma_f32_16x16x32_bf16 v[2:5], v[194:197], v[226:229], v[2:5]
	s_setprio 0
	s_barrier
	s_add_i32 s12, s12, 2
	s_add_u32 s0, s0, 0x100
	s_addc_u32 s1, s1, 0
	s_add_u32 s63, s63, 0x100
	s_addc_u32 s77, s77, 0
	s_cmp_gt_u32 s12, 13
	s_cbranch_scc0 .LBB0_991
	s_and_b64 vcc, exec, s[74:75]
	s_cbranch_vccz .LBB0_994
	s_barrier

.LBB0_1393:
	s_ashr_i32 s25, s24, 31
	s_lshl_b64 s[12:13], s[24:25], 19
	v_cmp_lt_i64_e32 vcc, s[26:27], v[150:151]
	s_add_u32 s26, s19, s12
	s_addc_u32 s27, s33, s13
	s_and_b64 s[12:13], vcc, exec
	s_cselect_b32 s25, s27, s43
	s_cselect_b32 s37, s26, s42
	s_ashr_i32 s23, s22, 31
	s_lshl_b64 s[12:13], s[22:23], 19
	s_add_u32 s28, s44, s12
	s_addc_u32 s29, s45, s13
	s_and_b64 s[12:13], vcc, exec
	s_cselect_b32 s23, s29, s41
	s_cselect_b32 s67, s28, s40
	s_add_u32 s30, s42, 0x40080
	s_addc_u32 s31, s43, 0
	s_add_u32 s68, s40, 0x100
	v_mov_b32_e32 v2, 0
	s_addc_u32 s69, s41, 0
	s_mov_b32 s12, -2
	s_waitcnt lgkmcnt(0)
	v_mov_b32_e32 v3, v2
	v_mov_b32_e32 v4, v2
	v_mov_b32_e32 v5, v2
	v_mov_b32_e32 v6, v2
	v_mov_b32_e32 v7, v2
	v_mov_b32_e32 v8, v2
	v_mov_b32_e32 v9, v2
	v_mov_b32_e32 v10, v2
	v_mov_b32_e32 v11, v2
	v_mov_b32_e32 v12, v2
	v_mov_b32_e32 v13, v2
	v_mov_b32_e32 v14, v2
	v_mov_b32_e32 v15, v2
	v_mov_b32_e32 v16, v2
	v_mov_b32_e32 v17, v2
	v_mov_b32_e32 v18, v2
	v_mov_b32_e32 v19, v2
	v_mov_b32_e32 v20, v2
	v_mov_b32_e32 v21, v2
	v_mov_b32_e32 v22, v2
	v_mov_b32_e32 v23, v2
	v_mov_b32_e32 v24, v2
	v_mov_b32_e32 v25, v2
	v_mov_b32_e32 v26, v2
	v_mov_b32_e32 v27, v2
	v_mov_b32_e32 v28, v2
	v_mov_b32_e32 v29, v2
	v_mov_b32_e32 v30, v2
	v_mov_b32_e32 v31, v2
	v_mov_b32_e32 v32, v2
	v_mov_b32_e32 v33, v2
	v_mov_b32_e32 v66, v2
	v_mov_b32_e32 v67, v2
	v_mov_b32_e32 v68, v2
	v_mov_b32_e32 v69, v2
	v_mov_b32_e32 v70, v2
	v_mov_b32_e32 v71, v2
	v_mov_b32_e32 v72, v2
	v_mov_b32_e32 v73, v2
	v_mov_b32_e32 v74, v2
	v_mov_b32_e32 v75, v2
	v_mov_b32_e32 v76, v2
	v_mov_b32_e32 v77, v2
	v_mov_b32_e32 v78, v2
	v_mov_b32_e32 v79, v2
	v_mov_b32_e32 v80, v2
	v_mov_b32_e32 v81, v2
	v_mov_b32_e32 v82, v2
	v_mov_b32_e32 v83, v2
	v_mov_b32_e32 v84, v2
	v_mov_b32_e32 v85, v2
	v_mov_b32_e32 v86, v2
	v_mov_b32_e32 v87, v2
	v_mov_b32_e32 v88, v2
	v_mov_b32_e32 v89, v2
	v_mov_b32_e32 v90, v2
	v_mov_b32_e32 v91, v2
	v_mov_b32_e32 v92, v2
	v_mov_b32_e32 v93, v2
	v_mov_b32_e32 v94, v2
	v_mov_b32_e32 v95, v2
	v_mov_b32_e32 v96, v2
	v_mov_b32_e32 v97, v2
	v_mov_b32_e32 v34, v2
	v_mov_b32_e32 v35, v2
	v_mov_b32_e32 v36, v2
	v_mov_b32_e32 v37, v2
	v_mov_b32_e32 v38, v2
	v_mov_b32_e32 v39, v2
	v_mov_b32_e32 v40, v2
	v_mov_b32_e32 v41, v2
	v_mov_b32_e32 v42, v2
	v_mov_b32_e32 v43, v2
	v_mov_b32_e32 v44, v2
	v_mov_b32_e32 v45, v2
	v_mov_b32_e32 v46, v2
	v_mov_b32_e32 v47, v2
	v_mov_b32_e32 v48, v2
	v_mov_b32_e32 v49, v2
	v_mov_b32_e32 v50, v2
	v_mov_b32_e32 v51, v2
	v_mov_b32_e32 v52, v2
	v_mov_b32_e32 v53, v2
	v_mov_b32_e32 v54, v2
	v_mov_b32_e32 v55, v2
	v_mov_b32_e32 v56, v2
	v_mov_b32_e32 v57, v2
	v_mov_b32_e32 v58, v2
	v_mov_b32_e32 v59, v2
	v_mov_b32_e32 v60, v2
	v_mov_b32_e32 v61, v2
	v_mov_b32_e32 v62, v2
	v_mov_b32_e32 v63, v2
	v_mov_b32_e32 v64, v2
	v_mov_b32_e32 v65, v2
	v_mov_b32_e32 v98, v2
	v_mov_b32_e32 v99, v2
	v_mov_b32_e32 v100, v2
	v_mov_b32_e32 v101, v2
	v_mov_b32_e32 v102, v2
	v_mov_b32_e32 v103, v2
	v_mov_b32_e32 v104, v2
	v_mov_b32_e32 v105, v2
	v_mov_b32_e32 v106, v2
	v_mov_b32_e32 v107, v2
	v_mov_b32_e32 v108, v2
	v_mov_b32_e32 v109, v2
	v_mov_b32_e32 v110, v2
	v_mov_b32_e32 v111, v2
	v_mov_b32_e32 v112, v2
	v_mov_b32_e32 v113, v2
	v_mov_b32_e32 v114, v2
	v_mov_b32_e32 v115, v2
	v_mov_b32_e32 v116, v2
	v_mov_b32_e32 v117, v2
	v_mov_b32_e32 v118, v2
	v_mov_b32_e32 v119, v2
	v_mov_b32_e32 v120, v2
	v_mov_b32_e32 v121, v2
	v_mov_b32_e32 v122, v2
	v_mov_b32_e32 v123, v2
	v_mov_b32_e32 v124, v2
	v_mov_b32_e32 v125, v2
	v_mov_b32_e32 v126, v2
	v_mov_b32_e32 v127, v2
	v_mov_b32_e32 v128, v2
	v_mov_b32_e32 v129, v2
	v_add_u32_e32 v251, 0x80, v140
.LBB0_1394:
	ds_read_b128 v[130:133], v228
	ds_read_b128 v[134:137], v228 offset:1024
	ds_read_b128 v[154:157], v228 offset:2048
	ds_read_b128 v[158:161], v228 offset:3072
	ds_read_b128 v[162:165], v229
	ds_read_b128 v[166:169], v229 offset:1024
	ds_read_b128 v[170:173], v229 offset:2048
	ds_read_b128 v[174:177], v229 offset:3072
	s_add_u32 s13, s30, 0xfffc0080
	s_addc_u32 s40, s31, -1
	s_cmp_eq_u32 s12, 12
	s_cselect_b32 s43, s25, s40
	s_cselect_b32 s42, s37, s13
	s_cselect_b32 s41, s23, s69
	s_cselect_b32 s40, s67, s68
	s_nop 0
	s_add_i32 m0, s39, 0xc000
	ds_read_b128 v[178:181], v230
	ds_read_b128 v[182:185], v230 offset:1024
	ds_read_b128 v[186:189], v230 offset:2048
	ds_read_b128 v[190:193], v230 offset:3072
	ds_read_b128 v[194:197], v230 offset:4096
	ds_read_b128 v[198:201], v230 offset:5120
	ds_read_b128 v[202:205], v230 offset:6144
	ds_read_b128 v[206:209], v230 offset:7168
	global_load_lds_dwordx4 v146, s[30:31]
	s_nop 0
	s_add_i32 m0, s39, 0xe000
	s_nop 0
	global_load_lds_dwordx4 v148, s[30:31]
	s_waitcnt vmcnt(8)
	s_waitcnt lgkmcnt(0)
	s_barrier
	s_setprio 1
	s_waitcnt lgkmcnt(0)
	v_mfma_f32_16x16x32_bf16 v[126:129], v[130:133], v[178:181], v[126:129]
	v_mfma_f32_16x16x32_bf16 v[122:125], v[154:157], v[178:181], v[122:125]
	v_mfma_f32_16x16x32_bf16 v[118:121], v[130:133], v[186:189], v[118:121]
	v_mfma_f32_16x16x32_bf16 v[114:117], v[154:157], v[186:189], v[114:117]
	v_mfma_f32_16x16x32_bf16 v[110:113], v[130:133], v[194:197], v[110:113]
	v_mfma_f32_16x16x32_bf16 v[106:109], v[154:157], v[194:197], v[106:109]
	v_mfma_f32_16x16x32_bf16 v[102:105], v[130:133], v[202:205], v[102:105]
	v_mfma_f32_16x16x32_bf16 v[98:101], v[154:157], v[202:205], v[98:101]
	v_mfma_f32_16x16x32_bf16 v[126:129], v[134:137], v[182:185], v[126:129]
	v_mfma_f32_16x16x32_bf16 v[122:125], v[158:161], v[182:185], v[122:125]
	v_mfma_f32_16x16x32_bf16 v[118:121], v[134:137], v[190:193], v[118:121]
	v_mfma_f32_16x16x32_bf16 v[114:117], v[158:161], v[190:193], v[114:117]
	v_mfma_f32_16x16x32_bf16 v[110:113], v[134:137], v[198:201], v[110:113]
	v_mfma_f32_16x16x32_bf16 v[106:109], v[158:161], v[198:201], v[106:109]
	v_mfma_f32_16x16x32_bf16 v[102:105], v[134:137], v[206:209], v[102:105]
	v_mfma_f32_16x16x32_bf16 v[98:101], v[158:161], v[206:209], v[98:101]
	s_setprio 0
	s_setprio 1
	v_mfma_f32_16x16x32_bf16 v[62:65], v[162:165], v[178:181], v[62:65]
	v_mfma_f32_16x16x32_bf16 v[58:61], v[170:173], v[178:181], v[58:61]
	v_mfma_f32_16x16x32_bf16 v[54:57], v[162:165], v[186:189], v[54:57]
	v_mfma_f32_16x16x32_bf16 v[50:53], v[170:173], v[186:189], v[50:53]
	v_mfma_f32_16x16x32_bf16 v[46:49], v[162:165], v[194:197], v[46:49]
	v_mfma_f32_16x16x32_bf16 v[42:45], v[170:173], v[194:197], v[42:45]
	v_mfma_f32_16x16x32_bf16 v[38:41], v[162:165], v[202:205], v[38:41]
	v_mfma_f32_16x16x32_bf16 v[34:37], v[170:173], v[202:205], v[34:37]
	v_mfma_f32_16x16x32_bf16 v[62:65], v[166:169], v[182:185], v[62:65]
	v_mfma_f32_16x16x32_bf16 v[58:61], v[174:177], v[182:185], v[58:61]
	v_mfma_f32_16x16x32_bf16 v[54:57], v[166:169], v[190:193], v[54:57]
	v_mfma_f32_16x16x32_bf16 v[50:53], v[174:177], v[190:193], v[50:53]
	v_mfma_f32_16x16x32_bf16 v[46:49], v[166:169], v[198:201], v[46:49]
	v_mfma_f32_16x16x32_bf16 v[42:45], v[174:177], v[198:201], v[42:45]
	v_mfma_f32_16x16x32_bf16 v[38:41], v[166:169], v[206:209], v[38:41]
	v_mfma_f32_16x16x32_bf16 v[34:37], v[174:177], v[206:209], v[34:37]
	s_setprio 0
	s_barrier
	s_add_i32 s13, s63, s46
	s_nop 0
	s_mov_b32 m0, s13
	ds_read_b128 v[178:181], v230 offset:16384
	ds_read_b128 v[182:185], v230 offset:17408
	ds_read_b128 v[186:189], v230 offset:18432
	ds_read_b128 v[190:193], v230 offset:19456
	ds_read_b128 v[194:197], v230 offset:20480
	ds_read_b128 v[198:201], v230 offset:21504
	ds_read_b128 v[202:205], v230 offset:22528
	ds_read_b128 v[206:209], v230 offset:23552
	global_load_lds_dwordx4 v140, s[40:41]
	s_add_i32 m0, s13, 0x2000
	s_add_u32 s70, s40, 0x40000
	v_lshl_add_u64 v[212:213], s[40:41], 0, v[144:145]
	s_addc_u32 s71, s41, 0
	s_add_i32 s13, s66, s46
	global_load_lds_dwordx4 v144, s[40:41]
	s_nop 0
	s_mov_b32 m0, s13
	v_lshl_add_u64 v[216:217], s[42:43], 0, v[142:143]
	global_load_lds_dwordx4 v140, s[70:71]
	s_nop 0
	s_add_i32 m0, s13, 0x2000
	s_nop 0
	global_load_lds_dwordx4 v144, s[70:71]
	v_lshl_add_u64 v[214:215], s[42:43], 0, v[138:139]
	s_mov_b32 m0, s39
	s_nop 0
	global_load_lds_dwordx4 v138, s[42:43]
	s_mov_b32 m0, s47
	s_nop 0
	global_load_lds_dwordx4 v142, s[42:43]
	s_waitcnt vmcnt(8)
	s_waitcnt lgkmcnt(0)
	s_barrier
	s_setprio 1
	s_waitcnt lgkmcnt(0)
	v_mfma_f32_16x16x32_bf16 v[94:97], v[130:133], v[178:181], v[94:97]
	v_mfma_f32_16x16x32_bf16 v[90:93], v[154:157], v[178:181], v[90:93]
	v_mfma_f32_16x16x32_bf16 v[86:89], v[130:133], v[186:189], v[86:89]
	v_mfma_f32_16x16x32_bf16 v[82:85], v[154:157], v[186:189], v[82:85]
	v_mfma_f32_16x16x32_bf16 v[78:81], v[130:133], v[194:197], v[78:81]
	v_mfma_f32_16x16x32_bf16 v[74:77], v[154:157], v[194:197], v[74:77]
	v_mfma_f32_16x16x32_bf16 v[70:73], v[130:133], v[202:205], v[70:73]
	v_mfma_f32_16x16x32_bf16 v[66:69], v[154:157], v[202:205], v[66:69]
	v_mfma_f32_16x16x32_bf16 v[94:97], v[134:137], v[182:185], v[94:97]
	v_mfma_f32_16x16x32_bf16 v[90:93], v[158:161], v[182:185], v[90:93]
	v_mfma_f32_16x16x32_bf16 v[86:89], v[134:137], v[190:193], v[86:89]
	v_mfma_f32_16x16x32_bf16 v[82:85], v[158:161], v[190:193], v[82:85]
	v_mfma_f32_16x16x32_bf16 v[78:81], v[134:137], v[198:201], v[78:81]
	v_mfma_f32_16x16x32_bf16 v[74:77], v[158:161], v[198:201], v[74:77]
	v_mfma_f32_16x16x32_bf16 v[70:73], v[134:137], v[206:209], v[70:73]
	v_mfma_f32_16x16x32_bf16 v[66:69], v[158:161], v[206:209], v[66:69]
	s_setprio 0
	s_setprio 1
	v_mfma_f32_16x16x32_bf16 v[30:33], v[162:165], v[178:181], v[30:33]
	v_mfma_f32_16x16x32_bf16 v[26:29], v[170:173], v[178:181], v[26:29]
	v_mfma_f32_16x16x32_bf16 v[22:25], v[162:165], v[186:189], v[22:25]
	v_mfma_f32_16x16x32_bf16 v[18:21], v[170:173], v[186:189], v[18:21]
	v_mfma_f32_16x16x32_bf16 v[14:17], v[162:165], v[194:197], v[14:17]
	v_mfma_f32_16x16x32_bf16 v[10:13], v[170:173], v[194:197], v[10:13]
	v_mfma_f32_16x16x32_bf16 v[6:9], v[162:165], v[202:205], v[6:9]
	v_mfma_f32_16x16x32_bf16 v[2:5], v[170:173], v[202:205], v[2:5]
	v_mfma_f32_16x16x32_bf16 v[30:33], v[166:169], v[182:185], v[30:33]
	v_mfma_f32_16x16x32_bf16 v[26:29], v[174:177], v[182:185], v[26:29]
	v_mfma_f32_16x16x32_bf16 v[22:25], v[166:169], v[190:193], v[22:25]
	v_mfma_f32_16x16x32_bf16 v[18:21], v[174:177], v[190:193], v[18:21]
	v_mfma_f32_16x16x32_bf16 v[14:17], v[166:169], v[198:201], v[14:17]
	v_mfma_f32_16x16x32_bf16 v[10:13], v[174:177], v[198:201], v[10:13]
	v_mfma_f32_16x16x32_bf16 v[6:9], v[166:169], v[206:209], v[6:9]
	v_mfma_f32_16x16x32_bf16 v[2:5], v[174:177], v[206:209], v[2:5]
	s_setprio 0
	s_barrier
	s_add_i32 s13, 0, 0x18000
	s_add_i32 s70, 0, 0x1c000
	v_add_u32_e32 v158, s13, v226
	v_add_u32_e32 v174, s70, v226
	ds_read_b128 v[130:133], v158
	ds_read_b128 v[134:137], v158 offset:1024
	ds_read_b128 v[154:157], v158 offset:2048
	ds_read_b128 v[158:161], v158 offset:3072
	ds_read_b128 v[162:165], v174
	ds_read_b128 v[166:169], v174 offset:1024
	ds_read_b128 v[170:173], v174 offset:2048
	ds_read_b128 v[174:177], v174 offset:3072
	s_add_u32 s42, s42, 0x40000
	s_addc_u32 s43, s43, 0
	s_mov_b32 m0, s48
	s_nop 0
	ds_read_b128 v[178:181], v230 offset:32768
	ds_read_b128 v[182:185], v230 offset:33792
	ds_read_b128 v[186:189], v230 offset:34816
	ds_read_b128 v[190:193], v230 offset:35840
	ds_read_b128 v[194:197], v230 offset:36864
	ds_read_b128 v[198:201], v230 offset:37888
	ds_read_b128 v[202:205], v230 offset:38912
	ds_read_b128 v[206:209], v230 offset:39936
	global_load_lds_dwordx4 v138, s[42:43]
	s_nop 0
	s_mov_b32 m0, s49
	s_nop 0
	global_load_lds_dwordx4 v142, s[42:43]
	s_waitcnt vmcnt(8)
	s_waitcnt lgkmcnt(0)
	s_barrier
	s_setprio 1
	s_waitcnt lgkmcnt(0)
	v_mfma_f32_16x16x32_bf16 v[126:129], v[130:133], v[178:181], v[126:129]
	v_mfma_f32_16x16x32_bf16 v[122:125], v[154:157], v[178:181], v[122:125]
	v_mfma_f32_16x16x32_bf16 v[118:121], v[130:133], v[186:189], v[118:121]
	v_mfma_f32_16x16x32_bf16 v[114:117], v[154:157], v[186:189], v[114:117]
	v_mfma_f32_16x16x32_bf16 v[110:113], v[130:133], v[194:197], v[110:113]
	v_mfma_f32_16x16x32_bf16 v[106:109], v[154:157], v[194:197], v[106:109]
	v_mfma_f32_16x16x32_bf16 v[102:105], v[130:133], v[202:205], v[102:105]
	v_mfma_f32_16x16x32_bf16 v[98:101], v[154:157], v[202:205], v[98:101]
	v_mfma_f32_16x16x32_bf16 v[126:129], v[134:137], v[182:185], v[126:129]
	v_mfma_f32_16x16x32_bf16 v[122:125], v[158:161], v[182:185], v[122:125]
	v_mfma_f32_16x16x32_bf16 v[118:121], v[134:137], v[190:193], v[118:121]
	v_mfma_f32_16x16x32_bf16 v[114:117], v[158:161], v[190:193], v[114:117]
	v_mfma_f32_16x16x32_bf16 v[110:113], v[134:137], v[198:201], v[110:113]
	v_mfma_f32_16x16x32_bf16 v[106:109], v[158:161], v[198:201], v[106:109]
	v_mfma_f32_16x16x32_bf16 v[102:105], v[134:137], v[206:209], v[102:105]
	v_mfma_f32_16x16x32_bf16 v[98:101], v[158:161], v[206:209], v[98:101]
	s_setprio 0
	s_setprio 1
	v_mfma_f32_16x16x32_bf16 v[62:65], v[162:165], v[178:181], v[62:65]
	v_mfma_f32_16x16x32_bf16 v[58:61], v[170:173], v[178:181], v[58:61]
	v_mfma_f32_16x16x32_bf16 v[54:57], v[162:165], v[186:189], v[54:57]
	v_mfma_f32_16x16x32_bf16 v[50:53], v[170:173], v[186:189], v[50:53]
	v_mfma_f32_16x16x32_bf16 v[46:49], v[162:165], v[194:197], v[46:49]
	v_mfma_f32_16x16x32_bf16 v[42:45], v[170:173], v[194:197], v[42:45]
	v_mfma_f32_16x16x32_bf16 v[38:41], v[162:165], v[202:205], v[38:41]
	v_mfma_f32_16x16x32_bf16 v[34:37], v[170:173], v[202:205], v[34:37]
	v_mfma_f32_16x16x32_bf16 v[62:65], v[166:169], v[182:185], v[62:65]
	v_mfma_f32_16x16x32_bf16 v[58:61], v[174:177], v[182:185], v[58:61]
	v_mfma_f32_16x16x32_bf16 v[54:57], v[166:169], v[190:193], v[54:57]
	v_mfma_f32_16x16x32_bf16 v[50:53], v[174:177], v[190:193], v[50:53]
	v_mfma_f32_16x16x32_bf16 v[46:49], v[166:169], v[198:201], v[46:49]
	v_mfma_f32_16x16x32_bf16 v[42:45], v[174:177], v[198:201], v[42:45]
	v_mfma_f32_16x16x32_bf16 v[38:41], v[166:169], v[206:209], v[38:41]
	v_mfma_f32_16x16x32_bf16 v[34:37], v[174:177], v[206:209], v[34:37]
	s_setprio 0
	s_barrier
	s_add_i32 s13, s13, s46
	s_nop 0
	s_mov_b32 m0, s13
	ds_read_b128 v[178:181], v230 offset:49152
	ds_read_b128 v[182:185], v230 offset:50176
	ds_read_b128 v[186:189], v230 offset:51200
	ds_read_b128 v[190:193], v230 offset:52224
	ds_read_b128 v[194:197], v230 offset:53248
	ds_read_b128 v[198:201], v230 offset:54272
	ds_read_b128 v[202:205], v230 offset:55296
	ds_read_b128 v[206:209], v230 offset:56320
	global_load_lds_dwordx4 v251, s[40:41]
	s_add_i32 m0, s13, 0x2000
	s_add_u32 s40, s40, 0x40080
	v_lshl_add_u64 v[210:211], v[212:213], 0, s[20:21]
	s_addc_u32 s41, s41, 0
	s_add_i32 s13, s70, s46
	global_load_lds_dwordx4 v[210:211], off
	s_nop 0
	s_mov_b32 m0, s13
	s_nop 0
	global_load_lds_dwordx4 v140, s[40:41]
	s_nop 0
	s_add_i32 m0, s13, 0x2000
	s_nop 0
	global_load_lds_dwordx4 v144, s[40:41]
	v_lshl_add_u64 v[210:211], v[214:215], 0, s[20:21]
	s_mov_b32 m0, s60
	s_nop 0
	global_load_lds_dwordx4 v[210:211], off
	v_lshl_add_u64 v[210:211], v[216:217], 0, s[20:21]
	s_mov_b32 m0, s61
	s_nop 0
	global_load_lds_dwordx4 v[210:211], off
	s_waitcnt vmcnt(8)
	s_waitcnt lgkmcnt(0)
	s_barrier
	s_setprio 1
	s_waitcnt lgkmcnt(0)
	v_mfma_f32_16x16x32_bf16 v[94:97], v[130:133], v[178:181], v[94:97]
	v_mfma_f32_16x16x32_bf16 v[90:93], v[154:157], v[178:181], v[90:93]
	v_mfma_f32_16x16x32_bf16 v[86:89], v[130:133], v[186:189], v[86:89]
	v_mfma_f32_16x16x32_bf16 v[82:85], v[154:157], v[186:189], v[82:85]
	v_mfma_f32_16x16x32_bf16 v[78:81], v[130:133], v[194:197], v[78:81]
	v_mfma_f32_16x16x32_bf16 v[74:77], v[154:157], v[194:197], v[74:77]
	v_mfma_f32_16x16x32_bf16 v[70:73], v[130:133], v[202:205], v[70:73]
	v_mfma_f32_16x16x32_bf16 v[66:69], v[154:157], v[202:205], v[66:69]
	v_mfma_f32_16x16x32_bf16 v[94:97], v[134:137], v[182:185], v[94:97]
	v_mfma_f32_16x16x32_bf16 v[90:93], v[158:161], v[182:185], v[90:93]
	v_mfma_f32_16x16x32_bf16 v[86:89], v[134:137], v[190:193], v[86:89]
	v_mfma_f32_16x16x32_bf16 v[82:85], v[158:161], v[190:193], v[82:85]
	v_mfma_f32_16x16x32_bf16 v[78:81], v[134:137], v[198:201], v[78:81]
	v_mfma_f32_16x16x32_bf16 v[74:77], v[158:161], v[198:201], v[74:77]
	v_mfma_f32_16x16x32_bf16 v[70:73], v[134:137], v[206:209], v[70:73]
	v_mfma_f32_16x16x32_bf16 v[66:69], v[158:161], v[206:209], v[66:69]
	s_setprio 0
	s_setprio 1
	v_mfma_f32_16x16x32_bf16 v[30:33], v[162:165], v[178:181], v[30:33]
	v_mfma_f32_16x16x32_bf16 v[26:29], v[170:173], v[178:181], v[26:29]
	v_mfma_f32_16x16x32_bf16 v[22:25], v[162:165], v[186:189], v[22:25]
	v_mfma_f32_16x16x32_bf16 v[18:21], v[170:173], v[186:189], v[18:21]
	v_mfma_f32_16x16x32_bf16 v[14:17], v[162:165], v[194:197], v[14:17]
	v_mfma_f32_16x16x32_bf16 v[10:13], v[170:173], v[194:197], v[10:13]
	v_mfma_f32_16x16x32_bf16 v[6:9], v[162:165], v[202:205], v[6:9]
	v_mfma_f32_16x16x32_bf16 v[2:5], v[170:173], v[202:205], v[2:5]
	v_mfma_f32_16x16x32_bf16 v[30:33], v[166:169], v[182:185], v[30:33]
	v_mfma_f32_16x16x32_bf16 v[26:29], v[174:177], v[182:185], v[26:29]
	v_mfma_f32_16x16x32_bf16 v[22:25], v[166:169], v[190:193], v[22:25]
	v_mfma_f32_16x16x32_bf16 v[18:21], v[174:177], v[190:193], v[18:21]
	v_mfma_f32_16x16x32_bf16 v[14:17], v[166:169], v[198:201], v[14:17]
	v_mfma_f32_16x16x32_bf16 v[10:13], v[174:177], v[198:201], v[10:13]
	v_mfma_f32_16x16x32_bf16 v[6:9], v[166:169], v[206:209], v[6:9]
	v_mfma_f32_16x16x32_bf16 v[2:5], v[174:177], v[206:209], v[2:5]
	s_setprio 0
	s_barrier
	s_add_i32 s12, s12, 2
	s_add_u32 s30, s30, 0x100
	s_addc_u32 s31, s31, 0
	s_add_u32 s68, s68, 0x100
	s_addc_u32 s69, s69, 0
	s_cmp_gt_u32 s12, 13
	s_cbranch_scc0 .LBB0_1394
	s_ashr_i32 s12, s36, 3
	s_ashr_i32 s37, s36, 31
	s_mul_i32 s25, s12, 0x6000
	s_mul_hi_i32 s23, s12, 0x6000
	s_add_u32 s12, s57, s25
	v_mov_b32_e32 v130, v1
	s_addc_u32 s13, s58, s23
	s_lshl_b64 s[30:31], s[36:37], 19
	v_lshl_or_b32 v166, s38, 8, v227
	s_add_u32 s40, s51, s30
	v_add_u32_e32 v160, s59, v130
	v_ashrrev_i32_e32 v167, 31, v166
	s_addc_u32 s41, s52, s31
	v_lshlrev_b64 v[156:157], 1, v[166:167]
	v_ashrrev_i32_e32 v161, 31, v160
	v_lshlrev_b64 v[130:131], 2, v[166:167]
	v_lshl_add_u64 v[162:163], s[40:41], 0, v[156:157]
	v_lshlrev_b64 v[154:155], 11, v[160:161]
	v_add_u32_e32 v170, 16, v160
	v_lshl_add_u64 v[172:173], s[12:13], 0, v[130:131]
	v_lshl_add_u64 v[174:175], v[162:163], 0, v[154:155]
	v_ashrrev_i32_e32 v171, 31, v170
	s_add_u32 s12, s53, s30
	v_lshl_add_u64 v[132:133], s[0:1], 0, v[130:131]
	global_load_dwordx4 v[180:183], v[172:173], off offset:16
	global_load_dwordx4 v[184:187], v[172:173], off
	global_load_dwordx4 v[188:191], v[132:133], off offset:16
	global_load_dwordx4 v[192:195], v[132:133], off
	global_load_dwordx4 v[196:199], v[174:175], off nt
	v_lshlrev_b64 v[204:205], 11, v[170:171]
	s_addc_u32 s13, s54, s31
	v_lshl_add_u64 v[178:179], v[162:163], 0, v[204:205]
	s_add_u32 s30, s55, s25
	global_load_dwordx4 v[200:203], v[178:179], off nt
	s_addc_u32 s31, s56, s23
	v_lshl_add_u64 v[176:177], s[30:31], 0, v[130:131]
	global_load_dwordx4 v[134:137], v[176:177], off
	global_load_dwordx4 v[130:133], v[176:177], off offset:16
	v_lshl_add_u64 v[158:159], s[12:13], 0, v[156:157]
	s_lshl_b32 s12, s36, 8
	v_lshl_add_u64 v[164:165], v[158:159], 0, v[154:155]
	v_add_u32_e32 v154, s12, v160
	v_ashrrev_i32_e32 v155, 31, v154
	v_lshlrev_b64 v[168:169], 11, v[154:155]
	v_lshl_add_u64 v[168:169], s[8:9], 0, v[168:169]
	v_add_u32_e32 v170, s12, v170
	v_lshl_add_u64 v[168:169], v[168:169], 0, v[156:157]
	v_ashrrev_i32_e32 v171, 31, v170
	v_lshlrev_b64 v[170:171], 11, v[170:171]
	v_lshl_add_u64 v[170:171], s[8:9], 0, v[170:171]
	s_waitcnt vmcnt(0)
	v_pk_add_f32 v[182:183], v[182:183], 1.0 op_sel_hi:[1,0]
	v_pk_add_f32 v[186:187], v[186:187], 1.0 op_sel_hi:[1,0]
	v_pk_add_f32 v[184:185], v[184:185], 1.0 op_sel_hi:[1,0]
	v_pk_add_f32 v[180:181], v[180:181], 1.0 op_sel_hi:[1,0]
	v_pk_mul_f32 v[216:217], v[194:195], v[186:187]
	v_pk_mul_f32 v[218:219], v[192:193], v[184:185]
	v_pk_mul_f32 v[220:221], v[190:191], v[182:183]
	v_pk_mul_f32 v[222:223], v[188:189], v[180:181]
	v_cvt_f32_f16_e32 v180, v198
	v_cvt_f32_f16_sdwa v181, v198 dst_sel:DWORD dst_unused:UNUSED_PAD src0_sel:WORD_1
	v_cvt_f32_f16_e32 v182, v199
	v_cvt_f32_f16_sdwa v183, v199 dst_sel:DWORD dst_unused:UNUSED_PAD src0_sel:WORD_1
	v_cvt_f32_f16_e32 v184, v196
	v_cvt_f32_f16_sdwa v185, v196 dst_sel:DWORD dst_unused:UNUSED_PAD src0_sel:WORD_1
	v_cvt_f32_f16_e32 v186, v197
	v_cvt_f32_f16_sdwa v187, v197 dst_sel:DWORD dst_unused:UNUSED_PAD src0_sel:WORD_1
	v_cvt_f32_f16_e32 v188, v202
	v_cvt_f32_f16_sdwa v189, v202 dst_sel:DWORD dst_unused:UNUSED_PAD src0_sel:WORD_1
	v_cvt_f32_f16_e32 v190, v203
	v_cvt_f32_f16_sdwa v191, v203 dst_sel:DWORD dst_unused:UNUSED_PAD src0_sel:WORD_1
	v_cvt_f32_f16_e32 v192, v200
	v_cvt_f32_f16_sdwa v193, v200 dst_sel:DWORD dst_unused:UNUSED_PAD src0_sel:WORD_1
	v_cvt_f32_f16_e32 v194, v201
	v_cvt_f32_f16_sdwa v195, v201 dst_sel:DWORD dst_unused:UNUSED_PAD src0_sel:WORD_1
	v_pk_fma_f32 v[128:129], v[128:129], v[136:137], v[186:187]
	v_pk_fma_f32 v[126:127], v[126:127], v[134:135], v[184:185]
	v_pk_fma_f32 v[124:125], v[124:125], v[132:133], v[182:183]
	v_pk_fma_f32 v[122:123], v[122:123], v[130:131], v[180:181]
	v_cvt_pk_f16_f32 v183, v124, v125
	v_cvt_pk_f16_f32 v181, v128, v129
	v_cvt_pk_f16_f32 v182, v122, v123
	v_cvt_pk_f16_f32 v180, v126, v127
	v_pk_fma_f32 v[120:121], v[120:121], v[136:137], v[194:195]
	v_pk_fma_f32 v[118:119], v[118:119], v[134:135], v[192:193]
	v_pk_fma_f32 v[116:117], v[116:117], v[132:133], v[190:191]
	v_pk_fma_f32 v[114:115], v[114:115], v[130:131], v[188:189]
	v_pk_mul_f32 v[188:189], v[216:217], v[128:129]
	v_pk_mul_f32 v[190:191], v[218:219], v[126:127]
	global_store_dwordx4 v[164:165], v[180:183], off
	v_pk_mul_f32 v[192:193], v[220:221], v[124:125]
	v_pk_mul_f32 v[194:195], v[222:223], v[122:123]
	v_cvt_pk_bf16_f32 v180, v190, v191
	v_cvt_pk_bf16_f32 v181, v188, v189
	v_cvt_pk_f16_f32 v187, v116, v117
	v_cvt_pk_f16_f32 v185, v120, v121
	v_cvt_pk_f16_f32 v186, v114, v115
	v_cvt_pk_bf16_f32 v182, v194, v195
	v_cvt_pk_bf16_f32 v183, v192, v193
	global_store_dwordx4 v[168:169], v[180:183], off
	v_cvt_pk_f16_f32 v184, v118, v119
	v_pk_mul_f32 v[188:189], v[222:223], v[114:115]
	v_lshl_add_u64 v[180:181], v[158:159], 0, v[204:205]
	global_store_dwordx4 v[180:181], v[184:187], off
	v_pk_mul_f32 v[182:183], v[218:219], v[118:119]
	v_add_u32_e32 v192, 48, v160
	v_pk_mul_f32 v[184:185], v[216:217], v[120:121]
	v_pk_mul_f32 v[186:187], v[220:221], v[116:117]
	v_cvt_pk_bf16_f32 v182, v182, v183
	v_cvt_pk_bf16_f32 v183, v184, v185
	v_cvt_pk_bf16_f32 v184, v188, v189
	v_ashrrev_i32_e32 v193, 31, v192
	v_cvt_pk_bf16_f32 v185, v186, v187
	v_lshl_add_u64 v[186:187], v[170:171], 0, v[156:157]
	global_store_dwordx4 v[186:187], v[182:185], off
	v_mul_f32_e32 v127, v127, v127
	v_mul_f32_e32 v129, v129, v129
	v_add_u32_e32 v182, 32, v160
	v_ashrrev_i32_e32 v183, 31, v182
	v_lshlrev_b64 v[170:171], 11, v[182:183]
	v_lshl_add_u64 v[188:189], v[162:163], 0, v[170:171]
	global_load_dwordx4 v[194:197], v[188:189], off nt
	v_lshlrev_b64 v[184:185], 11, v[192:193]
	v_lshl_add_u64 v[190:191], v[162:163], 0, v[184:185]
	global_load_dwordx4 v[198:201], v[190:191], off nt
	v_add_u32_e32 v182, s12, v182
	v_add_u32_e32 v192, s12, v192
	v_ashrrev_i32_e32 v183, 31, v182
	v_ashrrev_i32_e32 v193, 31, v192
	v_lshlrev_b64 v[182:183], 11, v[182:183]
	v_lshlrev_b64 v[192:193], 11, v[192:193]
	v_lshl_add_u64 v[182:183], s[8:9], 0, v[182:183]
	v_lshl_add_u64 v[202:203], s[8:9], 0, v[192:193]
	v_lshl_add_u64 v[192:193], v[182:183], 0, v[156:157]
	v_lshl_add_u64 v[170:171], v[158:159], 0, v[170:171]
	v_lshl_add_u64 v[184:185], v[158:159], 0, v[184:185]
	v_mul_f32_e32 v123, v123, v123
	v_mul_f32_e32 v125, v125, v125
	v_fmac_f32_e32 v127, v126, v126
	v_fmac_f32_e32 v129, v128, v128
	v_fmac_f32_e32 v123, v122, v122
	v_fmac_f32_e32 v125, v124, v124
	v_add_f32_e32 v122, v127, v129
	v_add_f32_e32 v123, v123, v125
	v_add_f32_e32 v122, v122, v123
	s_waitcnt vmcnt(1)
	v_cvt_f32_f16_e32 v182, v196
	v_cvt_f32_f16_sdwa v183, v196 dst_sel:DWORD dst_unused:UNUSED_PAD src0_sel:WORD_1
	v_cvt_f32_f16_e32 v196, v197
	v_cvt_f32_f16_sdwa v197, v197 dst_sel:DWORD dst_unused:UNUSED_PAD src0_sel:WORD_1
	v_cvt_f32_f16_e32 v204, v194
	v_cvt_f32_f16_sdwa v205, v194 dst_sel:DWORD dst_unused:UNUSED_PAD src0_sel:WORD_1
	v_cvt_f32_f16_e32 v194, v195
	v_cvt_f32_f16_sdwa v195, v195 dst_sel:DWORD dst_unused:UNUSED_PAD src0_sel:WORD_1
	s_waitcnt vmcnt(0)
	v_cvt_f32_f16_e32 v206, v200
	v_cvt_f32_f16_sdwa v207, v200 dst_sel:DWORD dst_unused:UNUSED_PAD src0_sel:WORD_1
	v_cvt_f32_f16_e32 v208, v198
	v_cvt_f32_f16_sdwa v209, v198 dst_sel:DWORD dst_unused:UNUSED_PAD src0_sel:WORD_1
	v_cvt_f32_f16_e32 v198, v199
	v_cvt_f32_f16_sdwa v199, v199 dst_sel:DWORD dst_unused:UNUSED_PAD src0_sel:WORD_1
	v_cvt_f32_f16_e32 v200, v201
	v_cvt_f32_f16_sdwa v201, v201 dst_sel:DWORD dst_unused:UNUSED_PAD src0_sel:WORD_1
	v_pk_fma_f32 v[112:113], v[112:113], v[136:137], v[194:195]
	v_pk_fma_f32 v[110:111], v[110:111], v[134:135], v[204:205]
	v_pk_fma_f32 v[108:109], v[108:109], v[132:133], v[196:197]
	v_pk_fma_f32 v[106:107], v[106:107], v[130:131], v[182:183]
	v_cvt_pk_f16_f32 v197, v108, v109
	v_cvt_pk_f16_f32 v195, v112, v113
	v_cvt_pk_f16_f32 v196, v106, v107
	v_cvt_pk_f16_f32 v194, v110, v111
	v_pk_mul_f32 v[182:183], v[216:217], v[112:113]
	v_pk_fma_f32 v[104:105], v[104:105], v[136:137], v[198:199]
	v_pk_fma_f32 v[102:103], v[102:103], v[134:135], v[208:209]
	v_pk_fma_f32 v[98:99], v[98:99], v[130:131], v[206:207]
	v_pk_mul_f32 v[204:205], v[218:219], v[110:111]
	v_pk_mul_f32 v[206:207], v[220:221], v[108:109]
	global_store_dwordx4 v[170:171], v[194:197], off
	v_pk_fma_f32 v[100:101], v[100:101], v[132:133], v[200:201]
	v_pk_mul_f32 v[208:209], v[222:223], v[106:107]
	v_cvt_pk_bf16_f32 v194, v204, v205
	v_cvt_pk_bf16_f32 v195, v182, v183
	v_add_u32_e32 v182, 0x80, v160
	v_cvt_pk_f16_f32 v199, v104, v105
	v_cvt_pk_f16_f32 v198, v102, v103
	v_cvt_pk_bf16_f32 v196, v208, v209
	v_cvt_pk_bf16_f32 v197, v206, v207
	v_ashrrev_i32_e32 v183, 31, v182
	v_add_u32_e32 v206, 0x90, v160
	v_cvt_pk_f16_f32 v201, v100, v101
	v_cvt_pk_f16_f32 v200, v98, v99
	v_pk_mul_f32 v[210:211], v[216:217], v[104:105]
	v_pk_mul_f32 v[212:213], v[218:219], v[102:103]
	global_store_dwordx4 v[192:193], v[194:197], off
	global_store_dwordx4 v[184:185], v[198:201], off
	v_ashrrev_i32_e32 v207, 31, v206
	v_lshl_add_u64 v[196:197], v[202:203], 0, v[156:157]
	v_cvt_pk_bf16_f32 v198, v212, v213
	v_cvt_pk_bf16_f32 v199, v210, v211
	v_lshlrev_b64 v[194:195], 11, v[182:183]
	v_pk_mul_f32 v[214:215], v[220:221], v[100:101]
	v_pk_mul_f32 v[224:225], v[222:223], v[98:99]
	v_lshlrev_b64 v[208:209], 11, v[206:207]
	v_cvt_pk_bf16_f32 v200, v224, v225
	v_cvt_pk_bf16_f32 v201, v214, v215
	global_store_dwordx4 v[196:197], v[198:201], off
	v_lshl_add_u64 v[204:205], v[162:163], 0, v[208:209]
	global_load_dwordx4 v[236:239], v[204:205], off nt
	v_lshl_add_u64 v[198:199], v[162:163], 0, v[194:195]
	global_load_dwordx4 v[232:235], v[198:199], off nt
	v_lshl_add_u64 v[212:213], v[158:159], 0, v[194:195]
	v_add_u32_e32 v182, s12, v182
	v_add_u32_e32 v194, s12, v206
	v_ashrrev_i32_e32 v183, 31, v182
	v_ashrrev_i32_e32 v195, 31, v194
	v_lshlrev_b64 v[182:183], 11, v[182:183]
	v_lshlrev_b64 v[194:195], 11, v[194:195]
	v_lshl_add_u64 v[182:183], s[8:9], 0, v[182:183]
	v_lshl_add_u64 v[194:195], s[8:9], 0, v[194:195]
	v_lshl_add_u64 v[210:211], v[158:159], 0, v[208:209]
	v_lshl_add_u64 v[214:215], v[182:183], 0, v[156:157]
	v_lshl_add_u64 v[208:209], v[194:195], 0, v[156:157]
	v_add_u32_e32 v200, 0xa0, v160
	v_ashrrev_i32_e32 v201, 31, v200
	v_lshlrev_b64 v[240:241], 11, v[200:201]
	v_lshl_add_u64 v[202:203], v[162:163], 0, v[240:241]
	s_waitcnt vmcnt(0)
	v_cvt_f32_f16_e32 v182, v234
	v_cvt_f32_f16_sdwa v183, v234 dst_sel:DWORD dst_unused:UNUSED_PAD src0_sel:WORD_1
	v_cvt_f32_f16_e32 v194, v235
	v_cvt_f32_f16_sdwa v195, v235 dst_sel:DWORD dst_unused:UNUSED_PAD src0_sel:WORD_1
	v_cvt_f32_f16_e32 v206, v232
	v_cvt_f32_f16_sdwa v207, v232 dst_sel:DWORD dst_unused:UNUSED_PAD src0_sel:WORD_1
	v_cvt_f32_f16_e32 v224, v233
	v_cvt_f32_f16_sdwa v225, v233 dst_sel:DWORD dst_unused:UNUSED_PAD src0_sel:WORD_1
	v_cvt_f32_f16_e32 v232, v238
	v_cvt_f32_f16_sdwa v233, v238 dst_sel:DWORD dst_unused:UNUSED_PAD src0_sel:WORD_1
	v_cvt_f32_f16_e32 v234, v239
	v_cvt_f32_f16_sdwa v235, v239 dst_sel:DWORD dst_unused:UNUSED_PAD src0_sel:WORD_1
	v_cvt_f32_f16_e32 v238, v236
	v_cvt_f32_f16_sdwa v239, v236 dst_sel:DWORD dst_unused:UNUSED_PAD src0_sel:WORD_1
	v_cvt_f32_f16_e32 v236, v237
	v_cvt_f32_f16_sdwa v237, v237 dst_sel:DWORD dst_unused:UNUSED_PAD src0_sel:WORD_1
	v_pk_fma_f32 v[96:97], v[96:97], v[136:137], v[224:225]
	v_pk_fma_f32 v[94:95], v[94:95], v[134:135], v[206:207]
	v_pk_fma_f32 v[92:93], v[92:93], v[132:133], v[194:195]
	v_pk_fma_f32 v[90:91], v[90:91], v[130:131], v[182:183]
	v_pk_fma_f32 v[84:85], v[84:85], v[132:133], v[234:235]
	v_pk_fma_f32 v[82:83], v[82:83], v[130:131], v[232:233]
	v_cvt_pk_f16_f32 v235, v92, v93
	v_cvt_pk_f16_f32 v233, v96, v97
	v_cvt_pk_f16_f32 v234, v90, v91
	v_cvt_pk_f16_f32 v232, v94, v95
	v_pk_mul_f32 v[206:207], v[220:221], v[92:93]
	v_pk_mul_f32 v[182:183], v[216:217], v[96:97]
	v_pk_mul_f32 v[194:195], v[218:219], v[94:95]
	v_pk_mul_f32 v[224:225], v[222:223], v[90:91]
	global_store_dwordx4 v[212:213], v[232:235], off
	v_pk_fma_f32 v[88:89], v[88:89], v[136:137], v[236:237]
	v_pk_fma_f32 v[86:87], v[86:87], v[134:135], v[238:239]
	v_cvt_pk_bf16_f32 v232, v194, v195
	v_cvt_pk_bf16_f32 v233, v182, v183
	v_cvt_pk_bf16_f32 v234, v224, v225
	v_cvt_pk_bf16_f32 v235, v206, v207
	v_add_u32_e32 v206, 0xb0, v160
	v_ashrrev_i32_e32 v207, 31, v206
	v_cvt_pk_f16_f32 v239, v84, v85
	v_cvt_pk_f16_f32 v237, v88, v89
	v_cvt_pk_f16_f32 v238, v82, v83
	v_cvt_pk_f16_f32 v236, v86, v87
	v_pk_mul_f32 v[242:243], v[216:217], v[88:89]
	v_pk_mul_f32 v[244:245], v[218:219], v[86:87]
	v_pk_mul_f32 v[246:247], v[220:221], v[84:85]
	v_pk_mul_f32 v[248:249], v[222:223], v[82:83]
	global_store_dwordx4 v[214:215], v[232:235], off
	global_store_dwordx4 v[210:211], v[236:239], off
	v_lshlrev_b64 v[194:195], 11, v[206:207]
	v_cvt_pk_bf16_f32 v232, v244, v245
	v_cvt_pk_bf16_f32 v233, v242, v243
	v_cvt_pk_bf16_f32 v234, v248, v249
	v_cvt_pk_bf16_f32 v235, v246, v247
	global_store_dwordx4 v[208:209], v[232:235], off
	global_load_dwordx4 v[232:235], v[202:203], off nt
	v_lshl_add_u64 v[224:225], v[162:163], 0, v[194:195]
	global_load_dwordx4 v[160:163], v[224:225], off nt
	v_lshl_add_u64 v[182:183], v[158:159], 0, v[240:241]
	v_lshl_add_u64 v[194:195], v[158:159], 0, v[194:195]
	v_add_u32_e32 v158, s12, v200
	v_add_u32_e32 v200, s12, v206
	v_ashrrev_i32_e32 v159, 31, v158
	v_ashrrev_i32_e32 v201, 31, v200
	v_lshlrev_b64 v[158:159], 11, v[158:159]
	v_lshlrev_b64 v[200:201], 11, v[200:201]
	v_lshl_add_u64 v[158:159], s[8:9], 0, v[158:159]
	v_lshl_add_u64 v[200:201], s[8:9], 0, v[200:201]
	v_lshl_add_u64 v[206:207], v[158:159], 0, v[156:157]
	v_lshl_add_u64 v[200:201], v[200:201], 0, v[156:157]
	s_waitcnt vmcnt(1)
	v_cvt_f32_f16_e32 v158, v234
	v_cvt_f32_f16_sdwa v159, v234 dst_sel:DWORD dst_unused:UNUSED_PAD src0_sel:WORD_1
	v_cvt_f32_f16_e32 v156, v235
	v_cvt_f32_f16_sdwa v157, v235 dst_sel:DWORD dst_unused:UNUSED_PAD src0_sel:WORD_1
	v_cvt_f32_f16_e32 v234, v232
	v_cvt_f32_f16_sdwa v235, v232 dst_sel:DWORD dst_unused:UNUSED_PAD src0_sel:WORD_1
	v_cvt_f32_f16_e32 v232, v233
	v_cvt_f32_f16_sdwa v233, v233 dst_sel:DWORD dst_unused:UNUSED_PAD src0_sel:WORD_1
	s_waitcnt vmcnt(0)
	v_cvt_f32_f16_e32 v236, v162
	v_cvt_f32_f16_sdwa v237, v162 dst_sel:DWORD dst_unused:UNUSED_PAD src0_sel:WORD_1
	v_cvt_f32_f16_e32 v238, v163
	v_cvt_f32_f16_sdwa v239, v163 dst_sel:DWORD dst_unused:UNUSED_PAD src0_sel:WORD_1
	v_cvt_f32_f16_e32 v240, v160
	v_cvt_f32_f16_sdwa v241, v160 dst_sel:DWORD dst_unused:UNUSED_PAD src0_sel:WORD_1
	v_cvt_f32_f16_e32 v242, v161
	v_cvt_f32_f16_sdwa v243, v161 dst_sel:DWORD dst_unused:UNUSED_PAD src0_sel:WORD_1
	v_pk_fma_f32 v[160:161], v[80:81], v[136:137], v[232:233]
	v_pk_fma_f32 v[162:163], v[78:79], v[134:135], v[234:235]
	v_pk_fma_f32 v[156:157], v[76:77], v[132:133], v[156:157]
	v_pk_fma_f32 v[158:159], v[74:75], v[130:131], v[158:159]
	v_pk_fma_f32 v[74:75], v[68:69], v[132:133], v[238:239]
	v_pk_fma_f32 v[76:77], v[66:67], v[130:131], v[236:237]
	v_cvt_pk_f16_f32 v69, v156, v157
	v_cvt_pk_f16_f32 v67, v160, v161
	v_cvt_pk_f16_f32 v68, v158, v159
	v_cvt_pk_f16_f32 v66, v162, v163
	v_pk_fma_f32 v[78:79], v[72:73], v[136:137], v[242:243]
	v_pk_fma_f32 v[80:81], v[70:71], v[134:135], v[240:241]
	v_pk_mul_f32 v[130:131], v[216:217], v[160:161]
	v_pk_mul_f32 v[132:133], v[218:219], v[162:163]
	v_pk_mul_f32 v[134:135], v[220:221], v[156:157]
	v_pk_mul_f32 v[136:137], v[222:223], v[158:159]
	global_store_dwordx4 v[182:183], v[66:69], off
	v_cvt_pk_f16_f32 v73, v74, v75
	v_cvt_pk_f16_f32 v71, v78, v79
	v_cvt_pk_bf16_f32 v66, v132, v133
	v_cvt_pk_bf16_f32 v67, v130, v131
	v_cvt_pk_bf16_f32 v68, v136, v137
	v_cvt_pk_bf16_f32 v69, v134, v135
	v_cvt_pk_f16_f32 v72, v76, v77
	v_cvt_pk_f16_f32 v70, v80, v81
	v_pk_mul_f32 v[216:217], v[216:217], v[78:79]
	v_pk_mul_f32 v[218:219], v[218:219], v[80:81]
	v_pk_mul_f32 v[220:221], v[220:221], v[74:75]
	v_pk_mul_f32 v[222:223], v[222:223], v[76:77]
	global_store_dwordx4 v[206:207], v[66:69], off
	global_store_dwordx4 v[194:195], v[70:73], off
	s_nop 0
	v_cvt_pk_bf16_f32 v66, v218, v219
	v_cvt_pk_bf16_f32 v67, v216, v217
	v_cvt_pk_bf16_f32 v68, v222, v223
	v_cvt_pk_bf16_f32 v69, v220, v221
	global_store_dwordx4 v[200:201], v[66:69], off
	global_load_dwordx4 v[130:133], v[172:173], off offset:512
	global_load_dwordx4 v[134:137], v[172:173], off offset:528
	s_nop 0
	global_load_dwordx4 v[172:175], v[174:175], off offset:256 nt
	s_nop 0
	global_load_dwordx4 v[216:219], v[178:179], off offset:256 nt
	v_or_b32_e32 v66, 0x80, v166
	v_ashrrev_i32_e32 v67, 31, v66
	v_lshl_add_u64 v[66:67], v[66:67], 2, s[0:1]
	global_load_dwordx4 v[220:223], v[66:67], off
	global_load_dwordx4 v[232:235], v[66:67], off offset:16
	global_load_dwordx4 v[70:73], v[176:177], off offset:512
	s_nop 0
	global_load_dwordx4 v[66:69], v[176:177], off offset:528
	s_waitcnt vmcnt(7)
	v_pk_add_f32 v[132:133], v[132:133], 1.0 op_sel_hi:[1,0]
	v_pk_add_f32 v[166:167], v[130:131], 1.0 op_sel_hi:[1,0]
	s_waitcnt vmcnt(5)
	v_cvt_f32_f16_e32 v178, v174
	v_cvt_f32_f16_sdwa v179, v174 dst_sel:DWORD dst_unused:UNUSED_PAD src0_sel:WORD_1
	v_cvt_f32_f16_e32 v174, v175
	v_cvt_f32_f16_sdwa v175, v175 dst_sel:DWORD dst_unused:UNUSED_PAD src0_sel:WORD_1
	v_cvt_f32_f16_e32 v236, v172
	v_cvt_f32_f16_sdwa v237, v172 dst_sel:DWORD dst_unused:UNUSED_PAD src0_sel:WORD_1
	v_cvt_f32_f16_e32 v172, v173
	v_cvt_f32_f16_sdwa v173, v173 dst_sel:DWORD dst_unused:UNUSED_PAD src0_sel:WORD_1
	s_waitcnt vmcnt(4)
	v_cvt_f32_f16_e32 v238, v218
	v_cvt_f32_f16_sdwa v239, v218 dst_sel:DWORD dst_unused:UNUSED_PAD src0_sel:WORD_1
	v_cvt_f32_f16_e32 v218, v219
	v_cvt_f32_f16_sdwa v219, v219 dst_sel:DWORD dst_unused:UNUSED_PAD src0_sel:WORD_1
	v_cvt_f32_f16_e32 v240, v216
	v_cvt_f32_f16_sdwa v241, v216 dst_sel:DWORD dst_unused:UNUSED_PAD src0_sel:WORD_1
	v_cvt_f32_f16_e32 v216, v217
	v_cvt_f32_f16_sdwa v217, v217 dst_sel:DWORD dst_unused:UNUSED_PAD src0_sel:WORD_1
	v_pk_add_f32 v[136:137], v[136:137], 1.0 op_sel_hi:[1,0]
	v_pk_add_f32 v[176:177], v[134:135], 1.0 op_sel_hi:[1,0]
	s_waitcnt vmcnt(3)
	v_pk_mul_f32 v[130:131], v[222:223], v[132:133]
	s_waitcnt vmcnt(1)
	v_pk_fma_f32 v[64:65], v[64:65], v[72:73], v[172:173]
	v_pk_fma_f32 v[62:63], v[62:63], v[70:71], v[236:237]
	s_waitcnt vmcnt(0)
	v_pk_fma_f32 v[60:61], v[60:61], v[68:69], v[174:175]
	v_pk_fma_f32 v[58:59], v[58:59], v[66:67], v[178:179]
	v_pk_mul_f32 v[132:133], v[220:221], v[166:167]
	v_pk_mul_f32 v[134:135], v[234:235], v[136:137]
	v_pk_mul_f32 v[136:137], v[232:233], v[176:177]
	v_cvt_pk_f16_f32 v175, v60, v61
	v_cvt_pk_f16_f32 v173, v64, v65
	v_cvt_pk_f16_f32 v174, v58, v59
	v_cvt_pk_f16_f32 v172, v62, v63
	v_pk_mul_f32 v[166:167], v[130:131], v[64:65]
	v_pk_fma_f32 v[56:57], v[56:57], v[72:73], v[216:217]
	v_pk_fma_f32 v[54:55], v[54:55], v[70:71], v[240:241]
	v_pk_fma_f32 v[52:53], v[52:53], v[68:69], v[218:219]
	v_pk_fma_f32 v[50:51], v[50:51], v[66:67], v[238:239]
	v_pk_mul_f32 v[216:217], v[132:133], v[62:63]
	v_pk_mul_f32 v[218:219], v[134:135], v[60:61]
	v_pk_mul_f32 v[220:221], v[136:137], v[58:59]
	global_store_dwordx4 v[164:165], v[172:175], off offset:256
	v_cvt_pk_bf16_f32 v164, v216, v217
	v_cvt_pk_bf16_f32 v165, v166, v167
	v_cvt_pk_bf16_f32 v166, v220, v221
	v_cvt_pk_bf16_f32 v167, v218, v219
	v_cvt_pk_f16_f32 v179, v52, v53
	v_cvt_pk_f16_f32 v177, v56, v57
	v_cvt_pk_f16_f32 v178, v50, v51
	v_cvt_pk_f16_f32 v176, v54, v55
	v_pk_mul_f32 v[222:223], v[130:131], v[56:57]
	v_pk_mul_f32 v[232:233], v[132:133], v[54:55]
	v_pk_mul_f32 v[234:235], v[134:135], v[52:53]
	v_pk_mul_f32 v[236:237], v[136:137], v[50:51]
	global_store_dwordx4 v[168:169], v[164:167], off offset:256
	global_store_dwordx4 v[180:181], v[176:179], off offset:256
	v_mul_f32_e32 v63, v63, v63
	v_cvt_pk_bf16_f32 v164, v232, v233
	v_cvt_pk_bf16_f32 v165, v222, v223
	v_cvt_pk_bf16_f32 v166, v236, v237
	v_cvt_pk_bf16_f32 v167, v234, v235
	global_store_dwordx4 v[186:187], v[164:167], off offset:256
	global_load_dwordx4 v[164:167], v[188:189], off offset:256 nt
	s_nop 0
	global_load_dwordx4 v[172:175], v[190:191], off offset:256 nt
	v_mul_f32_e32 v65, v65, v65
	v_mul_f32_e32 v59, v59, v59
	v_mul_f32_e32 v61, v61, v61
	v_fmac_f32_e32 v63, v62, v62
	v_fmac_f32_e32 v65, v64, v64
	v_fmac_f32_e32 v59, v58, v58
	v_fmac_f32_e32 v61, v60, v60
	v_add_f32_e32 v58, v63, v65
	v_add_f32_e32 v59, v59, v61
	v_add_f32_e32 v58, v58, v59
	v_add_f32_e32 v59, v122, v58
	v_xor_b32_e32 v58, 32, v231
	s_waitcnt vmcnt(1)
	v_cvt_f32_f16_e32 v168, v166
	v_cvt_f32_f16_sdwa v169, v166 dst_sel:DWORD dst_unused:UNUSED_PAD src0_sel:WORD_1
	v_cvt_f32_f16_e32 v166, v167
	v_cvt_f32_f16_sdwa v167, v167 dst_sel:DWORD dst_unused:UNUSED_PAD src0_sel:WORD_1
	v_cvt_f32_f16_e32 v176, v164
	v_cvt_f32_f16_sdwa v177, v164 dst_sel:DWORD dst_unused:UNUSED_PAD src0_sel:WORD_1
	v_cvt_f32_f16_e32 v164, v165
	v_cvt_f32_f16_sdwa v165, v165 dst_sel:DWORD dst_unused:UNUSED_PAD src0_sel:WORD_1
	s_waitcnt vmcnt(0)
	v_cvt_f32_f16_e32 v178, v174
	v_cvt_f32_f16_sdwa v179, v174 dst_sel:DWORD dst_unused:UNUSED_PAD src0_sel:WORD_1
	v_cvt_f32_f16_e32 v174, v175
	v_cvt_f32_f16_sdwa v175, v175 dst_sel:DWORD dst_unused:UNUSED_PAD src0_sel:WORD_1
	v_cvt_f32_f16_e32 v180, v172
	v_cvt_f32_f16_sdwa v181, v172 dst_sel:DWORD dst_unused:UNUSED_PAD src0_sel:WORD_1
	v_cvt_f32_f16_e32 v172, v173
	v_cvt_f32_f16_sdwa v173, v173 dst_sel:DWORD dst_unused:UNUSED_PAD src0_sel:WORD_1
	v_pk_fma_f32 v[48:49], v[48:49], v[72:73], v[164:165]
	v_pk_fma_f32 v[46:47], v[46:47], v[70:71], v[176:177]
	v_pk_fma_f32 v[44:45], v[44:45], v[68:69], v[166:167]
	v_pk_fma_f32 v[42:43], v[42:43], v[66:67], v[168:169]
	v_cvt_pk_f16_f32 v167, v44, v45
	v_cvt_pk_f16_f32 v165, v48, v49
	v_cvt_pk_f16_f32 v166, v42, v43
	v_cvt_pk_f16_f32 v164, v46, v47
	v_pk_fma_f32 v[40:41], v[40:41], v[72:73], v[172:173]
	v_pk_fma_f32 v[38:39], v[38:39], v[70:71], v[180:181]
	v_pk_fma_f32 v[36:37], v[36:37], v[68:69], v[174:175]
	v_pk_fma_f32 v[34:35], v[34:35], v[66:67], v[178:179]
	v_pk_mul_f32 v[168:169], v[130:131], v[48:49]
	v_pk_mul_f32 v[176:177], v[132:133], v[46:47]
	v_pk_mul_f32 v[178:179], v[134:135], v[44:45]
	v_pk_mul_f32 v[180:181], v[136:137], v[42:43]
	global_store_dwordx4 v[170:171], v[164:167], off offset:256
	v_cvt_pk_f16_f32 v175, v36, v37
	v_cvt_pk_f16_f32 v173, v40, v41
	v_cvt_pk_bf16_f32 v164, v176, v177
	v_cvt_pk_bf16_f32 v165, v168, v169
	v_cvt_pk_bf16_f32 v166, v180, v181
	v_cvt_pk_bf16_f32 v167, v178, v179
	v_cvt_pk_f16_f32 v174, v34, v35
	v_cvt_pk_f16_f32 v172, v38, v39
	v_pk_mul_f32 v[186:187], v[130:131], v[40:41]
	v_pk_mul_f32 v[188:189], v[132:133], v[38:39]
	v_pk_mul_f32 v[190:191], v[134:135], v[36:37]
	v_pk_mul_f32 v[216:217], v[136:137], v[34:35]
	global_store_dwordx4 v[192:193], v[164:167], off offset:256
	global_store_dwordx4 v[184:185], v[172:175], off offset:256
	s_nop 0
	v_cvt_pk_bf16_f32 v164, v188, v189
	v_cvt_pk_bf16_f32 v165, v186, v187
	v_cvt_pk_bf16_f32 v166, v216, v217
	v_cvt_pk_bf16_f32 v167, v190, v191
	global_store_dwordx4 v[196:197], v[164:167], off offset:256
	global_load_dwordx4 v[164:167], v[198:199], off offset:256 nt
	s_nop 0
	global_load_dwordx4 v[168:171], v[204:205], off offset:256 nt
	s_waitcnt vmcnt(1)
	v_cvt_f32_f16_e32 v172, v166
	v_cvt_f32_f16_sdwa v173, v166 dst_sel:DWORD dst_unused:UNUSED_PAD src0_sel:WORD_1
	v_cvt_f32_f16_e32 v166, v167
	v_cvt_f32_f16_sdwa v167, v167 dst_sel:DWORD dst_unused:UNUSED_PAD src0_sel:WORD_1
	v_cvt_f32_f16_e32 v174, v164
	v_cvt_f32_f16_sdwa v175, v164 dst_sel:DWORD dst_unused:UNUSED_PAD src0_sel:WORD_1
	v_cvt_f32_f16_e32 v164, v165
	v_cvt_f32_f16_sdwa v165, v165 dst_sel:DWORD dst_unused:UNUSED_PAD src0_sel:WORD_1
	s_waitcnt vmcnt(0)
	v_cvt_f32_f16_e32 v176, v170
	v_cvt_f32_f16_sdwa v177, v170 dst_sel:DWORD dst_unused:UNUSED_PAD src0_sel:WORD_1
	v_cvt_f32_f16_e32 v170, v171
	v_cvt_f32_f16_sdwa v171, v171 dst_sel:DWORD dst_unused:UNUSED_PAD src0_sel:WORD_1
	v_cvt_f32_f16_e32 v178, v168
	v_cvt_f32_f16_sdwa v179, v168 dst_sel:DWORD dst_unused:UNUSED_PAD src0_sel:WORD_1
	v_cvt_f32_f16_e32 v168, v169
	v_cvt_f32_f16_sdwa v169, v169 dst_sel:DWORD dst_unused:UNUSED_PAD src0_sel:WORD_1
	v_pk_fma_f32 v[32:33], v[32:33], v[72:73], v[164:165]
	v_pk_fma_f32 v[30:31], v[30:31], v[70:71], v[174:175]
	v_pk_fma_f32 v[28:29], v[28:29], v[68:69], v[166:167]
	v_pk_fma_f32 v[26:27], v[26:27], v[66:67], v[172:173]
	v_cvt_pk_f16_f32 v167, v28, v29
	v_cvt_pk_f16_f32 v165, v32, v33
	v_cvt_pk_f16_f32 v166, v26, v27
	v_cvt_pk_f16_f32 v164, v30, v31
	v_pk_fma_f32 v[24:25], v[24:25], v[72:73], v[168:169]
	v_pk_fma_f32 v[22:23], v[22:23], v[70:71], v[178:179]
	v_pk_fma_f32 v[20:21], v[20:21], v[68:69], v[170:171]
	v_pk_fma_f32 v[18:19], v[18:19], v[66:67], v[176:177]
	v_pk_mul_f32 v[172:173], v[130:131], v[32:33]
	v_pk_mul_f32 v[174:175], v[132:133], v[30:31]
	v_pk_mul_f32 v[176:177], v[134:135], v[28:29]
	v_pk_mul_f32 v[178:179], v[136:137], v[26:27]
	global_store_dwordx4 v[212:213], v[164:167], off offset:256
	v_cvt_pk_f16_f32 v171, v20, v21
	v_cvt_pk_f16_f32 v169, v24, v25
	v_cvt_pk_bf16_f32 v164, v174, v175
	v_cvt_pk_bf16_f32 v165, v172, v173
	v_cvt_pk_bf16_f32 v166, v178, v179
	v_cvt_pk_bf16_f32 v167, v176, v177
	v_cvt_pk_f16_f32 v170, v18, v19
	v_cvt_pk_f16_f32 v168, v22, v23
	v_pk_mul_f32 v[180:181], v[130:131], v[24:25]
	v_pk_mul_f32 v[184:185], v[132:133], v[22:23]
	v_pk_mul_f32 v[186:187], v[134:135], v[20:21]
	v_pk_mul_f32 v[188:189], v[136:137], v[18:19]
	global_store_dwordx4 v[214:215], v[164:167], off offset:256
	global_store_dwordx4 v[210:211], v[168:171], off offset:256
	s_nop 0
	v_cvt_pk_bf16_f32 v164, v184, v185
	v_cvt_pk_bf16_f32 v165, v180, v181
	v_cvt_pk_bf16_f32 v166, v188, v189
	v_cvt_pk_bf16_f32 v167, v186, v187
	global_store_dwordx4 v[208:209], v[164:167], off offset:256
	global_load_dwordx4 v[166:169], v[202:203], off offset:256 nt
	s_nop 0
	global_load_dwordx4 v[170:173], v[224:225], off offset:256 nt
	v_and_b32_e32 v165, 64, v231
	v_xor_b32_e32 v164, 16, v231
	v_add_u32_e32 v165, 64, v165
	v_cmp_lt_i32_e32 vcc, v164, v165
	s_waitcnt vmcnt(1)
	v_cvt_f32_f16_e32 v62, v168
	v_cndmask_b32_e32 v164, v231, v164, vcc
	v_lshlrev_b32_e32 v164, 2, v164
	ds_bpermute_b32 v60, v164, v59
	v_cmp_lt_i32_e32 vcc, v58, v165
	v_cvt_f32_f16_sdwa v63, v168 dst_sel:DWORD dst_unused:UNUSED_PAD src0_sel:WORD_1
	v_cvt_f32_f16_e32 v64, v169
	v_cndmask_b32_e32 v58, v231, v58, vcc
	v_cvt_f32_f16_sdwa v65, v169 dst_sel:DWORD dst_unused:UNUSED_PAD src0_sel:WORD_1
	v_cvt_f32_f16_e32 v122, v166
	v_cvt_f32_f16_sdwa v123, v166 dst_sel:DWORD dst_unused:UNUSED_PAD src0_sel:WORD_1
	v_cvt_f32_f16_e32 v124, v167
	v_cvt_f32_f16_sdwa v125, v167 dst_sel:DWORD dst_unused:UNUSED_PAD src0_sel:WORD_1
	v_lshlrev_b32_e32 v58, 2, v58
	s_waitcnt lgkmcnt(0)
	v_add_f32_e32 v59, v59, v60
	ds_bpermute_b32 v60, v58, v59
	s_waitcnt vmcnt(0)
	v_cvt_f32_f16_e32 v126, v172
	v_cvt_f32_f16_sdwa v127, v172 dst_sel:DWORD dst_unused:UNUSED_PAD src0_sel:WORD_1
	v_cvt_f32_f16_e32 v128, v173
	v_cvt_f32_f16_sdwa v129, v173 dst_sel:DWORD dst_unused:UNUSED_PAD src0_sel:WORD_1
	v_cvt_f32_f16_e32 v166, v170
	v_cvt_f32_f16_sdwa v167, v170 dst_sel:DWORD dst_unused:UNUSED_PAD src0_sel:WORD_1
	v_cvt_f32_f16_e32 v168, v171
	v_cvt_f32_f16_sdwa v169, v171 dst_sel:DWORD dst_unused:UNUSED_PAD src0_sel:WORD_1
	v_pk_fma_f32 v[16:17], v[16:17], v[72:73], v[124:125]
	v_pk_fma_f32 v[14:15], v[14:15], v[70:71], v[122:123]
	v_pk_fma_f32 v[12:13], v[12:13], v[68:69], v[64:65]
	v_pk_fma_f32 v[10:11], v[10:11], v[66:67], v[62:63]
	v_cvt_pk_f16_f32 v65, v12, v13
	v_cvt_pk_f16_f32 v63, v16, v17
	v_cvt_pk_f16_f32 v64, v10, v11
	v_cvt_pk_f16_f32 v62, v14, v15
	v_pk_fma_f32 v[8:9], v[8:9], v[72:73], v[168:169]
	v_pk_fma_f32 v[6:7], v[6:7], v[70:71], v[166:167]
	v_pk_fma_f32 v[4:5], v[4:5], v[68:69], v[128:129]
	v_pk_fma_f32 v[2:3], v[2:3], v[66:67], v[126:127]
	v_pk_mul_f32 v[70:71], v[130:131], v[16:17]
	v_pk_mul_f32 v[72:73], v[132:133], v[14:15]
	v_pk_mul_f32 v[122:123], v[134:135], v[12:13]
	v_pk_mul_f32 v[124:125], v[136:137], v[10:11]
	global_store_dwordx4 v[182:183], v[62:65], off offset:256
	v_cvt_pk_f16_f32 v69, v4, v5
	v_cvt_pk_f16_f32 v67, v8, v9
	v_cvt_pk_bf16_f32 v62, v72, v73
	v_cvt_pk_bf16_f32 v63, v70, v71
	v_cvt_pk_bf16_f32 v64, v124, v125
	v_cvt_pk_bf16_f32 v65, v122, v123
	v_cvt_pk_f16_f32 v68, v2, v3
	v_cvt_pk_f16_f32 v66, v6, v7
	v_pk_mul_f32 v[126:127], v[130:131], v[8:9]
	v_pk_mul_f32 v[128:129], v[132:133], v[6:7]
	v_pk_mul_f32 v[130:131], v[134:135], v[4:5]
	v_pk_mul_f32 v[132:133], v[136:137], v[2:3]
	global_store_dwordx4 v[206:207], v[62:65], off offset:256
	global_store_dwordx4 v[194:195], v[66:69], off offset:256
	s_nop 0
	v_cvt_pk_bf16_f32 v62, v128, v129
	v_cvt_pk_bf16_f32 v63, v126, v127
	v_cvt_pk_bf16_f32 v64, v132, v133
	v_cvt_pk_bf16_f32 v65, v130, v131
	global_store_dwordx4 v[200:201], v[62:65], off offset:256
	s_and_saveexec_b64 s[30:31], s[4:5]
	s_cbranch_execz .LBB0_1397
	v_lshl_add_u64 v[62:63], v[154:155], 2, s[10:11]
	s_waitcnt lgkmcnt(0)
	v_add_f32_e32 v59, v59, v60
	global_atomic_add_f32 v[62:63], v59, off

.LBB0_1478:
	s_ashr_i32 s31, s30, 31
	s_lshl_b64 s[12:13], s[30:31], 19
	s_add_u32 s36, s3, s12
	s_addc_u32 s37, s19, s13
	s_and_b64 s[12:13], s[4:5], exec
	s_cselect_b32 s31, s37, s1
	s_cselect_b32 s43, s36, s0
	s_ashr_i32 s29, s28, 31
	s_lshl_b64 s[12:13], s[28:29], 19
	s_add_u32 s38, s33, s12
	s_addc_u32 s39, s48, s13
	s_and_b64 s[12:13], s[4:5], exec
	s_cselect_b32 s29, s39, s45
	s_cselect_b32 s67, s38, s44
	s_add_u32 s0, s0, 0x40080
	s_addc_u32 s1, s1, 0
	s_add_u32 s68, s44, 0x100
	v_mov_b32_e32 v2, 0
	s_addc_u32 s69, s45, 0
	s_mov_b32 s12, -2
	v_mov_b32_e32 v3, v2
	v_mov_b32_e32 v4, v2
	v_mov_b32_e32 v5, v2
	v_mov_b32_e32 v6, v2
	v_mov_b32_e32 v7, v2
	v_mov_b32_e32 v8, v2
	v_mov_b32_e32 v9, v2
	v_mov_b32_e32 v18, v2
	v_mov_b32_e32 v19, v2
	v_mov_b32_e32 v20, v2
	v_mov_b32_e32 v21, v2
	v_mov_b32_e32 v22, v2
	v_mov_b32_e32 v23, v2
	v_mov_b32_e32 v24, v2
	v_mov_b32_e32 v25, v2
	v_mov_b32_e32 v34, v2
	v_mov_b32_e32 v35, v2
	v_mov_b32_e32 v36, v2
	v_mov_b32_e32 v37, v2
	v_mov_b32_e32 v38, v2
	v_mov_b32_e32 v39, v2
	v_mov_b32_e32 v40, v2
	v_mov_b32_e32 v41, v2
	v_mov_b32_e32 v50, v2
	v_mov_b32_e32 v51, v2
	v_mov_b32_e32 v52, v2
	v_mov_b32_e32 v53, v2
	v_mov_b32_e32 v54, v2
	v_mov_b32_e32 v55, v2
	v_mov_b32_e32 v56, v2
	v_mov_b32_e32 v57, v2
	v_mov_b32_e32 v10, v2
	v_mov_b32_e32 v11, v2
	v_mov_b32_e32 v12, v2
	v_mov_b32_e32 v13, v2
	v_mov_b32_e32 v14, v2
	v_mov_b32_e32 v15, v2
	v_mov_b32_e32 v16, v2
	v_mov_b32_e32 v17, v2
	v_mov_b32_e32 v26, v2
	v_mov_b32_e32 v27, v2
	v_mov_b32_e32 v28, v2
	v_mov_b32_e32 v29, v2
	v_mov_b32_e32 v30, v2
	v_mov_b32_e32 v31, v2
	v_mov_b32_e32 v32, v2
	v_mov_b32_e32 v33, v2
	v_mov_b32_e32 v42, v2
	v_mov_b32_e32 v43, v2
	v_mov_b32_e32 v44, v2
	v_mov_b32_e32 v45, v2
	v_mov_b32_e32 v46, v2
	v_mov_b32_e32 v47, v2
	v_mov_b32_e32 v48, v2
	v_mov_b32_e32 v49, v2
	v_mov_b32_e32 v58, v2
	v_mov_b32_e32 v59, v2
	v_mov_b32_e32 v60, v2
	v_mov_b32_e32 v61, v2
	v_mov_b32_e32 v62, v2
	v_mov_b32_e32 v63, v2
	v_mov_b32_e32 v64, v2
	v_mov_b32_e32 v65, v2
	v_mov_b32_e32 v66, v2
	v_mov_b32_e32 v67, v2
	v_mov_b32_e32 v68, v2
	v_mov_b32_e32 v69, v2
	v_mov_b32_e32 v70, v2
	v_mov_b32_e32 v71, v2
	v_mov_b32_e32 v72, v2
	v_mov_b32_e32 v73, v2
	v_mov_b32_e32 v82, v2
	v_mov_b32_e32 v83, v2
	v_mov_b32_e32 v84, v2
	v_mov_b32_e32 v85, v2
	v_mov_b32_e32 v86, v2
	v_mov_b32_e32 v87, v2
	v_mov_b32_e32 v88, v2
	v_mov_b32_e32 v89, v2
	v_mov_b32_e32 v114, v2
	v_mov_b32_e32 v115, v2
	v_mov_b32_e32 v116, v2
	v_mov_b32_e32 v117, v2
	v_mov_b32_e32 v118, v2
	v_mov_b32_e32 v119, v2
	v_mov_b32_e32 v120, v2
	v_mov_b32_e32 v121, v2
	v_mov_b32_e32 v130, v2
	v_mov_b32_e32 v131, v2
	v_mov_b32_e32 v132, v2
	v_mov_b32_e32 v133, v2
	v_mov_b32_e32 v134, v2
	v_mov_b32_e32 v135, v2
	v_mov_b32_e32 v136, v2
	v_mov_b32_e32 v137, v2
	v_mov_b32_e32 v74, v2
	v_mov_b32_e32 v75, v2
	v_mov_b32_e32 v76, v2
	v_mov_b32_e32 v77, v2
	v_mov_b32_e32 v78, v2
	v_mov_b32_e32 v79, v2
	v_mov_b32_e32 v80, v2
	v_mov_b32_e32 v81, v2
	v_mov_b32_e32 v90, v2
	v_mov_b32_e32 v91, v2
	v_mov_b32_e32 v92, v2
	v_mov_b32_e32 v93, v2
	v_mov_b32_e32 v94, v2
	v_mov_b32_e32 v95, v2
	v_mov_b32_e32 v96, v2
	v_mov_b32_e32 v97, v2
	v_mov_b32_e32 v122, v2
	v_mov_b32_e32 v123, v2
	v_mov_b32_e32 v124, v2
	v_mov_b32_e32 v125, v2
	v_mov_b32_e32 v126, v2
	v_mov_b32_e32 v127, v2
	v_mov_b32_e32 v128, v2
	v_mov_b32_e32 v129, v2
	v_mov_b32_e32 v138, v2
	v_mov_b32_e32 v139, v2
	v_mov_b32_e32 v140, v2
	v_mov_b32_e32 v141, v2
	v_mov_b32_e32 v142, v2
	v_mov_b32_e32 v143, v2
	v_mov_b32_e32 v144, v2
	v_mov_b32_e32 v145, v2
	v_add_u32_e32 v251, 0x80, v152
.LBB0_1479:
	ds_read_b128 v[98:101], v176
	ds_read_b128 v[102:105], v176 offset:1024
	ds_read_b128 v[106:109], v176 offset:2048
	ds_read_b128 v[110:113], v176 offset:3072
	ds_read_b128 v[182:185], v177
	ds_read_b128 v[186:189], v177 offset:1024
	ds_read_b128 v[190:193], v177 offset:2048
	ds_read_b128 v[194:197], v177 offset:3072
	s_add_u32 s13, s0, 0xfffc0080
	s_addc_u32 s44, s1, -1
	s_cmp_eq_u32 s12, 12
	s_cselect_b32 s47, s31, s44
	s_cselect_b32 s46, s43, s13
	s_cselect_b32 s45, s29, s69
	s_cselect_b32 s44, s67, s68
	v_lshl_add_u64 v[230:231], s[0:1], 0, v[158:159]
	s_add_i32 m0, s52, 0xc000
	ds_read_b128 v[198:201], v178
	ds_read_b128 v[202:205], v178 offset:1024
	ds_read_b128 v[206:209], v178 offset:2048
	ds_read_b128 v[210:213], v178 offset:3072
	ds_read_b128 v[214:217], v178 offset:4096
	ds_read_b128 v[218:221], v178 offset:5120
	ds_read_b128 v[222:225], v178 offset:6144
	ds_read_b128 v[226:229], v178 offset:7168
	global_load_lds_dwordx4 v158, s[0:1]
	v_lshl_add_u64 v[230:231], s[0:1], 0, v[160:161]
	s_add_i32 m0, s52, 0xe000
	s_nop 0
	global_load_lds_dwordx4 v160, s[0:1]
	s_waitcnt vmcnt(8)
	s_waitcnt lgkmcnt(0)
	s_barrier
	s_setprio 1
	s_waitcnt lgkmcnt(0)
	v_mfma_f32_16x16x32_bf16 v[142:145], v[98:101], v[198:201], v[142:145]
	v_mfma_f32_16x16x32_bf16 v[138:141], v[106:109], v[198:201], v[138:141]
	v_mfma_f32_16x16x32_bf16 v[126:129], v[98:101], v[206:209], v[126:129]
	v_mfma_f32_16x16x32_bf16 v[122:125], v[106:109], v[206:209], v[122:125]
	v_mfma_f32_16x16x32_bf16 v[94:97], v[98:101], v[214:217], v[94:97]
	v_mfma_f32_16x16x32_bf16 v[90:93], v[106:109], v[214:217], v[90:93]
	v_mfma_f32_16x16x32_bf16 v[78:81], v[98:101], v[222:225], v[78:81]
	v_mfma_f32_16x16x32_bf16 v[74:77], v[106:109], v[222:225], v[74:77]
	v_mfma_f32_16x16x32_bf16 v[142:145], v[102:105], v[202:205], v[142:145]
	v_mfma_f32_16x16x32_bf16 v[138:141], v[110:113], v[202:205], v[138:141]
	v_mfma_f32_16x16x32_bf16 v[126:129], v[102:105], v[210:213], v[126:129]
	v_mfma_f32_16x16x32_bf16 v[122:125], v[110:113], v[210:213], v[122:125]
	v_mfma_f32_16x16x32_bf16 v[94:97], v[102:105], v[218:221], v[94:97]
	v_mfma_f32_16x16x32_bf16 v[90:93], v[110:113], v[218:221], v[90:93]
	v_mfma_f32_16x16x32_bf16 v[78:81], v[102:105], v[226:229], v[78:81]
	v_mfma_f32_16x16x32_bf16 v[74:77], v[110:113], v[226:229], v[74:77]
	s_setprio 0
	s_setprio 1
	v_mfma_f32_16x16x32_bf16 v[134:137], v[182:185], v[198:201], v[134:137]
	v_mfma_f32_16x16x32_bf16 v[130:133], v[190:193], v[198:201], v[130:133]
	v_mfma_f32_16x16x32_bf16 v[118:121], v[182:185], v[206:209], v[118:121]
	v_mfma_f32_16x16x32_bf16 v[114:117], v[190:193], v[206:209], v[114:117]
	v_mfma_f32_16x16x32_bf16 v[86:89], v[182:185], v[214:217], v[86:89]
	v_mfma_f32_16x16x32_bf16 v[82:85], v[190:193], v[214:217], v[82:85]
	v_mfma_f32_16x16x32_bf16 v[70:73], v[182:185], v[222:225], v[70:73]
	v_mfma_f32_16x16x32_bf16 v[66:69], v[190:193], v[222:225], v[66:69]
	v_mfma_f32_16x16x32_bf16 v[134:137], v[186:189], v[202:205], v[134:137]
	v_mfma_f32_16x16x32_bf16 v[130:133], v[194:197], v[202:205], v[130:133]
	v_mfma_f32_16x16x32_bf16 v[118:121], v[186:189], v[210:213], v[118:121]
	v_mfma_f32_16x16x32_bf16 v[114:117], v[194:197], v[210:213], v[114:117]
	v_mfma_f32_16x16x32_bf16 v[86:89], v[186:189], v[218:221], v[86:89]
	v_mfma_f32_16x16x32_bf16 v[82:85], v[194:197], v[218:221], v[82:85]
	v_mfma_f32_16x16x32_bf16 v[70:73], v[186:189], v[226:229], v[70:73]
	v_mfma_f32_16x16x32_bf16 v[66:69], v[194:197], v[226:229], v[66:69]
	s_setprio 0
	s_barrier
	s_add_i32 s13, s61, s49
	v_lshl_add_u64 v[230:231], s[44:45], 0, v[152:153]
	s_mov_b32 m0, s13
	ds_read_b128 v[198:201], v178 offset:16384
	ds_read_b128 v[202:205], v178 offset:17408
	ds_read_b128 v[206:209], v178 offset:18432
	ds_read_b128 v[210:213], v178 offset:19456
	ds_read_b128 v[214:217], v178 offset:20480
	ds_read_b128 v[218:221], v178 offset:21504
	ds_read_b128 v[222:225], v178 offset:22528
	ds_read_b128 v[226:229], v178 offset:23552
	global_load_lds_dwordx4 v152, s[44:45]
	s_add_i32 m0, s13, 0x2000
	s_add_u32 s70, s44, 0x40000
	v_lshl_add_u64 v[232:233], s[44:45], 0, v[148:149]
	s_addc_u32 s71, s45, 0
	s_add_i32 s13, s62, s49
	global_load_lds_dwordx4 v148, s[44:45]
	s_nop 0
	s_mov_b32 m0, s13
	v_lshl_add_u64 v[236:237], s[46:47], 0, v[150:151]
	global_load_lds_dwordx4 v152, s[70:71]
	s_nop 0
	s_add_i32 m0, s13, 0x2000
	s_nop 0
	global_load_lds_dwordx4 v148, s[70:71]
	v_lshl_add_u64 v[234:235], s[46:47], 0, v[154:155]
	s_mov_b32 m0, s52
	s_nop 0
	global_load_lds_dwordx4 v154, s[46:47]
	s_mov_b32 m0, s53
	s_nop 0
	global_load_lds_dwordx4 v150, s[46:47]
	s_waitcnt vmcnt(8)
	s_waitcnt lgkmcnt(0)
	s_barrier
	s_setprio 1
	s_waitcnt lgkmcnt(0)
	v_mfma_f32_16x16x32_bf16 v[62:65], v[98:101], v[198:201], v[62:65]
	v_mfma_f32_16x16x32_bf16 v[58:61], v[106:109], v[198:201], v[58:61]
	v_mfma_f32_16x16x32_bf16 v[46:49], v[98:101], v[206:209], v[46:49]
	v_mfma_f32_16x16x32_bf16 v[42:45], v[106:109], v[206:209], v[42:45]
	v_mfma_f32_16x16x32_bf16 v[30:33], v[98:101], v[214:217], v[30:33]
	v_mfma_f32_16x16x32_bf16 v[26:29], v[106:109], v[214:217], v[26:29]
	v_mfma_f32_16x16x32_bf16 v[14:17], v[98:101], v[222:225], v[14:17]
	v_mfma_f32_16x16x32_bf16 v[10:13], v[106:109], v[222:225], v[10:13]
	v_mfma_f32_16x16x32_bf16 v[62:65], v[102:105], v[202:205], v[62:65]
	v_mfma_f32_16x16x32_bf16 v[58:61], v[110:113], v[202:205], v[58:61]
	v_mfma_f32_16x16x32_bf16 v[46:49], v[102:105], v[210:213], v[46:49]
	v_mfma_f32_16x16x32_bf16 v[42:45], v[110:113], v[210:213], v[42:45]
	v_mfma_f32_16x16x32_bf16 v[30:33], v[102:105], v[218:221], v[30:33]
	v_mfma_f32_16x16x32_bf16 v[26:29], v[110:113], v[218:221], v[26:29]
	v_mfma_f32_16x16x32_bf16 v[14:17], v[102:105], v[226:229], v[14:17]
	v_mfma_f32_16x16x32_bf16 v[10:13], v[110:113], v[226:229], v[10:13]
	s_setprio 0
	s_setprio 1
	v_mfma_f32_16x16x32_bf16 v[54:57], v[182:185], v[198:201], v[54:57]
	v_mfma_f32_16x16x32_bf16 v[50:53], v[190:193], v[198:201], v[50:53]
	v_mfma_f32_16x16x32_bf16 v[38:41], v[182:185], v[206:209], v[38:41]
	v_mfma_f32_16x16x32_bf16 v[34:37], v[190:193], v[206:209], v[34:37]
	v_mfma_f32_16x16x32_bf16 v[22:25], v[182:185], v[214:217], v[22:25]
	v_mfma_f32_16x16x32_bf16 v[18:21], v[190:193], v[214:217], v[18:21]
	v_mfma_f32_16x16x32_bf16 v[6:9], v[182:185], v[222:225], v[6:9]
	v_mfma_f32_16x16x32_bf16 v[2:5], v[190:193], v[222:225], v[2:5]
	v_mfma_f32_16x16x32_bf16 v[54:57], v[186:189], v[202:205], v[54:57]
	v_mfma_f32_16x16x32_bf16 v[50:53], v[194:197], v[202:205], v[50:53]
	v_mfma_f32_16x16x32_bf16 v[38:41], v[186:189], v[210:213], v[38:41]
	v_mfma_f32_16x16x32_bf16 v[34:37], v[194:197], v[210:213], v[34:37]
	v_mfma_f32_16x16x32_bf16 v[22:25], v[186:189], v[218:221], v[22:25]
	v_mfma_f32_16x16x32_bf16 v[18:21], v[194:197], v[218:221], v[18:21]
	v_mfma_f32_16x16x32_bf16 v[6:9], v[186:189], v[226:229], v[6:9]
	v_mfma_f32_16x16x32_bf16 v[2:5], v[194:197], v[226:229], v[2:5]
	s_setprio 0
	s_barrier
	s_add_i32 s13, 0, 0x18000
	s_add_i32 s70, 0, 0x1c000
	v_add_u32_e32 v110, s13, v167
	v_add_u32_e32 v181, s70, v167
	ds_read_b128 v[98:101], v110
	ds_read_b128 v[102:105], v110 offset:1024
	ds_read_b128 v[106:109], v110 offset:2048
	ds_read_b128 v[110:113], v110 offset:3072
	ds_read_b128 v[182:185], v181
	ds_read_b128 v[186:189], v181 offset:1024
	ds_read_b128 v[190:193], v181 offset:2048
	ds_read_b128 v[194:197], v181 offset:3072
	s_add_u32 s46, s46, 0x40000
	s_addc_u32 s47, s47, 0
	s_mov_b32 m0, s54
	s_nop 0
	ds_read_b128 v[198:201], v178 offset:32768
	ds_read_b128 v[202:205], v178 offset:33792
	ds_read_b128 v[206:209], v178 offset:34816
	ds_read_b128 v[210:213], v178 offset:35840
	ds_read_b128 v[214:217], v178 offset:36864
	ds_read_b128 v[218:221], v178 offset:37888
	ds_read_b128 v[222:225], v178 offset:38912
	ds_read_b128 v[226:229], v178 offset:39936
	global_load_lds_dwordx4 v154, s[46:47]
	s_nop 0
	s_mov_b32 m0, s55
	s_nop 0
	global_load_lds_dwordx4 v150, s[46:47]
	s_waitcnt vmcnt(8)
	s_waitcnt lgkmcnt(0)
	s_barrier
	s_setprio 1
	s_waitcnt lgkmcnt(0)
	v_mfma_f32_16x16x32_bf16 v[142:145], v[98:101], v[198:201], v[142:145]
	v_mfma_f32_16x16x32_bf16 v[138:141], v[106:109], v[198:201], v[138:141]
	v_mfma_f32_16x16x32_bf16 v[126:129], v[98:101], v[206:209], v[126:129]
	v_mfma_f32_16x16x32_bf16 v[122:125], v[106:109], v[206:209], v[122:125]
	v_mfma_f32_16x16x32_bf16 v[94:97], v[98:101], v[214:217], v[94:97]
	v_mfma_f32_16x16x32_bf16 v[90:93], v[106:109], v[214:217], v[90:93]
	v_mfma_f32_16x16x32_bf16 v[78:81], v[98:101], v[222:225], v[78:81]
	v_mfma_f32_16x16x32_bf16 v[74:77], v[106:109], v[222:225], v[74:77]
	v_mfma_f32_16x16x32_bf16 v[142:145], v[102:105], v[202:205], v[142:145]
	v_mfma_f32_16x16x32_bf16 v[138:141], v[110:113], v[202:205], v[138:141]
	v_mfma_f32_16x16x32_bf16 v[126:129], v[102:105], v[210:213], v[126:129]
	v_mfma_f32_16x16x32_bf16 v[122:125], v[110:113], v[210:213], v[122:125]
	v_mfma_f32_16x16x32_bf16 v[94:97], v[102:105], v[218:221], v[94:97]
	v_mfma_f32_16x16x32_bf16 v[90:93], v[110:113], v[218:221], v[90:93]
	v_mfma_f32_16x16x32_bf16 v[78:81], v[102:105], v[226:229], v[78:81]
	v_mfma_f32_16x16x32_bf16 v[74:77], v[110:113], v[226:229], v[74:77]
	s_setprio 0
	s_setprio 1
	v_mfma_f32_16x16x32_bf16 v[134:137], v[182:185], v[198:201], v[134:137]
	v_mfma_f32_16x16x32_bf16 v[130:133], v[190:193], v[198:201], v[130:133]
	v_mfma_f32_16x16x32_bf16 v[118:121], v[182:185], v[206:209], v[118:121]
	v_mfma_f32_16x16x32_bf16 v[114:117], v[190:193], v[206:209], v[114:117]
	v_mfma_f32_16x16x32_bf16 v[86:89], v[182:185], v[214:217], v[86:89]
	v_mfma_f32_16x16x32_bf16 v[82:85], v[190:193], v[214:217], v[82:85]
	v_mfma_f32_16x16x32_bf16 v[70:73], v[182:185], v[222:225], v[70:73]
	v_mfma_f32_16x16x32_bf16 v[66:69], v[190:193], v[222:225], v[66:69]
	v_mfma_f32_16x16x32_bf16 v[134:137], v[186:189], v[202:205], v[134:137]
	v_mfma_f32_16x16x32_bf16 v[130:133], v[194:197], v[202:205], v[130:133]
	v_mfma_f32_16x16x32_bf16 v[118:121], v[186:189], v[210:213], v[118:121]
	v_mfma_f32_16x16x32_bf16 v[114:117], v[194:197], v[210:213], v[114:117]
	v_mfma_f32_16x16x32_bf16 v[86:89], v[186:189], v[218:221], v[86:89]
	v_mfma_f32_16x16x32_bf16 v[82:85], v[194:197], v[218:221], v[82:85]
	v_mfma_f32_16x16x32_bf16 v[70:73], v[186:189], v[226:229], v[70:73]
	v_mfma_f32_16x16x32_bf16 v[66:69], v[194:197], v[226:229], v[66:69]
	s_setprio 0
	s_barrier
	s_add_i32 s13, s13, s49
	v_lshl_add_u64 v[230:231], v[230:231], 0, s[20:21]
	s_mov_b32 m0, s13
	ds_read_b128 v[198:201], v178 offset:49152
	ds_read_b128 v[202:205], v178 offset:50176
	ds_read_b128 v[206:209], v178 offset:51200
	ds_read_b128 v[210:213], v178 offset:52224
	ds_read_b128 v[214:217], v178 offset:53248
	ds_read_b128 v[218:221], v178 offset:54272
	ds_read_b128 v[222:225], v178 offset:55296
	ds_read_b128 v[226:229], v178 offset:56320
	global_load_lds_dwordx4 v251, s[44:45]
	s_add_i32 m0, s13, 0x2000
	s_add_u32 s44, s44, 0x40080
	v_lshl_add_u64 v[230:231], v[232:233], 0, s[20:21]
	s_addc_u32 s45, s45, 0
	s_add_i32 s13, s70, s49
	global_load_lds_dwordx4 v[230:231], off
	v_lshl_add_u64 v[230:231], s[44:45], 0, v[152:153]
	s_mov_b32 m0, s13
	s_nop 0
	global_load_lds_dwordx4 v152, s[44:45]
	v_lshl_add_u64 v[230:231], s[44:45], 0, v[148:149]
	s_add_i32 m0, s13, 0x2000
	s_nop 0
	global_load_lds_dwordx4 v148, s[44:45]
	v_lshl_add_u64 v[230:231], v[234:235], 0, s[20:21]
	s_mov_b32 m0, s58
	s_nop 0
	global_load_lds_dwordx4 v[230:231], off
	v_lshl_add_u64 v[230:231], v[236:237], 0, s[20:21]
	s_mov_b32 m0, s59
	s_nop 0
	global_load_lds_dwordx4 v[230:231], off
	s_waitcnt vmcnt(8)
	s_waitcnt lgkmcnt(0)
	s_barrier
	s_setprio 1
	s_waitcnt lgkmcnt(0)
	v_mfma_f32_16x16x32_bf16 v[62:65], v[98:101], v[198:201], v[62:65]
	v_mfma_f32_16x16x32_bf16 v[58:61], v[106:109], v[198:201], v[58:61]
	v_mfma_f32_16x16x32_bf16 v[46:49], v[98:101], v[206:209], v[46:49]
	v_mfma_f32_16x16x32_bf16 v[42:45], v[106:109], v[206:209], v[42:45]
	v_mfma_f32_16x16x32_bf16 v[30:33], v[98:101], v[214:217], v[30:33]
	v_mfma_f32_16x16x32_bf16 v[26:29], v[106:109], v[214:217], v[26:29]
	v_mfma_f32_16x16x32_bf16 v[14:17], v[98:101], v[222:225], v[14:17]
	v_mfma_f32_16x16x32_bf16 v[10:13], v[106:109], v[222:225], v[10:13]
	v_mfma_f32_16x16x32_bf16 v[62:65], v[102:105], v[202:205], v[62:65]
	v_mfma_f32_16x16x32_bf16 v[58:61], v[110:113], v[202:205], v[58:61]
	v_mfma_f32_16x16x32_bf16 v[46:49], v[102:105], v[210:213], v[46:49]
	v_mfma_f32_16x16x32_bf16 v[42:45], v[110:113], v[210:213], v[42:45]
	v_mfma_f32_16x16x32_bf16 v[30:33], v[102:105], v[218:221], v[30:33]
	v_mfma_f32_16x16x32_bf16 v[26:29], v[110:113], v[218:221], v[26:29]
	v_mfma_f32_16x16x32_bf16 v[14:17], v[102:105], v[226:229], v[14:17]
	v_mfma_f32_16x16x32_bf16 v[10:13], v[110:113], v[226:229], v[10:13]
	s_setprio 0
	s_setprio 1
	v_mfma_f32_16x16x32_bf16 v[54:57], v[182:185], v[198:201], v[54:57]
	v_mfma_f32_16x16x32_bf16 v[50:53], v[190:193], v[198:201], v[50:53]
	v_mfma_f32_16x16x32_bf16 v[38:41], v[182:185], v[206:209], v[38:41]
	v_mfma_f32_16x16x32_bf16 v[34:37], v[190:193], v[206:209], v[34:37]
	v_mfma_f32_16x16x32_bf16 v[22:25], v[182:185], v[214:217], v[22:25]
	v_mfma_f32_16x16x32_bf16 v[18:21], v[190:193], v[214:217], v[18:21]
	v_mfma_f32_16x16x32_bf16 v[6:9], v[182:185], v[222:225], v[6:9]
	v_mfma_f32_16x16x32_bf16 v[2:5], v[190:193], v[222:225], v[2:5]
	v_mfma_f32_16x16x32_bf16 v[54:57], v[186:189], v[202:205], v[54:57]
	v_mfma_f32_16x16x32_bf16 v[50:53], v[194:197], v[202:205], v[50:53]
	v_mfma_f32_16x16x32_bf16 v[38:41], v[186:189], v[210:213], v[38:41]
	v_mfma_f32_16x16x32_bf16 v[34:37], v[194:197], v[210:213], v[34:37]
	v_mfma_f32_16x16x32_bf16 v[22:25], v[186:189], v[218:221], v[22:25]
	v_mfma_f32_16x16x32_bf16 v[18:21], v[194:197], v[218:221], v[18:21]
	v_mfma_f32_16x16x32_bf16 v[6:9], v[186:189], v[226:229], v[6:9]
	v_mfma_f32_16x16x32_bf16 v[2:5], v[194:197], v[226:229], v[2:5]
	s_setprio 0
	s_barrier
	s_add_i32 s12, s12, 2
	s_add_u32 s0, s0, 0x100
	s_addc_u32 s1, s1, 0
	s_add_u32 s68, s68, 0x100
	s_addc_u32 s69, s69, 0
	s_cmp_gt_u32 s12, 13
	s_cbranch_scc0 .LBB0_1479
	s_and_b64 vcc, exec, s[24:25]
	s_cbranch_vccz .LBB0_1482
	s_barrier

.LBB0_1560:
	s_add_u32 s27, s30, 0x100
	v_mov_b32_e32 v2, 0
	s_addc_u32 s67, s31, 0
	s_mov_b32 s12, -2
	s_waitcnt lgkmcnt(0)
	v_mov_b32_e32 v3, v2
	v_mov_b32_e32 v4, v2
	v_mov_b32_e32 v5, v2
	v_mov_b32_e32 v6, v2
	v_mov_b32_e32 v7, v2
	v_mov_b32_e32 v8, v2
	v_mov_b32_e32 v9, v2
	v_mov_b32_e32 v10, v2
	v_mov_b32_e32 v11, v2
	v_mov_b32_e32 v12, v2
	v_mov_b32_e32 v13, v2
	v_mov_b32_e32 v14, v2
	v_mov_b32_e32 v15, v2
	v_mov_b32_e32 v16, v2
	v_mov_b32_e32 v17, v2
	v_mov_b32_e32 v18, v2
	v_mov_b32_e32 v19, v2
	v_mov_b32_e32 v20, v2
	v_mov_b32_e32 v21, v2
	v_mov_b32_e32 v22, v2
	v_mov_b32_e32 v23, v2
	v_mov_b32_e32 v24, v2
	v_mov_b32_e32 v25, v2
	v_mov_b32_e32 v26, v2
	v_mov_b32_e32 v27, v2
	v_mov_b32_e32 v28, v2
	v_mov_b32_e32 v29, v2
	v_mov_b32_e32 v30, v2
	v_mov_b32_e32 v31, v2
	v_mov_b32_e32 v32, v2
	v_mov_b32_e32 v33, v2
	v_mov_b32_e32 v66, v2
	v_mov_b32_e32 v67, v2
	v_mov_b32_e32 v68, v2
	v_mov_b32_e32 v69, v2
	v_mov_b32_e32 v70, v2
	v_mov_b32_e32 v71, v2
	v_mov_b32_e32 v72, v2
	v_mov_b32_e32 v73, v2
	v_mov_b32_e32 v74, v2
	v_mov_b32_e32 v75, v2
	v_mov_b32_e32 v76, v2
	v_mov_b32_e32 v77, v2
	v_mov_b32_e32 v78, v2
	v_mov_b32_e32 v79, v2
	v_mov_b32_e32 v80, v2
	v_mov_b32_e32 v81, v2
	v_mov_b32_e32 v82, v2
	v_mov_b32_e32 v83, v2
	v_mov_b32_e32 v84, v2
	v_mov_b32_e32 v85, v2
	v_mov_b32_e32 v86, v2
	v_mov_b32_e32 v87, v2
	v_mov_b32_e32 v88, v2
	v_mov_b32_e32 v89, v2
	v_mov_b32_e32 v90, v2
	v_mov_b32_e32 v91, v2
	v_mov_b32_e32 v92, v2
	v_mov_b32_e32 v93, v2
	v_mov_b32_e32 v94, v2
	v_mov_b32_e32 v95, v2
	v_mov_b32_e32 v96, v2
	v_mov_b32_e32 v97, v2
	v_mov_b32_e32 v34, v2
	v_mov_b32_e32 v35, v2
	v_mov_b32_e32 v36, v2
	v_mov_b32_e32 v37, v2
	v_mov_b32_e32 v38, v2
	v_mov_b32_e32 v39, v2
	v_mov_b32_e32 v40, v2
	v_mov_b32_e32 v41, v2
	v_mov_b32_e32 v42, v2
	v_mov_b32_e32 v43, v2
	v_mov_b32_e32 v44, v2
	v_mov_b32_e32 v45, v2
	v_mov_b32_e32 v46, v2
	v_mov_b32_e32 v47, v2
	v_mov_b32_e32 v48, v2
	v_mov_b32_e32 v49, v2
	v_mov_b32_e32 v50, v2
	v_mov_b32_e32 v51, v2
	v_mov_b32_e32 v52, v2
	v_mov_b32_e32 v53, v2
	v_mov_b32_e32 v54, v2
	v_mov_b32_e32 v55, v2
	v_mov_b32_e32 v56, v2
	v_mov_b32_e32 v57, v2
	v_mov_b32_e32 v58, v2
	v_mov_b32_e32 v59, v2
	v_mov_b32_e32 v60, v2
	v_mov_b32_e32 v61, v2
	v_mov_b32_e32 v62, v2
	v_mov_b32_e32 v63, v2
	v_mov_b32_e32 v64, v2
	v_mov_b32_e32 v65, v2
	v_mov_b32_e32 v98, v2
	v_mov_b32_e32 v99, v2
	v_mov_b32_e32 v100, v2
	v_mov_b32_e32 v101, v2
	v_mov_b32_e32 v102, v2
	v_mov_b32_e32 v103, v2
	v_mov_b32_e32 v104, v2
	v_mov_b32_e32 v105, v2
	v_mov_b32_e32 v106, v2
	v_mov_b32_e32 v107, v2
	v_mov_b32_e32 v108, v2
	v_mov_b32_e32 v109, v2
	v_mov_b32_e32 v110, v2
	v_mov_b32_e32 v111, v2
	v_mov_b32_e32 v112, v2
	v_mov_b32_e32 v113, v2
	v_mov_b32_e32 v114, v2
	v_mov_b32_e32 v115, v2
	v_mov_b32_e32 v116, v2
	v_mov_b32_e32 v117, v2
	v_mov_b32_e32 v118, v2
	v_mov_b32_e32 v119, v2
	v_mov_b32_e32 v120, v2
	v_mov_b32_e32 v121, v2
	v_mov_b32_e32 v122, v2
	v_mov_b32_e32 v123, v2
	v_mov_b32_e32 v124, v2
	v_mov_b32_e32 v125, v2
	v_mov_b32_e32 v126, v2
	v_mov_b32_e32 v127, v2
	v_mov_b32_e32 v128, v2
	v_mov_b32_e32 v129, v2
	v_add_u32_e32 v251, 0x80, v140
	v_add_u32_e32 v252, 0x80, v144
	v_add_u32_e32 v253, 0x80, v138
	v_add_u32_e32 v254, 0x80, v142
.LBB0_1561:
	ds_read_b128 v[130:133], v228
	ds_read_b128 v[134:137], v228 offset:1024
	ds_read_b128 v[154:157], v228 offset:2048
	ds_read_b128 v[158:161], v228 offset:3072
	ds_read_b128 v[162:165], v229
	ds_read_b128 v[166:169], v229 offset:1024
	ds_read_b128 v[170:173], v229 offset:2048
	ds_read_b128 v[174:177], v229 offset:3072
	s_add_u32 s30, s28, 0x100
	s_addc_u32 s31, s29, 0
	s_cmp_eq_u32 s12, 40
	s_cselect_b32 s39, s1, s31
	s_cselect_b32 s38, s0, s30
	s_cselect_b32 s37, s9, s67
	s_cselect_b32 s36, s8, s27
	v_lshl_add_u64 v[210:211], s[28:29], 0, v[146:147]
	s_add_i32 m0, s41, 0xc000
	ds_read_b128 v[178:181], v230
	ds_read_b128 v[182:185], v230 offset:1024
	ds_read_b128 v[186:189], v230 offset:2048
	ds_read_b128 v[190:193], v230 offset:3072
	ds_read_b128 v[194:197], v230 offset:4096
	ds_read_b128 v[198:201], v230 offset:5120
	ds_read_b128 v[202:205], v230 offset:6144
	ds_read_b128 v[206:209], v230 offset:7168
	global_load_lds_dwordx4 v[210:211], off
	v_lshl_add_u64 v[210:211], s[28:29], 0, v[148:149]
	s_add_i32 m0, s41, 0xe000
	s_nop 0
	global_load_lds_dwordx4 v[210:211], off
	s_waitcnt vmcnt(8)
	s_waitcnt lgkmcnt(0)
	s_barrier
	s_setprio 1
	s_waitcnt lgkmcnt(0)
	v_mfma_f32_16x16x32_bf16 v[126:129], v[130:133], v[178:181], v[126:129]
	v_mfma_f32_16x16x32_bf16 v[122:125], v[154:157], v[178:181], v[122:125]
	v_mfma_f32_16x16x32_bf16 v[118:121], v[130:133], v[186:189], v[118:121]
	v_mfma_f32_16x16x32_bf16 v[114:117], v[154:157], v[186:189], v[114:117]
	v_mfma_f32_16x16x32_bf16 v[110:113], v[130:133], v[194:197], v[110:113]
	v_mfma_f32_16x16x32_bf16 v[106:109], v[154:157], v[194:197], v[106:109]
	v_mfma_f32_16x16x32_bf16 v[102:105], v[130:133], v[202:205], v[102:105]
	v_mfma_f32_16x16x32_bf16 v[98:101], v[154:157], v[202:205], v[98:101]
	v_mfma_f32_16x16x32_bf16 v[126:129], v[134:137], v[182:185], v[126:129]
	v_mfma_f32_16x16x32_bf16 v[122:125], v[158:161], v[182:185], v[122:125]
	v_mfma_f32_16x16x32_bf16 v[118:121], v[134:137], v[190:193], v[118:121]
	v_mfma_f32_16x16x32_bf16 v[114:117], v[158:161], v[190:193], v[114:117]
	v_mfma_f32_16x16x32_bf16 v[110:113], v[134:137], v[198:201], v[110:113]
	v_mfma_f32_16x16x32_bf16 v[106:109], v[158:161], v[198:201], v[106:109]
	v_mfma_f32_16x16x32_bf16 v[102:105], v[134:137], v[206:209], v[102:105]
	v_mfma_f32_16x16x32_bf16 v[98:101], v[158:161], v[206:209], v[98:101]
	s_setprio 0
	s_setprio 1
	v_mfma_f32_16x16x32_bf16 v[62:65], v[162:165], v[178:181], v[62:65]
	v_mfma_f32_16x16x32_bf16 v[58:61], v[170:173], v[178:181], v[58:61]
	v_mfma_f32_16x16x32_bf16 v[54:57], v[162:165], v[186:189], v[54:57]
	v_mfma_f32_16x16x32_bf16 v[50:53], v[170:173], v[186:189], v[50:53]
	v_mfma_f32_16x16x32_bf16 v[46:49], v[162:165], v[194:197], v[46:49]
	v_mfma_f32_16x16x32_bf16 v[42:45], v[170:173], v[194:197], v[42:45]
	v_mfma_f32_16x16x32_bf16 v[38:41], v[162:165], v[202:205], v[38:41]
	v_mfma_f32_16x16x32_bf16 v[34:37], v[170:173], v[202:205], v[34:37]
	v_mfma_f32_16x16x32_bf16 v[62:65], v[166:169], v[182:185], v[62:65]
	v_mfma_f32_16x16x32_bf16 v[58:61], v[174:177], v[182:185], v[58:61]
	v_mfma_f32_16x16x32_bf16 v[54:57], v[166:169], v[190:193], v[54:57]
	v_mfma_f32_16x16x32_bf16 v[50:53], v[174:177], v[190:193], v[50:53]
	v_mfma_f32_16x16x32_bf16 v[46:49], v[166:169], v[198:201], v[46:49]
	v_mfma_f32_16x16x32_bf16 v[42:45], v[174:177], v[198:201], v[42:45]
	v_mfma_f32_16x16x32_bf16 v[38:41], v[166:169], v[206:209], v[38:41]
	v_mfma_f32_16x16x32_bf16 v[34:37], v[174:177], v[206:209], v[34:37]
	s_setprio 0
	s_barrier
	s_add_i32 s13, s60, s40
	s_nop 0
	s_mov_b32 m0, s13
	ds_read_b128 v[178:181], v230 offset:16384
	ds_read_b128 v[182:185], v230 offset:17408
	ds_read_b128 v[186:189], v230 offset:18432
	ds_read_b128 v[190:193], v230 offset:19456
	ds_read_b128 v[194:197], v230 offset:20480
	ds_read_b128 v[198:201], v230 offset:21504
	ds_read_b128 v[202:205], v230 offset:22528
	ds_read_b128 v[206:209], v230 offset:23552
	global_load_lds_dwordx4 v140, s[36:37]
	s_add_i32 m0, s13, 0x2000
	s_add_u32 s28, s36, 0xb0000
	v_lshl_add_u64 v[212:213], s[36:37], 0, v[144:145]
	s_addc_u32 s29, s37, 0
	s_add_i32 s13, s61, s40
	global_load_lds_dwordx4 v144, s[36:37]
	s_nop 0
	s_mov_b32 m0, s13
	v_lshl_add_u64 v[216:217], s[38:39], 0, v[142:143]
	global_load_lds_dwordx4 v140, s[28:29]
	s_nop 0
	s_add_i32 m0, s13, 0x2000
	s_nop 0
	global_load_lds_dwordx4 v144, s[28:29]
	s_nop 0
	s_mov_b32 m0, s41
	s_nop 0
	global_load_lds_dwordx4 v138, s[38:39]
	s_mov_b32 m0, s42
	s_nop 0
	global_load_lds_dwordx4 v142, s[38:39]
	s_waitcnt vmcnt(8)
	s_waitcnt lgkmcnt(0)
	s_barrier
	s_setprio 1
	s_waitcnt lgkmcnt(0)
	v_mfma_f32_16x16x32_bf16 v[94:97], v[130:133], v[178:181], v[94:97]
	v_mfma_f32_16x16x32_bf16 v[90:93], v[154:157], v[178:181], v[90:93]
	v_mfma_f32_16x16x32_bf16 v[86:89], v[130:133], v[186:189], v[86:89]
	v_mfma_f32_16x16x32_bf16 v[82:85], v[154:157], v[186:189], v[82:85]
	v_mfma_f32_16x16x32_bf16 v[78:81], v[130:133], v[194:197], v[78:81]
	v_mfma_f32_16x16x32_bf16 v[74:77], v[154:157], v[194:197], v[74:77]
	v_mfma_f32_16x16x32_bf16 v[70:73], v[130:133], v[202:205], v[70:73]
	v_mfma_f32_16x16x32_bf16 v[66:69], v[154:157], v[202:205], v[66:69]
	v_mfma_f32_16x16x32_bf16 v[94:97], v[134:137], v[182:185], v[94:97]
	v_mfma_f32_16x16x32_bf16 v[90:93], v[158:161], v[182:185], v[90:93]
	v_mfma_f32_16x16x32_bf16 v[86:89], v[134:137], v[190:193], v[86:89]
	v_mfma_f32_16x16x32_bf16 v[82:85], v[158:161], v[190:193], v[82:85]
	v_mfma_f32_16x16x32_bf16 v[78:81], v[134:137], v[198:201], v[78:81]
	v_mfma_f32_16x16x32_bf16 v[74:77], v[158:161], v[198:201], v[74:77]
	v_mfma_f32_16x16x32_bf16 v[70:73], v[134:137], v[206:209], v[70:73]
	v_mfma_f32_16x16x32_bf16 v[66:69], v[158:161], v[206:209], v[66:69]
	s_setprio 0
	s_setprio 1
	v_mfma_f32_16x16x32_bf16 v[30:33], v[162:165], v[178:181], v[30:33]
	v_mfma_f32_16x16x32_bf16 v[26:29], v[170:173], v[178:181], v[26:29]
	v_mfma_f32_16x16x32_bf16 v[22:25], v[162:165], v[186:189], v[22:25]
	v_mfma_f32_16x16x32_bf16 v[18:21], v[170:173], v[186:189], v[18:21]
	v_mfma_f32_16x16x32_bf16 v[14:17], v[162:165], v[194:197], v[14:17]
	v_mfma_f32_16x16x32_bf16 v[10:13], v[170:173], v[194:197], v[10:13]
	v_mfma_f32_16x16x32_bf16 v[6:9], v[162:165], v[202:205], v[6:9]
	v_mfma_f32_16x16x32_bf16 v[2:5], v[170:173], v[202:205], v[2:5]
	v_mfma_f32_16x16x32_bf16 v[30:33], v[166:169], v[182:185], v[30:33]
	v_mfma_f32_16x16x32_bf16 v[26:29], v[174:177], v[182:185], v[26:29]
	v_mfma_f32_16x16x32_bf16 v[22:25], v[166:169], v[190:193], v[22:25]
	v_mfma_f32_16x16x32_bf16 v[18:21], v[174:177], v[190:193], v[18:21]
	v_mfma_f32_16x16x32_bf16 v[14:17], v[166:169], v[198:201], v[14:17]
	v_mfma_f32_16x16x32_bf16 v[10:13], v[174:177], v[198:201], v[10:13]
	v_mfma_f32_16x16x32_bf16 v[6:9], v[166:169], v[206:209], v[6:9]
	v_mfma_f32_16x16x32_bf16 v[2:5], v[174:177], v[206:209], v[2:5]
	s_setprio 0
	s_barrier
	s_add_i32 s13, 0, 0x18000
	s_add_i32 s68, 0, 0x1c000
	v_add_u32_e32 v158, s13, v226
	v_add_u32_e32 v174, s68, v226
	ds_read_b128 v[130:133], v158
	ds_read_b128 v[134:137], v158 offset:1024
	ds_read_b128 v[154:157], v158 offset:2048
	ds_read_b128 v[158:161], v158 offset:3072
	ds_read_b128 v[162:165], v174
	ds_read_b128 v[166:169], v174 offset:1024
	ds_read_b128 v[170:173], v174 offset:2048
	ds_read_b128 v[174:177], v174 offset:3072
	s_add_u32 s28, s38, 0xb0000
	s_addc_u32 s29, s39, 0
	s_mov_b32 m0, s43
	s_nop 0
	ds_read_b128 v[178:181], v230 offset:32768
	ds_read_b128 v[182:185], v230 offset:33792
	ds_read_b128 v[186:189], v230 offset:34816
	ds_read_b128 v[190:193], v230 offset:35840
	ds_read_b128 v[194:197], v230 offset:36864
	ds_read_b128 v[198:201], v230 offset:37888
	ds_read_b128 v[202:205], v230 offset:38912
	ds_read_b128 v[206:209], v230 offset:39936
	global_load_lds_dwordx4 v138, s[28:29]
	s_nop 0
	s_mov_b32 m0, s44
	s_nop 0
	global_load_lds_dwordx4 v142, s[28:29]
	s_waitcnt vmcnt(8)
	s_waitcnt lgkmcnt(0)
	s_barrier
	s_setprio 1
	s_waitcnt lgkmcnt(0)
	v_mfma_f32_16x16x32_bf16 v[126:129], v[130:133], v[178:181], v[126:129]
	v_mfma_f32_16x16x32_bf16 v[122:125], v[154:157], v[178:181], v[122:125]
	v_mfma_f32_16x16x32_bf16 v[118:121], v[130:133], v[186:189], v[118:121]
	v_mfma_f32_16x16x32_bf16 v[114:117], v[154:157], v[186:189], v[114:117]
	v_mfma_f32_16x16x32_bf16 v[110:113], v[130:133], v[194:197], v[110:113]
	v_mfma_f32_16x16x32_bf16 v[106:109], v[154:157], v[194:197], v[106:109]
	v_mfma_f32_16x16x32_bf16 v[102:105], v[130:133], v[202:205], v[102:105]
	v_mfma_f32_16x16x32_bf16 v[98:101], v[154:157], v[202:205], v[98:101]
	v_mfma_f32_16x16x32_bf16 v[126:129], v[134:137], v[182:185], v[126:129]
	v_mfma_f32_16x16x32_bf16 v[122:125], v[158:161], v[182:185], v[122:125]
	v_mfma_f32_16x16x32_bf16 v[118:121], v[134:137], v[190:193], v[118:121]
	v_mfma_f32_16x16x32_bf16 v[114:117], v[158:161], v[190:193], v[114:117]
	v_mfma_f32_16x16x32_bf16 v[110:113], v[134:137], v[198:201], v[110:113]
	v_mfma_f32_16x16x32_bf16 v[106:109], v[158:161], v[198:201], v[106:109]
	v_mfma_f32_16x16x32_bf16 v[102:105], v[134:137], v[206:209], v[102:105]
	v_mfma_f32_16x16x32_bf16 v[98:101], v[158:161], v[206:209], v[98:101]
	s_setprio 0
	s_setprio 1
	v_mfma_f32_16x16x32_bf16 v[62:65], v[162:165], v[178:181], v[62:65]
	v_mfma_f32_16x16x32_bf16 v[58:61], v[170:173], v[178:181], v[58:61]
	v_mfma_f32_16x16x32_bf16 v[54:57], v[162:165], v[186:189], v[54:57]
	v_mfma_f32_16x16x32_bf16 v[50:53], v[170:173], v[186:189], v[50:53]
	v_mfma_f32_16x16x32_bf16 v[46:49], v[162:165], v[194:197], v[46:49]
	v_mfma_f32_16x16x32_bf16 v[42:45], v[170:173], v[194:197], v[42:45]
	v_mfma_f32_16x16x32_bf16 v[38:41], v[162:165], v[202:205], v[38:41]
	v_mfma_f32_16x16x32_bf16 v[34:37], v[170:173], v[202:205], v[34:37]
	v_mfma_f32_16x16x32_bf16 v[62:65], v[166:169], v[182:185], v[62:65]
	v_mfma_f32_16x16x32_bf16 v[58:61], v[174:177], v[182:185], v[58:61]
	v_mfma_f32_16x16x32_bf16 v[54:57], v[166:169], v[190:193], v[54:57]
	v_mfma_f32_16x16x32_bf16 v[50:53], v[174:177], v[190:193], v[50:53]
	v_mfma_f32_16x16x32_bf16 v[46:49], v[166:169], v[198:201], v[46:49]
	v_mfma_f32_16x16x32_bf16 v[42:45], v[174:177], v[198:201], v[42:45]
	v_mfma_f32_16x16x32_bf16 v[38:41], v[166:169], v[206:209], v[38:41]
	v_mfma_f32_16x16x32_bf16 v[34:37], v[174:177], v[206:209], v[34:37]
	s_setprio 0
	s_barrier
	s_add_i32 s13, s13, s40
	s_nop 0
	s_mov_b32 m0, s13
	ds_read_b128 v[178:181], v230 offset:49152
	ds_read_b128 v[182:185], v230 offset:50176
	ds_read_b128 v[186:189], v230 offset:51200
	ds_read_b128 v[190:193], v230 offset:52224
	ds_read_b128 v[194:197], v230 offset:53248
	ds_read_b128 v[198:201], v230 offset:54272
	ds_read_b128 v[202:205], v230 offset:55296
	ds_read_b128 v[206:209], v230 offset:56320
	global_load_lds_dwordx4 v251, s[36:37]
	s_add_i32 m0, s13, 0x2000
	s_add_u32 s28, s36, 0xb0080
	s_nop 0
	s_addc_u32 s29, s37, 0
	s_add_i32 s13, s68, s40
	global_load_lds_dwordx4 v252, s[36:37]
	s_nop 0
	s_mov_b32 m0, s13
	s_nop 0
	global_load_lds_dwordx4 v140, s[28:29]
	s_nop 0
	s_add_i32 m0, s13, 0x2000
	s_nop 0
	global_load_lds_dwordx4 v144, s[28:29]
	s_nop 0
	s_mov_b32 m0, s57
	s_nop 0
	global_load_lds_dwordx4 v253, s[38:39]
	s_nop 0
	s_mov_b32 m0, s58
	s_nop 0
	global_load_lds_dwordx4 v254, s[38:39]
	s_waitcnt vmcnt(8)
	s_waitcnt lgkmcnt(0)
	s_barrier
	s_setprio 1
	s_waitcnt lgkmcnt(0)
	v_mfma_f32_16x16x32_bf16 v[94:97], v[130:133], v[178:181], v[94:97]
	v_mfma_f32_16x16x32_bf16 v[90:93], v[154:157], v[178:181], v[90:93]
	v_mfma_f32_16x16x32_bf16 v[86:89], v[130:133], v[186:189], v[86:89]
	v_mfma_f32_16x16x32_bf16 v[82:85], v[154:157], v[186:189], v[82:85]
	v_mfma_f32_16x16x32_bf16 v[78:81], v[130:133], v[194:197], v[78:81]
	v_mfma_f32_16x16x32_bf16 v[74:77], v[154:157], v[194:197], v[74:77]
	v_mfma_f32_16x16x32_bf16 v[70:73], v[130:133], v[202:205], v[70:73]
	v_mfma_f32_16x16x32_bf16 v[66:69], v[154:157], v[202:205], v[66:69]
	v_mfma_f32_16x16x32_bf16 v[94:97], v[134:137], v[182:185], v[94:97]
	v_mfma_f32_16x16x32_bf16 v[90:93], v[158:161], v[182:185], v[90:93]
	v_mfma_f32_16x16x32_bf16 v[86:89], v[134:137], v[190:193], v[86:89]
	v_mfma_f32_16x16x32_bf16 v[82:85], v[158:161], v[190:193], v[82:85]
	v_mfma_f32_16x16x32_bf16 v[78:81], v[134:137], v[198:201], v[78:81]
	v_mfma_f32_16x16x32_bf16 v[74:77], v[158:161], v[198:201], v[74:77]
	v_mfma_f32_16x16x32_bf16 v[70:73], v[134:137], v[206:209], v[70:73]
	v_mfma_f32_16x16x32_bf16 v[66:69], v[158:161], v[206:209], v[66:69]
	s_setprio 0
	s_setprio 1
	v_mfma_f32_16x16x32_bf16 v[30:33], v[162:165], v[178:181], v[30:33]
	v_mfma_f32_16x16x32_bf16 v[26:29], v[170:173], v[178:181], v[26:29]
	v_mfma_f32_16x16x32_bf16 v[22:25], v[162:165], v[186:189], v[22:25]
	v_mfma_f32_16x16x32_bf16 v[18:21], v[170:173], v[186:189], v[18:21]
	v_mfma_f32_16x16x32_bf16 v[14:17], v[162:165], v[194:197], v[14:17]
	v_mfma_f32_16x16x32_bf16 v[10:13], v[170:173], v[194:197], v[10:13]
	v_mfma_f32_16x16x32_bf16 v[6:9], v[162:165], v[202:205], v[6:9]
	v_mfma_f32_16x16x32_bf16 v[2:5], v[170:173], v[202:205], v[2:5]
	v_mfma_f32_16x16x32_bf16 v[30:33], v[166:169], v[182:185], v[30:33]
	v_mfma_f32_16x16x32_bf16 v[26:29], v[174:177], v[182:185], v[26:29]
	v_mfma_f32_16x16x32_bf16 v[22:25], v[166:169], v[190:193], v[22:25]
	v_mfma_f32_16x16x32_bf16 v[18:21], v[174:177], v[190:193], v[18:21]
	v_mfma_f32_16x16x32_bf16 v[14:17], v[166:169], v[198:201], v[14:17]
	v_mfma_f32_16x16x32_bf16 v[10:13], v[174:177], v[198:201], v[10:13]
	v_mfma_f32_16x16x32_bf16 v[6:9], v[166:169], v[206:209], v[6:9]
	v_mfma_f32_16x16x32_bf16 v[2:5], v[174:177], v[206:209], v[2:5]
	s_setprio 0
	s_barrier
	s_add_i32 s12, s12, 2
	s_add_u32 s27, s27, 0x100
	s_addc_u32 s67, s67, 0
	s_cmp_gt_u32 s12, 41
	s_mov_b64 s[28:29], s[30:31]
	s_cbranch_scc0 .LBB0_1561
	s_ashr_i32 s12, s26, 3
	s_ashr_i32 s27, s26, 31
	s_mul_i32 s37, s12, 0x6000
	s_mul_hi_i32 s36, s12, 0x6000
	s_add_u32 s12, s54, s37
	v_mov_b32_e32 v130, v1
	s_addc_u32 s13, s55, s36
	s_lshl_b64 s[28:29], s[26:27], 19
	v_lshl_or_b32 v166, s66, 8, v227
	s_add_u32 s30, s46, s28
	v_add_u32_e32 v160, s56, v130
	v_ashrrev_i32_e32 v167, 31, v166
	s_addc_u32 s31, s47, s29
	v_lshlrev_b64 v[156:157], 1, v[166:167]
	v_ashrrev_i32_e32 v161, 31, v160
	v_lshlrev_b64 v[130:131], 2, v[166:167]
	v_lshl_add_u64 v[162:163], s[30:31], 0, v[156:157]
	v_lshlrev_b64 v[154:155], 11, v[160:161]
	v_add_u32_e32 v170, 16, v160
	v_lshl_add_u64 v[172:173], s[12:13], 0, v[130:131]
	v_lshl_add_u64 v[174:175], v[162:163], 0, v[154:155]
	v_ashrrev_i32_e32 v171, 31, v170
	s_add_u32 s12, s48, s28
	v_lshl_add_u64 v[132:133], s[16:17], 0, v[130:131]
	global_load_dwordx4 v[180:183], v[172:173], off offset:16
	global_load_dwordx4 v[184:187], v[172:173], off
	global_load_dwordx4 v[188:191], v[132:133], off offset:16
	global_load_dwordx4 v[192:195], v[132:133], off
	global_load_dwordx4 v[196:199], v[174:175], off nt
	v_lshlrev_b64 v[204:205], 11, v[170:171]
	s_addc_u32 s13, s49, s29
	v_lshl_add_u64 v[178:179], v[162:163], 0, v[204:205]
	s_add_u32 s28, s50, s37
	global_load_dwordx4 v[200:203], v[178:179], off nt
	s_addc_u32 s29, s51, s36
	v_lshl_add_u64 v[176:177], s[28:29], 0, v[130:131]
	global_load_dwordx4 v[134:137], v[176:177], off
	global_load_dwordx4 v[130:133], v[176:177], off offset:16
	v_lshl_add_u64 v[158:159], s[12:13], 0, v[156:157]
	s_lshl_b32 s12, s26, 8
	v_lshl_add_u64 v[164:165], v[158:159], 0, v[154:155]
	v_add_u32_e32 v154, s12, v160
	v_ashrrev_i32_e32 v155, 31, v154
	v_lshlrev_b64 v[168:169], 11, v[154:155]
	v_lshl_add_u64 v[168:169], s[10:11], 0, v[168:169]
	v_add_u32_e32 v170, s12, v170
	v_lshl_add_u64 v[168:169], v[168:169], 0, v[156:157]
	v_ashrrev_i32_e32 v171, 31, v170
	v_lshlrev_b64 v[170:171], 11, v[170:171]
	v_lshl_add_u64 v[170:171], s[10:11], 0, v[170:171]
	s_waitcnt vmcnt(0)
	v_pk_add_f32 v[182:183], v[182:183], 1.0 op_sel_hi:[1,0]
	v_pk_add_f32 v[186:187], v[186:187], 1.0 op_sel_hi:[1,0]
	v_pk_add_f32 v[184:185], v[184:185], 1.0 op_sel_hi:[1,0]
	v_pk_add_f32 v[180:181], v[180:181], 1.0 op_sel_hi:[1,0]
	v_pk_mul_f32 v[216:217], v[194:195], v[186:187]
	v_pk_mul_f32 v[218:219], v[192:193], v[184:185]
	v_pk_mul_f32 v[220:221], v[190:191], v[182:183]
	v_pk_mul_f32 v[222:223], v[188:189], v[180:181]
	v_cvt_f32_f16_e32 v180, v198
	v_cvt_f32_f16_sdwa v181, v198 dst_sel:DWORD dst_unused:UNUSED_PAD src0_sel:WORD_1
	v_cvt_f32_f16_e32 v182, v199
	v_cvt_f32_f16_sdwa v183, v199 dst_sel:DWORD dst_unused:UNUSED_PAD src0_sel:WORD_1
	v_cvt_f32_f16_e32 v184, v196
	v_cvt_f32_f16_sdwa v185, v196 dst_sel:DWORD dst_unused:UNUSED_PAD src0_sel:WORD_1
	v_cvt_f32_f16_e32 v186, v197
	v_cvt_f32_f16_sdwa v187, v197 dst_sel:DWORD dst_unused:UNUSED_PAD src0_sel:WORD_1
	v_cvt_f32_f16_e32 v188, v202
	v_cvt_f32_f16_sdwa v189, v202 dst_sel:DWORD dst_unused:UNUSED_PAD src0_sel:WORD_1
	v_cvt_f32_f16_e32 v190, v203
	v_cvt_f32_f16_sdwa v191, v203 dst_sel:DWORD dst_unused:UNUSED_PAD src0_sel:WORD_1
	v_cvt_f32_f16_e32 v192, v200
	v_cvt_f32_f16_sdwa v193, v200 dst_sel:DWORD dst_unused:UNUSED_PAD src0_sel:WORD_1
	v_cvt_f32_f16_e32 v194, v201
	v_cvt_f32_f16_sdwa v195, v201 dst_sel:DWORD dst_unused:UNUSED_PAD src0_sel:WORD_1
	v_pk_fma_f32 v[128:129], v[128:129], v[136:137], v[186:187]
	v_pk_fma_f32 v[126:127], v[126:127], v[134:135], v[184:185]
	v_pk_fma_f32 v[124:125], v[124:125], v[132:133], v[182:183]
	v_pk_fma_f32 v[122:123], v[122:123], v[130:131], v[180:181]
	v_cvt_pk_f16_f32 v183, v124, v125
	v_cvt_pk_f16_f32 v181, v128, v129
	v_cvt_pk_f16_f32 v182, v122, v123
	v_cvt_pk_f16_f32 v180, v126, v127
	v_pk_fma_f32 v[120:121], v[120:121], v[136:137], v[194:195]
	v_pk_fma_f32 v[118:119], v[118:119], v[134:135], v[192:193]
	v_pk_fma_f32 v[116:117], v[116:117], v[132:133], v[190:191]
	v_pk_fma_f32 v[114:115], v[114:115], v[130:131], v[188:189]
	v_pk_mul_f32 v[188:189], v[216:217], v[128:129]
	v_pk_mul_f32 v[190:191], v[218:219], v[126:127]
	global_store_dwordx4 v[164:165], v[180:183], off
	v_pk_mul_f32 v[192:193], v[220:221], v[124:125]
	v_pk_mul_f32 v[194:195], v[222:223], v[122:123]
	v_cvt_pk_bf16_f32 v180, v190, v191
	v_cvt_pk_bf16_f32 v181, v188, v189
	v_cvt_pk_f16_f32 v187, v116, v117
	v_cvt_pk_f16_f32 v185, v120, v121
	v_cvt_pk_f16_f32 v186, v114, v115
	v_cvt_pk_bf16_f32 v182, v194, v195
	v_cvt_pk_bf16_f32 v183, v192, v193
	global_store_dwordx4 v[168:169], v[180:183], off
	v_cvt_pk_f16_f32 v184, v118, v119
	v_pk_mul_f32 v[188:189], v[222:223], v[114:115]
	v_lshl_add_u64 v[180:181], v[158:159], 0, v[204:205]
	global_store_dwordx4 v[180:181], v[184:187], off
	v_pk_mul_f32 v[182:183], v[218:219], v[118:119]
	v_add_u32_e32 v192, 48, v160
	v_pk_mul_f32 v[184:185], v[216:217], v[120:121]
	v_pk_mul_f32 v[186:187], v[220:221], v[116:117]
	v_cvt_pk_bf16_f32 v182, v182, v183
	v_cvt_pk_bf16_f32 v183, v184, v185
	v_cvt_pk_bf16_f32 v184, v188, v189
	v_ashrrev_i32_e32 v193, 31, v192
	v_cvt_pk_bf16_f32 v185, v186, v187
	v_lshl_add_u64 v[186:187], v[170:171], 0, v[156:157]
	global_store_dwordx4 v[186:187], v[182:185], off
	v_mul_f32_e32 v127, v127, v127
	v_mul_f32_e32 v129, v129, v129
	v_add_u32_e32 v182, 32, v160
	v_ashrrev_i32_e32 v183, 31, v182
	v_lshlrev_b64 v[170:171], 11, v[182:183]
	v_lshl_add_u64 v[188:189], v[162:163], 0, v[170:171]
	global_load_dwordx4 v[194:197], v[188:189], off nt
	v_lshlrev_b64 v[184:185], 11, v[192:193]
	v_lshl_add_u64 v[190:191], v[162:163], 0, v[184:185]
	global_load_dwordx4 v[198:201], v[190:191], off nt
	v_add_u32_e32 v182, s12, v182
	v_add_u32_e32 v192, s12, v192
	v_ashrrev_i32_e32 v183, 31, v182
	v_ashrrev_i32_e32 v193, 31, v192
	v_lshlrev_b64 v[182:183], 11, v[182:183]
	v_lshlrev_b64 v[192:193], 11, v[192:193]
	v_lshl_add_u64 v[182:183], s[10:11], 0, v[182:183]
	v_lshl_add_u64 v[202:203], s[10:11], 0, v[192:193]
	v_lshl_add_u64 v[192:193], v[182:183], 0, v[156:157]
	v_lshl_add_u64 v[170:171], v[158:159], 0, v[170:171]
	v_lshl_add_u64 v[184:185], v[158:159], 0, v[184:185]
	v_mul_f32_e32 v123, v123, v123
	v_mul_f32_e32 v125, v125, v125
	v_fmac_f32_e32 v127, v126, v126
	v_fmac_f32_e32 v129, v128, v128
	v_fmac_f32_e32 v123, v122, v122
	v_fmac_f32_e32 v125, v124, v124
	v_add_f32_e32 v122, v127, v129
	v_add_f32_e32 v123, v123, v125
	v_add_f32_e32 v122, v122, v123
	s_waitcnt vmcnt(1)
	v_cvt_f32_f16_e32 v182, v196
	v_cvt_f32_f16_sdwa v183, v196 dst_sel:DWORD dst_unused:UNUSED_PAD src0_sel:WORD_1
	v_cvt_f32_f16_e32 v196, v197
	v_cvt_f32_f16_sdwa v197, v197 dst_sel:DWORD dst_unused:UNUSED_PAD src0_sel:WORD_1
	v_cvt_f32_f16_e32 v204, v194
	v_cvt_f32_f16_sdwa v205, v194 dst_sel:DWORD dst_unused:UNUSED_PAD src0_sel:WORD_1
	v_cvt_f32_f16_e32 v194, v195
	v_cvt_f32_f16_sdwa v195, v195 dst_sel:DWORD dst_unused:UNUSED_PAD src0_sel:WORD_1
	s_waitcnt vmcnt(0)
	v_cvt_f32_f16_e32 v206, v200
	v_cvt_f32_f16_sdwa v207, v200 dst_sel:DWORD dst_unused:UNUSED_PAD src0_sel:WORD_1
	v_cvt_f32_f16_e32 v208, v198
	v_cvt_f32_f16_sdwa v209, v198 dst_sel:DWORD dst_unused:UNUSED_PAD src0_sel:WORD_1
	v_cvt_f32_f16_e32 v198, v199
	v_cvt_f32_f16_sdwa v199, v199 dst_sel:DWORD dst_unused:UNUSED_PAD src0_sel:WORD_1
	v_cvt_f32_f16_e32 v200, v201
	v_cvt_f32_f16_sdwa v201, v201 dst_sel:DWORD dst_unused:UNUSED_PAD src0_sel:WORD_1
	v_pk_fma_f32 v[112:113], v[112:113], v[136:137], v[194:195]
	v_pk_fma_f32 v[110:111], v[110:111], v[134:135], v[204:205]
	v_pk_fma_f32 v[108:109], v[108:109], v[132:133], v[196:197]
	v_pk_fma_f32 v[106:107], v[106:107], v[130:131], v[182:183]
	v_cvt_pk_f16_f32 v197, v108, v109
	v_cvt_pk_f16_f32 v195, v112, v113
	v_cvt_pk_f16_f32 v196, v106, v107
	v_cvt_pk_f16_f32 v194, v110, v111
	v_pk_mul_f32 v[182:183], v[216:217], v[112:113]
	v_pk_fma_f32 v[104:105], v[104:105], v[136:137], v[198:199]
	v_pk_fma_f32 v[102:103], v[102:103], v[134:135], v[208:209]
	v_pk_fma_f32 v[98:99], v[98:99], v[130:131], v[206:207]
	v_pk_mul_f32 v[204:205], v[218:219], v[110:111]
	v_pk_mul_f32 v[206:207], v[220:221], v[108:109]
	global_store_dwordx4 v[170:171], v[194:197], off
	v_pk_fma_f32 v[100:101], v[100:101], v[132:133], v[200:201]
	v_pk_mul_f32 v[208:209], v[222:223], v[106:107]
	v_cvt_pk_bf16_f32 v194, v204, v205
	v_cvt_pk_bf16_f32 v195, v182, v183
	v_add_u32_e32 v182, 0x80, v160
	v_cvt_pk_f16_f32 v199, v104, v105
	v_cvt_pk_f16_f32 v198, v102, v103
	v_cvt_pk_bf16_f32 v196, v208, v209
	v_cvt_pk_bf16_f32 v197, v206, v207
	v_ashrrev_i32_e32 v183, 31, v182
	v_add_u32_e32 v206, 0x90, v160
	v_cvt_pk_f16_f32 v201, v100, v101
	v_cvt_pk_f16_f32 v200, v98, v99
	v_pk_mul_f32 v[210:211], v[216:217], v[104:105]
	v_pk_mul_f32 v[212:213], v[218:219], v[102:103]
	global_store_dwordx4 v[192:193], v[194:197], off
	global_store_dwordx4 v[184:185], v[198:201], off
	v_ashrrev_i32_e32 v207, 31, v206
	v_lshl_add_u64 v[196:197], v[202:203], 0, v[156:157]
	v_cvt_pk_bf16_f32 v198, v212, v213
	v_cvt_pk_bf16_f32 v199, v210, v211
	v_lshlrev_b64 v[194:195], 11, v[182:183]
	v_pk_mul_f32 v[214:215], v[220:221], v[100:101]
	v_pk_mul_f32 v[224:225], v[222:223], v[98:99]
	v_lshlrev_b64 v[208:209], 11, v[206:207]
	v_cvt_pk_bf16_f32 v200, v224, v225
	v_cvt_pk_bf16_f32 v201, v214, v215
	global_store_dwordx4 v[196:197], v[198:201], off
	v_lshl_add_u64 v[204:205], v[162:163], 0, v[208:209]
	global_load_dwordx4 v[236:239], v[204:205], off nt
	v_lshl_add_u64 v[198:199], v[162:163], 0, v[194:195]
	global_load_dwordx4 v[232:235], v[198:199], off nt
	v_lshl_add_u64 v[212:213], v[158:159], 0, v[194:195]
	v_add_u32_e32 v182, s12, v182
	v_add_u32_e32 v194, s12, v206
	v_ashrrev_i32_e32 v183, 31, v182
	v_ashrrev_i32_e32 v195, 31, v194
	v_lshlrev_b64 v[182:183], 11, v[182:183]
	v_lshlrev_b64 v[194:195], 11, v[194:195]
	v_lshl_add_u64 v[182:183], s[10:11], 0, v[182:183]
	v_lshl_add_u64 v[194:195], s[10:11], 0, v[194:195]
	v_lshl_add_u64 v[210:211], v[158:159], 0, v[208:209]
	v_lshl_add_u64 v[214:215], v[182:183], 0, v[156:157]
	v_lshl_add_u64 v[208:209], v[194:195], 0, v[156:157]
	v_add_u32_e32 v200, 0xa0, v160
	v_ashrrev_i32_e32 v201, 31, v200
	v_lshlrev_b64 v[240:241], 11, v[200:201]
	v_lshl_add_u64 v[202:203], v[162:163], 0, v[240:241]
	s_waitcnt vmcnt(0)
	v_cvt_f32_f16_e32 v182, v234
	v_cvt_f32_f16_sdwa v183, v234 dst_sel:DWORD dst_unused:UNUSED_PAD src0_sel:WORD_1
	v_cvt_f32_f16_e32 v194, v235
	v_cvt_f32_f16_sdwa v195, v235 dst_sel:DWORD dst_unused:UNUSED_PAD src0_sel:WORD_1
	v_cvt_f32_f16_e32 v206, v232
	v_cvt_f32_f16_sdwa v207, v232 dst_sel:DWORD dst_unused:UNUSED_PAD src0_sel:WORD_1
	v_cvt_f32_f16_e32 v224, v233
	v_cvt_f32_f16_sdwa v225, v233 dst_sel:DWORD dst_unused:UNUSED_PAD src0_sel:WORD_1
	v_cvt_f32_f16_e32 v232, v238
	v_cvt_f32_f16_sdwa v233, v238 dst_sel:DWORD dst_unused:UNUSED_PAD src0_sel:WORD_1
	v_cvt_f32_f16_e32 v234, v239
	v_cvt_f32_f16_sdwa v235, v239 dst_sel:DWORD dst_unused:UNUSED_PAD src0_sel:WORD_1
	v_cvt_f32_f16_e32 v238, v236
	v_cvt_f32_f16_sdwa v239, v236 dst_sel:DWORD dst_unused:UNUSED_PAD src0_sel:WORD_1
	v_cvt_f32_f16_e32 v236, v237
	v_cvt_f32_f16_sdwa v237, v237 dst_sel:DWORD dst_unused:UNUSED_PAD src0_sel:WORD_1
	v_pk_fma_f32 v[96:97], v[96:97], v[136:137], v[224:225]
	v_pk_fma_f32 v[94:95], v[94:95], v[134:135], v[206:207]
	v_pk_fma_f32 v[92:93], v[92:93], v[132:133], v[194:195]
	v_pk_fma_f32 v[90:91], v[90:91], v[130:131], v[182:183]
	v_pk_fma_f32 v[84:85], v[84:85], v[132:133], v[234:235]
	v_pk_fma_f32 v[82:83], v[82:83], v[130:131], v[232:233]
	v_cvt_pk_f16_f32 v235, v92, v93
	v_cvt_pk_f16_f32 v233, v96, v97
	v_cvt_pk_f16_f32 v234, v90, v91
	v_cvt_pk_f16_f32 v232, v94, v95
	v_pk_mul_f32 v[206:207], v[220:221], v[92:93]
	v_pk_mul_f32 v[182:183], v[216:217], v[96:97]
	v_pk_mul_f32 v[194:195], v[218:219], v[94:95]
	v_pk_mul_f32 v[224:225], v[222:223], v[90:91]
	global_store_dwordx4 v[212:213], v[232:235], off
	v_pk_fma_f32 v[88:89], v[88:89], v[136:137], v[236:237]
	v_pk_fma_f32 v[86:87], v[86:87], v[134:135], v[238:239]
	v_cvt_pk_bf16_f32 v232, v194, v195
	v_cvt_pk_bf16_f32 v233, v182, v183
	v_cvt_pk_bf16_f32 v234, v224, v225
	v_cvt_pk_bf16_f32 v235, v206, v207
	v_add_u32_e32 v206, 0xb0, v160
	v_ashrrev_i32_e32 v207, 31, v206
	v_cvt_pk_f16_f32 v239, v84, v85
	v_cvt_pk_f16_f32 v237, v88, v89
	v_cvt_pk_f16_f32 v238, v82, v83
	v_cvt_pk_f16_f32 v236, v86, v87
	v_pk_mul_f32 v[242:243], v[216:217], v[88:89]
	v_pk_mul_f32 v[244:245], v[218:219], v[86:87]
	v_pk_mul_f32 v[246:247], v[220:221], v[84:85]
	v_pk_mul_f32 v[248:249], v[222:223], v[82:83]
	global_store_dwordx4 v[214:215], v[232:235], off
	global_store_dwordx4 v[210:211], v[236:239], off
	v_lshlrev_b64 v[194:195], 11, v[206:207]
	v_cvt_pk_bf16_f32 v232, v244, v245
	v_cvt_pk_bf16_f32 v233, v242, v243
	v_cvt_pk_bf16_f32 v234, v248, v249
	v_cvt_pk_bf16_f32 v235, v246, v247
	global_store_dwordx4 v[208:209], v[232:235], off
	global_load_dwordx4 v[232:235], v[202:203], off nt
	v_lshl_add_u64 v[224:225], v[162:163], 0, v[194:195]
	global_load_dwordx4 v[160:163], v[224:225], off nt
	v_lshl_add_u64 v[182:183], v[158:159], 0, v[240:241]
	v_lshl_add_u64 v[194:195], v[158:159], 0, v[194:195]
	v_add_u32_e32 v158, s12, v200
	v_add_u32_e32 v200, s12, v206
	v_ashrrev_i32_e32 v159, 31, v158
	v_ashrrev_i32_e32 v201, 31, v200
	v_lshlrev_b64 v[158:159], 11, v[158:159]
	v_lshlrev_b64 v[200:201], 11, v[200:201]
	v_lshl_add_u64 v[158:159], s[10:11], 0, v[158:159]
	v_lshl_add_u64 v[200:201], s[10:11], 0, v[200:201]
	v_lshl_add_u64 v[206:207], v[158:159], 0, v[156:157]
	v_lshl_add_u64 v[200:201], v[200:201], 0, v[156:157]
	s_waitcnt vmcnt(1)
	v_cvt_f32_f16_e32 v158, v234
	v_cvt_f32_f16_sdwa v159, v234 dst_sel:DWORD dst_unused:UNUSED_PAD src0_sel:WORD_1
	v_cvt_f32_f16_e32 v156, v235
	v_cvt_f32_f16_sdwa v157, v235 dst_sel:DWORD dst_unused:UNUSED_PAD src0_sel:WORD_1
	v_cvt_f32_f16_e32 v234, v232
	v_cvt_f32_f16_sdwa v235, v232 dst_sel:DWORD dst_unused:UNUSED_PAD src0_sel:WORD_1
	v_cvt_f32_f16_e32 v232, v233
	v_cvt_f32_f16_sdwa v233, v233 dst_sel:DWORD dst_unused:UNUSED_PAD src0_sel:WORD_1
	s_waitcnt vmcnt(0)
	v_cvt_f32_f16_e32 v236, v162
	v_cvt_f32_f16_sdwa v237, v162 dst_sel:DWORD dst_unused:UNUSED_PAD src0_sel:WORD_1
	v_cvt_f32_f16_e32 v238, v163
	v_cvt_f32_f16_sdwa v239, v163 dst_sel:DWORD dst_unused:UNUSED_PAD src0_sel:WORD_1
	v_cvt_f32_f16_e32 v240, v160
	v_cvt_f32_f16_sdwa v241, v160 dst_sel:DWORD dst_unused:UNUSED_PAD src0_sel:WORD_1
	v_cvt_f32_f16_e32 v242, v161
	v_cvt_f32_f16_sdwa v243, v161 dst_sel:DWORD dst_unused:UNUSED_PAD src0_sel:WORD_1
	v_pk_fma_f32 v[160:161], v[80:81], v[136:137], v[232:233]
	v_pk_fma_f32 v[162:163], v[78:79], v[134:135], v[234:235]
	v_pk_fma_f32 v[156:157], v[76:77], v[132:133], v[156:157]
	v_pk_fma_f32 v[158:159], v[74:75], v[130:131], v[158:159]
	v_pk_fma_f32 v[74:75], v[68:69], v[132:133], v[238:239]
	v_pk_fma_f32 v[76:77], v[66:67], v[130:131], v[236:237]
	v_cvt_pk_f16_f32 v69, v156, v157
	v_cvt_pk_f16_f32 v67, v160, v161
	v_cvt_pk_f16_f32 v68, v158, v159
	v_cvt_pk_f16_f32 v66, v162, v163
	v_pk_fma_f32 v[78:79], v[72:73], v[136:137], v[242:243]
	v_pk_fma_f32 v[80:81], v[70:71], v[134:135], v[240:241]
	v_pk_mul_f32 v[130:131], v[216:217], v[160:161]
	v_pk_mul_f32 v[132:133], v[218:219], v[162:163]
	v_pk_mul_f32 v[134:135], v[220:221], v[156:157]
	v_pk_mul_f32 v[136:137], v[222:223], v[158:159]
	global_store_dwordx4 v[182:183], v[66:69], off
	v_cvt_pk_f16_f32 v73, v74, v75
	v_cvt_pk_f16_f32 v71, v78, v79
	v_cvt_pk_bf16_f32 v66, v132, v133
	v_cvt_pk_bf16_f32 v67, v130, v131
	v_cvt_pk_bf16_f32 v68, v136, v137
	v_cvt_pk_bf16_f32 v69, v134, v135
	v_cvt_pk_f16_f32 v72, v76, v77
	v_cvt_pk_f16_f32 v70, v80, v81
	v_pk_mul_f32 v[216:217], v[216:217], v[78:79]
	v_pk_mul_f32 v[218:219], v[218:219], v[80:81]
	v_pk_mul_f32 v[220:221], v[220:221], v[74:75]
	v_pk_mul_f32 v[222:223], v[222:223], v[76:77]
	global_store_dwordx4 v[206:207], v[66:69], off
	global_store_dwordx4 v[194:195], v[70:73], off
	s_nop 0
	v_cvt_pk_bf16_f32 v66, v218, v219
	v_cvt_pk_bf16_f32 v67, v216, v217
	v_cvt_pk_bf16_f32 v68, v222, v223
	v_cvt_pk_bf16_f32 v69, v220, v221
	global_store_dwordx4 v[200:201], v[66:69], off
	global_load_dwordx4 v[130:133], v[172:173], off offset:512
	global_load_dwordx4 v[134:137], v[172:173], off offset:528
	s_nop 0
	global_load_dwordx4 v[172:175], v[174:175], off offset:256 nt
	s_nop 0
	global_load_dwordx4 v[216:219], v[178:179], off offset:256 nt
	v_or_b32_e32 v66, 0x80, v166
	v_ashrrev_i32_e32 v67, 31, v66
	v_lshl_add_u64 v[66:67], v[66:67], 2, s[16:17]
	global_load_dwordx4 v[220:223], v[66:67], off
	global_load_dwordx4 v[232:235], v[66:67], off offset:16
	global_load_dwordx4 v[70:73], v[176:177], off offset:512
	s_nop 0
	global_load_dwordx4 v[66:69], v[176:177], off offset:528
	s_waitcnt vmcnt(7)
	v_pk_add_f32 v[132:133], v[132:133], 1.0 op_sel_hi:[1,0]
	v_pk_add_f32 v[166:167], v[130:131], 1.0 op_sel_hi:[1,0]
	s_waitcnt vmcnt(5)
	v_cvt_f32_f16_e32 v178, v174
	v_cvt_f32_f16_sdwa v179, v174 dst_sel:DWORD dst_unused:UNUSED_PAD src0_sel:WORD_1
	v_cvt_f32_f16_e32 v174, v175
	v_cvt_f32_f16_sdwa v175, v175 dst_sel:DWORD dst_unused:UNUSED_PAD src0_sel:WORD_1
	v_cvt_f32_f16_e32 v236, v172
	v_cvt_f32_f16_sdwa v237, v172 dst_sel:DWORD dst_unused:UNUSED_PAD src0_sel:WORD_1
	v_cvt_f32_f16_e32 v172, v173
	v_cvt_f32_f16_sdwa v173, v173 dst_sel:DWORD dst_unused:UNUSED_PAD src0_sel:WORD_1
	s_waitcnt vmcnt(4)
	v_cvt_f32_f16_e32 v238, v218
	v_cvt_f32_f16_sdwa v239, v218 dst_sel:DWORD dst_unused:UNUSED_PAD src0_sel:WORD_1
	v_cvt_f32_f16_e32 v218, v219
	v_cvt_f32_f16_sdwa v219, v219 dst_sel:DWORD dst_unused:UNUSED_PAD src0_sel:WORD_1
	v_cvt_f32_f16_e32 v240, v216
	v_cvt_f32_f16_sdwa v241, v216 dst_sel:DWORD dst_unused:UNUSED_PAD src0_sel:WORD_1
	v_cvt_f32_f16_e32 v216, v217
	v_cvt_f32_f16_sdwa v217, v217 dst_sel:DWORD dst_unused:UNUSED_PAD src0_sel:WORD_1
	v_pk_add_f32 v[136:137], v[136:137], 1.0 op_sel_hi:[1,0]
	v_pk_add_f32 v[176:177], v[134:135], 1.0 op_sel_hi:[1,0]
	s_waitcnt vmcnt(3)
	v_pk_mul_f32 v[130:131], v[222:223], v[132:133]
	s_waitcnt vmcnt(1)
	v_pk_fma_f32 v[64:65], v[64:65], v[72:73], v[172:173]
	v_pk_fma_f32 v[62:63], v[62:63], v[70:71], v[236:237]
	s_waitcnt vmcnt(0)
	v_pk_fma_f32 v[60:61], v[60:61], v[68:69], v[174:175]
	v_pk_fma_f32 v[58:59], v[58:59], v[66:67], v[178:179]
	v_pk_mul_f32 v[132:133], v[220:221], v[166:167]
	v_pk_mul_f32 v[134:135], v[234:235], v[136:137]
	v_pk_mul_f32 v[136:137], v[232:233], v[176:177]
	v_cvt_pk_f16_f32 v175, v60, v61
	v_cvt_pk_f16_f32 v173, v64, v65
	v_cvt_pk_f16_f32 v174, v58, v59
	v_cvt_pk_f16_f32 v172, v62, v63
	v_pk_mul_f32 v[166:167], v[130:131], v[64:65]
	v_pk_fma_f32 v[56:57], v[56:57], v[72:73], v[216:217]
	v_pk_fma_f32 v[54:55], v[54:55], v[70:71], v[240:241]
	v_pk_fma_f32 v[52:53], v[52:53], v[68:69], v[218:219]
	v_pk_fma_f32 v[50:51], v[50:51], v[66:67], v[238:239]
	v_pk_mul_f32 v[216:217], v[132:133], v[62:63]
	v_pk_mul_f32 v[218:219], v[134:135], v[60:61]
	v_pk_mul_f32 v[220:221], v[136:137], v[58:59]
	global_store_dwordx4 v[164:165], v[172:175], off offset:256
	v_cvt_pk_bf16_f32 v164, v216, v217
	v_cvt_pk_bf16_f32 v165, v166, v167
	v_cvt_pk_bf16_f32 v166, v220, v221
	v_cvt_pk_bf16_f32 v167, v218, v219
	v_cvt_pk_f16_f32 v179, v52, v53
	v_cvt_pk_f16_f32 v177, v56, v57
	v_cvt_pk_f16_f32 v178, v50, v51
	v_cvt_pk_f16_f32 v176, v54, v55
	v_pk_mul_f32 v[222:223], v[130:131], v[56:57]
	v_pk_mul_f32 v[232:233], v[132:133], v[54:55]
	v_pk_mul_f32 v[234:235], v[134:135], v[52:53]
	v_pk_mul_f32 v[236:237], v[136:137], v[50:51]
	global_store_dwordx4 v[168:169], v[164:167], off offset:256
	global_store_dwordx4 v[180:181], v[176:179], off offset:256
	v_mul_f32_e32 v63, v63, v63
	v_cvt_pk_bf16_f32 v164, v232, v233
	v_cvt_pk_bf16_f32 v165, v222, v223
	v_cvt_pk_bf16_f32 v166, v236, v237
	v_cvt_pk_bf16_f32 v167, v234, v235
	global_store_dwordx4 v[186:187], v[164:167], off offset:256
	global_load_dwordx4 v[164:167], v[188:189], off offset:256 nt
	s_nop 0
	global_load_dwordx4 v[172:175], v[190:191], off offset:256 nt
	v_mul_f32_e32 v65, v65, v65
	v_mul_f32_e32 v59, v59, v59
	v_mul_f32_e32 v61, v61, v61
	v_fmac_f32_e32 v63, v62, v62
	v_fmac_f32_e32 v65, v64, v64
	v_fmac_f32_e32 v59, v58, v58
	v_fmac_f32_e32 v61, v60, v60
	v_add_f32_e32 v58, v63, v65
	v_add_f32_e32 v59, v59, v61
	v_add_f32_e32 v58, v58, v59
	v_add_f32_e32 v59, v122, v58
	v_xor_b32_e32 v58, 32, v231
	s_waitcnt vmcnt(1)
	v_cvt_f32_f16_e32 v168, v166
	v_cvt_f32_f16_sdwa v169, v166 dst_sel:DWORD dst_unused:UNUSED_PAD src0_sel:WORD_1
	v_cvt_f32_f16_e32 v166, v167
	v_cvt_f32_f16_sdwa v167, v167 dst_sel:DWORD dst_unused:UNUSED_PAD src0_sel:WORD_1
	v_cvt_f32_f16_e32 v176, v164
	v_cvt_f32_f16_sdwa v177, v164 dst_sel:DWORD dst_unused:UNUSED_PAD src0_sel:WORD_1
	v_cvt_f32_f16_e32 v164, v165
	v_cvt_f32_f16_sdwa v165, v165 dst_sel:DWORD dst_unused:UNUSED_PAD src0_sel:WORD_1
	s_waitcnt vmcnt(0)
	v_cvt_f32_f16_e32 v178, v174
	v_cvt_f32_f16_sdwa v179, v174 dst_sel:DWORD dst_unused:UNUSED_PAD src0_sel:WORD_1
	v_cvt_f32_f16_e32 v174, v175
	v_cvt_f32_f16_sdwa v175, v175 dst_sel:DWORD dst_unused:UNUSED_PAD src0_sel:WORD_1
	v_cvt_f32_f16_e32 v180, v172
	v_cvt_f32_f16_sdwa v181, v172 dst_sel:DWORD dst_unused:UNUSED_PAD src0_sel:WORD_1
	v_cvt_f32_f16_e32 v172, v173
	v_cvt_f32_f16_sdwa v173, v173 dst_sel:DWORD dst_unused:UNUSED_PAD src0_sel:WORD_1
	v_pk_fma_f32 v[48:49], v[48:49], v[72:73], v[164:165]
	v_pk_fma_f32 v[46:47], v[46:47], v[70:71], v[176:177]
	v_pk_fma_f32 v[44:45], v[44:45], v[68:69], v[166:167]
	v_pk_fma_f32 v[42:43], v[42:43], v[66:67], v[168:169]
	v_cvt_pk_f16_f32 v167, v44, v45
	v_cvt_pk_f16_f32 v165, v48, v49
	v_cvt_pk_f16_f32 v166, v42, v43
	v_cvt_pk_f16_f32 v164, v46, v47
	v_pk_fma_f32 v[40:41], v[40:41], v[72:73], v[172:173]
	v_pk_fma_f32 v[38:39], v[38:39], v[70:71], v[180:181]
	v_pk_fma_f32 v[36:37], v[36:37], v[68:69], v[174:175]
	v_pk_fma_f32 v[34:35], v[34:35], v[66:67], v[178:179]
	v_pk_mul_f32 v[168:169], v[130:131], v[48:49]
	v_pk_mul_f32 v[176:177], v[132:133], v[46:47]
	v_pk_mul_f32 v[178:179], v[134:135], v[44:45]
	v_pk_mul_f32 v[180:181], v[136:137], v[42:43]
	global_store_dwordx4 v[170:171], v[164:167], off offset:256
	v_cvt_pk_f16_f32 v175, v36, v37
	v_cvt_pk_f16_f32 v173, v40, v41
	v_cvt_pk_bf16_f32 v164, v176, v177
	v_cvt_pk_bf16_f32 v165, v168, v169
	v_cvt_pk_bf16_f32 v166, v180, v181
	v_cvt_pk_bf16_f32 v167, v178, v179
	v_cvt_pk_f16_f32 v174, v34, v35
	v_cvt_pk_f16_f32 v172, v38, v39
	v_pk_mul_f32 v[186:187], v[130:131], v[40:41]
	v_pk_mul_f32 v[188:189], v[132:133], v[38:39]
	v_pk_mul_f32 v[190:191], v[134:135], v[36:37]
	v_pk_mul_f32 v[216:217], v[136:137], v[34:35]
	global_store_dwordx4 v[192:193], v[164:167], off offset:256
	global_store_dwordx4 v[184:185], v[172:175], off offset:256
	s_nop 0
	v_cvt_pk_bf16_f32 v164, v188, v189
	v_cvt_pk_bf16_f32 v165, v186, v187
	v_cvt_pk_bf16_f32 v166, v216, v217
	v_cvt_pk_bf16_f32 v167, v190, v191
	global_store_dwordx4 v[196:197], v[164:167], off offset:256
	global_load_dwordx4 v[164:167], v[198:199], off offset:256 nt
	s_nop 0
	global_load_dwordx4 v[168:171], v[204:205], off offset:256 nt
	s_waitcnt vmcnt(1)
	v_cvt_f32_f16_e32 v172, v166
	v_cvt_f32_f16_sdwa v173, v166 dst_sel:DWORD dst_unused:UNUSED_PAD src0_sel:WORD_1
	v_cvt_f32_f16_e32 v166, v167
	v_cvt_f32_f16_sdwa v167, v167 dst_sel:DWORD dst_unused:UNUSED_PAD src0_sel:WORD_1
	v_cvt_f32_f16_e32 v174, v164
	v_cvt_f32_f16_sdwa v175, v164 dst_sel:DWORD dst_unused:UNUSED_PAD src0_sel:WORD_1
	v_cvt_f32_f16_e32 v164, v165
	v_cvt_f32_f16_sdwa v165, v165 dst_sel:DWORD dst_unused:UNUSED_PAD src0_sel:WORD_1
	s_waitcnt vmcnt(0)
	v_cvt_f32_f16_e32 v176, v170
	v_cvt_f32_f16_sdwa v177, v170 dst_sel:DWORD dst_unused:UNUSED_PAD src0_sel:WORD_1
	v_cvt_f32_f16_e32 v170, v171
	v_cvt_f32_f16_sdwa v171, v171 dst_sel:DWORD dst_unused:UNUSED_PAD src0_sel:WORD_1
	v_cvt_f32_f16_e32 v178, v168
	v_cvt_f32_f16_sdwa v179, v168 dst_sel:DWORD dst_unused:UNUSED_PAD src0_sel:WORD_1
	v_cvt_f32_f16_e32 v168, v169
	v_cvt_f32_f16_sdwa v169, v169 dst_sel:DWORD dst_unused:UNUSED_PAD src0_sel:WORD_1
	v_pk_fma_f32 v[32:33], v[32:33], v[72:73], v[164:165]
	v_pk_fma_f32 v[30:31], v[30:31], v[70:71], v[174:175]
	v_pk_fma_f32 v[28:29], v[28:29], v[68:69], v[166:167]
	v_pk_fma_f32 v[26:27], v[26:27], v[66:67], v[172:173]
	v_cvt_pk_f16_f32 v167, v28, v29
	v_cvt_pk_f16_f32 v165, v32, v33
	v_cvt_pk_f16_f32 v166, v26, v27
	v_cvt_pk_f16_f32 v164, v30, v31
	v_pk_fma_f32 v[24:25], v[24:25], v[72:73], v[168:169]
	v_pk_fma_f32 v[22:23], v[22:23], v[70:71], v[178:179]
	v_pk_fma_f32 v[20:21], v[20:21], v[68:69], v[170:171]
	v_pk_fma_f32 v[18:19], v[18:19], v[66:67], v[176:177]
	v_pk_mul_f32 v[172:173], v[130:131], v[32:33]
	v_pk_mul_f32 v[174:175], v[132:133], v[30:31]
	v_pk_mul_f32 v[176:177], v[134:135], v[28:29]
	v_pk_mul_f32 v[178:179], v[136:137], v[26:27]
	global_store_dwordx4 v[212:213], v[164:167], off offset:256
	v_cvt_pk_f16_f32 v171, v20, v21
	v_cvt_pk_f16_f32 v169, v24, v25
	v_cvt_pk_bf16_f32 v164, v174, v175
	v_cvt_pk_bf16_f32 v165, v172, v173
	v_cvt_pk_bf16_f32 v166, v178, v179
	v_cvt_pk_bf16_f32 v167, v176, v177
	v_cvt_pk_f16_f32 v170, v18, v19
	v_cvt_pk_f16_f32 v168, v22, v23
	v_pk_mul_f32 v[180:181], v[130:131], v[24:25]
	v_pk_mul_f32 v[184:185], v[132:133], v[22:23]
	v_pk_mul_f32 v[186:187], v[134:135], v[20:21]
	v_pk_mul_f32 v[188:189], v[136:137], v[18:19]
	global_store_dwordx4 v[214:215], v[164:167], off offset:256
	global_store_dwordx4 v[210:211], v[168:171], off offset:256
	s_nop 0
	v_cvt_pk_bf16_f32 v164, v184, v185
	v_cvt_pk_bf16_f32 v165, v180, v181
	v_cvt_pk_bf16_f32 v166, v188, v189
	v_cvt_pk_bf16_f32 v167, v186, v187
	global_store_dwordx4 v[208:209], v[164:167], off offset:256
	global_load_dwordx4 v[166:169], v[202:203], off offset:256 nt
	s_nop 0
	global_load_dwordx4 v[170:173], v[224:225], off offset:256 nt
	v_and_b32_e32 v165, 64, v231
	v_xor_b32_e32 v164, 16, v231
	v_add_u32_e32 v165, 64, v165
	v_cmp_lt_i32_e32 vcc, v164, v165
	s_waitcnt vmcnt(1)
	v_cvt_f32_f16_e32 v62, v168
	v_cndmask_b32_e32 v164, v231, v164, vcc
	v_lshlrev_b32_e32 v164, 2, v164
	ds_bpermute_b32 v60, v164, v59
	v_cmp_lt_i32_e32 vcc, v58, v165
	v_cvt_f32_f16_sdwa v63, v168 dst_sel:DWORD dst_unused:UNUSED_PAD src0_sel:WORD_1
	v_cvt_f32_f16_e32 v64, v169
	v_cndmask_b32_e32 v58, v231, v58, vcc
	v_cvt_f32_f16_sdwa v65, v169 dst_sel:DWORD dst_unused:UNUSED_PAD src0_sel:WORD_1
	v_cvt_f32_f16_e32 v122, v166
	v_cvt_f32_f16_sdwa v123, v166 dst_sel:DWORD dst_unused:UNUSED_PAD src0_sel:WORD_1
	v_cvt_f32_f16_e32 v124, v167
	v_cvt_f32_f16_sdwa v125, v167 dst_sel:DWORD dst_unused:UNUSED_PAD src0_sel:WORD_1
	v_lshlrev_b32_e32 v58, 2, v58
	s_waitcnt lgkmcnt(0)
	v_add_f32_e32 v59, v59, v60
	ds_bpermute_b32 v60, v58, v59
	s_waitcnt vmcnt(0)
	v_cvt_f32_f16_e32 v126, v172
	v_cvt_f32_f16_sdwa v127, v172 dst_sel:DWORD dst_unused:UNUSED_PAD src0_sel:WORD_1
	v_cvt_f32_f16_e32 v128, v173
	v_cvt_f32_f16_sdwa v129, v173 dst_sel:DWORD dst_unused:UNUSED_PAD src0_sel:WORD_1
	v_cvt_f32_f16_e32 v166, v170
	v_cvt_f32_f16_sdwa v167, v170 dst_sel:DWORD dst_unused:UNUSED_PAD src0_sel:WORD_1
	v_cvt_f32_f16_e32 v168, v171
	v_cvt_f32_f16_sdwa v169, v171 dst_sel:DWORD dst_unused:UNUSED_PAD src0_sel:WORD_1
	v_pk_fma_f32 v[16:17], v[16:17], v[72:73], v[124:125]
	v_pk_fma_f32 v[14:15], v[14:15], v[70:71], v[122:123]
	v_pk_fma_f32 v[12:13], v[12:13], v[68:69], v[64:65]
	v_pk_fma_f32 v[10:11], v[10:11], v[66:67], v[62:63]
	v_cvt_pk_f16_f32 v65, v12, v13
	v_cvt_pk_f16_f32 v63, v16, v17
	v_cvt_pk_f16_f32 v64, v10, v11
	v_cvt_pk_f16_f32 v62, v14, v15
	v_pk_fma_f32 v[8:9], v[8:9], v[72:73], v[168:169]
	v_pk_fma_f32 v[6:7], v[6:7], v[70:71], v[166:167]
	v_pk_fma_f32 v[4:5], v[4:5], v[68:69], v[128:129]
	v_pk_fma_f32 v[2:3], v[2:3], v[66:67], v[126:127]
	v_pk_mul_f32 v[70:71], v[130:131], v[16:17]
	v_pk_mul_f32 v[72:73], v[132:133], v[14:15]
	v_pk_mul_f32 v[122:123], v[134:135], v[12:13]
	v_pk_mul_f32 v[124:125], v[136:137], v[10:11]
	global_store_dwordx4 v[182:183], v[62:65], off offset:256
	v_cvt_pk_f16_f32 v69, v4, v5
	v_cvt_pk_f16_f32 v67, v8, v9
	v_cvt_pk_bf16_f32 v62, v72, v73
	v_cvt_pk_bf16_f32 v63, v70, v71
	v_cvt_pk_bf16_f32 v64, v124, v125
	v_cvt_pk_bf16_f32 v65, v122, v123
	v_cvt_pk_f16_f32 v68, v2, v3
	v_cvt_pk_f16_f32 v66, v6, v7
	v_pk_mul_f32 v[126:127], v[130:131], v[8:9]
	v_pk_mul_f32 v[128:129], v[132:133], v[6:7]
	v_pk_mul_f32 v[130:131], v[134:135], v[4:5]
	v_pk_mul_f32 v[132:133], v[136:137], v[2:3]
	global_store_dwordx4 v[206:207], v[62:65], off offset:256
	global_store_dwordx4 v[194:195], v[66:69], off offset:256
	s_nop 0
	v_cvt_pk_bf16_f32 v62, v128, v129
	v_cvt_pk_bf16_f32 v63, v126, v127
	v_cvt_pk_bf16_f32 v64, v132, v133
	v_cvt_pk_bf16_f32 v65, v130, v131
	global_store_dwordx4 v[200:201], v[62:65], off offset:256
	s_and_saveexec_b64 s[26:27], s[4:5]
	s_cbranch_execz .LBB0_1564
	v_lshl_add_u64 v[62:63], v[154:155], 2, s[22:23]
	s_waitcnt lgkmcnt(0)
	v_add_f32_e32 v59, v59, v60
	global_atomic_add_f32 v[62:63], v59, off

.LBB0_1605:
	s_add_u32 s9, s48, 0x100
	v_mov_b32_e32 v42, 0
	s_addc_u32 s77, s49, 0
	s_mov_b32 s12, -2
	v_mov_b32_e32 v43, v42
	v_mov_b32_e32 v44, v42
	v_mov_b32_e32 v45, v42
	v_mov_b32_e32 v46, v42
	v_mov_b32_e32 v47, v42
	v_mov_b32_e32 v48, v42
	v_mov_b32_e32 v49, v42
	v_mov_b32_e32 v2, v42
	v_mov_b32_e32 v3, v42
	v_mov_b32_e32 v4, v42
	v_mov_b32_e32 v5, v42
	v_mov_b32_e32 v6, v42
	v_mov_b32_e32 v7, v42
	v_mov_b32_e32 v8, v42
	v_mov_b32_e32 v9, v42
	v_mov_b32_e32 v66, v42
	v_mov_b32_e32 v67, v42
	v_mov_b32_e32 v68, v42
	v_mov_b32_e32 v69, v42
	v_mov_b32_e32 v78, v42
	v_mov_b32_e32 v79, v42
	v_mov_b32_e32 v80, v42
	v_mov_b32_e32 v81, v42
	v_mov_b32_e32 v18, v42
	v_mov_b32_e32 v19, v42
	v_mov_b32_e32 v20, v42
	v_mov_b32_e32 v21, v42
	v_mov_b32_e32 v22, v42
	v_mov_b32_e32 v23, v42
	v_mov_b32_e32 v24, v42
	v_mov_b32_e32 v25, v42
	v_mov_b32_e32 v98, v42
	v_mov_b32_e32 v99, v42
	v_mov_b32_e32 v100, v42
	v_mov_b32_e32 v101, v42
	v_mov_b32_e32 v102, v42
	v_mov_b32_e32 v103, v42
	v_mov_b32_e32 v104, v42
	v_mov_b32_e32 v105, v42
	v_mov_b32_e32 v10, v42
	v_mov_b32_e32 v11, v42
	v_mov_b32_e32 v12, v42
	v_mov_b32_e32 v13, v42
	v_mov_b32_e32 v14, v42
	v_mov_b32_e32 v15, v42
	v_mov_b32_e32 v16, v42
	v_mov_b32_e32 v17, v42
	v_mov_b32_e32 v114, v42
	v_mov_b32_e32 v115, v42
	v_mov_b32_e32 v116, v42
	v_mov_b32_e32 v117, v42
	v_mov_b32_e32 v118, v42
	v_mov_b32_e32 v119, v42
	v_mov_b32_e32 v120, v42
	v_mov_b32_e32 v121, v42
	v_mov_b32_e32 v26, v42
	v_mov_b32_e32 v27, v42
	v_mov_b32_e32 v28, v42
	v_mov_b32_e32 v29, v42
	v_mov_b32_e32 v30, v42
	v_mov_b32_e32 v31, v42
	v_mov_b32_e32 v32, v42
	v_mov_b32_e32 v33, v42
	v_mov_b32_e32 v82, v42
	v_mov_b32_e32 v83, v42
	v_mov_b32_e32 v84, v42
	v_mov_b32_e32 v85, v42
	v_mov_b32_e32 v86, v42
	v_mov_b32_e32 v87, v42
	v_mov_b32_e32 v88, v42
	v_mov_b32_e32 v89, v42
	v_mov_b32_e32 v34, v42
	v_mov_b32_e32 v35, v42
	v_mov_b32_e32 v36, v42
	v_mov_b32_e32 v37, v42
	v_mov_b32_e32 v38, v42
	v_mov_b32_e32 v39, v42
	v_mov_b32_e32 v40, v42
	v_mov_b32_e32 v41, v42
	v_mov_b32_e32 v90, v42
	v_mov_b32_e32 v91, v42
	v_mov_b32_e32 v92, v42
	v_mov_b32_e32 v93, v42
	v_mov_b32_e32 v94, v42
	v_mov_b32_e32 v95, v42
	v_mov_b32_e32 v96, v42
	v_mov_b32_e32 v97, v42
	v_mov_b32_e32 v58, v42
	v_mov_b32_e32 v59, v42
	v_mov_b32_e32 v60, v42
	v_mov_b32_e32 v61, v42
	v_mov_b32_e32 v62, v42
	v_mov_b32_e32 v63, v42
	v_mov_b32_e32 v64, v42
	v_mov_b32_e32 v65, v42
	v_mov_b32_e32 v122, v42
	v_mov_b32_e32 v123, v42
	v_mov_b32_e32 v124, v42
	v_mov_b32_e32 v125, v42
	v_mov_b32_e32 v126, v42
	v_mov_b32_e32 v127, v42
	v_mov_b32_e32 v128, v42
	v_mov_b32_e32 v129, v42
	v_mov_b32_e32 v50, v42
	v_mov_b32_e32 v51, v42
	v_mov_b32_e32 v52, v42
	v_mov_b32_e32 v53, v42
	v_mov_b32_e32 v54, v42
	v_mov_b32_e32 v55, v42
	v_mov_b32_e32 v56, v42
	v_mov_b32_e32 v57, v42
	v_mov_b32_e32 v130, v42
	v_mov_b32_e32 v131, v42
	v_mov_b32_e32 v132, v42
	v_mov_b32_e32 v133, v42
	v_mov_b32_e32 v134, v42
	v_mov_b32_e32 v135, v42
	v_mov_b32_e32 v136, v42
	v_mov_b32_e32 v137, v42
	v_mov_b32_e32 v70, v42
	v_mov_b32_e32 v71, v42
	v_mov_b32_e32 v72, v42
	v_mov_b32_e32 v73, v42
	v_mov_b32_e32 v74, v42
	v_mov_b32_e32 v75, v42
	v_mov_b32_e32 v76, v42
	v_mov_b32_e32 v77, v42
	v_add_u32_e32 v251, 0x80, v144
	v_add_u32_e32 v252, 0x80, v148
	v_add_u32_e32 v253, 0x80, v142
	v_add_u32_e32 v254, 0x80, v146
.LBB0_1606:
	ds_read_b128 v[106:109], v201
	ds_read_b128 v[110:113], v201 offset:1024
	ds_read_b128 v[138:141], v201 offset:2048
	ds_read_b128 v[158:161], v201 offset:3072
	ds_read_b128 v[162:165], v202
	ds_read_b128 v[166:169], v202 offset:1024
	ds_read_b128 v[170:173], v202 offset:2048
	ds_read_b128 v[174:177], v202 offset:3072
	s_add_u32 s0, s10, 0x100
	s_addc_u32 s1, s11, 0
	s_cmp_eq_u32 s12, 40
	s_cselect_b32 s51, s45, s1
	s_cselect_b32 s50, s44, s0
	s_cselect_b32 s49, s47, s77
	s_cselect_b32 s48, s46, s9
	v_lshl_add_u64 v[220:221], s[10:11], 0, v[150:151]
	s_add_i32 m0, s54, 0xc000
	ds_read_b128 v[178:181], v203
	ds_read_b128 v[182:185], v203 offset:1024
	ds_read_b128 v[186:189], v203 offset:2048
	ds_read_b128 v[190:193], v203 offset:3072
	ds_read_b128 v[194:197], v203 offset:4096
	ds_read_b128 v[208:211], v203 offset:5120
	ds_read_b128 v[212:215], v203 offset:6144
	ds_read_b128 v[216:219], v203 offset:7168
	global_load_lds_dwordx4 v[220:221], off
	v_lshl_add_u64 v[220:221], s[10:11], 0, v[152:153]
	s_add_i32 m0, s54, 0xe000
	s_nop 0
	global_load_lds_dwordx4 v[220:221], off
	s_waitcnt vmcnt(8)
	s_waitcnt lgkmcnt(0)
	s_barrier
	s_setprio 1
	s_waitcnt lgkmcnt(0)
	v_mfma_f32_16x16x32_bf16 v[74:77], v[106:109], v[178:181], v[74:77]
	v_mfma_f32_16x16x32_bf16 v[70:73], v[138:141], v[178:181], v[70:73]
	v_mfma_f32_16x16x32_bf16 v[134:137], v[106:109], v[186:189], v[134:137]
	v_mfma_f32_16x16x32_bf16 v[130:133], v[138:141], v[186:189], v[130:133]
	v_mfma_f32_16x16x32_bf16 v[54:57], v[106:109], v[194:197], v[54:57]
	v_mfma_f32_16x16x32_bf16 v[50:53], v[138:141], v[194:197], v[50:53]
	v_mfma_f32_16x16x32_bf16 v[126:129], v[106:109], v[212:215], v[126:129]
	v_mfma_f32_16x16x32_bf16 v[122:125], v[138:141], v[212:215], v[122:125]
	v_mfma_f32_16x16x32_bf16 v[74:77], v[110:113], v[182:185], v[74:77]
	v_mfma_f32_16x16x32_bf16 v[70:73], v[158:161], v[182:185], v[70:73]
	v_mfma_f32_16x16x32_bf16 v[134:137], v[110:113], v[190:193], v[134:137]
	v_mfma_f32_16x16x32_bf16 v[130:133], v[158:161], v[190:193], v[130:133]
	v_mfma_f32_16x16x32_bf16 v[54:57], v[110:113], v[208:211], v[54:57]
	v_mfma_f32_16x16x32_bf16 v[50:53], v[158:161], v[208:211], v[50:53]
	v_mfma_f32_16x16x32_bf16 v[126:129], v[110:113], v[216:219], v[126:129]
	v_mfma_f32_16x16x32_bf16 v[122:125], v[158:161], v[216:219], v[122:125]
	s_setprio 0
	s_setprio 1
	v_mfma_f32_16x16x32_bf16 v[62:65], v[162:165], v[178:181], v[62:65]
	v_mfma_f32_16x16x32_bf16 v[58:61], v[170:173], v[178:181], v[58:61]
	v_mfma_f32_16x16x32_bf16 v[94:97], v[162:165], v[186:189], v[94:97]
	v_mfma_f32_16x16x32_bf16 v[90:93], v[170:173], v[186:189], v[90:93]
	v_mfma_f32_16x16x32_bf16 v[38:41], v[162:165], v[194:197], v[38:41]
	v_mfma_f32_16x16x32_bf16 v[34:37], v[170:173], v[194:197], v[34:37]
	v_mfma_f32_16x16x32_bf16 v[86:89], v[162:165], v[212:215], v[86:89]
	v_mfma_f32_16x16x32_bf16 v[82:85], v[170:173], v[212:215], v[82:85]
	v_mfma_f32_16x16x32_bf16 v[62:65], v[166:169], v[182:185], v[62:65]
	v_mfma_f32_16x16x32_bf16 v[58:61], v[174:177], v[182:185], v[58:61]
	v_mfma_f32_16x16x32_bf16 v[94:97], v[166:169], v[190:193], v[94:97]
	v_mfma_f32_16x16x32_bf16 v[90:93], v[174:177], v[190:193], v[90:93]
	v_mfma_f32_16x16x32_bf16 v[38:41], v[166:169], v[208:211], v[38:41]
	v_mfma_f32_16x16x32_bf16 v[34:37], v[174:177], v[208:211], v[34:37]
	v_mfma_f32_16x16x32_bf16 v[86:89], v[166:169], v[216:219], v[86:89]
	v_mfma_f32_16x16x32_bf16 v[82:85], v[174:177], v[216:219], v[82:85]
	s_setprio 0
	s_barrier
	s_add_i32 s10, s70, s33
	v_lshl_add_u64 v[220:221], s[48:49], 0, v[144:145]
	s_mov_b32 m0, s10
	ds_read_b128 v[178:181], v203 offset:16384
	ds_read_b128 v[182:185], v203 offset:17408
	ds_read_b128 v[186:189], v203 offset:18432
	ds_read_b128 v[190:193], v203 offset:19456
	ds_read_b128 v[194:197], v203 offset:20480
	ds_read_b128 v[208:211], v203 offset:21504
	ds_read_b128 v[212:215], v203 offset:22528
	ds_read_b128 v[216:219], v203 offset:23552
	global_load_lds_dwordx4 v144, s[48:49]
	s_add_i32 m0, s10, 0x2000
	s_add_u32 s10, s48, 0xb0000
	v_lshl_add_u64 v[222:223], s[48:49], 0, v[148:149]
	s_addc_u32 s11, s49, 0
	s_add_i32 s13, s71, s33
	global_load_lds_dwordx4 v148, s[48:49]
	v_lshl_add_u64 v[224:225], s[10:11], 0, v[144:145]
	s_mov_b32 m0, s13
	v_lshl_add_u64 v[226:227], s[50:51], 0, v[146:147]
	global_load_lds_dwordx4 v144, s[10:11]
	v_lshl_add_u64 v[224:225], s[10:11], 0, v[148:149]
	s_add_i32 m0, s13, 0x2000
	s_nop 0
	global_load_lds_dwordx4 v148, s[10:11]
	v_lshl_add_u64 v[224:225], s[50:51], 0, v[142:143]
	s_mov_b32 m0, s54
	s_nop 0
	global_load_lds_dwordx4 v142, s[50:51]
	s_mov_b32 m0, s55
	s_nop 0
	global_load_lds_dwordx4 v146, s[50:51]
	s_waitcnt vmcnt(8)
	s_waitcnt lgkmcnt(0)
	s_barrier
	s_setprio 1
	s_waitcnt lgkmcnt(0)
	v_mfma_f32_16x16x32_bf16 v[30:33], v[106:109], v[178:181], v[30:33]
	v_mfma_f32_16x16x32_bf16 v[26:29], v[138:141], v[178:181], v[26:29]
	v_mfma_f32_16x16x32_bf16 v[118:121], v[106:109], v[186:189], v[118:121]
	v_mfma_f32_16x16x32_bf16 v[114:117], v[138:141], v[186:189], v[114:117]
	v_mfma_f32_16x16x32_bf16 v[14:17], v[106:109], v[194:197], v[14:17]
	v_mfma_f32_16x16x32_bf16 v[10:13], v[138:141], v[194:197], v[10:13]
	v_mfma_f32_16x16x32_bf16 v[102:105], v[106:109], v[212:215], v[102:105]
	v_mfma_f32_16x16x32_bf16 v[98:101], v[138:141], v[212:215], v[98:101]
	v_mfma_f32_16x16x32_bf16 v[30:33], v[110:113], v[182:185], v[30:33]
	v_mfma_f32_16x16x32_bf16 v[26:29], v[158:161], v[182:185], v[26:29]
	v_mfma_f32_16x16x32_bf16 v[118:121], v[110:113], v[190:193], v[118:121]
	v_mfma_f32_16x16x32_bf16 v[114:117], v[158:161], v[190:193], v[114:117]
	v_mfma_f32_16x16x32_bf16 v[14:17], v[110:113], v[208:211], v[14:17]
	v_mfma_f32_16x16x32_bf16 v[10:13], v[158:161], v[208:211], v[10:13]
	v_mfma_f32_16x16x32_bf16 v[102:105], v[110:113], v[216:219], v[102:105]
	v_mfma_f32_16x16x32_bf16 v[98:101], v[158:161], v[216:219], v[98:101]
	s_setprio 0
	s_setprio 1
	v_mfma_f32_16x16x32_bf16 v[22:25], v[162:165], v[178:181], v[22:25]
	v_mfma_f32_16x16x32_bf16 v[18:21], v[170:173], v[178:181], v[18:21]
	v_mfma_f32_16x16x32_bf16 v[78:81], v[162:165], v[186:189], v[78:81]
	v_mfma_f32_16x16x32_bf16 v[66:69], v[170:173], v[186:189], v[66:69]
	v_mfma_f32_16x16x32_bf16 v[6:9], v[162:165], v[194:197], v[6:9]
	v_mfma_f32_16x16x32_bf16 v[2:5], v[170:173], v[194:197], v[2:5]
	v_mfma_f32_16x16x32_bf16 v[46:49], v[162:165], v[212:215], v[46:49]
	v_mfma_f32_16x16x32_bf16 v[42:45], v[170:173], v[212:215], v[42:45]
	v_mfma_f32_16x16x32_bf16 v[22:25], v[166:169], v[182:185], v[22:25]
	v_mfma_f32_16x16x32_bf16 v[18:21], v[174:177], v[182:185], v[18:21]
	v_mfma_f32_16x16x32_bf16 v[78:81], v[166:169], v[190:193], v[78:81]
	v_mfma_f32_16x16x32_bf16 v[66:69], v[174:177], v[190:193], v[66:69]
	v_mfma_f32_16x16x32_bf16 v[6:9], v[166:169], v[208:211], v[6:9]
	v_mfma_f32_16x16x32_bf16 v[2:5], v[174:177], v[208:211], v[2:5]
	v_mfma_f32_16x16x32_bf16 v[46:49], v[166:169], v[216:219], v[46:49]
	v_mfma_f32_16x16x32_bf16 v[42:45], v[174:177], v[216:219], v[42:45]
	s_setprio 0
	s_barrier
	s_add_i32 s13, 0, 0x18000
	s_add_i32 s78, 0, 0x1c000
	v_add_u32_e32 v158, s13, v199
	v_add_u32_e32 v174, s78, v199
	ds_read_b128 v[106:109], v158
	ds_read_b128 v[110:113], v158 offset:1024
	ds_read_b128 v[138:141], v158 offset:2048
	ds_read_b128 v[158:161], v158 offset:3072
	ds_read_b128 v[162:165], v174
	ds_read_b128 v[166:169], v174 offset:1024
	ds_read_b128 v[170:173], v174 offset:2048
	ds_read_b128 v[174:177], v174 offset:3072
	s_add_u32 s10, s50, 0xb0000
	s_addc_u32 s11, s51, 0
	s_mov_b32 m0, s56
	s_nop 0
	ds_read_b128 v[178:181], v203 offset:32768
	ds_read_b128 v[182:185], v203 offset:33792
	ds_read_b128 v[186:189], v203 offset:34816
	ds_read_b128 v[190:193], v203 offset:35840
	ds_read_b128 v[194:197], v203 offset:36864
	ds_read_b128 v[208:211], v203 offset:37888
	ds_read_b128 v[212:215], v203 offset:38912
	ds_read_b128 v[216:219], v203 offset:39936
	global_load_lds_dwordx4 v142, s[10:11]
	s_nop 0
	s_mov_b32 m0, s57
	s_nop 0
	global_load_lds_dwordx4 v146, s[10:11]
	s_waitcnt vmcnt(8)
	s_waitcnt lgkmcnt(0)
	s_barrier
	s_setprio 1
	s_waitcnt lgkmcnt(0)
	v_mfma_f32_16x16x32_bf16 v[74:77], v[106:109], v[178:181], v[74:77]
	v_mfma_f32_16x16x32_bf16 v[70:73], v[138:141], v[178:181], v[70:73]
	v_mfma_f32_16x16x32_bf16 v[134:137], v[106:109], v[186:189], v[134:137]
	v_mfma_f32_16x16x32_bf16 v[130:133], v[138:141], v[186:189], v[130:133]
	v_mfma_f32_16x16x32_bf16 v[54:57], v[106:109], v[194:197], v[54:57]
	v_mfma_f32_16x16x32_bf16 v[50:53], v[138:141], v[194:197], v[50:53]
	v_mfma_f32_16x16x32_bf16 v[126:129], v[106:109], v[212:215], v[126:129]
	v_mfma_f32_16x16x32_bf16 v[122:125], v[138:141], v[212:215], v[122:125]
	v_mfma_f32_16x16x32_bf16 v[74:77], v[110:113], v[182:185], v[74:77]
	v_mfma_f32_16x16x32_bf16 v[70:73], v[158:161], v[182:185], v[70:73]
	v_mfma_f32_16x16x32_bf16 v[134:137], v[110:113], v[190:193], v[134:137]
	v_mfma_f32_16x16x32_bf16 v[130:133], v[158:161], v[190:193], v[130:133]
	v_mfma_f32_16x16x32_bf16 v[54:57], v[110:113], v[208:211], v[54:57]
	v_mfma_f32_16x16x32_bf16 v[50:53], v[158:161], v[208:211], v[50:53]
	v_mfma_f32_16x16x32_bf16 v[126:129], v[110:113], v[216:219], v[126:129]
	v_mfma_f32_16x16x32_bf16 v[122:125], v[158:161], v[216:219], v[122:125]
	s_setprio 0
	s_setprio 1
	v_mfma_f32_16x16x32_bf16 v[62:65], v[162:165], v[178:181], v[62:65]
	v_mfma_f32_16x16x32_bf16 v[58:61], v[170:173], v[178:181], v[58:61]
	v_mfma_f32_16x16x32_bf16 v[94:97], v[162:165], v[186:189], v[94:97]
	v_mfma_f32_16x16x32_bf16 v[90:93], v[170:173], v[186:189], v[90:93]
	v_mfma_f32_16x16x32_bf16 v[38:41], v[162:165], v[194:197], v[38:41]
	v_mfma_f32_16x16x32_bf16 v[34:37], v[170:173], v[194:197], v[34:37]
	v_mfma_f32_16x16x32_bf16 v[86:89], v[162:165], v[212:215], v[86:89]
	v_mfma_f32_16x16x32_bf16 v[82:85], v[170:173], v[212:215], v[82:85]
	v_mfma_f32_16x16x32_bf16 v[62:65], v[166:169], v[182:185], v[62:65]
	v_mfma_f32_16x16x32_bf16 v[58:61], v[174:177], v[182:185], v[58:61]
	v_mfma_f32_16x16x32_bf16 v[94:97], v[166:169], v[190:193], v[94:97]
	v_mfma_f32_16x16x32_bf16 v[90:93], v[174:177], v[190:193], v[90:93]
	v_mfma_f32_16x16x32_bf16 v[38:41], v[166:169], v[208:211], v[38:41]
	v_mfma_f32_16x16x32_bf16 v[34:37], v[174:177], v[208:211], v[34:37]
	v_mfma_f32_16x16x32_bf16 v[86:89], v[166:169], v[216:219], v[86:89]
	v_mfma_f32_16x16x32_bf16 v[82:85], v[174:177], v[216:219], v[82:85]
	s_setprio 0
	s_barrier
	s_add_i32 s10, s13, s33
	v_lshl_add_u64 v[220:221], v[220:221], 0, s[26:27]
	s_mov_b32 m0, s10
	ds_read_b128 v[178:181], v203 offset:49152
	ds_read_b128 v[182:185], v203 offset:50176
	ds_read_b128 v[186:189], v203 offset:51200
	ds_read_b128 v[190:193], v203 offset:52224
	ds_read_b128 v[194:197], v203 offset:53248
	ds_read_b128 v[208:211], v203 offset:54272
	ds_read_b128 v[212:215], v203 offset:55296
	ds_read_b128 v[216:219], v203 offset:56320
	global_load_lds_dwordx4 v251, s[48:49]
	s_add_i32 m0, s10, 0x2000
	s_add_u32 s10, s48, 0xb0080
	v_lshl_add_u64 v[220:221], v[222:223], 0, s[26:27]
	s_addc_u32 s11, s49, 0
	s_add_i32 s13, s78, s33
	global_load_lds_dwordx4 v252, s[48:49]
	v_lshl_add_u64 v[220:221], s[10:11], 0, v[144:145]
	s_mov_b32 m0, s13
	s_nop 0
	global_load_lds_dwordx4 v144, s[10:11]
	v_lshl_add_u64 v[220:221], s[10:11], 0, v[148:149]
	s_add_i32 m0, s13, 0x2000
	s_nop 0
	global_load_lds_dwordx4 v148, s[10:11]
	v_lshl_add_u64 v[220:221], v[224:225], 0, s[26:27]
	s_mov_b32 m0, s67
	s_nop 0
	global_load_lds_dwordx4 v253, s[50:51]
	v_lshl_add_u64 v[220:221], v[226:227], 0, s[26:27]
	s_mov_b32 m0, s68
	s_nop 0
	global_load_lds_dwordx4 v254, s[50:51]
	s_waitcnt vmcnt(8)
	s_waitcnt lgkmcnt(0)
	s_barrier
	s_setprio 1
	s_waitcnt lgkmcnt(0)
	v_mfma_f32_16x16x32_bf16 v[30:33], v[106:109], v[178:181], v[30:33]
	v_mfma_f32_16x16x32_bf16 v[26:29], v[138:141], v[178:181], v[26:29]
	v_mfma_f32_16x16x32_bf16 v[118:121], v[106:109], v[186:189], v[118:121]
	v_mfma_f32_16x16x32_bf16 v[114:117], v[138:141], v[186:189], v[114:117]
	v_mfma_f32_16x16x32_bf16 v[14:17], v[106:109], v[194:197], v[14:17]
	v_mfma_f32_16x16x32_bf16 v[10:13], v[138:141], v[194:197], v[10:13]
	v_mfma_f32_16x16x32_bf16 v[102:105], v[106:109], v[212:215], v[102:105]
	v_mfma_f32_16x16x32_bf16 v[98:101], v[138:141], v[212:215], v[98:101]
	v_mfma_f32_16x16x32_bf16 v[30:33], v[110:113], v[182:185], v[30:33]
	v_mfma_f32_16x16x32_bf16 v[26:29], v[158:161], v[182:185], v[26:29]
	v_mfma_f32_16x16x32_bf16 v[118:121], v[110:113], v[190:193], v[118:121]
	v_mfma_f32_16x16x32_bf16 v[114:117], v[158:161], v[190:193], v[114:117]
	v_mfma_f32_16x16x32_bf16 v[14:17], v[110:113], v[208:211], v[14:17]
	v_mfma_f32_16x16x32_bf16 v[10:13], v[158:161], v[208:211], v[10:13]
	v_mfma_f32_16x16x32_bf16 v[102:105], v[110:113], v[216:219], v[102:105]
	v_mfma_f32_16x16x32_bf16 v[98:101], v[158:161], v[216:219], v[98:101]
	s_setprio 0
	s_setprio 1
	v_mfma_f32_16x16x32_bf16 v[22:25], v[162:165], v[178:181], v[22:25]
	v_mfma_f32_16x16x32_bf16 v[18:21], v[170:173], v[178:181], v[18:21]
	v_mfma_f32_16x16x32_bf16 v[78:81], v[162:165], v[186:189], v[78:81]
	v_mfma_f32_16x16x32_bf16 v[66:69], v[170:173], v[186:189], v[66:69]
	v_mfma_f32_16x16x32_bf16 v[6:9], v[162:165], v[194:197], v[6:9]
	v_mfma_f32_16x16x32_bf16 v[2:5], v[170:173], v[194:197], v[2:5]
	v_mfma_f32_16x16x32_bf16 v[46:49], v[162:165], v[212:215], v[46:49]
	v_mfma_f32_16x16x32_bf16 v[42:45], v[170:173], v[212:215], v[42:45]
	v_mfma_f32_16x16x32_bf16 v[22:25], v[166:169], v[182:185], v[22:25]
	v_mfma_f32_16x16x32_bf16 v[18:21], v[174:177], v[182:185], v[18:21]
	v_mfma_f32_16x16x32_bf16 v[78:81], v[166:169], v[190:193], v[78:81]
	v_mfma_f32_16x16x32_bf16 v[66:69], v[174:177], v[190:193], v[66:69]
	v_mfma_f32_16x16x32_bf16 v[6:9], v[166:169], v[208:211], v[6:9]
	v_mfma_f32_16x16x32_bf16 v[2:5], v[174:177], v[208:211], v[2:5]
	v_mfma_f32_16x16x32_bf16 v[46:49], v[166:169], v[216:219], v[46:49]
	v_mfma_f32_16x16x32_bf16 v[42:45], v[174:177], v[216:219], v[42:45]
	s_setprio 0
	s_barrier
	s_add_i32 s12, s12, 2
	s_add_u32 s9, s9, 0x100
	s_addc_u32 s77, s77, 0
	s_cmp_gt_u32 s12, 41
	s_mov_b64 s[10:11], s[0:1]
	s_cbranch_scc0 .LBB0_1606
	s_and_b64 vcc, exec, s[28:29]
	s_cbranch_vccz .LBB0_1609
	s_barrier
